# GEMM K-loops: LDS-DMA addresses via SGPR base + 32-bit lane offset (saddr) instead of 64-bit VALU adds
# speedup vs baseline: 1.0069x; 1.0069x over previous
; #define PG8_STAGE(bufoff, gbase, voff) do { _Pragma("unroll") for (int _i = 0; _i < 2; ++_i) \
;         __builtin_amdgcn_global_load_lds((const unsigned*)((const char*)(gbase) + (voff)[_i]), (PG8_LAS unsigned*)(lds + (bufoff) + ldsw + _i * 8192), 16, 0, 0); } while (0)
; #define PG8_LDA(dst, b, h) do { _Pragma("unroll") for (int m = 0; m < 4; ++m) _Pragma("unroll") for (int k = 0; k < 2; ++k) dst[m][k] = *(const PG8_LAS bf16x8*)(lds + PG8_SA(b, h) + aoff + m * 2048 + k * 1024); } while (0)
; #define PG8_LDB(dst, b, h) do { _Pragma("unroll") for (int n = 0; n < 2; ++n) _Pragma("unroll") for (int k = 0; k < 2; ++k) dst[n][k] = *(const PG8_LAS bf16x8*)(lds + PG8_SB(b, h) + boff + n * 2048 + k * 1024); } while (0)
; #define PG8_WAIT_V(n) asm volatile("s_waitcnt vmcnt(" #n ")" ::: "memory")
; #define PG8_WAIT_L(n) asm volatile("s_waitcnt lgkmcnt(" #n ")" ::: "memory")
; #define PG8_BAR __builtin_amdgcn_s_barrier()
; #define PG8_SCHED __builtin_amdgcn_sched_barrier(0)
; template <class Epi, class Sched, bool ALIGN_EPI = false, bool SP2 = false>
; __device__ __forceinline__ void gemm_phase(PG8_LAS unsigned char* lds, const Gemm g, const Sched& S, const Epi& E) {
;     ...
;         const bool has_next = S.next(ui + 1, nxt);
;         const char* nA = has_next ? (const char*)g.A + (size_t)nxt.pm * tstep : cA; const char* nB = has_next ? (const char*)g.Bt + (size_t)nxt.pn * tstep : cB;
;         for (int t = 0; t < nt; t += 2) {
;             const bool last = (t == nt - 2);
;             const char* a1 = cA + (size_t)(t + 1) * kstep;
;             const char* a2 = last ? nA : cA + (size_t)(t + 2) * kstep; const char* b2 = last ? nB : cB + (size_t)(t + 2) * kstep;
;             const char* a3 = a2 + kstep; const char* b3 = b2 + kstep;
;             if (last && has_next) S.a_ready(nxt);
;             if constexpr (SP2) {
;             PG8_LDB(B0, 0, 0); PG8_LDB(B1, 0, 1); PG8_SCHED; PG8_LDA(At, 0, 0); PG8_STAGE(PG8_SA(1, 1), a1 + hstep, voffA);
;             PG8_WAIT_V(8); PG8_WAIT_L(0); PG8_BAR; PG8_MMA(0, 0, At, B0); PG8_MMA(0, 1, At, B1); PG8_BAR; PG8_SCHED;
;             PG8_LDA(At, 0, 1); PG8_STAGE(PG8_SB(0, 0), b2, voffB); PG8_STAGE(PG8_SB(0, 1), b2 + hstep, voffB); PG8_STAGE(PG8_SA(0, 0), a2, voffA);
;             PG8_WAIT_V(8); PG8_WAIT_L(0); PG8_BAR; PG8_MMA(1, 0, At, B0); PG8_MMA(1, 1, At, B1); PG8_BAR; PG8_SCHED;
.LBB0_223:
	s_ashr_i32 s15, s14, 31
	s_lshl_b64 s[16:17], s[14:15], 19
	s_add_u32 s16, s36, s16
	s_addc_u32 s17, s37, s17
	s_and_b64 s[18:19], s[4:5], exec
	s_cselect_b32 s15, s17, s21
	s_cselect_b32 s68, s16, s20
	s_ashr_i32 s13, s12, 31
	s_lshl_b64 s[18:19], s[12:13], 19
	s_add_u32 s18, s53, s18
	s_addc_u32 s19, s54, s19
	s_and_b64 s[46:47], s[4:5], exec
	s_cselect_b32 s13, s19, s43
	s_cselect_b32 s69, s18, s42
	s_add_u32 s20, s20, 0x40080
	s_addc_u32 s21, s21, 0
	s_add_u32 s70, s42, 0x100
	s_addc_u32 s71, s43, 0
	s_mov_b32 s72, -2
	ds_read_b128 v[154:157], v150
	ds_read_b128 v[158:161], v150 offset:1024
	ds_read_b128 v[162:165], v150 offset:2048
	ds_read_b128 v[166:169], v150 offset:3072
	ds_read_b128 v[170:173], v151
	ds_read_b128 v[174:177], v151 offset:1024
	ds_read_b128 v[178:181], v151 offset:2048
	ds_read_b128 v[182:185], v151 offset:3072
	s_add_u32 s42, s20, 0xfffc0080
	s_addc_u32 s43, s21, -1
	s_cmp_eq_u32 s72, 12
	s_cselect_b32 s47, s15, s43
	s_cselect_b32 s46, s68, s42
	s_cselect_b32 s43, s13, s71
	s_cselect_b32 s42, s69, s70
	s_add_i32 m0, s35, 0xc000
	ds_read_b128 v[186:189], v152
	ds_read_b128 v[190:193], v152 offset:1024
	ds_read_b128 v[198:201], v152 offset:2048
	ds_read_b128 v[202:205], v152 offset:3072
	ds_read_b128 v[206:209], v152 offset:4096
	ds_read_b128 v[210:213], v152 offset:5120
	ds_read_b128 v[214:217], v152 offset:6144
	ds_read_b128 v[218:221], v152 offset:7168
	global_load_lds_dwordx4 v136, s[20:21]
	s_add_i32 m0, s35, 0xe000
	s_nop 0
	global_load_lds_dwordx4 v138, s[20:21]
	s_waitcnt vmcnt(8)
	s_waitcnt lgkmcnt(0)
	s_barrier
	s_setprio 1
	s_waitcnt lgkmcnt(0)
	v_mfma_f32_16x16x32_bf16 v[124:127], v[154:157], v[186:189], 0
	v_mfma_f32_16x16x32_bf16 v[116:119], v[162:165], v[186:189], 0
	v_mfma_f32_16x16x32_bf16 v[108:111], v[154:157], v[198:201], 0
	v_mfma_f32_16x16x32_bf16 v[100:103], v[162:165], v[198:201], 0
	v_mfma_f32_16x16x32_bf16 v[92:95], v[154:157], v[206:209], 0
	v_mfma_f32_16x16x32_bf16 v[84:87], v[162:165], v[206:209], 0
	v_mfma_f32_16x16x32_bf16 v[76:79], v[154:157], v[214:217], 0
	v_mfma_f32_16x16x32_bf16 v[68:71], v[162:165], v[214:217], 0
	v_mfma_f32_16x16x32_bf16 v[124:127], v[158:161], v[190:193], v[124:127]
	v_mfma_f32_16x16x32_bf16 v[116:119], v[166:169], v[190:193], v[116:119]
	v_mfma_f32_16x16x32_bf16 v[108:111], v[158:161], v[202:205], v[108:111]
	v_mfma_f32_16x16x32_bf16 v[100:103], v[166:169], v[202:205], v[100:103]
	v_mfma_f32_16x16x32_bf16 v[92:95], v[158:161], v[210:213], v[92:95]
	v_mfma_f32_16x16x32_bf16 v[84:87], v[166:169], v[210:213], v[84:87]
	v_mfma_f32_16x16x32_bf16 v[76:79], v[158:161], v[218:221], v[76:79]
	v_mfma_f32_16x16x32_bf16 v[68:71], v[166:169], v[218:221], v[68:71]
	v_mfma_f32_16x16x32_bf16 v[120:123], v[170:173], v[186:189], 0
	v_mfma_f32_16x16x32_bf16 v[112:115], v[178:181], v[186:189], 0
	v_mfma_f32_16x16x32_bf16 v[104:107], v[170:173], v[198:201], 0
	v_mfma_f32_16x16x32_bf16 v[96:99], v[178:181], v[198:201], 0
	v_mfma_f32_16x16x32_bf16 v[88:91], v[170:173], v[206:209], 0
	v_mfma_f32_16x16x32_bf16 v[80:83], v[178:181], v[206:209], 0
	v_mfma_f32_16x16x32_bf16 v[72:75], v[170:173], v[214:217], 0
	v_mfma_f32_16x16x32_bf16 v[64:67], v[178:181], v[214:217], 0
	v_mfma_f32_16x16x32_bf16 v[120:123], v[174:177], v[190:193], v[120:123]
	v_mfma_f32_16x16x32_bf16 v[112:115], v[182:185], v[190:193], v[112:115]
	v_mfma_f32_16x16x32_bf16 v[104:107], v[174:177], v[202:205], v[104:107]
	v_mfma_f32_16x16x32_bf16 v[96:99], v[182:185], v[202:205], v[96:99]
	v_mfma_f32_16x16x32_bf16 v[88:91], v[174:177], v[210:213], v[88:91]
	v_mfma_f32_16x16x32_bf16 v[80:83], v[182:185], v[210:213], v[80:83]
	v_mfma_f32_16x16x32_bf16 v[72:75], v[174:177], v[218:221], v[72:75]
	v_mfma_f32_16x16x32_bf16 v[64:67], v[182:185], v[218:221], v[64:67]
	s_setprio 0
	s_barrier
	s_add_i32 s73, s63, s55
	s_add_u32 s98, s42, s8
	s_addc_u32 s99, s43, s9
	s_add_u32 s100, s46, s8
	s_addc_u32 s101, s47, s9
	s_mov_b32 m0, s73
	ds_read_b128 v[186:189], v152 offset:16384
	ds_read_b128 v[190:193], v152 offset:17408
	ds_read_b128 v[198:201], v152 offset:18432
	ds_read_b128 v[202:205], v152 offset:19456
	ds_read_b128 v[206:209], v152 offset:20480
	ds_read_b128 v[210:213], v152 offset:21504
	ds_read_b128 v[214:217], v152 offset:22528
	ds_read_b128 v[218:221], v152 offset:23552
	global_load_lds_dwordx4 v132, s[42:43]
	s_add_i32 m0, s73, 0x2000
	s_add_u32 s74, s42, 0x40000
	s_addc_u32 s75, s43, 0
	s_add_i32 s73, s64, s55
	global_load_lds_dwordx4 v128, s[42:43]
	s_mov_b32 m0, s73
	s_nop 0
	global_load_lds_dwordx4 v132, s[74:75]
	s_add_i32 m0, s73, 0x2000
	s_nop 0
	global_load_lds_dwordx4 v128, s[74:75]
	s_mov_b32 m0, s35
	s_nop 0
	global_load_lds_dwordx4 v134, s[46:47]
	s_mov_b32 m0, s57
	s_nop 0
	global_load_lds_dwordx4 v130, s[46:47]
	s_waitcnt vmcnt(8)
	s_waitcnt lgkmcnt(0)
	s_barrier
; #define PG8_STAGE(bufoff, gbase, voff) do { _Pragma("unroll") for (int _i = 0; _i < 2; ++_i) \
;         __builtin_amdgcn_global_load_lds((const unsigned*)((const char*)(gbase) + (voff)[_i]), (PG8_LAS unsigned*)(lds + (bufoff) + ldsw + _i * 8192), 16, 0, 0); } while (0)
; #define PG8_LDA(dst, b, h) do { _Pragma("unroll") for (int m = 0; m < 4; ++m) _Pragma("unroll") for (int k = 0; k < 2; ++k) dst[m][k] = *(const PG8_LAS bf16x8*)(lds + PG8_SA(b, h) + aoff + m * 2048 + k * 1024); } while (0)
; #define PG8_LDB(dst, b, h) do { _Pragma("unroll") for (int n = 0; n < 2; ++n) _Pragma("unroll") for (int k = 0; k < 2; ++k) dst[n][k] = *(const PG8_LAS bf16x8*)(lds + PG8_SB(b, h) + boff + n * 2048 + k * 1024); } while (0)
; #define PG8_MMA(ai, bj, At, Bt) do { __builtin_amdgcn_s_setprio(1); _Pragma("unroll") for (int m = 0; m < 4; ++m) _Pragma("unroll") for (int n = 0; n < 2; ++n) _Pragma("unroll") for (int k = 0; k < 2; ++k) \
;         acc[ai][bj][m][n] = __builtin_amdgcn_mfma_f32_16x16x32_bf16(Bt[n][k], At[m][k], acc[ai][bj][m][n], 0, 0, 0); __builtin_amdgcn_s_setprio(0); } while (0)
; #define PG8_WAIT_V(n) asm volatile("s_waitcnt vmcnt(" #n ")" ::: "memory")
; #define PG8_WAIT_L(n) asm volatile("s_waitcnt lgkmcnt(" #n ")" ::: "memory")
; #define PG8_BAR __builtin_amdgcn_s_barrier()
; #define PG8_SCHED __builtin_amdgcn_sched_barrier(0)
; template <class Epi, class Sched, bool ALIGN_EPI = false, bool SP2 = false>
; __device__ __forceinline__ void gemm_phase(PG8_LAS unsigned char* lds, const Gemm g, const Sched& S, const Epi& E) {
;     ...
;             PG8_WAIT_V(8); PG8_WAIT_L(0); PG8_BAR; PG8_MMA(1, 0, At, B0); PG8_MMA(1, 1, At, B1); PG8_BAR; PG8_SCHED;
;             PG8_LDB(B0, 1, 0); PG8_LDB(B1, 1, 1); PG8_SCHED; PG8_LDA(At, 1, 0); PG8_STAGE(PG8_SA(0, 1), a2 + hstep, voffA);
;             PG8_WAIT_V(8); PG8_WAIT_L(0); PG8_BAR; PG8_MMA(0, 0, At, B0); PG8_MMA(0, 1, At, B1); PG8_BAR; PG8_SCHED;
	s_setprio 1
	s_waitcnt lgkmcnt(0)
	v_mfma_f32_16x16x32_bf16 v[60:63], v[154:157], v[186:189], 0
	v_mfma_f32_16x16x32_bf16 v[52:55], v[162:165], v[186:189], 0
	v_mfma_f32_16x16x32_bf16 v[44:47], v[154:157], v[198:201], 0
	v_mfma_f32_16x16x32_bf16 v[36:39], v[162:165], v[198:201], 0
	v_mfma_f32_16x16x32_bf16 v[28:31], v[154:157], v[206:209], 0
	v_mfma_f32_16x16x32_bf16 v[20:23], v[162:165], v[206:209], 0
	v_mfma_f32_16x16x32_bf16 v[12:15], v[154:157], v[214:217], 0
	v_mfma_f32_16x16x32_bf16 v[4:7], v[162:165], v[214:217], 0
	v_mfma_f32_16x16x32_bf16 v[60:63], v[158:161], v[190:193], v[60:63]
	v_mfma_f32_16x16x32_bf16 v[52:55], v[166:169], v[190:193], v[52:55]
	v_mfma_f32_16x16x32_bf16 v[44:47], v[158:161], v[202:205], v[44:47]
	v_mfma_f32_16x16x32_bf16 v[36:39], v[166:169], v[202:205], v[36:39]
	v_mfma_f32_16x16x32_bf16 v[28:31], v[158:161], v[210:213], v[28:31]
	v_mfma_f32_16x16x32_bf16 v[20:23], v[166:169], v[210:213], v[20:23]
	v_mfma_f32_16x16x32_bf16 v[12:15], v[158:161], v[218:221], v[12:15]
	v_mfma_f32_16x16x32_bf16 v[4:7], v[166:169], v[218:221], v[4:7]
	v_mfma_f32_16x16x32_bf16 v[56:59], v[170:173], v[186:189], 0
	v_mfma_f32_16x16x32_bf16 v[48:51], v[178:181], v[186:189], 0
	v_mfma_f32_16x16x32_bf16 v[40:43], v[170:173], v[198:201], 0
	v_mfma_f32_16x16x32_bf16 v[32:35], v[178:181], v[198:201], 0
	v_mfma_f32_16x16x32_bf16 v[24:27], v[170:173], v[206:209], 0
	v_mfma_f32_16x16x32_bf16 v[16:19], v[178:181], v[206:209], 0
	v_mfma_f32_16x16x32_bf16 v[8:11], v[170:173], v[214:217], 0
	v_mfma_f32_16x16x32_bf16 v[0:3], v[178:181], v[214:217], 0
	v_mfma_f32_16x16x32_bf16 v[56:59], v[174:177], v[190:193], v[56:59]
	v_mfma_f32_16x16x32_bf16 v[48:51], v[182:185], v[190:193], v[48:51]
	v_mfma_f32_16x16x32_bf16 v[40:43], v[174:177], v[202:205], v[40:43]
	v_mfma_f32_16x16x32_bf16 v[32:35], v[182:185], v[202:205], v[32:35]
	v_mfma_f32_16x16x32_bf16 v[24:27], v[174:177], v[210:213], v[24:27]
	v_mfma_f32_16x16x32_bf16 v[16:19], v[182:185], v[210:213], v[16:19]
	v_mfma_f32_16x16x32_bf16 v[8:11], v[174:177], v[218:221], v[8:11]
	v_mfma_f32_16x16x32_bf16 v[0:3], v[182:185], v[218:221], v[0:3]
	s_setprio 0
	s_barrier
	s_add_i32 s73, 0, 0x18000
	v_add_u32_e32 v153, s73, v147
	s_add_i32 s74, 0, 0x1c000
	ds_read_b128 v[154:157], v153
	ds_read_b128 v[158:161], v153 offset:1024
	ds_read_b128 v[162:165], v153 offset:2048
	ds_read_b128 v[166:169], v153 offset:3072
	v_add_u32_e32 v153, s74, v147
	ds_read_b128 v[170:173], v153
	ds_read_b128 v[174:177], v153 offset:1024
	ds_read_b128 v[178:181], v153 offset:2048
	ds_read_b128 v[182:185], v153 offset:3072
	s_add_u32 s46, s46, 0x40000
	s_addc_u32 s47, s47, 0
	s_mov_b32 m0, s58
	ds_read_b128 v[186:189], v152 offset:32768
	ds_read_b128 v[190:193], v152 offset:33792
	ds_read_b128 v[198:201], v152 offset:34816
	ds_read_b128 v[202:205], v152 offset:35840
	ds_read_b128 v[206:209], v152 offset:36864
	ds_read_b128 v[210:213], v152 offset:37888
	ds_read_b128 v[214:217], v152 offset:38912
	ds_read_b128 v[218:221], v152 offset:39936
	global_load_lds_dwordx4 v134, s[46:47]
	s_mov_b32 m0, s59
	s_nop 0
	global_load_lds_dwordx4 v130, s[46:47]
	s_waitcnt vmcnt(8)
	s_waitcnt lgkmcnt(0)
	s_barrier
	s_setprio 1
	s_waitcnt lgkmcnt(0)
	v_mfma_f32_16x16x32_bf16 v[124:127], v[154:157], v[186:189], v[124:127]
	v_mfma_f32_16x16x32_bf16 v[116:119], v[162:165], v[186:189], v[116:119]
	v_mfma_f32_16x16x32_bf16 v[108:111], v[154:157], v[198:201], v[108:111]
	v_mfma_f32_16x16x32_bf16 v[100:103], v[162:165], v[198:201], v[100:103]
	v_mfma_f32_16x16x32_bf16 v[92:95], v[154:157], v[206:209], v[92:95]
	v_mfma_f32_16x16x32_bf16 v[84:87], v[162:165], v[206:209], v[84:87]
	v_mfma_f32_16x16x32_bf16 v[76:79], v[154:157], v[214:217], v[76:79]
	v_mfma_f32_16x16x32_bf16 v[68:71], v[162:165], v[214:217], v[68:71]
	v_mfma_f32_16x16x32_bf16 v[124:127], v[158:161], v[190:193], v[124:127]
	v_mfma_f32_16x16x32_bf16 v[116:119], v[166:169], v[190:193], v[116:119]
	v_mfma_f32_16x16x32_bf16 v[108:111], v[158:161], v[202:205], v[108:111]
	v_mfma_f32_16x16x32_bf16 v[100:103], v[166:169], v[202:205], v[100:103]
	v_mfma_f32_16x16x32_bf16 v[92:95], v[158:161], v[210:213], v[92:95]
	v_mfma_f32_16x16x32_bf16 v[84:87], v[166:169], v[210:213], v[84:87]
	v_mfma_f32_16x16x32_bf16 v[76:79], v[158:161], v[218:221], v[76:79]
	v_mfma_f32_16x16x32_bf16 v[68:71], v[166:169], v[218:221], v[68:71]
	v_mfma_f32_16x16x32_bf16 v[120:123], v[170:173], v[186:189], v[120:123]
	v_mfma_f32_16x16x32_bf16 v[112:115], v[178:181], v[186:189], v[112:115]
	v_mfma_f32_16x16x32_bf16 v[104:107], v[170:173], v[198:201], v[104:107]
	v_mfma_f32_16x16x32_bf16 v[96:99], v[178:181], v[198:201], v[96:99]
	v_mfma_f32_16x16x32_bf16 v[88:91], v[170:173], v[206:209], v[88:91]
	v_mfma_f32_16x16x32_bf16 v[80:83], v[178:181], v[206:209], v[80:83]
	v_mfma_f32_16x16x32_bf16 v[72:75], v[170:173], v[214:217], v[72:75]
	v_mfma_f32_16x16x32_bf16 v[64:67], v[178:181], v[214:217], v[64:67]
	v_mfma_f32_16x16x32_bf16 v[120:123], v[174:177], v[190:193], v[120:123]
	v_mfma_f32_16x16x32_bf16 v[112:115], v[182:185], v[190:193], v[112:115]
	v_mfma_f32_16x16x32_bf16 v[104:107], v[174:177], v[202:205], v[104:107]
	v_mfma_f32_16x16x32_bf16 v[96:99], v[182:185], v[202:205], v[96:99]
	v_mfma_f32_16x16x32_bf16 v[88:91], v[174:177], v[210:213], v[88:91]
	v_mfma_f32_16x16x32_bf16 v[80:83], v[182:185], v[210:213], v[80:83]
	v_mfma_f32_16x16x32_bf16 v[72:75], v[174:177], v[218:221], v[72:75]
	v_mfma_f32_16x16x32_bf16 v[64:67], v[182:185], v[218:221], v[64:67]
	s_setprio 0
	s_barrier
; #define PG8_STAGE(bufoff, gbase, voff) do { _Pragma("unroll") for (int _i = 0; _i < 2; ++_i) \
;         __builtin_amdgcn_global_load_lds((const unsigned*)((const char*)(gbase) + (voff)[_i]), (PG8_LAS unsigned*)(lds + (bufoff) + ldsw + _i * 8192), 16, 0, 0); } while (0)
; #define PG8_LDA(dst, b, h) do { _Pragma("unroll") for (int m = 0; m < 4; ++m) _Pragma("unroll") for (int k = 0; k < 2; ++k) dst[m][k] = *(const PG8_LAS bf16x8*)(lds + PG8_SA(b, h) + aoff + m * 2048 + k * 1024); } while (0)
; #define PG8_LDB(dst, b, h) do { _Pragma("unroll") for (int n = 0; n < 2; ++n) _Pragma("unroll") for (int k = 0; k < 2; ++k) dst[n][k] = *(const PG8_LAS bf16x8*)(lds + PG8_SB(b, h) + boff + n * 2048 + k * 1024); } while (0)
; #define PG8_WAIT_V(n) asm volatile("s_waitcnt vmcnt(" #n ")" ::: "memory")
; #define PG8_BAR __builtin_amdgcn_s_barrier()
; template <class Epi, class Sched, bool ALIGN_EPI = false, bool SP2 = false>
; __device__ __forceinline__ void gemm_phase(PG8_LAS unsigned char* lds, const Gemm g, const Sched& S, const Epi& E) {
;     ...
;         for (int t = 0; t < nt; t += 2) {
;             const bool last = (t == nt - 2);
;             const char* a1 = cA + (size_t)(t + 1) * kstep;
;             const char* a2 = last ? nA : cA + (size_t)(t + 2) * kstep; const char* b2 = last ? nB : cB + (size_t)(t + 2) * kstep;
;             const char* a3 = a2 + kstep; const char* b3 = b2 + kstep;
;             if (last && has_next) S.a_ready(nxt);
;             if constexpr (SP2) {
;             PG8_LDB(B0, 0, 0); PG8_LDB(B1, 0, 1); PG8_SCHED; PG8_LDA(At, 0, 0); PG8_STAGE(PG8_SA(1, 1), a1 + hstep, voffA);
;             PG8_WAIT_V(8); PG8_WAIT_L(0); PG8_BAR; PG8_MMA(0, 0, At, B0); PG8_MMA(0, 1, At, B1); PG8_BAR; PG8_SCHED;
;             PG8_LDA(At, 0, 1); PG8_STAGE(PG8_SB(0, 0), b2, voffB); PG8_STAGE(PG8_SB(0, 1), b2 + hstep, voffB); PG8_STAGE(PG8_SA(0, 0), a2, voffA);
;             PG8_WAIT_V(8); PG8_WAIT_L(0); PG8_BAR; PG8_MMA(1, 0, At, B0); PG8_MMA(1, 1, At, B1); PG8_BAR; PG8_SCHED;
;     ...
;             PG8_WAIT_V(8); PG8_WAIT_L(0); PG8_BAR; PG8_MMA(0, 0, At, B0); PG8_MMA(0, 1, At, B1); PG8_BAR; PG8_SCHED;
;             PG8_LDA(At, 1, 1); PG8_STAGE(PG8_SB(1, 0), b3, voffB); PG8_STAGE(PG8_SB(1, 1), b3 + hstep, voffB); PG8_STAGE(PG8_SA(1, 0), a3, voffA);
;             PG8_WAIT_V(8); PG8_WAIT_L(0); PG8_BAR; PG8_MMA(1, 0, At, B0); PG8_MMA(1, 1, At, B1); PG8_BAR; PG8_SCHED;
	s_add_i32 s46, s73, s55
	s_mov_b32 m0, s46
	ds_read_b128 v[186:189], v152 offset:49152
	ds_read_b128 v[190:193], v152 offset:50176
	ds_read_b128 v[198:201], v152 offset:51200
	ds_read_b128 v[202:205], v152 offset:52224
	ds_read_b128 v[206:209], v152 offset:53248
	ds_read_b128 v[210:213], v152 offset:54272
	ds_read_b128 v[214:217], v152 offset:55296
	ds_read_b128 v[218:221], v152 offset:56320
	global_load_lds_dwordx4 v132, s[98:99]
	s_add_i32 m0, s46, 0x2000
	s_add_u32 s42, s42, 0x40080
	s_addc_u32 s43, s43, 0
	s_add_i32 s46, s74, s55
	global_load_lds_dwordx4 v128, s[98:99]
	s_mov_b32 m0, s46
	s_nop 0
	global_load_lds_dwordx4 v132, s[42:43]
	s_add_i32 m0, s46, 0x2000
	s_nop 0
	global_load_lds_dwordx4 v128, s[42:43]
	s_mov_b32 m0, s61
	s_nop 0
	global_load_lds_dwordx4 v134, s[100:101]
	s_mov_b32 m0, s62
	s_nop 0
	global_load_lds_dwordx4 v130, s[100:101]
	s_waitcnt vmcnt(8)
	s_waitcnt lgkmcnt(0)
	s_barrier
	s_setprio 1
	s_waitcnt lgkmcnt(0)
	v_mfma_f32_16x16x32_bf16 v[60:63], v[154:157], v[186:189], v[60:63]
	v_mfma_f32_16x16x32_bf16 v[52:55], v[162:165], v[186:189], v[52:55]
	v_mfma_f32_16x16x32_bf16 v[44:47], v[154:157], v[198:201], v[44:47]
	v_mfma_f32_16x16x32_bf16 v[36:39], v[162:165], v[198:201], v[36:39]
	v_mfma_f32_16x16x32_bf16 v[28:31], v[154:157], v[206:209], v[28:31]
	v_mfma_f32_16x16x32_bf16 v[20:23], v[162:165], v[206:209], v[20:23]
	v_mfma_f32_16x16x32_bf16 v[12:15], v[154:157], v[214:217], v[12:15]
	v_mfma_f32_16x16x32_bf16 v[4:7], v[162:165], v[214:217], v[4:7]
	v_mfma_f32_16x16x32_bf16 v[60:63], v[158:161], v[190:193], v[60:63]
	v_mfma_f32_16x16x32_bf16 v[52:55], v[166:169], v[190:193], v[52:55]
	v_mfma_f32_16x16x32_bf16 v[44:47], v[158:161], v[202:205], v[44:47]
	v_mfma_f32_16x16x32_bf16 v[36:39], v[166:169], v[202:205], v[36:39]
	v_mfma_f32_16x16x32_bf16 v[28:31], v[158:161], v[210:213], v[28:31]
	v_mfma_f32_16x16x32_bf16 v[20:23], v[166:169], v[210:213], v[20:23]
	v_mfma_f32_16x16x32_bf16 v[12:15], v[158:161], v[218:221], v[12:15]
	v_mfma_f32_16x16x32_bf16 v[4:7], v[166:169], v[218:221], v[4:7]
	v_mfma_f32_16x16x32_bf16 v[56:59], v[170:173], v[186:189], v[56:59]
	v_mfma_f32_16x16x32_bf16 v[48:51], v[178:181], v[186:189], v[48:51]
	v_mfma_f32_16x16x32_bf16 v[40:43], v[170:173], v[198:201], v[40:43]
	v_mfma_f32_16x16x32_bf16 v[32:35], v[178:181], v[198:201], v[32:35]
	v_mfma_f32_16x16x32_bf16 v[24:27], v[170:173], v[206:209], v[24:27]
	v_mfma_f32_16x16x32_bf16 v[16:19], v[178:181], v[206:209], v[16:19]
	v_mfma_f32_16x16x32_bf16 v[8:11], v[170:173], v[214:217], v[8:11]
	v_mfma_f32_16x16x32_bf16 v[0:3], v[178:181], v[214:217], v[0:3]
	v_mfma_f32_16x16x32_bf16 v[56:59], v[174:177], v[190:193], v[56:59]
	v_mfma_f32_16x16x32_bf16 v[48:51], v[182:185], v[190:193], v[48:51]
	v_mfma_f32_16x16x32_bf16 v[40:43], v[174:177], v[202:205], v[40:43]
	v_mfma_f32_16x16x32_bf16 v[32:35], v[182:185], v[202:205], v[32:35]
	v_mfma_f32_16x16x32_bf16 v[24:27], v[174:177], v[210:213], v[24:27]
	v_mfma_f32_16x16x32_bf16 v[16:19], v[182:185], v[210:213], v[16:19]
	v_mfma_f32_16x16x32_bf16 v[8:11], v[174:177], v[218:221], v[8:11]
	v_mfma_f32_16x16x32_bf16 v[0:3], v[182:185], v[218:221], v[0:3]
	s_setprio 0
	s_barrier
	s_add_i32 s72, s72, 2
	s_add_u32 s20, s20, 0x100
	s_addc_u32 s21, s21, 0
	s_add_u32 s70, s70, 0x100
	s_addc_u32 s71, s71, 0
	s_cmp_gt_u32 s72, 13
.LBB0_224:
	ds_read_b128 v[154:157], v150
	ds_read_b128 v[158:161], v150 offset:1024
	ds_read_b128 v[162:165], v150 offset:2048
	ds_read_b128 v[166:169], v150 offset:3072
	ds_read_b128 v[170:173], v151
	ds_read_b128 v[174:177], v151 offset:1024
	ds_read_b128 v[178:181], v151 offset:2048
	ds_read_b128 v[182:185], v151 offset:3072
	s_add_u32 s42, s20, 0xfffc0080
	s_addc_u32 s43, s21, -1
	s_cmp_eq_u32 s72, 12
	s_cselect_b32 s47, s15, s43
	s_cselect_b32 s46, s68, s42
	s_cselect_b32 s43, s13, s71
	s_cselect_b32 s42, s69, s70
	s_add_i32 m0, s35, 0xc000
	ds_read_b128 v[186:189], v152
	ds_read_b128 v[190:193], v152 offset:1024
	ds_read_b128 v[198:201], v152 offset:2048
	ds_read_b128 v[202:205], v152 offset:3072
	ds_read_b128 v[206:209], v152 offset:4096
	ds_read_b128 v[210:213], v152 offset:5120
	ds_read_b128 v[214:217], v152 offset:6144
	ds_read_b128 v[218:221], v152 offset:7168
	global_load_lds_dwordx4 v136, s[20:21]
	s_add_i32 m0, s35, 0xe000
	s_nop 0
	global_load_lds_dwordx4 v138, s[20:21]
	s_waitcnt vmcnt(8)
	s_waitcnt lgkmcnt(0)
	s_barrier
	s_setprio 1
	s_waitcnt lgkmcnt(0)
	v_mfma_f32_16x16x32_bf16 v[124:127], v[154:157], v[186:189], v[124:127]
	v_mfma_f32_16x16x32_bf16 v[116:119], v[162:165], v[186:189], v[116:119]
	v_mfma_f32_16x16x32_bf16 v[108:111], v[154:157], v[198:201], v[108:111]
	v_mfma_f32_16x16x32_bf16 v[100:103], v[162:165], v[198:201], v[100:103]
	v_mfma_f32_16x16x32_bf16 v[92:95], v[154:157], v[206:209], v[92:95]
	v_mfma_f32_16x16x32_bf16 v[84:87], v[162:165], v[206:209], v[84:87]
	v_mfma_f32_16x16x32_bf16 v[76:79], v[154:157], v[214:217], v[76:79]
	v_mfma_f32_16x16x32_bf16 v[68:71], v[162:165], v[214:217], v[68:71]
	v_mfma_f32_16x16x32_bf16 v[124:127], v[158:161], v[190:193], v[124:127]
	v_mfma_f32_16x16x32_bf16 v[116:119], v[166:169], v[190:193], v[116:119]
	v_mfma_f32_16x16x32_bf16 v[108:111], v[158:161], v[202:205], v[108:111]
	v_mfma_f32_16x16x32_bf16 v[100:103], v[166:169], v[202:205], v[100:103]
	v_mfma_f32_16x16x32_bf16 v[92:95], v[158:161], v[210:213], v[92:95]
	v_mfma_f32_16x16x32_bf16 v[84:87], v[166:169], v[210:213], v[84:87]
	v_mfma_f32_16x16x32_bf16 v[76:79], v[158:161], v[218:221], v[76:79]
	v_mfma_f32_16x16x32_bf16 v[68:71], v[166:169], v[218:221], v[68:71]
	v_mfma_f32_16x16x32_bf16 v[120:123], v[170:173], v[186:189], v[120:123]
	v_mfma_f32_16x16x32_bf16 v[112:115], v[178:181], v[186:189], v[112:115]
	v_mfma_f32_16x16x32_bf16 v[104:107], v[170:173], v[198:201], v[104:107]
	v_mfma_f32_16x16x32_bf16 v[96:99], v[178:181], v[198:201], v[96:99]
	v_mfma_f32_16x16x32_bf16 v[88:91], v[170:173], v[206:209], v[88:91]
	v_mfma_f32_16x16x32_bf16 v[80:83], v[178:181], v[206:209], v[80:83]
	v_mfma_f32_16x16x32_bf16 v[72:75], v[170:173], v[214:217], v[72:75]
	v_mfma_f32_16x16x32_bf16 v[64:67], v[178:181], v[214:217], v[64:67]
	v_mfma_f32_16x16x32_bf16 v[120:123], v[174:177], v[190:193], v[120:123]
	v_mfma_f32_16x16x32_bf16 v[112:115], v[182:185], v[190:193], v[112:115]
	v_mfma_f32_16x16x32_bf16 v[104:107], v[174:177], v[202:205], v[104:107]
	v_mfma_f32_16x16x32_bf16 v[96:99], v[182:185], v[202:205], v[96:99]
	v_mfma_f32_16x16x32_bf16 v[88:91], v[174:177], v[210:213], v[88:91]
	v_mfma_f32_16x16x32_bf16 v[80:83], v[182:185], v[210:213], v[80:83]
	v_mfma_f32_16x16x32_bf16 v[72:75], v[174:177], v[218:221], v[72:75]
	v_mfma_f32_16x16x32_bf16 v[64:67], v[182:185], v[218:221], v[64:67]
	s_setprio 0
	s_barrier
; #define PG8_STAGE(bufoff, gbase, voff) do { _Pragma("unroll") for (int _i = 0; _i < 2; ++_i) \
;         __builtin_amdgcn_global_load_lds((const unsigned*)((const char*)(gbase) + (voff)[_i]), (PG8_LAS unsigned*)(lds + (bufoff) + ldsw + _i * 8192), 16, 0, 0); } while (0)
; #define PG8_LDA(dst, b, h) do { _Pragma("unroll") for (int m = 0; m < 4; ++m) _Pragma("unroll") for (int k = 0; k < 2; ++k) dst[m][k] = *(const PG8_LAS bf16x8*)(lds + PG8_SA(b, h) + aoff + m * 2048 + k * 1024); } while (0)
; #define PG8_LDB(dst, b, h) do { _Pragma("unroll") for (int n = 0; n < 2; ++n) _Pragma("unroll") for (int k = 0; k < 2; ++k) dst[n][k] = *(const PG8_LAS bf16x8*)(lds + PG8_SB(b, h) + boff + n * 2048 + k * 1024); } while (0)
; #define PG8_MMA(ai, bj, At, Bt) do { __builtin_amdgcn_s_setprio(1); _Pragma("unroll") for (int m = 0; m < 4; ++m) _Pragma("unroll") for (int n = 0; n < 2; ++n) _Pragma("unroll") for (int k = 0; k < 2; ++k) \
;         acc[ai][bj][m][n] = __builtin_amdgcn_mfma_f32_16x16x32_bf16(Bt[n][k], At[m][k], acc[ai][bj][m][n], 0, 0, 0); __builtin_amdgcn_s_setprio(0); } while (0)
; #define PG8_WAIT_V(n) asm volatile("s_waitcnt vmcnt(" #n ")" ::: "memory")
; #define PG8_WAIT_L(n) asm volatile("s_waitcnt lgkmcnt(" #n ")" ::: "memory")
; #define PG8_BAR __builtin_amdgcn_s_barrier()
; #define PG8_SCHED __builtin_amdgcn_sched_barrier(0)
; template <class Epi, class Sched, bool ALIGN_EPI = false, bool SP2 = false>
; __device__ __forceinline__ void gemm_phase(PG8_LAS unsigned char* lds, const Gemm g, const Sched& S, const Epi& E) {
;     ...
;             PG8_WAIT_V(8); PG8_WAIT_L(0); PG8_BAR; PG8_MMA(0, 0, At, B0); PG8_MMA(0, 1, At, B1); PG8_BAR; PG8_SCHED;
;             PG8_LDA(At, 0, 1); PG8_STAGE(PG8_SB(0, 0), b2, voffB); PG8_STAGE(PG8_SB(0, 1), b2 + hstep, voffB); PG8_STAGE(PG8_SA(0, 0), a2, voffA);
;             PG8_WAIT_V(8); PG8_WAIT_L(0); PG8_BAR; PG8_MMA(1, 0, At, B0); PG8_MMA(1, 1, At, B1); PG8_BAR; PG8_SCHED;
;             PG8_LDB(B0, 1, 0); PG8_LDB(B1, 1, 1); PG8_SCHED; PG8_LDA(At, 1, 0); PG8_STAGE(PG8_SA(0, 1), a2 + hstep, voffA);
;             PG8_WAIT_V(8); PG8_WAIT_L(0); PG8_BAR; PG8_MMA(0, 0, At, B0); PG8_MMA(0, 1, At, B1); PG8_BAR; PG8_SCHED;
	s_add_i32 s73, s63, s55
	s_add_u32 s98, s42, s8
	s_addc_u32 s99, s43, s9
	s_add_u32 s100, s46, s8
	s_addc_u32 s101, s47, s9
	s_mov_b32 m0, s73
	ds_read_b128 v[186:189], v152 offset:16384
	ds_read_b128 v[190:193], v152 offset:17408
	ds_read_b128 v[198:201], v152 offset:18432
	ds_read_b128 v[202:205], v152 offset:19456
	ds_read_b128 v[206:209], v152 offset:20480
	ds_read_b128 v[210:213], v152 offset:21504
	ds_read_b128 v[214:217], v152 offset:22528
	ds_read_b128 v[218:221], v152 offset:23552
	global_load_lds_dwordx4 v132, s[42:43]
	s_add_i32 m0, s73, 0x2000
	s_add_u32 s74, s42, 0x40000
	s_addc_u32 s75, s43, 0
	s_add_i32 s73, s64, s55
	global_load_lds_dwordx4 v128, s[42:43]
	s_mov_b32 m0, s73
	s_nop 0
	global_load_lds_dwordx4 v132, s[74:75]
	s_add_i32 m0, s73, 0x2000
	s_nop 0
	global_load_lds_dwordx4 v128, s[74:75]
	s_mov_b32 m0, s35
	s_nop 0
	global_load_lds_dwordx4 v134, s[46:47]
	s_mov_b32 m0, s57
	s_nop 0
	global_load_lds_dwordx4 v130, s[46:47]
	s_waitcnt vmcnt(8)
	s_waitcnt lgkmcnt(0)
	s_barrier
	s_setprio 1
	s_waitcnt lgkmcnt(0)
	v_mfma_f32_16x16x32_bf16 v[60:63], v[154:157], v[186:189], v[60:63]
	v_mfma_f32_16x16x32_bf16 v[52:55], v[162:165], v[186:189], v[52:55]
	v_mfma_f32_16x16x32_bf16 v[44:47], v[154:157], v[198:201], v[44:47]
	v_mfma_f32_16x16x32_bf16 v[36:39], v[162:165], v[198:201], v[36:39]
	v_mfma_f32_16x16x32_bf16 v[28:31], v[154:157], v[206:209], v[28:31]
	v_mfma_f32_16x16x32_bf16 v[20:23], v[162:165], v[206:209], v[20:23]
	v_mfma_f32_16x16x32_bf16 v[12:15], v[154:157], v[214:217], v[12:15]
	v_mfma_f32_16x16x32_bf16 v[4:7], v[162:165], v[214:217], v[4:7]
	v_mfma_f32_16x16x32_bf16 v[60:63], v[158:161], v[190:193], v[60:63]
	v_mfma_f32_16x16x32_bf16 v[52:55], v[166:169], v[190:193], v[52:55]
	v_mfma_f32_16x16x32_bf16 v[44:47], v[158:161], v[202:205], v[44:47]
	v_mfma_f32_16x16x32_bf16 v[36:39], v[166:169], v[202:205], v[36:39]
	v_mfma_f32_16x16x32_bf16 v[28:31], v[158:161], v[210:213], v[28:31]
	v_mfma_f32_16x16x32_bf16 v[20:23], v[166:169], v[210:213], v[20:23]
	v_mfma_f32_16x16x32_bf16 v[12:15], v[158:161], v[218:221], v[12:15]
	v_mfma_f32_16x16x32_bf16 v[4:7], v[166:169], v[218:221], v[4:7]
	v_mfma_f32_16x16x32_bf16 v[56:59], v[170:173], v[186:189], v[56:59]
	v_mfma_f32_16x16x32_bf16 v[48:51], v[178:181], v[186:189], v[48:51]
	v_mfma_f32_16x16x32_bf16 v[40:43], v[170:173], v[198:201], v[40:43]
	v_mfma_f32_16x16x32_bf16 v[32:35], v[178:181], v[198:201], v[32:35]
	v_mfma_f32_16x16x32_bf16 v[24:27], v[170:173], v[206:209], v[24:27]
	v_mfma_f32_16x16x32_bf16 v[16:19], v[178:181], v[206:209], v[16:19]
	v_mfma_f32_16x16x32_bf16 v[8:11], v[170:173], v[214:217], v[8:11]
	v_mfma_f32_16x16x32_bf16 v[0:3], v[178:181], v[214:217], v[0:3]
	v_mfma_f32_16x16x32_bf16 v[56:59], v[174:177], v[190:193], v[56:59]
	v_mfma_f32_16x16x32_bf16 v[48:51], v[182:185], v[190:193], v[48:51]
	v_mfma_f32_16x16x32_bf16 v[40:43], v[174:177], v[202:205], v[40:43]
	v_mfma_f32_16x16x32_bf16 v[32:35], v[182:185], v[202:205], v[32:35]
	v_mfma_f32_16x16x32_bf16 v[24:27], v[174:177], v[210:213], v[24:27]
	v_mfma_f32_16x16x32_bf16 v[16:19], v[182:185], v[210:213], v[16:19]
	v_mfma_f32_16x16x32_bf16 v[8:11], v[174:177], v[218:221], v[8:11]
	v_mfma_f32_16x16x32_bf16 v[0:3], v[182:185], v[218:221], v[0:3]
	s_setprio 0
	s_barrier
	s_add_i32 s73, 0, 0x18000
	v_add_u32_e32 v153, s73, v147
	s_add_i32 s74, 0, 0x1c000
	ds_read_b128 v[154:157], v153
	ds_read_b128 v[158:161], v153 offset:1024
	ds_read_b128 v[162:165], v153 offset:2048
	ds_read_b128 v[166:169], v153 offset:3072
	v_add_u32_e32 v153, s74, v147
	ds_read_b128 v[170:173], v153
	ds_read_b128 v[174:177], v153 offset:1024
	ds_read_b128 v[178:181], v153 offset:2048
	ds_read_b128 v[182:185], v153 offset:3072
	s_add_u32 s46, s46, 0x40000
	s_addc_u32 s47, s47, 0
	s_mov_b32 m0, s58
	ds_read_b128 v[186:189], v152 offset:32768
	ds_read_b128 v[190:193], v152 offset:33792
	ds_read_b128 v[198:201], v152 offset:34816
	ds_read_b128 v[202:205], v152 offset:35840
	ds_read_b128 v[206:209], v152 offset:36864
	ds_read_b128 v[210:213], v152 offset:37888
	ds_read_b128 v[214:217], v152 offset:38912
	ds_read_b128 v[218:221], v152 offset:39936
	global_load_lds_dwordx4 v134, s[46:47]
	s_mov_b32 m0, s59
	s_nop 0
	global_load_lds_dwordx4 v130, s[46:47]
	s_waitcnt vmcnt(8)
	s_waitcnt lgkmcnt(0)
	s_barrier
; #define PG8_STAGE(bufoff, gbase, voff) do { _Pragma("unroll") for (int _i = 0; _i < 2; ++_i) \
;         __builtin_amdgcn_global_load_lds((const unsigned*)((const char*)(gbase) + (voff)[_i]), (PG8_LAS unsigned*)(lds + (bufoff) + ldsw + _i * 8192), 16, 0, 0); } while (0)
; #define PG8_LDA(dst, b, h) do { _Pragma("unroll") for (int m = 0; m < 4; ++m) _Pragma("unroll") for (int k = 0; k < 2; ++k) dst[m][k] = *(const PG8_LAS bf16x8*)(lds + PG8_SA(b, h) + aoff + m * 2048 + k * 1024); } while (0)
; #define PG8_MMA(ai, bj, At, Bt) do { __builtin_amdgcn_s_setprio(1); _Pragma("unroll") for (int m = 0; m < 4; ++m) _Pragma("unroll") for (int n = 0; n < 2; ++n) _Pragma("unroll") for (int k = 0; k < 2; ++k) \
;         acc[ai][bj][m][n] = __builtin_amdgcn_mfma_f32_16x16x32_bf16(Bt[n][k], At[m][k], acc[ai][bj][m][n], 0, 0, 0); __builtin_amdgcn_s_setprio(0); } while (0)
; #define PG8_WAIT_V(n) asm volatile("s_waitcnt vmcnt(" #n ")" ::: "memory")
; #define PG8_WAIT_L(n) asm volatile("s_waitcnt lgkmcnt(" #n ")" ::: "memory")
; #define PG8_BAR __builtin_amdgcn_s_barrier()
; #define PG8_SCHED __builtin_amdgcn_sched_barrier(0)
; template <class Epi, class Sched, bool ALIGN_EPI = false, bool SP2 = false>
; __device__ __forceinline__ void gemm_phase(PG8_LAS unsigned char* lds, const Gemm g, const Sched& S, const Epi& E) {
;     ...
;             PG8_WAIT_V(8); PG8_WAIT_L(0); PG8_BAR; PG8_MMA(0, 0, At, B0); PG8_MMA(0, 1, At, B1); PG8_BAR; PG8_SCHED;
;             PG8_LDA(At, 1, 1); PG8_STAGE(PG8_SB(1, 0), b3, voffB); PG8_STAGE(PG8_SB(1, 1), b3 + hstep, voffB); PG8_STAGE(PG8_SA(1, 0), a3, voffA);
;             PG8_WAIT_V(8); PG8_WAIT_L(0); PG8_BAR; PG8_MMA(1, 0, At, B0); PG8_MMA(1, 1, At, B1); PG8_BAR; PG8_SCHED;
	s_setprio 1
	s_waitcnt lgkmcnt(0)
	v_mfma_f32_16x16x32_bf16 v[124:127], v[154:157], v[186:189], v[124:127]
	v_mfma_f32_16x16x32_bf16 v[116:119], v[162:165], v[186:189], v[116:119]
	v_mfma_f32_16x16x32_bf16 v[108:111], v[154:157], v[198:201], v[108:111]
	v_mfma_f32_16x16x32_bf16 v[100:103], v[162:165], v[198:201], v[100:103]
	v_mfma_f32_16x16x32_bf16 v[92:95], v[154:157], v[206:209], v[92:95]
	v_mfma_f32_16x16x32_bf16 v[84:87], v[162:165], v[206:209], v[84:87]
	v_mfma_f32_16x16x32_bf16 v[76:79], v[154:157], v[214:217], v[76:79]
	v_mfma_f32_16x16x32_bf16 v[68:71], v[162:165], v[214:217], v[68:71]
	v_mfma_f32_16x16x32_bf16 v[124:127], v[158:161], v[190:193], v[124:127]
	v_mfma_f32_16x16x32_bf16 v[116:119], v[166:169], v[190:193], v[116:119]
	v_mfma_f32_16x16x32_bf16 v[108:111], v[158:161], v[202:205], v[108:111]
	v_mfma_f32_16x16x32_bf16 v[100:103], v[166:169], v[202:205], v[100:103]
	v_mfma_f32_16x16x32_bf16 v[92:95], v[158:161], v[210:213], v[92:95]
	v_mfma_f32_16x16x32_bf16 v[84:87], v[166:169], v[210:213], v[84:87]
	v_mfma_f32_16x16x32_bf16 v[76:79], v[158:161], v[218:221], v[76:79]
	v_mfma_f32_16x16x32_bf16 v[68:71], v[166:169], v[218:221], v[68:71]
	v_mfma_f32_16x16x32_bf16 v[120:123], v[170:173], v[186:189], v[120:123]
	v_mfma_f32_16x16x32_bf16 v[112:115], v[178:181], v[186:189], v[112:115]
	v_mfma_f32_16x16x32_bf16 v[104:107], v[170:173], v[198:201], v[104:107]
	v_mfma_f32_16x16x32_bf16 v[96:99], v[178:181], v[198:201], v[96:99]
	v_mfma_f32_16x16x32_bf16 v[88:91], v[170:173], v[206:209], v[88:91]
	v_mfma_f32_16x16x32_bf16 v[80:83], v[178:181], v[206:209], v[80:83]
	v_mfma_f32_16x16x32_bf16 v[72:75], v[170:173], v[214:217], v[72:75]
	v_mfma_f32_16x16x32_bf16 v[64:67], v[178:181], v[214:217], v[64:67]
	v_mfma_f32_16x16x32_bf16 v[120:123], v[174:177], v[190:193], v[120:123]
	v_mfma_f32_16x16x32_bf16 v[112:115], v[182:185], v[190:193], v[112:115]
	v_mfma_f32_16x16x32_bf16 v[104:107], v[174:177], v[202:205], v[104:107]
	v_mfma_f32_16x16x32_bf16 v[96:99], v[182:185], v[202:205], v[96:99]
	v_mfma_f32_16x16x32_bf16 v[88:91], v[174:177], v[210:213], v[88:91]
	v_mfma_f32_16x16x32_bf16 v[80:83], v[182:185], v[210:213], v[80:83]
	v_mfma_f32_16x16x32_bf16 v[72:75], v[174:177], v[218:221], v[72:75]
	v_mfma_f32_16x16x32_bf16 v[64:67], v[182:185], v[218:221], v[64:67]
	s_setprio 0
	s_barrier
	s_add_i32 s46, s73, s55
	s_mov_b32 m0, s46
	ds_read_b128 v[186:189], v152 offset:49152
	ds_read_b128 v[190:193], v152 offset:50176
	ds_read_b128 v[198:201], v152 offset:51200
	ds_read_b128 v[202:205], v152 offset:52224
	ds_read_b128 v[206:209], v152 offset:53248
	ds_read_b128 v[210:213], v152 offset:54272
	ds_read_b128 v[214:217], v152 offset:55296
	ds_read_b128 v[218:221], v152 offset:56320
	global_load_lds_dwordx4 v132, s[98:99]
	s_add_i32 m0, s46, 0x2000
	s_add_u32 s42, s42, 0x40080
	s_addc_u32 s43, s43, 0
	s_add_i32 s46, s74, s55
	global_load_lds_dwordx4 v128, s[98:99]
	s_mov_b32 m0, s46
	s_nop 0
	global_load_lds_dwordx4 v132, s[42:43]
	s_add_i32 m0, s46, 0x2000
	s_nop 0
	global_load_lds_dwordx4 v128, s[42:43]
	s_mov_b32 m0, s61
	s_nop 0
	global_load_lds_dwordx4 v134, s[100:101]
	s_mov_b32 m0, s62
	s_nop 0
	global_load_lds_dwordx4 v130, s[100:101]
	s_waitcnt vmcnt(8)
	s_waitcnt lgkmcnt(0)
	s_barrier
	s_setprio 1
	s_waitcnt lgkmcnt(0)
	v_mfma_f32_16x16x32_bf16 v[60:63], v[154:157], v[186:189], v[60:63]
	v_mfma_f32_16x16x32_bf16 v[52:55], v[162:165], v[186:189], v[52:55]
	v_mfma_f32_16x16x32_bf16 v[44:47], v[154:157], v[198:201], v[44:47]
	v_mfma_f32_16x16x32_bf16 v[36:39], v[162:165], v[198:201], v[36:39]
	v_mfma_f32_16x16x32_bf16 v[28:31], v[154:157], v[206:209], v[28:31]
	v_mfma_f32_16x16x32_bf16 v[20:23], v[162:165], v[206:209], v[20:23]
	v_mfma_f32_16x16x32_bf16 v[12:15], v[154:157], v[214:217], v[12:15]
	v_mfma_f32_16x16x32_bf16 v[4:7], v[162:165], v[214:217], v[4:7]
	v_mfma_f32_16x16x32_bf16 v[60:63], v[158:161], v[190:193], v[60:63]
	v_mfma_f32_16x16x32_bf16 v[52:55], v[166:169], v[190:193], v[52:55]
	v_mfma_f32_16x16x32_bf16 v[44:47], v[158:161], v[202:205], v[44:47]
	v_mfma_f32_16x16x32_bf16 v[36:39], v[166:169], v[202:205], v[36:39]
	v_mfma_f32_16x16x32_bf16 v[28:31], v[158:161], v[210:213], v[28:31]
	v_mfma_f32_16x16x32_bf16 v[20:23], v[166:169], v[210:213], v[20:23]
	v_mfma_f32_16x16x32_bf16 v[12:15], v[158:161], v[218:221], v[12:15]
	v_mfma_f32_16x16x32_bf16 v[4:7], v[166:169], v[218:221], v[4:7]
	v_mfma_f32_16x16x32_bf16 v[56:59], v[170:173], v[186:189], v[56:59]
	v_mfma_f32_16x16x32_bf16 v[48:51], v[178:181], v[186:189], v[48:51]
	v_mfma_f32_16x16x32_bf16 v[40:43], v[170:173], v[198:201], v[40:43]
	v_mfma_f32_16x16x32_bf16 v[32:35], v[178:181], v[198:201], v[32:35]
	v_mfma_f32_16x16x32_bf16 v[24:27], v[170:173], v[206:209], v[24:27]
	v_mfma_f32_16x16x32_bf16 v[16:19], v[178:181], v[206:209], v[16:19]
	v_mfma_f32_16x16x32_bf16 v[8:11], v[170:173], v[214:217], v[8:11]
	v_mfma_f32_16x16x32_bf16 v[0:3], v[178:181], v[214:217], v[0:3]
	v_mfma_f32_16x16x32_bf16 v[56:59], v[174:177], v[190:193], v[56:59]
	v_mfma_f32_16x16x32_bf16 v[48:51], v[182:185], v[190:193], v[48:51]
	v_mfma_f32_16x16x32_bf16 v[40:43], v[174:177], v[202:205], v[40:43]
	v_mfma_f32_16x16x32_bf16 v[32:35], v[182:185], v[202:205], v[32:35]
	v_mfma_f32_16x16x32_bf16 v[24:27], v[174:177], v[210:213], v[24:27]
	v_mfma_f32_16x16x32_bf16 v[16:19], v[182:185], v[210:213], v[16:19]
	v_mfma_f32_16x16x32_bf16 v[8:11], v[174:177], v[218:221], v[8:11]
	v_mfma_f32_16x16x32_bf16 v[0:3], v[182:185], v[218:221], v[0:3]
	s_setprio 0
	s_barrier
	s_add_i32 s72, s72, 2
	s_add_u32 s20, s20, 0x100
	s_addc_u32 s21, s21, 0
	s_add_u32 s70, s70, 0x100
	s_addc_u32 s71, s71, 0
	s_cmp_gt_u32 s72, 13
	s_cbranch_scc0 .LBB0_224
	s_and_b64 vcc, exec, s[10:11]
	s_cbranch_vccz .LBB0_227
	s_barrier

; #define PG8_STAGE(bufoff, gbase, voff) do { _Pragma("unroll") for (int _i = 0; _i < 2; ++_i) \
;         __builtin_amdgcn_global_load_lds((const unsigned*)((const char*)(gbase) + (voff)[_i]), (PG8_LAS unsigned*)(lds + (bufoff) + ldsw + _i * 8192), 16, 0, 0); } while (0)
; #define PG8_LDA(dst, b, h) do { _Pragma("unroll") for (int m = 0; m < 4; ++m) _Pragma("unroll") for (int k = 0; k < 2; ++k) dst[m][k] = *(const PG8_LAS bf16x8*)(lds + PG8_SA(b, h) + aoff + m * 2048 + k * 1024); } while (0)
; #define PG8_LDB(dst, b, h) do { _Pragma("unroll") for (int n = 0; n < 2; ++n) _Pragma("unroll") for (int k = 0; k < 2; ++k) dst[n][k] = *(const PG8_LAS bf16x8*)(lds + PG8_SB(b, h) + boff + n * 2048 + k * 1024); } while (0)
; #define PG8_BAR __builtin_amdgcn_s_barrier()
; template <class Epi, class Sched, bool ALIGN_EPI = false, bool SP2 = false>
; __device__ __forceinline__ void gemm_phase(PG8_LAS unsigned char* lds, const Gemm g, const Sched& S, const Epi& E) {
;     ...
;         const bool has_next = S.next(ui + 1, nxt);
;         const char* nA = has_next ? (const char*)g.A + (size_t)nxt.pm * tstep : cA; const char* nB = has_next ? (const char*)g.Bt + (size_t)nxt.pn * tstep : cB;
;         for (int t = 0; t < nt; t += 2) {
;             const bool last = (t == nt - 2);
;             const char* a1 = cA + (size_t)(t + 1) * kstep;
;             const char* a2 = last ? nA : cA + (size_t)(t + 2) * kstep; const char* b2 = last ? nB : cB + (size_t)(t + 2) * kstep;
;             const char* a3 = a2 + kstep; const char* b3 = b2 + kstep;
;             if (last && has_next) S.a_ready(nxt);
;             if constexpr (SP2) {
;             PG8_LDB(B0, 0, 0); PG8_LDB(B1, 0, 1); PG8_SCHED; PG8_LDA(At, 0, 0); PG8_STAGE(PG8_SA(1, 1), a1 + hstep, voffA);
;             PG8_WAIT_V(8); PG8_WAIT_L(0); PG8_BAR; PG8_MMA(0, 0, At, B0); PG8_MMA(0, 1, At, B1); PG8_BAR; PG8_SCHED;
;             PG8_LDA(At, 0, 1); PG8_STAGE(PG8_SB(0, 0), b2, voffB); PG8_STAGE(PG8_SB(0, 1), b2 + hstep, voffB); PG8_STAGE(PG8_SA(0, 0), a2, voffA);
;             PG8_WAIT_V(8); PG8_WAIT_L(0); PG8_BAR; PG8_MMA(1, 0, At, B0); PG8_MMA(1, 1, At, B1); PG8_BAR; PG8_SCHED;
;             PG8_LDB(B0, 1, 0); PG8_LDB(B1, 1, 1); PG8_SCHED; PG8_LDA(At, 1, 0); PG8_STAGE(PG8_SA(0, 1), a2 + hstep, voffA);
;             PG8_WAIT_V(8); PG8_WAIT_L(0); PG8_BAR; PG8_MMA(0, 0, At, B0); PG8_MMA(0, 1, At, B1); PG8_BAR; PG8_SCHED;
.LBB0_308:
	s_add_u32 s20, s20, 0xb0080
	s_addc_u32 s21, s21, 0
	s_add_u32 s73, s34, 0x100
	s_addc_u32 s74, s35, 0
	s_mov_b32 s75, -2
	s_waitcnt lgkmcnt(0)
	s_waitcnt lgkmcnt(0)
	ds_read_b128 v[96:99], v223
	ds_read_b128 v[108:111], v223 offset:1024
	ds_read_b128 v[120:123], v223 offset:2048
	ds_read_b128 v[128:131], v223 offset:3072
	ds_read_b128 v[144:147], v224
	ds_read_b128 v[148:151], v224 offset:1024
	ds_read_b128 v[152:155], v224 offset:2048
	ds_read_b128 v[156:159], v224 offset:3072
	s_add_u32 s34, s20, 0xfff50080
	s_addc_u32 s35, s21, -1
	s_cmp_eq_u32 s75, 40
	s_cselect_b32 s51, s1, s35
	s_cselect_b32 s50, s0, s34
	s_cselect_b32 s35, s49, s74
	s_cselect_b32 s34, s48, s73
	s_add_i32 m0, s54, 0xc000
	ds_read_b128 v[160:163], v225
	ds_read_b128 v[164:167], v225 offset:1024
	ds_read_b128 v[168:171], v225 offset:2048
	ds_read_b128 v[172:175], v225 offset:3072
	ds_read_b128 v[176:179], v225 offset:4096
	ds_read_b128 v[180:183], v225 offset:5120
	ds_read_b128 v[202:205], v225 offset:6144
	ds_read_b128 v[206:209], v225 offset:7168
	global_load_lds_dwordx4 v192, s[20:21]
	s_add_i32 m0, s54, 0xe000
	s_nop 0
	global_load_lds_dwordx4 v194, s[20:21]
	s_waitcnt vmcnt(8)
	s_waitcnt lgkmcnt(0)
	s_barrier
	s_setprio 1
	s_waitcnt lgkmcnt(0)
	v_mfma_f32_16x16x32_bf16 v[140:143], v[96:99], v[160:163], 0
	v_mfma_f32_16x16x32_bf16 v[136:139], v[120:123], v[160:163], 0
	v_mfma_f32_16x16x32_bf16 v[116:119], v[96:99], v[168:171], 0
	v_mfma_f32_16x16x32_bf16 v[112:115], v[120:123], v[168:171], 0
	v_mfma_f32_16x16x32_bf16 v[92:95], v[96:99], v[176:179], 0
	v_mfma_f32_16x16x32_bf16 v[88:91], v[120:123], v[176:179], 0
	v_mfma_f32_16x16x32_bf16 v[76:79], v[96:99], v[202:205], 0
	v_mfma_f32_16x16x32_bf16 v[72:75], v[120:123], v[202:205], 0
	v_mfma_f32_16x16x32_bf16 v[140:143], v[108:111], v[164:167], v[140:143]
	v_mfma_f32_16x16x32_bf16 v[136:139], v[128:131], v[164:167], v[136:139]
	v_mfma_f32_16x16x32_bf16 v[116:119], v[108:111], v[172:175], v[116:119]
	v_mfma_f32_16x16x32_bf16 v[112:115], v[128:131], v[172:175], v[112:115]
	v_mfma_f32_16x16x32_bf16 v[92:95], v[108:111], v[180:183], v[92:95]
	v_mfma_f32_16x16x32_bf16 v[88:91], v[128:131], v[180:183], v[88:91]
	v_mfma_f32_16x16x32_bf16 v[76:79], v[108:111], v[206:209], v[76:79]
	v_mfma_f32_16x16x32_bf16 v[72:75], v[128:131], v[206:209], v[72:75]
	v_mfma_f32_16x16x32_bf16 v[132:135], v[144:147], v[160:163], 0
	v_mfma_f32_16x16x32_bf16 v[124:127], v[152:155], v[160:163], 0
	v_mfma_f32_16x16x32_bf16 v[104:107], v[144:147], v[168:171], 0
	v_mfma_f32_16x16x32_bf16 v[100:103], v[152:155], v[168:171], 0
	v_mfma_f32_16x16x32_bf16 v[84:87], v[144:147], v[176:179], 0
	v_mfma_f32_16x16x32_bf16 v[80:83], v[152:155], v[176:179], 0
	v_mfma_f32_16x16x32_bf16 v[68:71], v[144:147], v[202:205], 0
	v_mfma_f32_16x16x32_bf16 v[64:67], v[152:155], v[202:205], 0
	v_mfma_f32_16x16x32_bf16 v[132:135], v[148:151], v[164:167], v[132:135]
	v_mfma_f32_16x16x32_bf16 v[124:127], v[156:159], v[164:167], v[124:127]
	v_mfma_f32_16x16x32_bf16 v[104:107], v[148:151], v[172:175], v[104:107]
	v_mfma_f32_16x16x32_bf16 v[100:103], v[156:159], v[172:175], v[100:103]
	v_mfma_f32_16x16x32_bf16 v[84:87], v[148:151], v[180:183], v[84:87]
	v_mfma_f32_16x16x32_bf16 v[80:83], v[156:159], v[180:183], v[80:83]
	v_mfma_f32_16x16x32_bf16 v[68:71], v[148:151], v[206:209], v[68:71]
	v_mfma_f32_16x16x32_bf16 v[64:67], v[156:159], v[206:209], v[64:67]
	s_setprio 0
	s_barrier
	s_add_i32 s76, s67, s53
	s_add_u32 s98, s34, s12
	s_addc_u32 s99, s35, s13
	s_add_u32 s100, s50, s12
	s_addc_u32 s101, s51, s13
	s_mov_b32 m0, s76
	ds_read_b128 v[160:163], v225 offset:16384
	ds_read_b128 v[164:167], v225 offset:17408
	ds_read_b128 v[168:171], v225 offset:18432
	ds_read_b128 v[172:175], v225 offset:19456
	ds_read_b128 v[176:179], v225 offset:20480
	ds_read_b128 v[180:183], v225 offset:21504
	ds_read_b128 v[202:205], v225 offset:22528
	ds_read_b128 v[206:209], v225 offset:23552
	global_load_lds_dwordx4 v186, s[34:35]
	s_add_i32 m0, s76, 0x2000
	s_add_u32 s76, s34, 0xb0000
	s_addc_u32 s77, s35, 0
	s_add_i32 s78, s68, s53
	global_load_lds_dwordx4 v190, s[34:35]
	s_mov_b32 m0, s78
	s_nop 0
	global_load_lds_dwordx4 v186, s[76:77]
	s_add_i32 m0, s78, 0x2000
	s_nop 0
	global_load_lds_dwordx4 v190, s[76:77]
	s_mov_b32 m0, s54
	s_nop 0
	global_load_lds_dwordx4 v184, s[50:51]
	s_mov_b32 m0, s55
	s_nop 0
	global_load_lds_dwordx4 v188, s[50:51]
	s_waitcnt vmcnt(8)
	s_waitcnt lgkmcnt(0)
	s_barrier
	s_setprio 1
	s_waitcnt lgkmcnt(0)
	v_mfma_f32_16x16x32_bf16 v[60:63], v[96:99], v[160:163], 0
	v_mfma_f32_16x16x32_bf16 v[56:59], v[120:123], v[160:163], 0
	v_mfma_f32_16x16x32_bf16 v[44:47], v[96:99], v[168:171], 0
	v_mfma_f32_16x16x32_bf16 v[40:43], v[120:123], v[168:171], 0
	v_mfma_f32_16x16x32_bf16 v[28:31], v[96:99], v[176:179], 0
	v_mfma_f32_16x16x32_bf16 v[24:27], v[120:123], v[176:179], 0
	v_mfma_f32_16x16x32_bf16 v[12:15], v[96:99], v[202:205], 0
	v_mfma_f32_16x16x32_bf16 v[8:11], v[120:123], v[202:205], 0
	v_mfma_f32_16x16x32_bf16 v[60:63], v[108:111], v[164:167], v[60:63]
	v_mfma_f32_16x16x32_bf16 v[56:59], v[128:131], v[164:167], v[56:59]
	v_mfma_f32_16x16x32_bf16 v[44:47], v[108:111], v[172:175], v[44:47]
	v_mfma_f32_16x16x32_bf16 v[40:43], v[128:131], v[172:175], v[40:43]
	v_mfma_f32_16x16x32_bf16 v[28:31], v[108:111], v[180:183], v[28:31]
	v_mfma_f32_16x16x32_bf16 v[24:27], v[128:131], v[180:183], v[24:27]
	v_mfma_f32_16x16x32_bf16 v[12:15], v[108:111], v[206:209], v[12:15]
	v_mfma_f32_16x16x32_bf16 v[8:11], v[128:131], v[206:209], v[8:11]
	v_mfma_f32_16x16x32_bf16 v[52:55], v[144:147], v[160:163], 0
	v_mfma_f32_16x16x32_bf16 v[48:51], v[152:155], v[160:163], 0
	v_mfma_f32_16x16x32_bf16 v[36:39], v[144:147], v[168:171], 0
	v_mfma_f32_16x16x32_bf16 v[32:35], v[152:155], v[168:171], 0
	v_mfma_f32_16x16x32_bf16 v[20:23], v[144:147], v[176:179], 0
	v_mfma_f32_16x16x32_bf16 v[16:19], v[152:155], v[176:179], 0
	v_mfma_f32_16x16x32_bf16 v[4:7], v[144:147], v[202:205], 0
	v_mfma_f32_16x16x32_bf16 v[0:3], v[152:155], v[202:205], 0
	v_mfma_f32_16x16x32_bf16 v[52:55], v[148:151], v[164:167], v[52:55]
	v_mfma_f32_16x16x32_bf16 v[48:51], v[156:159], v[164:167], v[48:51]
	v_mfma_f32_16x16x32_bf16 v[36:39], v[148:151], v[172:175], v[36:39]
	v_mfma_f32_16x16x32_bf16 v[32:35], v[156:159], v[172:175], v[32:35]
	v_mfma_f32_16x16x32_bf16 v[20:23], v[148:151], v[180:183], v[20:23]
	v_mfma_f32_16x16x32_bf16 v[16:19], v[156:159], v[180:183], v[16:19]
	v_mfma_f32_16x16x32_bf16 v[4:7], v[148:151], v[206:209], v[4:7]
	v_mfma_f32_16x16x32_bf16 v[0:3], v[156:159], v[206:209], v[0:3]
	s_setprio 0
	s_barrier
; #define PG8_STAGE(bufoff, gbase, voff) do { _Pragma("unroll") for (int _i = 0; _i < 2; ++_i) \
;         __builtin_amdgcn_global_load_lds((const unsigned*)((const char*)(gbase) + (voff)[_i]), (PG8_LAS unsigned*)(lds + (bufoff) + ldsw + _i * 8192), 16, 0, 0); } while (0)
; #define PG8_LDA(dst, b, h) do { _Pragma("unroll") for (int m = 0; m < 4; ++m) _Pragma("unroll") for (int k = 0; k < 2; ++k) dst[m][k] = *(const PG8_LAS bf16x8*)(lds + PG8_SA(b, h) + aoff + m * 2048 + k * 1024); } while (0)
; #define PG8_MMA(ai, bj, At, Bt) do { __builtin_amdgcn_s_setprio(1); _Pragma("unroll") for (int m = 0; m < 4; ++m) _Pragma("unroll") for (int n = 0; n < 2; ++n) _Pragma("unroll") for (int k = 0; k < 2; ++k) \
;         acc[ai][bj][m][n] = __builtin_amdgcn_mfma_f32_16x16x32_bf16(Bt[n][k], At[m][k], acc[ai][bj][m][n], 0, 0, 0); __builtin_amdgcn_s_setprio(0); } while (0)
; #define PG8_WAIT_V(n) asm volatile("s_waitcnt vmcnt(" #n ")" ::: "memory")
; #define PG8_WAIT_L(n) asm volatile("s_waitcnt lgkmcnt(" #n ")" ::: "memory")
; #define PG8_BAR __builtin_amdgcn_s_barrier()
; #define PG8_SCHED __builtin_amdgcn_sched_barrier(0)
; template <class Epi, class Sched, bool ALIGN_EPI = false, bool SP2 = false>
; __device__ __forceinline__ void gemm_phase(PG8_LAS unsigned char* lds, const Gemm g, const Sched& S, const Epi& E) {
;     ...
;             PG8_WAIT_V(8); PG8_WAIT_L(0); PG8_BAR; PG8_MMA(0, 0, At, B0); PG8_MMA(0, 1, At, B1); PG8_BAR; PG8_SCHED;
;             PG8_LDA(At, 1, 1); PG8_STAGE(PG8_SB(1, 0), b3, voffB); PG8_STAGE(PG8_SB(1, 1), b3 + hstep, voffB); PG8_STAGE(PG8_SA(1, 0), a3, voffA);
;             PG8_WAIT_V(8); PG8_WAIT_L(0); PG8_BAR; PG8_MMA(1, 0, At, B0); PG8_MMA(1, 1, At, B1); PG8_BAR; PG8_SCHED;
	s_add_i32 s76, 0, 0x18000
	s_add_i32 s77, 0, 0x1c000
	v_add_u32_e32 v128, s76, v221
	v_add_u32_e32 v156, s77, v221
	ds_read_b128 v[96:99], v128
	ds_read_b128 v[108:111], v128 offset:1024
	ds_read_b128 v[120:123], v128 offset:2048
	ds_read_b128 v[128:131], v128 offset:3072
	ds_read_b128 v[144:147], v156
	ds_read_b128 v[148:151], v156 offset:1024
	ds_read_b128 v[152:155], v156 offset:2048
	ds_read_b128 v[156:159], v156 offset:3072
	s_add_u32 s50, s50, 0xb0000
	s_addc_u32 s51, s51, 0
	s_mov_b32 m0, s56
	ds_read_b128 v[160:163], v225 offset:32768
	ds_read_b128 v[164:167], v225 offset:33792
	ds_read_b128 v[168:171], v225 offset:34816
	ds_read_b128 v[172:175], v225 offset:35840
	ds_read_b128 v[176:179], v225 offset:36864
	ds_read_b128 v[180:183], v225 offset:37888
	ds_read_b128 v[202:205], v225 offset:38912
	ds_read_b128 v[206:209], v225 offset:39936
	global_load_lds_dwordx4 v184, s[50:51]
	s_mov_b32 m0, s57
	s_nop 0
	global_load_lds_dwordx4 v188, s[50:51]
	s_waitcnt vmcnt(8)
	s_waitcnt lgkmcnt(0)
	s_barrier
	s_setprio 1
	s_waitcnt lgkmcnt(0)
	v_mfma_f32_16x16x32_bf16 v[140:143], v[96:99], v[160:163], v[140:143]
	v_mfma_f32_16x16x32_bf16 v[136:139], v[120:123], v[160:163], v[136:139]
	v_mfma_f32_16x16x32_bf16 v[116:119], v[96:99], v[168:171], v[116:119]
	v_mfma_f32_16x16x32_bf16 v[112:115], v[120:123], v[168:171], v[112:115]
	v_mfma_f32_16x16x32_bf16 v[92:95], v[96:99], v[176:179], v[92:95]
	v_mfma_f32_16x16x32_bf16 v[88:91], v[120:123], v[176:179], v[88:91]
	v_mfma_f32_16x16x32_bf16 v[76:79], v[96:99], v[202:205], v[76:79]
	v_mfma_f32_16x16x32_bf16 v[72:75], v[120:123], v[202:205], v[72:75]
	v_mfma_f32_16x16x32_bf16 v[140:143], v[108:111], v[164:167], v[140:143]
	v_mfma_f32_16x16x32_bf16 v[136:139], v[128:131], v[164:167], v[136:139]
	v_mfma_f32_16x16x32_bf16 v[116:119], v[108:111], v[172:175], v[116:119]
	v_mfma_f32_16x16x32_bf16 v[112:115], v[128:131], v[172:175], v[112:115]
	v_mfma_f32_16x16x32_bf16 v[92:95], v[108:111], v[180:183], v[92:95]
	v_mfma_f32_16x16x32_bf16 v[88:91], v[128:131], v[180:183], v[88:91]
	v_mfma_f32_16x16x32_bf16 v[76:79], v[108:111], v[206:209], v[76:79]
	v_mfma_f32_16x16x32_bf16 v[72:75], v[128:131], v[206:209], v[72:75]
	v_mfma_f32_16x16x32_bf16 v[132:135], v[144:147], v[160:163], v[132:135]
	v_mfma_f32_16x16x32_bf16 v[124:127], v[152:155], v[160:163], v[124:127]
	v_mfma_f32_16x16x32_bf16 v[104:107], v[144:147], v[168:171], v[104:107]
	v_mfma_f32_16x16x32_bf16 v[100:103], v[152:155], v[168:171], v[100:103]
	v_mfma_f32_16x16x32_bf16 v[84:87], v[144:147], v[176:179], v[84:87]
	v_mfma_f32_16x16x32_bf16 v[80:83], v[152:155], v[176:179], v[80:83]
	v_mfma_f32_16x16x32_bf16 v[68:71], v[144:147], v[202:205], v[68:71]
	v_mfma_f32_16x16x32_bf16 v[64:67], v[152:155], v[202:205], v[64:67]
	v_mfma_f32_16x16x32_bf16 v[132:135], v[148:151], v[164:167], v[132:135]
	v_mfma_f32_16x16x32_bf16 v[124:127], v[156:159], v[164:167], v[124:127]
	v_mfma_f32_16x16x32_bf16 v[104:107], v[148:151], v[172:175], v[104:107]
	v_mfma_f32_16x16x32_bf16 v[100:103], v[156:159], v[172:175], v[100:103]
	v_mfma_f32_16x16x32_bf16 v[84:87], v[148:151], v[180:183], v[84:87]
	v_mfma_f32_16x16x32_bf16 v[80:83], v[156:159], v[180:183], v[80:83]
	v_mfma_f32_16x16x32_bf16 v[68:71], v[148:151], v[206:209], v[68:71]
	v_mfma_f32_16x16x32_bf16 v[64:67], v[156:159], v[206:209], v[64:67]
	s_setprio 0
	s_barrier
	s_add_i32 s50, s76, s53
	s_mov_b32 m0, s50
	ds_read_b128 v[160:163], v225 offset:49152
	ds_read_b128 v[164:167], v225 offset:50176
	ds_read_b128 v[168:171], v225 offset:51200
	ds_read_b128 v[172:175], v225 offset:52224
	ds_read_b128 v[176:179], v225 offset:53248
	ds_read_b128 v[180:183], v225 offset:54272
	ds_read_b128 v[202:205], v225 offset:55296
	ds_read_b128 v[206:209], v225 offset:56320
	global_load_lds_dwordx4 v186, s[98:99]
	s_add_i32 m0, s50, 0x2000
	s_add_u32 s34, s34, 0xb0080
	s_addc_u32 s35, s35, 0
	s_add_i32 s50, s77, s53
	global_load_lds_dwordx4 v190, s[98:99]
	s_mov_b32 m0, s50
	s_nop 0
	global_load_lds_dwordx4 v186, s[34:35]
	s_add_i32 m0, s50, 0x2000
	s_nop 0
	global_load_lds_dwordx4 v190, s[34:35]
	s_mov_b32 m0, s62
	s_nop 0
	global_load_lds_dwordx4 v184, s[100:101]
	s_mov_b32 m0, s63
	s_nop 0
	global_load_lds_dwordx4 v188, s[100:101]
	s_waitcnt vmcnt(8)
	s_waitcnt lgkmcnt(0)
	s_barrier
	s_setprio 1
	s_waitcnt lgkmcnt(0)
	v_mfma_f32_16x16x32_bf16 v[60:63], v[96:99], v[160:163], v[60:63]
	v_mfma_f32_16x16x32_bf16 v[56:59], v[120:123], v[160:163], v[56:59]
	v_mfma_f32_16x16x32_bf16 v[44:47], v[96:99], v[168:171], v[44:47]
	v_mfma_f32_16x16x32_bf16 v[40:43], v[120:123], v[168:171], v[40:43]
	v_mfma_f32_16x16x32_bf16 v[28:31], v[96:99], v[176:179], v[28:31]
	v_mfma_f32_16x16x32_bf16 v[24:27], v[120:123], v[176:179], v[24:27]
	v_mfma_f32_16x16x32_bf16 v[12:15], v[96:99], v[202:205], v[12:15]
	v_mfma_f32_16x16x32_bf16 v[8:11], v[120:123], v[202:205], v[8:11]
	v_mfma_f32_16x16x32_bf16 v[60:63], v[108:111], v[164:167], v[60:63]
	v_mfma_f32_16x16x32_bf16 v[56:59], v[128:131], v[164:167], v[56:59]
	v_mfma_f32_16x16x32_bf16 v[44:47], v[108:111], v[172:175], v[44:47]
	v_mfma_f32_16x16x32_bf16 v[40:43], v[128:131], v[172:175], v[40:43]
	v_mfma_f32_16x16x32_bf16 v[28:31], v[108:111], v[180:183], v[28:31]
	v_mfma_f32_16x16x32_bf16 v[24:27], v[128:131], v[180:183], v[24:27]
	v_mfma_f32_16x16x32_bf16 v[12:15], v[108:111], v[206:209], v[12:15]
	v_mfma_f32_16x16x32_bf16 v[8:11], v[128:131], v[206:209], v[8:11]
	v_mfma_f32_16x16x32_bf16 v[52:55], v[144:147], v[160:163], v[52:55]
	v_mfma_f32_16x16x32_bf16 v[48:51], v[152:155], v[160:163], v[48:51]
	v_mfma_f32_16x16x32_bf16 v[36:39], v[144:147], v[168:171], v[36:39]
	v_mfma_f32_16x16x32_bf16 v[32:35], v[152:155], v[168:171], v[32:35]
	v_mfma_f32_16x16x32_bf16 v[20:23], v[144:147], v[176:179], v[20:23]
	v_mfma_f32_16x16x32_bf16 v[16:19], v[152:155], v[176:179], v[16:19]
	v_mfma_f32_16x16x32_bf16 v[4:7], v[144:147], v[202:205], v[4:7]
	v_mfma_f32_16x16x32_bf16 v[0:3], v[152:155], v[202:205], v[0:3]
	v_mfma_f32_16x16x32_bf16 v[52:55], v[148:151], v[164:167], v[52:55]
	v_mfma_f32_16x16x32_bf16 v[48:51], v[156:159], v[164:167], v[48:51]
	v_mfma_f32_16x16x32_bf16 v[36:39], v[148:151], v[172:175], v[36:39]
	v_mfma_f32_16x16x32_bf16 v[32:35], v[156:159], v[172:175], v[32:35]
	v_mfma_f32_16x16x32_bf16 v[20:23], v[148:151], v[180:183], v[20:23]
	v_mfma_f32_16x16x32_bf16 v[16:19], v[156:159], v[180:183], v[16:19]
	v_mfma_f32_16x16x32_bf16 v[4:7], v[148:151], v[206:209], v[4:7]
	v_mfma_f32_16x16x32_bf16 v[0:3], v[156:159], v[206:209], v[0:3]
	s_setprio 0
	s_barrier
	s_add_i32 s75, s75, 2
	s_add_u32 s20, s20, 0x100
	s_addc_u32 s21, s21, 0
	s_add_u32 s73, s73, 0x100
	s_addc_u32 s74, s74, 0
	s_cmp_gt_u32 s75, 41
; #define PG8_STAGE(bufoff, gbase, voff) do { _Pragma("unroll") for (int _i = 0; _i < 2; ++_i) \
;         __builtin_amdgcn_global_load_lds((const unsigned*)((const char*)(gbase) + (voff)[_i]), (PG8_LAS unsigned*)(lds + (bufoff) + ldsw + _i * 8192), 16, 0, 0); } while (0)
; #define PG8_LDA(dst, b, h) do { _Pragma("unroll") for (int m = 0; m < 4; ++m) _Pragma("unroll") for (int k = 0; k < 2; ++k) dst[m][k] = *(const PG8_LAS bf16x8*)(lds + PG8_SA(b, h) + aoff + m * 2048 + k * 1024); } while (0)
; #define PG8_LDB(dst, b, h) do { _Pragma("unroll") for (int n = 0; n < 2; ++n) _Pragma("unroll") for (int k = 0; k < 2; ++k) dst[n][k] = *(const PG8_LAS bf16x8*)(lds + PG8_SB(b, h) + boff + n * 2048 + k * 1024); } while (0)
; #define PG8_WAIT_V(n) asm volatile("s_waitcnt vmcnt(" #n ")" ::: "memory")
; #define PG8_WAIT_L(n) asm volatile("s_waitcnt lgkmcnt(" #n ")" ::: "memory")
; #define PG8_BAR __builtin_amdgcn_s_barrier()
; #define PG8_SCHED __builtin_amdgcn_sched_barrier(0)
; template <class Epi, class Sched, bool ALIGN_EPI = false, bool SP2 = false>
; __device__ __forceinline__ void gemm_phase(PG8_LAS unsigned char* lds, const Gemm g, const Sched& S, const Epi& E) {
;     ...
;         for (int t = 0; t < nt; t += 2) {
;             const bool last = (t == nt - 2);
;             const char* a1 = cA + (size_t)(t + 1) * kstep;
;             const char* a2 = last ? nA : cA + (size_t)(t + 2) * kstep; const char* b2 = last ? nB : cB + (size_t)(t + 2) * kstep;
;             const char* a3 = a2 + kstep; const char* b3 = b2 + kstep;
;             if (last && has_next) S.a_ready(nxt);
;             if constexpr (SP2) {
;             PG8_LDB(B0, 0, 0); PG8_LDB(B1, 0, 1); PG8_SCHED; PG8_LDA(At, 0, 0); PG8_STAGE(PG8_SA(1, 1), a1 + hstep, voffA);
;             PG8_WAIT_V(8); PG8_WAIT_L(0); PG8_BAR; PG8_MMA(0, 0, At, B0); PG8_MMA(0, 1, At, B1); PG8_BAR; PG8_SCHED;
;             PG8_LDA(At, 0, 1); PG8_STAGE(PG8_SB(0, 0), b2, voffB); PG8_STAGE(PG8_SB(0, 1), b2 + hstep, voffB); PG8_STAGE(PG8_SA(0, 0), a2, voffA);
;             PG8_WAIT_V(8); PG8_WAIT_L(0); PG8_BAR; PG8_MMA(1, 0, At, B0); PG8_MMA(1, 1, At, B1); PG8_BAR; PG8_SCHED;
;             PG8_LDB(B0, 1, 0); PG8_LDB(B1, 1, 1); PG8_SCHED; PG8_LDA(At, 1, 0); PG8_STAGE(PG8_SA(0, 1), a2 + hstep, voffA);
;             PG8_WAIT_V(8); PG8_WAIT_L(0); PG8_BAR; PG8_MMA(0, 0, At, B0); PG8_MMA(0, 1, At, B1); PG8_BAR; PG8_SCHED;
.LBB0_309:
	ds_read_b128 v[96:99], v223
	ds_read_b128 v[108:111], v223 offset:1024
	ds_read_b128 v[120:123], v223 offset:2048
	ds_read_b128 v[128:131], v223 offset:3072
	ds_read_b128 v[144:147], v224
	ds_read_b128 v[148:151], v224 offset:1024
	ds_read_b128 v[152:155], v224 offset:2048
	ds_read_b128 v[156:159], v224 offset:3072
	s_add_u32 s34, s20, 0xfff50080
	s_addc_u32 s35, s21, -1
	s_cmp_eq_u32 s75, 40
	s_cselect_b32 s51, s1, s35
	s_cselect_b32 s50, s0, s34
	s_cselect_b32 s35, s49, s74
	s_cselect_b32 s34, s48, s73
	s_add_i32 m0, s54, 0xc000
	ds_read_b128 v[160:163], v225
	ds_read_b128 v[164:167], v225 offset:1024
	ds_read_b128 v[168:171], v225 offset:2048
	ds_read_b128 v[172:175], v225 offset:3072
	ds_read_b128 v[176:179], v225 offset:4096
	ds_read_b128 v[180:183], v225 offset:5120
	ds_read_b128 v[202:205], v225 offset:6144
	ds_read_b128 v[206:209], v225 offset:7168
	global_load_lds_dwordx4 v192, s[20:21]
	s_add_i32 m0, s54, 0xe000
	s_nop 0
	global_load_lds_dwordx4 v194, s[20:21]
	s_waitcnt vmcnt(8)
	s_waitcnt lgkmcnt(0)
	s_barrier
	s_setprio 1
	s_waitcnt lgkmcnt(0)
	v_mfma_f32_16x16x32_bf16 v[140:143], v[96:99], v[160:163], v[140:143]
	v_mfma_f32_16x16x32_bf16 v[136:139], v[120:123], v[160:163], v[136:139]
	v_mfma_f32_16x16x32_bf16 v[116:119], v[96:99], v[168:171], v[116:119]
	v_mfma_f32_16x16x32_bf16 v[112:115], v[120:123], v[168:171], v[112:115]
	v_mfma_f32_16x16x32_bf16 v[92:95], v[96:99], v[176:179], v[92:95]
	v_mfma_f32_16x16x32_bf16 v[88:91], v[120:123], v[176:179], v[88:91]
	v_mfma_f32_16x16x32_bf16 v[76:79], v[96:99], v[202:205], v[76:79]
	v_mfma_f32_16x16x32_bf16 v[72:75], v[120:123], v[202:205], v[72:75]
	v_mfma_f32_16x16x32_bf16 v[140:143], v[108:111], v[164:167], v[140:143]
	v_mfma_f32_16x16x32_bf16 v[136:139], v[128:131], v[164:167], v[136:139]
	v_mfma_f32_16x16x32_bf16 v[116:119], v[108:111], v[172:175], v[116:119]
	v_mfma_f32_16x16x32_bf16 v[112:115], v[128:131], v[172:175], v[112:115]
	v_mfma_f32_16x16x32_bf16 v[92:95], v[108:111], v[180:183], v[92:95]
	v_mfma_f32_16x16x32_bf16 v[88:91], v[128:131], v[180:183], v[88:91]
	v_mfma_f32_16x16x32_bf16 v[76:79], v[108:111], v[206:209], v[76:79]
	v_mfma_f32_16x16x32_bf16 v[72:75], v[128:131], v[206:209], v[72:75]
	v_mfma_f32_16x16x32_bf16 v[132:135], v[144:147], v[160:163], v[132:135]
	v_mfma_f32_16x16x32_bf16 v[124:127], v[152:155], v[160:163], v[124:127]
	v_mfma_f32_16x16x32_bf16 v[104:107], v[144:147], v[168:171], v[104:107]
	v_mfma_f32_16x16x32_bf16 v[100:103], v[152:155], v[168:171], v[100:103]
	v_mfma_f32_16x16x32_bf16 v[84:87], v[144:147], v[176:179], v[84:87]
	v_mfma_f32_16x16x32_bf16 v[80:83], v[152:155], v[176:179], v[80:83]
	v_mfma_f32_16x16x32_bf16 v[68:71], v[144:147], v[202:205], v[68:71]
	v_mfma_f32_16x16x32_bf16 v[64:67], v[152:155], v[202:205], v[64:67]
	v_mfma_f32_16x16x32_bf16 v[132:135], v[148:151], v[164:167], v[132:135]
	v_mfma_f32_16x16x32_bf16 v[124:127], v[156:159], v[164:167], v[124:127]
	v_mfma_f32_16x16x32_bf16 v[104:107], v[148:151], v[172:175], v[104:107]
	v_mfma_f32_16x16x32_bf16 v[100:103], v[156:159], v[172:175], v[100:103]
	v_mfma_f32_16x16x32_bf16 v[84:87], v[148:151], v[180:183], v[84:87]
	v_mfma_f32_16x16x32_bf16 v[80:83], v[156:159], v[180:183], v[80:83]
	v_mfma_f32_16x16x32_bf16 v[68:71], v[148:151], v[206:209], v[68:71]
	v_mfma_f32_16x16x32_bf16 v[64:67], v[156:159], v[206:209], v[64:67]
	s_setprio 0
	s_barrier
	s_add_i32 s76, s67, s53
	s_add_u32 s98, s34, s12
	s_addc_u32 s99, s35, s13
	s_add_u32 s100, s50, s12
	s_addc_u32 s101, s51, s13
	s_mov_b32 m0, s76
	ds_read_b128 v[160:163], v225 offset:16384
	ds_read_b128 v[164:167], v225 offset:17408
	ds_read_b128 v[168:171], v225 offset:18432
	ds_read_b128 v[172:175], v225 offset:19456
	ds_read_b128 v[176:179], v225 offset:20480
	ds_read_b128 v[180:183], v225 offset:21504
	ds_read_b128 v[202:205], v225 offset:22528
	ds_read_b128 v[206:209], v225 offset:23552
	global_load_lds_dwordx4 v186, s[34:35]
	s_add_i32 m0, s76, 0x2000
	s_add_u32 s76, s34, 0xb0000
	s_addc_u32 s77, s35, 0
	s_add_i32 s78, s68, s53
	global_load_lds_dwordx4 v190, s[34:35]
	s_mov_b32 m0, s78
	s_nop 0
	global_load_lds_dwordx4 v186, s[76:77]
	s_add_i32 m0, s78, 0x2000
	s_nop 0
	global_load_lds_dwordx4 v190, s[76:77]
	s_mov_b32 m0, s54
	s_nop 0
	global_load_lds_dwordx4 v184, s[50:51]
	s_mov_b32 m0, s55
	s_nop 0
	global_load_lds_dwordx4 v188, s[50:51]
	s_waitcnt vmcnt(8)
	s_waitcnt lgkmcnt(0)
	s_barrier
	s_setprio 1
	s_waitcnt lgkmcnt(0)
	v_mfma_f32_16x16x32_bf16 v[60:63], v[96:99], v[160:163], v[60:63]
	v_mfma_f32_16x16x32_bf16 v[56:59], v[120:123], v[160:163], v[56:59]
	v_mfma_f32_16x16x32_bf16 v[44:47], v[96:99], v[168:171], v[44:47]
	v_mfma_f32_16x16x32_bf16 v[40:43], v[120:123], v[168:171], v[40:43]
	v_mfma_f32_16x16x32_bf16 v[28:31], v[96:99], v[176:179], v[28:31]
	v_mfma_f32_16x16x32_bf16 v[24:27], v[120:123], v[176:179], v[24:27]
	v_mfma_f32_16x16x32_bf16 v[12:15], v[96:99], v[202:205], v[12:15]
	v_mfma_f32_16x16x32_bf16 v[8:11], v[120:123], v[202:205], v[8:11]
	v_mfma_f32_16x16x32_bf16 v[60:63], v[108:111], v[164:167], v[60:63]
	v_mfma_f32_16x16x32_bf16 v[56:59], v[128:131], v[164:167], v[56:59]
	v_mfma_f32_16x16x32_bf16 v[44:47], v[108:111], v[172:175], v[44:47]
	v_mfma_f32_16x16x32_bf16 v[40:43], v[128:131], v[172:175], v[40:43]
	v_mfma_f32_16x16x32_bf16 v[28:31], v[108:111], v[180:183], v[28:31]
	v_mfma_f32_16x16x32_bf16 v[24:27], v[128:131], v[180:183], v[24:27]
	v_mfma_f32_16x16x32_bf16 v[12:15], v[108:111], v[206:209], v[12:15]
	v_mfma_f32_16x16x32_bf16 v[8:11], v[128:131], v[206:209], v[8:11]
	v_mfma_f32_16x16x32_bf16 v[52:55], v[144:147], v[160:163], v[52:55]
	v_mfma_f32_16x16x32_bf16 v[48:51], v[152:155], v[160:163], v[48:51]
	v_mfma_f32_16x16x32_bf16 v[36:39], v[144:147], v[168:171], v[36:39]
	v_mfma_f32_16x16x32_bf16 v[32:35], v[152:155], v[168:171], v[32:35]
	v_mfma_f32_16x16x32_bf16 v[20:23], v[144:147], v[176:179], v[20:23]
	v_mfma_f32_16x16x32_bf16 v[16:19], v[152:155], v[176:179], v[16:19]
	v_mfma_f32_16x16x32_bf16 v[4:7], v[144:147], v[202:205], v[4:7]
	v_mfma_f32_16x16x32_bf16 v[0:3], v[152:155], v[202:205], v[0:3]
	v_mfma_f32_16x16x32_bf16 v[52:55], v[148:151], v[164:167], v[52:55]
	v_mfma_f32_16x16x32_bf16 v[48:51], v[156:159], v[164:167], v[48:51]
	v_mfma_f32_16x16x32_bf16 v[36:39], v[148:151], v[172:175], v[36:39]
	v_mfma_f32_16x16x32_bf16 v[32:35], v[156:159], v[172:175], v[32:35]
	v_mfma_f32_16x16x32_bf16 v[20:23], v[148:151], v[180:183], v[20:23]
	v_mfma_f32_16x16x32_bf16 v[16:19], v[156:159], v[180:183], v[16:19]
	v_mfma_f32_16x16x32_bf16 v[4:7], v[148:151], v[206:209], v[4:7]
	v_mfma_f32_16x16x32_bf16 v[0:3], v[156:159], v[206:209], v[0:3]
	s_setprio 0
	s_barrier
; #define PG8_STAGE(bufoff, gbase, voff) do { _Pragma("unroll") for (int _i = 0; _i < 2; ++_i) \
;         __builtin_amdgcn_global_load_lds((const unsigned*)((const char*)(gbase) + (voff)[_i]), (PG8_LAS unsigned*)(lds + (bufoff) + ldsw + _i * 8192), 16, 0, 0); } while (0)
; #define PG8_LDA(dst, b, h) do { _Pragma("unroll") for (int m = 0; m < 4; ++m) _Pragma("unroll") for (int k = 0; k < 2; ++k) dst[m][k] = *(const PG8_LAS bf16x8*)(lds + PG8_SA(b, h) + aoff + m * 2048 + k * 1024); } while (0)
; #define PG8_MMA(ai, bj, At, Bt) do { __builtin_amdgcn_s_setprio(1); _Pragma("unroll") for (int m = 0; m < 4; ++m) _Pragma("unroll") for (int n = 0; n < 2; ++n) _Pragma("unroll") for (int k = 0; k < 2; ++k) \
;         acc[ai][bj][m][n] = __builtin_amdgcn_mfma_f32_16x16x32_bf16(Bt[n][k], At[m][k], acc[ai][bj][m][n], 0, 0, 0); __builtin_amdgcn_s_setprio(0); } while (0)
; #define PG8_WAIT_V(n) asm volatile("s_waitcnt vmcnt(" #n ")" ::: "memory")
; #define PG8_WAIT_L(n) asm volatile("s_waitcnt lgkmcnt(" #n ")" ::: "memory")
; #define PG8_BAR __builtin_amdgcn_s_barrier()
; #define PG8_SCHED __builtin_amdgcn_sched_barrier(0)
; template <class Epi, class Sched, bool ALIGN_EPI = false, bool SP2 = false>
; __device__ __forceinline__ void gemm_phase(PG8_LAS unsigned char* lds, const Gemm g, const Sched& S, const Epi& E) {
;     ...
;             PG8_WAIT_V(8); PG8_WAIT_L(0); PG8_BAR; PG8_MMA(0, 0, At, B0); PG8_MMA(0, 1, At, B1); PG8_BAR; PG8_SCHED;
;             PG8_LDA(At, 1, 1); PG8_STAGE(PG8_SB(1, 0), b3, voffB); PG8_STAGE(PG8_SB(1, 1), b3 + hstep, voffB); PG8_STAGE(PG8_SA(1, 0), a3, voffA);
;             PG8_WAIT_V(8); PG8_WAIT_L(0); PG8_BAR; PG8_MMA(1, 0, At, B0); PG8_MMA(1, 1, At, B1); PG8_BAR; PG8_SCHED;
	s_add_i32 s76, 0, 0x18000
	s_add_i32 s77, 0, 0x1c000
	v_add_u32_e32 v128, s76, v221
	v_add_u32_e32 v156, s77, v221
	ds_read_b128 v[96:99], v128
	ds_read_b128 v[108:111], v128 offset:1024
	ds_read_b128 v[120:123], v128 offset:2048
	ds_read_b128 v[128:131], v128 offset:3072
	ds_read_b128 v[144:147], v156
	ds_read_b128 v[148:151], v156 offset:1024
	ds_read_b128 v[152:155], v156 offset:2048
	ds_read_b128 v[156:159], v156 offset:3072
	s_add_u32 s50, s50, 0xb0000
	s_addc_u32 s51, s51, 0
	s_mov_b32 m0, s56
	ds_read_b128 v[160:163], v225 offset:32768
	ds_read_b128 v[164:167], v225 offset:33792
	ds_read_b128 v[168:171], v225 offset:34816
	ds_read_b128 v[172:175], v225 offset:35840
	ds_read_b128 v[176:179], v225 offset:36864
	ds_read_b128 v[180:183], v225 offset:37888
	ds_read_b128 v[202:205], v225 offset:38912
	ds_read_b128 v[206:209], v225 offset:39936
	global_load_lds_dwordx4 v184, s[50:51]
	s_mov_b32 m0, s57
	s_nop 0
	global_load_lds_dwordx4 v188, s[50:51]
	s_waitcnt vmcnt(8)
	s_waitcnt lgkmcnt(0)
	s_barrier
	s_setprio 1
	s_waitcnt lgkmcnt(0)
	v_mfma_f32_16x16x32_bf16 v[140:143], v[96:99], v[160:163], v[140:143]
	v_mfma_f32_16x16x32_bf16 v[136:139], v[120:123], v[160:163], v[136:139]
	v_mfma_f32_16x16x32_bf16 v[116:119], v[96:99], v[168:171], v[116:119]
	v_mfma_f32_16x16x32_bf16 v[112:115], v[120:123], v[168:171], v[112:115]
	v_mfma_f32_16x16x32_bf16 v[92:95], v[96:99], v[176:179], v[92:95]
	v_mfma_f32_16x16x32_bf16 v[88:91], v[120:123], v[176:179], v[88:91]
	v_mfma_f32_16x16x32_bf16 v[76:79], v[96:99], v[202:205], v[76:79]
	v_mfma_f32_16x16x32_bf16 v[72:75], v[120:123], v[202:205], v[72:75]
	v_mfma_f32_16x16x32_bf16 v[140:143], v[108:111], v[164:167], v[140:143]
	v_mfma_f32_16x16x32_bf16 v[136:139], v[128:131], v[164:167], v[136:139]
	v_mfma_f32_16x16x32_bf16 v[116:119], v[108:111], v[172:175], v[116:119]
	v_mfma_f32_16x16x32_bf16 v[112:115], v[128:131], v[172:175], v[112:115]
	v_mfma_f32_16x16x32_bf16 v[92:95], v[108:111], v[180:183], v[92:95]
	v_mfma_f32_16x16x32_bf16 v[88:91], v[128:131], v[180:183], v[88:91]
	v_mfma_f32_16x16x32_bf16 v[76:79], v[108:111], v[206:209], v[76:79]
	v_mfma_f32_16x16x32_bf16 v[72:75], v[128:131], v[206:209], v[72:75]
	v_mfma_f32_16x16x32_bf16 v[132:135], v[144:147], v[160:163], v[132:135]
	v_mfma_f32_16x16x32_bf16 v[124:127], v[152:155], v[160:163], v[124:127]
	v_mfma_f32_16x16x32_bf16 v[104:107], v[144:147], v[168:171], v[104:107]
	v_mfma_f32_16x16x32_bf16 v[100:103], v[152:155], v[168:171], v[100:103]
	v_mfma_f32_16x16x32_bf16 v[84:87], v[144:147], v[176:179], v[84:87]
	v_mfma_f32_16x16x32_bf16 v[80:83], v[152:155], v[176:179], v[80:83]
	v_mfma_f32_16x16x32_bf16 v[68:71], v[144:147], v[202:205], v[68:71]
	v_mfma_f32_16x16x32_bf16 v[64:67], v[152:155], v[202:205], v[64:67]
	v_mfma_f32_16x16x32_bf16 v[132:135], v[148:151], v[164:167], v[132:135]
	v_mfma_f32_16x16x32_bf16 v[124:127], v[156:159], v[164:167], v[124:127]
	v_mfma_f32_16x16x32_bf16 v[104:107], v[148:151], v[172:175], v[104:107]
	v_mfma_f32_16x16x32_bf16 v[100:103], v[156:159], v[172:175], v[100:103]
	v_mfma_f32_16x16x32_bf16 v[84:87], v[148:151], v[180:183], v[84:87]
	v_mfma_f32_16x16x32_bf16 v[80:83], v[156:159], v[180:183], v[80:83]
	v_mfma_f32_16x16x32_bf16 v[68:71], v[148:151], v[206:209], v[68:71]
	v_mfma_f32_16x16x32_bf16 v[64:67], v[156:159], v[206:209], v[64:67]
	s_setprio 0
	s_barrier
	s_add_i32 s50, s76, s53
	s_mov_b32 m0, s50
	ds_read_b128 v[160:163], v225 offset:49152
	ds_read_b128 v[164:167], v225 offset:50176
	ds_read_b128 v[168:171], v225 offset:51200
	ds_read_b128 v[172:175], v225 offset:52224
	ds_read_b128 v[176:179], v225 offset:53248
	ds_read_b128 v[180:183], v225 offset:54272
	ds_read_b128 v[202:205], v225 offset:55296
	ds_read_b128 v[206:209], v225 offset:56320
	global_load_lds_dwordx4 v186, s[98:99]
	s_add_i32 m0, s50, 0x2000
	s_add_u32 s34, s34, 0xb0080
	s_addc_u32 s35, s35, 0
	s_add_i32 s50, s77, s53
	global_load_lds_dwordx4 v190, s[98:99]
	s_mov_b32 m0, s50
	s_nop 0
	global_load_lds_dwordx4 v186, s[34:35]
	s_add_i32 m0, s50, 0x2000
	s_nop 0
	global_load_lds_dwordx4 v190, s[34:35]
	s_mov_b32 m0, s62
	s_nop 0
	global_load_lds_dwordx4 v184, s[100:101]
	s_mov_b32 m0, s63
	s_nop 0
	global_load_lds_dwordx4 v188, s[100:101]
	s_waitcnt vmcnt(8)
	s_waitcnt lgkmcnt(0)
	s_barrier
	s_setprio 1
	s_waitcnt lgkmcnt(0)
	v_mfma_f32_16x16x32_bf16 v[60:63], v[96:99], v[160:163], v[60:63]
	v_mfma_f32_16x16x32_bf16 v[56:59], v[120:123], v[160:163], v[56:59]
	v_mfma_f32_16x16x32_bf16 v[44:47], v[96:99], v[168:171], v[44:47]
	v_mfma_f32_16x16x32_bf16 v[40:43], v[120:123], v[168:171], v[40:43]
	v_mfma_f32_16x16x32_bf16 v[28:31], v[96:99], v[176:179], v[28:31]
	v_mfma_f32_16x16x32_bf16 v[24:27], v[120:123], v[176:179], v[24:27]
	v_mfma_f32_16x16x32_bf16 v[12:15], v[96:99], v[202:205], v[12:15]
	v_mfma_f32_16x16x32_bf16 v[8:11], v[120:123], v[202:205], v[8:11]
	v_mfma_f32_16x16x32_bf16 v[60:63], v[108:111], v[164:167], v[60:63]
	v_mfma_f32_16x16x32_bf16 v[56:59], v[128:131], v[164:167], v[56:59]
	v_mfma_f32_16x16x32_bf16 v[44:47], v[108:111], v[172:175], v[44:47]
	v_mfma_f32_16x16x32_bf16 v[40:43], v[128:131], v[172:175], v[40:43]
	v_mfma_f32_16x16x32_bf16 v[28:31], v[108:111], v[180:183], v[28:31]
	v_mfma_f32_16x16x32_bf16 v[24:27], v[128:131], v[180:183], v[24:27]
	v_mfma_f32_16x16x32_bf16 v[12:15], v[108:111], v[206:209], v[12:15]
	v_mfma_f32_16x16x32_bf16 v[8:11], v[128:131], v[206:209], v[8:11]
	v_mfma_f32_16x16x32_bf16 v[52:55], v[144:147], v[160:163], v[52:55]
	v_mfma_f32_16x16x32_bf16 v[48:51], v[152:155], v[160:163], v[48:51]
	v_mfma_f32_16x16x32_bf16 v[36:39], v[144:147], v[168:171], v[36:39]
	v_mfma_f32_16x16x32_bf16 v[32:35], v[152:155], v[168:171], v[32:35]
	v_mfma_f32_16x16x32_bf16 v[20:23], v[144:147], v[176:179], v[20:23]
	v_mfma_f32_16x16x32_bf16 v[16:19], v[152:155], v[176:179], v[16:19]
	v_mfma_f32_16x16x32_bf16 v[4:7], v[144:147], v[202:205], v[4:7]
	v_mfma_f32_16x16x32_bf16 v[0:3], v[152:155], v[202:205], v[0:3]
	v_mfma_f32_16x16x32_bf16 v[52:55], v[148:151], v[164:167], v[52:55]
	v_mfma_f32_16x16x32_bf16 v[48:51], v[156:159], v[164:167], v[48:51]
	v_mfma_f32_16x16x32_bf16 v[36:39], v[148:151], v[172:175], v[36:39]
	v_mfma_f32_16x16x32_bf16 v[32:35], v[156:159], v[172:175], v[32:35]
	v_mfma_f32_16x16x32_bf16 v[20:23], v[148:151], v[180:183], v[20:23]
	v_mfma_f32_16x16x32_bf16 v[16:19], v[156:159], v[180:183], v[16:19]
	v_mfma_f32_16x16x32_bf16 v[4:7], v[148:151], v[206:209], v[4:7]
	v_mfma_f32_16x16x32_bf16 v[0:3], v[156:159], v[206:209], v[0:3]
	s_setprio 0
	s_barrier
	s_add_i32 s75, s75, 2
	s_add_u32 s20, s20, 0x100
	s_addc_u32 s21, s21, 0
	s_add_u32 s73, s73, 0x100
	s_addc_u32 s74, s74, 0
	s_cmp_gt_u32 s75, 41
	s_cbranch_scc0 .LBB0_309
	s_and_b64 vcc, exec, s[14:15]
	s_cbranch_vccz .LBB0_312
	s_barrier

; #define PG8_STAGE(bufoff, gbase, voff) do { _Pragma("unroll") for (int _i = 0; _i < 2; ++_i) \
;         __builtin_amdgcn_global_load_lds((const unsigned*)((const char*)(gbase) + (voff)[_i]), (PG8_LAS unsigned*)(lds + (bufoff) + ldsw + _i * 8192), 16, 0, 0); } while (0)
; #define PG8_LDA(dst, b, h) do { _Pragma("unroll") for (int m = 0; m < 4; ++m) _Pragma("unroll") for (int k = 0; k < 2; ++k) dst[m][k] = *(const PG8_LAS bf16x8*)(lds + PG8_SA(b, h) + aoff + m * 2048 + k * 1024); } while (0)
; #define PG8_LDB(dst, b, h) do { _Pragma("unroll") for (int n = 0; n < 2; ++n) _Pragma("unroll") for (int k = 0; k < 2; ++k) dst[n][k] = *(const PG8_LAS bf16x8*)(lds + PG8_SB(b, h) + boff + n * 2048 + k * 1024); } while (0)
; #define PG8_BAR __builtin_amdgcn_s_barrier()
; template <class Epi, class Sched, bool ALIGN_EPI = false, bool SP2 = false>
; __device__ __forceinline__ void gemm_phase(PG8_LAS unsigned char* lds, const Gemm g, const Sched& S, const Epi& E) {
;     ...
;         const bool has_next = S.next(ui + 1, nxt);
;         const char* nA = has_next ? (const char*)g.A + (size_t)nxt.pm * tstep : cA; const char* nB = has_next ? (const char*)g.Bt + (size_t)nxt.pn * tstep : cB;
;         for (int t = 0; t < nt; t += 2) {
;             const bool last = (t == nt - 2);
;             const char* a1 = cA + (size_t)(t + 1) * kstep;
;             const char* a2 = last ? nA : cA + (size_t)(t + 2) * kstep; const char* b2 = last ? nB : cB + (size_t)(t + 2) * kstep;
;             const char* a3 = a2 + kstep; const char* b3 = b2 + kstep;
;             if (last && has_next) S.a_ready(nxt);
;             if constexpr (SP2) {
;             PG8_LDB(B0, 0, 0); PG8_LDB(B1, 0, 1); PG8_SCHED; PG8_LDA(At, 0, 0); PG8_STAGE(PG8_SA(1, 1), a1 + hstep, voffA);
;             PG8_WAIT_V(8); PG8_WAIT_L(0); PG8_BAR; PG8_MMA(0, 0, At, B0); PG8_MMA(0, 1, At, B1); PG8_BAR; PG8_SCHED;
;             PG8_LDA(At, 0, 1); PG8_STAGE(PG8_SB(0, 0), b2, voffB); PG8_STAGE(PG8_SB(0, 1), b2 + hstep, voffB); PG8_STAGE(PG8_SA(0, 0), a2, voffA);
;             PG8_WAIT_V(8); PG8_WAIT_L(0); PG8_BAR; PG8_MMA(1, 0, At, B0); PG8_MMA(1, 1, At, B1); PG8_BAR; PG8_SCHED;
;             PG8_LDB(B0, 1, 0); PG8_LDB(B1, 1, 1); PG8_SCHED; PG8_LDA(At, 1, 0); PG8_STAGE(PG8_SA(0, 1), a2 + hstep, voffA);
;             PG8_WAIT_V(8); PG8_WAIT_L(0); PG8_BAR; PG8_MMA(0, 0, At, B0); PG8_MMA(0, 1, At, B1); PG8_BAR; PG8_SCHED;
.LBB0_413:
	s_ashr_i32 s43, s42, 31
	s_lshl_b64 s[48:49], s[42:43], 19
	s_add_u32 s48, s36, s48
	s_addc_u32 s49, s37, s49
	s_and_b64 s[50:51], s[4:5], exec
	s_cselect_b32 s43, s49, s21
	s_cselect_b32 s78, s48, s20
	s_ashr_i32 s19, s18, 31
	s_lshl_b64 s[50:51], s[18:19], 19
	s_add_u32 s50, s61, s50
	s_addc_u32 s51, s62, s51
	s_and_b64 s[54:55], s[4:5], exec
	s_cselect_b32 s19, s51, s53
	s_cselect_b32 s79, s50, s52
	s_add_u32 s20, s20, 0x40080
	s_addc_u32 s21, s21, 0
	s_add_u32 s80, s52, 0x100
	s_addc_u32 s81, s53, 0
	s_mov_b32 s84, -2
	ds_read_b128 v[146:149], v165
	ds_read_b128 v[150:153], v165 offset:1024
	ds_read_b128 v[154:157], v165 offset:2048
	ds_read_b128 v[168:171], v165 offset:3072
	ds_read_b128 v[172:175], v166
	ds_read_b128 v[176:179], v166 offset:1024
	ds_read_b128 v[180:183], v166 offset:2048
	ds_read_b128 v[184:187], v166 offset:3072
	s_add_u32 s52, s20, 0xfffc0080
	s_addc_u32 s53, s21, -1
	s_cmp_eq_u32 s84, 12
	s_cselect_b32 s55, s43, s53
	s_cselect_b32 s54, s78, s52
	s_cselect_b32 s53, s19, s81
	s_cselect_b32 s52, s79, s80
	s_add_i32 m0, s35, 0xc000
	ds_read_b128 v[188:191], v167
	ds_read_b128 v[192:195], v167 offset:1024
	ds_read_b128 v[198:201], v167 offset:2048
	ds_read_b128 v[202:205], v167 offset:3072
	ds_read_b128 v[206:209], v167 offset:4096
	ds_read_b128 v[210:213], v167 offset:5120
	ds_read_b128 v[214:217], v167 offset:6144
	ds_read_b128 v[218:221], v167 offset:7168
	global_load_lds_dwordx4 v138, s[20:21]
	s_add_i32 m0, s35, 0xe000
	s_nop 0
	global_load_lds_dwordx4 v140, s[20:21]
	s_waitcnt vmcnt(8)
	s_waitcnt lgkmcnt(0)
	s_barrier
	s_setprio 1
	s_waitcnt lgkmcnt(0)
	v_mfma_f32_16x16x32_bf16 v[124:127], v[146:149], v[188:191], 0
	v_mfma_f32_16x16x32_bf16 v[120:123], v[154:157], v[188:191], 0
	v_mfma_f32_16x16x32_bf16 v[108:111], v[146:149], v[198:201], 0
	v_mfma_f32_16x16x32_bf16 v[104:107], v[154:157], v[198:201], 0
	v_mfma_f32_16x16x32_bf16 v[92:95], v[146:149], v[206:209], 0
	v_mfma_f32_16x16x32_bf16 v[88:91], v[154:157], v[206:209], 0
	v_mfma_f32_16x16x32_bf16 v[76:79], v[146:149], v[214:217], 0
	v_mfma_f32_16x16x32_bf16 v[72:75], v[154:157], v[214:217], 0
	v_mfma_f32_16x16x32_bf16 v[124:127], v[150:153], v[192:195], v[124:127]
	v_mfma_f32_16x16x32_bf16 v[120:123], v[168:171], v[192:195], v[120:123]
	v_mfma_f32_16x16x32_bf16 v[108:111], v[150:153], v[202:205], v[108:111]
	v_mfma_f32_16x16x32_bf16 v[104:107], v[168:171], v[202:205], v[104:107]
	v_mfma_f32_16x16x32_bf16 v[92:95], v[150:153], v[210:213], v[92:95]
	v_mfma_f32_16x16x32_bf16 v[88:91], v[168:171], v[210:213], v[88:91]
	v_mfma_f32_16x16x32_bf16 v[76:79], v[150:153], v[218:221], v[76:79]
	v_mfma_f32_16x16x32_bf16 v[72:75], v[168:171], v[218:221], v[72:75]
	v_mfma_f32_16x16x32_bf16 v[116:119], v[172:175], v[188:191], 0
	v_mfma_f32_16x16x32_bf16 v[112:115], v[180:183], v[188:191], 0
	v_mfma_f32_16x16x32_bf16 v[100:103], v[172:175], v[198:201], 0
	v_mfma_f32_16x16x32_bf16 v[96:99], v[180:183], v[198:201], 0
	v_mfma_f32_16x16x32_bf16 v[84:87], v[172:175], v[206:209], 0
	v_mfma_f32_16x16x32_bf16 v[80:83], v[180:183], v[206:209], 0
	v_mfma_f32_16x16x32_bf16 v[68:71], v[172:175], v[214:217], 0
	v_mfma_f32_16x16x32_bf16 v[64:67], v[180:183], v[214:217], 0
	v_mfma_f32_16x16x32_bf16 v[116:119], v[176:179], v[192:195], v[116:119]
	v_mfma_f32_16x16x32_bf16 v[112:115], v[184:187], v[192:195], v[112:115]
	v_mfma_f32_16x16x32_bf16 v[100:103], v[176:179], v[202:205], v[100:103]
	v_mfma_f32_16x16x32_bf16 v[96:99], v[184:187], v[202:205], v[96:99]
	v_mfma_f32_16x16x32_bf16 v[84:87], v[176:179], v[210:213], v[84:87]
	v_mfma_f32_16x16x32_bf16 v[80:83], v[184:187], v[210:213], v[80:83]
	v_mfma_f32_16x16x32_bf16 v[68:71], v[176:179], v[218:221], v[68:71]
	v_mfma_f32_16x16x32_bf16 v[64:67], v[184:187], v[218:221], v[64:67]
	s_setprio 0
	s_barrier
	s_add_i32 s85, s72, s63
	s_add_u32 s98, s52, s8
	s_addc_u32 s99, s53, s9
	s_add_u32 s100, s54, s8
	s_addc_u32 s101, s55, s9
	s_mov_b32 m0, s85
	ds_read_b128 v[188:191], v167 offset:16384
	ds_read_b128 v[192:195], v167 offset:17408
	ds_read_b128 v[198:201], v167 offset:18432
	ds_read_b128 v[202:205], v167 offset:19456
	ds_read_b128 v[206:209], v167 offset:20480
	ds_read_b128 v[210:213], v167 offset:21504
	ds_read_b128 v[214:217], v167 offset:22528
	ds_read_b128 v[218:221], v167 offset:23552
	global_load_lds_dwordx4 v132, s[52:53]
	s_add_i32 m0, s85, 0x2000
	s_add_u32 s86, s52, 0x40000
	s_addc_u32 s87, s53, 0
	s_add_i32 s85, s73, s63
	global_load_lds_dwordx4 v128, s[52:53]
	s_mov_b32 m0, s85
	s_nop 0
	global_load_lds_dwordx4 v132, s[86:87]
	s_add_i32 m0, s85, 0x2000
	s_nop 0
	global_load_lds_dwordx4 v128, s[86:87]
	s_mov_b32 m0, s35
	s_nop 0
	global_load_lds_dwordx4 v134, s[54:55]
	s_mov_b32 m0, s65
	s_nop 0
	global_load_lds_dwordx4 v130, s[54:55]
	s_waitcnt vmcnt(8)
	s_waitcnt lgkmcnt(0)
	s_barrier
; #define PG8_STAGE(bufoff, gbase, voff) do { _Pragma("unroll") for (int _i = 0; _i < 2; ++_i) \
;         __builtin_amdgcn_global_load_lds((const unsigned*)((const char*)(gbase) + (voff)[_i]), (PG8_LAS unsigned*)(lds + (bufoff) + ldsw + _i * 8192), 16, 0, 0); } while (0)
; #define PG8_LDA(dst, b, h) do { _Pragma("unroll") for (int m = 0; m < 4; ++m) _Pragma("unroll") for (int k = 0; k < 2; ++k) dst[m][k] = *(const PG8_LAS bf16x8*)(lds + PG8_SA(b, h) + aoff + m * 2048 + k * 1024); } while (0)
; #define PG8_LDB(dst, b, h) do { _Pragma("unroll") for (int n = 0; n < 2; ++n) _Pragma("unroll") for (int k = 0; k < 2; ++k) dst[n][k] = *(const PG8_LAS bf16x8*)(lds + PG8_SB(b, h) + boff + n * 2048 + k * 1024); } while (0)
; #define PG8_MMA(ai, bj, At, Bt) do { __builtin_amdgcn_s_setprio(1); _Pragma("unroll") for (int m = 0; m < 4; ++m) _Pragma("unroll") for (int n = 0; n < 2; ++n) _Pragma("unroll") for (int k = 0; k < 2; ++k) \
;         acc[ai][bj][m][n] = __builtin_amdgcn_mfma_f32_16x16x32_bf16(Bt[n][k], At[m][k], acc[ai][bj][m][n], 0, 0, 0); __builtin_amdgcn_s_setprio(0); } while (0)
; #define PG8_WAIT_V(n) asm volatile("s_waitcnt vmcnt(" #n ")" ::: "memory")
; #define PG8_WAIT_L(n) asm volatile("s_waitcnt lgkmcnt(" #n ")" ::: "memory")
; #define PG8_BAR __builtin_amdgcn_s_barrier()
; #define PG8_SCHED __builtin_amdgcn_sched_barrier(0)
; template <class Epi, class Sched, bool ALIGN_EPI = false, bool SP2 = false>
; __device__ __forceinline__ void gemm_phase(PG8_LAS unsigned char* lds, const Gemm g, const Sched& S, const Epi& E) {
;     ...
;             PG8_WAIT_V(8); PG8_WAIT_L(0); PG8_BAR; PG8_MMA(1, 0, At, B0); PG8_MMA(1, 1, At, B1); PG8_BAR; PG8_SCHED;
;             PG8_LDB(B0, 1, 0); PG8_LDB(B1, 1, 1); PG8_SCHED; PG8_LDA(At, 1, 0); PG8_STAGE(PG8_SA(0, 1), a2 + hstep, voffA);
;             PG8_WAIT_V(8); PG8_WAIT_L(0); PG8_BAR; PG8_MMA(0, 0, At, B0); PG8_MMA(0, 1, At, B1); PG8_BAR; PG8_SCHED;
	s_setprio 1
	s_waitcnt lgkmcnt(0)
	v_mfma_f32_16x16x32_bf16 v[60:63], v[146:149], v[188:191], 0
	v_mfma_f32_16x16x32_bf16 v[56:59], v[154:157], v[188:191], 0
	v_mfma_f32_16x16x32_bf16 v[44:47], v[146:149], v[198:201], 0
	v_mfma_f32_16x16x32_bf16 v[40:43], v[154:157], v[198:201], 0
	v_mfma_f32_16x16x32_bf16 v[28:31], v[146:149], v[206:209], 0
	v_mfma_f32_16x16x32_bf16 v[24:27], v[154:157], v[206:209], 0
	v_mfma_f32_16x16x32_bf16 v[12:15], v[146:149], v[214:217], 0
	v_mfma_f32_16x16x32_bf16 v[8:11], v[154:157], v[214:217], 0
	v_mfma_f32_16x16x32_bf16 v[60:63], v[150:153], v[192:195], v[60:63]
	v_mfma_f32_16x16x32_bf16 v[56:59], v[168:171], v[192:195], v[56:59]
	v_mfma_f32_16x16x32_bf16 v[44:47], v[150:153], v[202:205], v[44:47]
	v_mfma_f32_16x16x32_bf16 v[40:43], v[168:171], v[202:205], v[40:43]
	v_mfma_f32_16x16x32_bf16 v[28:31], v[150:153], v[210:213], v[28:31]
	v_mfma_f32_16x16x32_bf16 v[24:27], v[168:171], v[210:213], v[24:27]
	v_mfma_f32_16x16x32_bf16 v[12:15], v[150:153], v[218:221], v[12:15]
	v_mfma_f32_16x16x32_bf16 v[8:11], v[168:171], v[218:221], v[8:11]
	v_mfma_f32_16x16x32_bf16 v[52:55], v[172:175], v[188:191], 0
	v_mfma_f32_16x16x32_bf16 v[48:51], v[180:183], v[188:191], 0
	v_mfma_f32_16x16x32_bf16 v[36:39], v[172:175], v[198:201], 0
	v_mfma_f32_16x16x32_bf16 v[32:35], v[180:183], v[198:201], 0
	v_mfma_f32_16x16x32_bf16 v[20:23], v[172:175], v[206:209], 0
	v_mfma_f32_16x16x32_bf16 v[16:19], v[180:183], v[206:209], 0
	v_mfma_f32_16x16x32_bf16 v[4:7], v[172:175], v[214:217], 0
	v_mfma_f32_16x16x32_bf16 v[0:3], v[180:183], v[214:217], 0
	v_mfma_f32_16x16x32_bf16 v[52:55], v[176:179], v[192:195], v[52:55]
	v_mfma_f32_16x16x32_bf16 v[48:51], v[184:187], v[192:195], v[48:51]
	v_mfma_f32_16x16x32_bf16 v[36:39], v[176:179], v[202:205], v[36:39]
	v_mfma_f32_16x16x32_bf16 v[32:35], v[184:187], v[202:205], v[32:35]
	v_mfma_f32_16x16x32_bf16 v[20:23], v[176:179], v[210:213], v[20:23]
	v_mfma_f32_16x16x32_bf16 v[16:19], v[184:187], v[210:213], v[16:19]
	v_mfma_f32_16x16x32_bf16 v[4:7], v[176:179], v[218:221], v[4:7]
	v_mfma_f32_16x16x32_bf16 v[0:3], v[184:187], v[218:221], v[0:3]
	s_setprio 0
	s_barrier
	s_add_i32 s85, 0, 0x18000
	v_add_u32_e32 v136, s85, v161
	s_add_i32 s86, 0, 0x1c000
	ds_read_b128 v[146:149], v136
	ds_read_b128 v[150:153], v136 offset:1024
	ds_read_b128 v[154:157], v136 offset:2048
	ds_read_b128 v[168:171], v136 offset:3072
	v_add_u32_e32 v136, s86, v161
	ds_read_b128 v[172:175], v136
	ds_read_b128 v[176:179], v136 offset:1024
	ds_read_b128 v[180:183], v136 offset:2048
	ds_read_b128 v[184:187], v136 offset:3072
	s_add_u32 s54, s54, 0x40000
	s_addc_u32 s55, s55, 0
	s_mov_b32 m0, s66
	ds_read_b128 v[188:191], v167 offset:32768
	ds_read_b128 v[192:195], v167 offset:33792
	ds_read_b128 v[198:201], v167 offset:34816
	ds_read_b128 v[202:205], v167 offset:35840
	ds_read_b128 v[206:209], v167 offset:36864
	ds_read_b128 v[210:213], v167 offset:37888
	ds_read_b128 v[214:217], v167 offset:38912
	ds_read_b128 v[218:221], v167 offset:39936
	global_load_lds_dwordx4 v134, s[54:55]
	s_mov_b32 m0, s67
	s_nop 0
	global_load_lds_dwordx4 v130, s[54:55]
	s_waitcnt vmcnt(8)
	s_waitcnt lgkmcnt(0)
	s_barrier
	s_setprio 1
	s_waitcnt lgkmcnt(0)
	v_mfma_f32_16x16x32_bf16 v[124:127], v[146:149], v[188:191], v[124:127]
	v_mfma_f32_16x16x32_bf16 v[120:123], v[154:157], v[188:191], v[120:123]
	v_mfma_f32_16x16x32_bf16 v[108:111], v[146:149], v[198:201], v[108:111]
	v_mfma_f32_16x16x32_bf16 v[104:107], v[154:157], v[198:201], v[104:107]
	v_mfma_f32_16x16x32_bf16 v[92:95], v[146:149], v[206:209], v[92:95]
	v_mfma_f32_16x16x32_bf16 v[88:91], v[154:157], v[206:209], v[88:91]
	v_mfma_f32_16x16x32_bf16 v[76:79], v[146:149], v[214:217], v[76:79]
	v_mfma_f32_16x16x32_bf16 v[72:75], v[154:157], v[214:217], v[72:75]
	v_mfma_f32_16x16x32_bf16 v[124:127], v[150:153], v[192:195], v[124:127]
	v_mfma_f32_16x16x32_bf16 v[120:123], v[168:171], v[192:195], v[120:123]
	v_mfma_f32_16x16x32_bf16 v[108:111], v[150:153], v[202:205], v[108:111]
	v_mfma_f32_16x16x32_bf16 v[104:107], v[168:171], v[202:205], v[104:107]
	v_mfma_f32_16x16x32_bf16 v[92:95], v[150:153], v[210:213], v[92:95]
	v_mfma_f32_16x16x32_bf16 v[88:91], v[168:171], v[210:213], v[88:91]
	v_mfma_f32_16x16x32_bf16 v[76:79], v[150:153], v[218:221], v[76:79]
	v_mfma_f32_16x16x32_bf16 v[72:75], v[168:171], v[218:221], v[72:75]
	v_mfma_f32_16x16x32_bf16 v[116:119], v[172:175], v[188:191], v[116:119]
	v_mfma_f32_16x16x32_bf16 v[112:115], v[180:183], v[188:191], v[112:115]
	v_mfma_f32_16x16x32_bf16 v[100:103], v[172:175], v[198:201], v[100:103]
	v_mfma_f32_16x16x32_bf16 v[96:99], v[180:183], v[198:201], v[96:99]
	v_mfma_f32_16x16x32_bf16 v[84:87], v[172:175], v[206:209], v[84:87]
	v_mfma_f32_16x16x32_bf16 v[80:83], v[180:183], v[206:209], v[80:83]
	v_mfma_f32_16x16x32_bf16 v[68:71], v[172:175], v[214:217], v[68:71]
	v_mfma_f32_16x16x32_bf16 v[64:67], v[180:183], v[214:217], v[64:67]
	v_mfma_f32_16x16x32_bf16 v[116:119], v[176:179], v[192:195], v[116:119]
	v_mfma_f32_16x16x32_bf16 v[112:115], v[184:187], v[192:195], v[112:115]
	v_mfma_f32_16x16x32_bf16 v[100:103], v[176:179], v[202:205], v[100:103]
	v_mfma_f32_16x16x32_bf16 v[96:99], v[184:187], v[202:205], v[96:99]
	v_mfma_f32_16x16x32_bf16 v[84:87], v[176:179], v[210:213], v[84:87]
	v_mfma_f32_16x16x32_bf16 v[80:83], v[184:187], v[210:213], v[80:83]
	v_mfma_f32_16x16x32_bf16 v[68:71], v[176:179], v[218:221], v[68:71]
	v_mfma_f32_16x16x32_bf16 v[64:67], v[184:187], v[218:221], v[64:67]
	s_setprio 0
	s_barrier
; #define PG8_STAGE(bufoff, gbase, voff) do { _Pragma("unroll") for (int _i = 0; _i < 2; ++_i) \
;         __builtin_amdgcn_global_load_lds((const unsigned*)((const char*)(gbase) + (voff)[_i]), (PG8_LAS unsigned*)(lds + (bufoff) + ldsw + _i * 8192), 16, 0, 0); } while (0)
; #define PG8_LDA(dst, b, h) do { _Pragma("unroll") for (int m = 0; m < 4; ++m) _Pragma("unroll") for (int k = 0; k < 2; ++k) dst[m][k] = *(const PG8_LAS bf16x8*)(lds + PG8_SA(b, h) + aoff + m * 2048 + k * 1024); } while (0)
; #define PG8_LDB(dst, b, h) do { _Pragma("unroll") for (int n = 0; n < 2; ++n) _Pragma("unroll") for (int k = 0; k < 2; ++k) dst[n][k] = *(const PG8_LAS bf16x8*)(lds + PG8_SB(b, h) + boff + n * 2048 + k * 1024); } while (0)
; #define PG8_MMA(ai, bj, At, Bt) do { __builtin_amdgcn_s_setprio(1); _Pragma("unroll") for (int m = 0; m < 4; ++m) _Pragma("unroll") for (int n = 0; n < 2; ++n) _Pragma("unroll") for (int k = 0; k < 2; ++k) \
;         acc[ai][bj][m][n] = __builtin_amdgcn_mfma_f32_16x16x32_bf16(Bt[n][k], At[m][k], acc[ai][bj][m][n], 0, 0, 0); __builtin_amdgcn_s_setprio(0); } while (0)
; #define PG8_WAIT_V(n) asm volatile("s_waitcnt vmcnt(" #n ")" ::: "memory")
; template <class Epi, class Sched, bool ALIGN_EPI = false, bool SP2 = false>
; __device__ __forceinline__ void gemm_phase(PG8_LAS unsigned char* lds, const Gemm g, const Sched& S, const Epi& E) {
;     ...
;             PG8_LDB(B0, 0, 0); PG8_LDB(B1, 0, 1); PG8_SCHED; PG8_LDA(At, 0, 0); PG8_STAGE(PG8_SA(1, 1), a1 + hstep, voffA);
;             PG8_WAIT_V(8); PG8_WAIT_L(0); PG8_BAR; PG8_MMA(0, 0, At, B0); PG8_MMA(0, 1, At, B1); PG8_BAR; PG8_SCHED;
;             PG8_LDA(At, 0, 1); PG8_STAGE(PG8_SB(0, 0), b2, voffB); PG8_STAGE(PG8_SB(0, 1), b2 + hstep, voffB); PG8_STAGE(PG8_SA(0, 0), a2, voffA);
;             PG8_WAIT_V(8); PG8_WAIT_L(0); PG8_BAR; PG8_MMA(1, 0, At, B0); PG8_MMA(1, 1, At, B1); PG8_BAR; PG8_SCHED;
;             PG8_LDB(B0, 1, 0); PG8_LDB(B1, 1, 1); PG8_SCHED; PG8_LDA(At, 1, 0); PG8_STAGE(PG8_SA(0, 1), a2 + hstep, voffA);
;             PG8_WAIT_V(8); PG8_WAIT_L(0); PG8_BAR; PG8_MMA(0, 0, At, B0); PG8_MMA(0, 1, At, B1); PG8_BAR; PG8_SCHED;
;             PG8_LDA(At, 1, 1); PG8_STAGE(PG8_SB(1, 0), b3, voffB); PG8_STAGE(PG8_SB(1, 1), b3 + hstep, voffB); PG8_STAGE(PG8_SA(1, 0), a3, voffA);
;             PG8_WAIT_V(8); PG8_WAIT_L(0); PG8_BAR; PG8_MMA(1, 0, At, B0); PG8_MMA(1, 1, At, B1); PG8_BAR; PG8_SCHED;
	s_add_i32 s54, s85, s63
	s_mov_b32 m0, s54
	ds_read_b128 v[188:191], v167 offset:49152
	ds_read_b128 v[192:195], v167 offset:50176
	ds_read_b128 v[198:201], v167 offset:51200
	ds_read_b128 v[202:205], v167 offset:52224
	ds_read_b128 v[206:209], v167 offset:53248
	ds_read_b128 v[210:213], v167 offset:54272
	ds_read_b128 v[214:217], v167 offset:55296
	ds_read_b128 v[218:221], v167 offset:56320
	global_load_lds_dwordx4 v132, s[98:99]
	s_add_i32 m0, s54, 0x2000
	s_add_u32 s52, s52, 0x40080
	s_addc_u32 s53, s53, 0
	s_add_i32 s54, s86, s63
	global_load_lds_dwordx4 v128, s[98:99]
	s_mov_b32 m0, s54
	s_nop 0
	global_load_lds_dwordx4 v132, s[52:53]
	s_add_i32 m0, s54, 0x2000
	s_nop 0
	global_load_lds_dwordx4 v128, s[52:53]
	s_mov_b32 m0, s69
	s_nop 0
	global_load_lds_dwordx4 v134, s[100:101]
	s_mov_b32 m0, s70
	s_nop 0
	global_load_lds_dwordx4 v130, s[100:101]
	s_waitcnt vmcnt(8)
	s_waitcnt lgkmcnt(0)
	s_barrier
	s_setprio 1
	s_waitcnt lgkmcnt(0)
	v_mfma_f32_16x16x32_bf16 v[60:63], v[146:149], v[188:191], v[60:63]
	v_mfma_f32_16x16x32_bf16 v[56:59], v[154:157], v[188:191], v[56:59]
	v_mfma_f32_16x16x32_bf16 v[44:47], v[146:149], v[198:201], v[44:47]
	v_mfma_f32_16x16x32_bf16 v[40:43], v[154:157], v[198:201], v[40:43]
	v_mfma_f32_16x16x32_bf16 v[28:31], v[146:149], v[206:209], v[28:31]
	v_mfma_f32_16x16x32_bf16 v[24:27], v[154:157], v[206:209], v[24:27]
	v_mfma_f32_16x16x32_bf16 v[12:15], v[146:149], v[214:217], v[12:15]
	v_mfma_f32_16x16x32_bf16 v[8:11], v[154:157], v[214:217], v[8:11]
	v_mfma_f32_16x16x32_bf16 v[60:63], v[150:153], v[192:195], v[60:63]
	v_mfma_f32_16x16x32_bf16 v[56:59], v[168:171], v[192:195], v[56:59]
	v_mfma_f32_16x16x32_bf16 v[44:47], v[150:153], v[202:205], v[44:47]
	v_mfma_f32_16x16x32_bf16 v[40:43], v[168:171], v[202:205], v[40:43]
	v_mfma_f32_16x16x32_bf16 v[28:31], v[150:153], v[210:213], v[28:31]
	v_mfma_f32_16x16x32_bf16 v[24:27], v[168:171], v[210:213], v[24:27]
	v_mfma_f32_16x16x32_bf16 v[12:15], v[150:153], v[218:221], v[12:15]
	v_mfma_f32_16x16x32_bf16 v[8:11], v[168:171], v[218:221], v[8:11]
	v_mfma_f32_16x16x32_bf16 v[52:55], v[172:175], v[188:191], v[52:55]
	v_mfma_f32_16x16x32_bf16 v[48:51], v[180:183], v[188:191], v[48:51]
	v_mfma_f32_16x16x32_bf16 v[36:39], v[172:175], v[198:201], v[36:39]
	v_mfma_f32_16x16x32_bf16 v[32:35], v[180:183], v[198:201], v[32:35]
	v_mfma_f32_16x16x32_bf16 v[20:23], v[172:175], v[206:209], v[20:23]
	v_mfma_f32_16x16x32_bf16 v[16:19], v[180:183], v[206:209], v[16:19]
	v_mfma_f32_16x16x32_bf16 v[4:7], v[172:175], v[214:217], v[4:7]
	v_mfma_f32_16x16x32_bf16 v[0:3], v[180:183], v[214:217], v[0:3]
	v_mfma_f32_16x16x32_bf16 v[52:55], v[176:179], v[192:195], v[52:55]
	v_mfma_f32_16x16x32_bf16 v[48:51], v[184:187], v[192:195], v[48:51]
	v_mfma_f32_16x16x32_bf16 v[36:39], v[176:179], v[202:205], v[36:39]
	v_mfma_f32_16x16x32_bf16 v[32:35], v[184:187], v[202:205], v[32:35]
	v_mfma_f32_16x16x32_bf16 v[20:23], v[176:179], v[210:213], v[20:23]
	v_mfma_f32_16x16x32_bf16 v[16:19], v[184:187], v[210:213], v[16:19]
	v_mfma_f32_16x16x32_bf16 v[4:7], v[176:179], v[218:221], v[4:7]
	v_mfma_f32_16x16x32_bf16 v[0:3], v[184:187], v[218:221], v[0:3]
	s_setprio 0
	s_barrier
	s_add_i32 s84, s84, 2
	s_add_u32 s20, s20, 0x100
	s_addc_u32 s21, s21, 0
	s_add_u32 s80, s80, 0x100
	s_addc_u32 s81, s81, 0
	s_cmp_gt_u32 s84, 13
.LBB0_414:
	ds_read_b128 v[146:149], v165
	ds_read_b128 v[150:153], v165 offset:1024
	ds_read_b128 v[154:157], v165 offset:2048
	ds_read_b128 v[168:171], v165 offset:3072
	ds_read_b128 v[172:175], v166
	ds_read_b128 v[176:179], v166 offset:1024
	ds_read_b128 v[180:183], v166 offset:2048
	ds_read_b128 v[184:187], v166 offset:3072
	s_add_u32 s52, s20, 0xfffc0080
	s_addc_u32 s53, s21, -1
	s_cmp_eq_u32 s84, 12
	s_cselect_b32 s55, s43, s53
	s_cselect_b32 s54, s78, s52
	s_cselect_b32 s53, s19, s81
	s_cselect_b32 s52, s79, s80
	s_add_i32 m0, s35, 0xc000
	ds_read_b128 v[188:191], v167
	ds_read_b128 v[192:195], v167 offset:1024
	ds_read_b128 v[198:201], v167 offset:2048
	ds_read_b128 v[202:205], v167 offset:3072
	ds_read_b128 v[206:209], v167 offset:4096
	ds_read_b128 v[210:213], v167 offset:5120
	ds_read_b128 v[214:217], v167 offset:6144
	ds_read_b128 v[218:221], v167 offset:7168
	global_load_lds_dwordx4 v138, s[20:21]
	s_add_i32 m0, s35, 0xe000
	s_nop 0
	global_load_lds_dwordx4 v140, s[20:21]
	s_waitcnt vmcnt(8)
	s_waitcnt lgkmcnt(0)
	s_barrier
	s_setprio 1
	s_waitcnt lgkmcnt(0)
	v_mfma_f32_16x16x32_bf16 v[124:127], v[146:149], v[188:191], v[124:127]
	v_mfma_f32_16x16x32_bf16 v[120:123], v[154:157], v[188:191], v[120:123]
	v_mfma_f32_16x16x32_bf16 v[108:111], v[146:149], v[198:201], v[108:111]
	v_mfma_f32_16x16x32_bf16 v[104:107], v[154:157], v[198:201], v[104:107]
	v_mfma_f32_16x16x32_bf16 v[92:95], v[146:149], v[206:209], v[92:95]
	v_mfma_f32_16x16x32_bf16 v[88:91], v[154:157], v[206:209], v[88:91]
	v_mfma_f32_16x16x32_bf16 v[76:79], v[146:149], v[214:217], v[76:79]
	v_mfma_f32_16x16x32_bf16 v[72:75], v[154:157], v[214:217], v[72:75]
	v_mfma_f32_16x16x32_bf16 v[124:127], v[150:153], v[192:195], v[124:127]
	v_mfma_f32_16x16x32_bf16 v[120:123], v[168:171], v[192:195], v[120:123]
	v_mfma_f32_16x16x32_bf16 v[108:111], v[150:153], v[202:205], v[108:111]
	v_mfma_f32_16x16x32_bf16 v[104:107], v[168:171], v[202:205], v[104:107]
	v_mfma_f32_16x16x32_bf16 v[92:95], v[150:153], v[210:213], v[92:95]
	v_mfma_f32_16x16x32_bf16 v[88:91], v[168:171], v[210:213], v[88:91]
	v_mfma_f32_16x16x32_bf16 v[76:79], v[150:153], v[218:221], v[76:79]
	v_mfma_f32_16x16x32_bf16 v[72:75], v[168:171], v[218:221], v[72:75]
	v_mfma_f32_16x16x32_bf16 v[116:119], v[172:175], v[188:191], v[116:119]
	v_mfma_f32_16x16x32_bf16 v[112:115], v[180:183], v[188:191], v[112:115]
	v_mfma_f32_16x16x32_bf16 v[100:103], v[172:175], v[198:201], v[100:103]
	v_mfma_f32_16x16x32_bf16 v[96:99], v[180:183], v[198:201], v[96:99]
	v_mfma_f32_16x16x32_bf16 v[84:87], v[172:175], v[206:209], v[84:87]
	v_mfma_f32_16x16x32_bf16 v[80:83], v[180:183], v[206:209], v[80:83]
	v_mfma_f32_16x16x32_bf16 v[68:71], v[172:175], v[214:217], v[68:71]
	v_mfma_f32_16x16x32_bf16 v[64:67], v[180:183], v[214:217], v[64:67]
	v_mfma_f32_16x16x32_bf16 v[116:119], v[176:179], v[192:195], v[116:119]
	v_mfma_f32_16x16x32_bf16 v[112:115], v[184:187], v[192:195], v[112:115]
	v_mfma_f32_16x16x32_bf16 v[100:103], v[176:179], v[202:205], v[100:103]
	v_mfma_f32_16x16x32_bf16 v[96:99], v[184:187], v[202:205], v[96:99]
	v_mfma_f32_16x16x32_bf16 v[84:87], v[176:179], v[210:213], v[84:87]
	v_mfma_f32_16x16x32_bf16 v[80:83], v[184:187], v[210:213], v[80:83]
	v_mfma_f32_16x16x32_bf16 v[68:71], v[176:179], v[218:221], v[68:71]
	v_mfma_f32_16x16x32_bf16 v[64:67], v[184:187], v[218:221], v[64:67]
	s_setprio 0
	s_barrier
; #define PG8_STAGE(bufoff, gbase, voff) do { _Pragma("unroll") for (int _i = 0; _i < 2; ++_i) \
;         __builtin_amdgcn_global_load_lds((const unsigned*)((const char*)(gbase) + (voff)[_i]), (PG8_LAS unsigned*)(lds + (bufoff) + ldsw + _i * 8192), 16, 0, 0); } while (0)
; #define PG8_LDA(dst, b, h) do { _Pragma("unroll") for (int m = 0; m < 4; ++m) _Pragma("unroll") for (int k = 0; k < 2; ++k) dst[m][k] = *(const PG8_LAS bf16x8*)(lds + PG8_SA(b, h) + aoff + m * 2048 + k * 1024); } while (0)
; #define PG8_LDB(dst, b, h) do { _Pragma("unroll") for (int n = 0; n < 2; ++n) _Pragma("unroll") for (int k = 0; k < 2; ++k) dst[n][k] = *(const PG8_LAS bf16x8*)(lds + PG8_SB(b, h) + boff + n * 2048 + k * 1024); } while (0)
; #define PG8_MMA(ai, bj, At, Bt) do { __builtin_amdgcn_s_setprio(1); _Pragma("unroll") for (int m = 0; m < 4; ++m) _Pragma("unroll") for (int n = 0; n < 2; ++n) _Pragma("unroll") for (int k = 0; k < 2; ++k) \
;         acc[ai][bj][m][n] = __builtin_amdgcn_mfma_f32_16x16x32_bf16(Bt[n][k], At[m][k], acc[ai][bj][m][n], 0, 0, 0); __builtin_amdgcn_s_setprio(0); } while (0)
; #define PG8_WAIT_V(n) asm volatile("s_waitcnt vmcnt(" #n ")" ::: "memory")
; #define PG8_WAIT_L(n) asm volatile("s_waitcnt lgkmcnt(" #n ")" ::: "memory")
; #define PG8_BAR __builtin_amdgcn_s_barrier()
; #define PG8_SCHED __builtin_amdgcn_sched_barrier(0)
; template <class Epi, class Sched, bool ALIGN_EPI = false, bool SP2 = false>
; __device__ __forceinline__ void gemm_phase(PG8_LAS unsigned char* lds, const Gemm g, const Sched& S, const Epi& E) {
;     ...
;             PG8_LDA(At, 0, 1); PG8_STAGE(PG8_SB(0, 0), b2, voffB); PG8_STAGE(PG8_SB(0, 1), b2 + hstep, voffB); PG8_STAGE(PG8_SA(0, 0), a2, voffA);
;             PG8_WAIT_V(8); PG8_WAIT_L(0); PG8_BAR; PG8_MMA(1, 0, At, B0); PG8_MMA(1, 1, At, B1); PG8_BAR; PG8_SCHED;
;             PG8_LDB(B0, 1, 0); PG8_LDB(B1, 1, 1); PG8_SCHED; PG8_LDA(At, 1, 0); PG8_STAGE(PG8_SA(0, 1), a2 + hstep, voffA);
	s_add_i32 s85, s72, s63
	s_add_u32 s98, s52, s8
	s_addc_u32 s99, s53, s9
	s_add_u32 s100, s54, s8
	s_addc_u32 s101, s55, s9
	s_mov_b32 m0, s85
	ds_read_b128 v[188:191], v167 offset:16384
	ds_read_b128 v[192:195], v167 offset:17408
	ds_read_b128 v[198:201], v167 offset:18432
	ds_read_b128 v[202:205], v167 offset:19456
	ds_read_b128 v[206:209], v167 offset:20480
	ds_read_b128 v[210:213], v167 offset:21504
	ds_read_b128 v[214:217], v167 offset:22528
	ds_read_b128 v[218:221], v167 offset:23552
	global_load_lds_dwordx4 v132, s[52:53]
	s_add_i32 m0, s85, 0x2000
	s_add_u32 s86, s52, 0x40000
	s_addc_u32 s87, s53, 0
	s_add_i32 s85, s73, s63
	global_load_lds_dwordx4 v128, s[52:53]
	s_mov_b32 m0, s85
	s_nop 0
	global_load_lds_dwordx4 v132, s[86:87]
	s_add_i32 m0, s85, 0x2000
	s_nop 0
	global_load_lds_dwordx4 v128, s[86:87]
	s_mov_b32 m0, s35
	s_nop 0
	global_load_lds_dwordx4 v134, s[54:55]
	s_mov_b32 m0, s65
	s_nop 0
	global_load_lds_dwordx4 v130, s[54:55]
	s_waitcnt vmcnt(8)
	s_waitcnt lgkmcnt(0)
	s_barrier
	s_setprio 1
	s_waitcnt lgkmcnt(0)
	v_mfma_f32_16x16x32_bf16 v[60:63], v[146:149], v[188:191], v[60:63]
	v_mfma_f32_16x16x32_bf16 v[56:59], v[154:157], v[188:191], v[56:59]
	v_mfma_f32_16x16x32_bf16 v[44:47], v[146:149], v[198:201], v[44:47]
	v_mfma_f32_16x16x32_bf16 v[40:43], v[154:157], v[198:201], v[40:43]
	v_mfma_f32_16x16x32_bf16 v[28:31], v[146:149], v[206:209], v[28:31]
	v_mfma_f32_16x16x32_bf16 v[24:27], v[154:157], v[206:209], v[24:27]
	v_mfma_f32_16x16x32_bf16 v[12:15], v[146:149], v[214:217], v[12:15]
	v_mfma_f32_16x16x32_bf16 v[8:11], v[154:157], v[214:217], v[8:11]
	v_mfma_f32_16x16x32_bf16 v[60:63], v[150:153], v[192:195], v[60:63]
	v_mfma_f32_16x16x32_bf16 v[56:59], v[168:171], v[192:195], v[56:59]
	v_mfma_f32_16x16x32_bf16 v[44:47], v[150:153], v[202:205], v[44:47]
	v_mfma_f32_16x16x32_bf16 v[40:43], v[168:171], v[202:205], v[40:43]
	v_mfma_f32_16x16x32_bf16 v[28:31], v[150:153], v[210:213], v[28:31]
	v_mfma_f32_16x16x32_bf16 v[24:27], v[168:171], v[210:213], v[24:27]
	v_mfma_f32_16x16x32_bf16 v[12:15], v[150:153], v[218:221], v[12:15]
	v_mfma_f32_16x16x32_bf16 v[8:11], v[168:171], v[218:221], v[8:11]
	v_mfma_f32_16x16x32_bf16 v[52:55], v[172:175], v[188:191], v[52:55]
	v_mfma_f32_16x16x32_bf16 v[48:51], v[180:183], v[188:191], v[48:51]
	v_mfma_f32_16x16x32_bf16 v[36:39], v[172:175], v[198:201], v[36:39]
	v_mfma_f32_16x16x32_bf16 v[32:35], v[180:183], v[198:201], v[32:35]
	v_mfma_f32_16x16x32_bf16 v[20:23], v[172:175], v[206:209], v[20:23]
	v_mfma_f32_16x16x32_bf16 v[16:19], v[180:183], v[206:209], v[16:19]
	v_mfma_f32_16x16x32_bf16 v[4:7], v[172:175], v[214:217], v[4:7]
	v_mfma_f32_16x16x32_bf16 v[0:3], v[180:183], v[214:217], v[0:3]
	v_mfma_f32_16x16x32_bf16 v[52:55], v[176:179], v[192:195], v[52:55]
	v_mfma_f32_16x16x32_bf16 v[48:51], v[184:187], v[192:195], v[48:51]
	v_mfma_f32_16x16x32_bf16 v[36:39], v[176:179], v[202:205], v[36:39]
	v_mfma_f32_16x16x32_bf16 v[32:35], v[184:187], v[202:205], v[32:35]
	v_mfma_f32_16x16x32_bf16 v[20:23], v[176:179], v[210:213], v[20:23]
	v_mfma_f32_16x16x32_bf16 v[16:19], v[184:187], v[210:213], v[16:19]
	v_mfma_f32_16x16x32_bf16 v[4:7], v[176:179], v[218:221], v[4:7]
	v_mfma_f32_16x16x32_bf16 v[0:3], v[184:187], v[218:221], v[0:3]
	s_setprio 0
	s_barrier
	s_add_i32 s85, 0, 0x18000
	v_add_u32_e32 v136, s85, v161
	s_add_i32 s86, 0, 0x1c000
	ds_read_b128 v[146:149], v136
	ds_read_b128 v[150:153], v136 offset:1024
	ds_read_b128 v[154:157], v136 offset:2048
	ds_read_b128 v[168:171], v136 offset:3072
	v_add_u32_e32 v136, s86, v161
	ds_read_b128 v[172:175], v136
	ds_read_b128 v[176:179], v136 offset:1024
	ds_read_b128 v[180:183], v136 offset:2048
	ds_read_b128 v[184:187], v136 offset:3072
	s_add_u32 s54, s54, 0x40000
	s_addc_u32 s55, s55, 0
	s_mov_b32 m0, s66
	ds_read_b128 v[188:191], v167 offset:32768
	ds_read_b128 v[192:195], v167 offset:33792
	ds_read_b128 v[198:201], v167 offset:34816
	ds_read_b128 v[202:205], v167 offset:35840
	ds_read_b128 v[206:209], v167 offset:36864
	ds_read_b128 v[210:213], v167 offset:37888
	ds_read_b128 v[214:217], v167 offset:38912
	ds_read_b128 v[218:221], v167 offset:39936
	global_load_lds_dwordx4 v134, s[54:55]
	s_mov_b32 m0, s67
	s_nop 0
	global_load_lds_dwordx4 v130, s[54:55]
	s_waitcnt vmcnt(8)
	s_waitcnt lgkmcnt(0)
	s_barrier
; #define PG8_STAGE(bufoff, gbase, voff) do { _Pragma("unroll") for (int _i = 0; _i < 2; ++_i) \
;         __builtin_amdgcn_global_load_lds((const unsigned*)((const char*)(gbase) + (voff)[_i]), (PG8_LAS unsigned*)(lds + (bufoff) + ldsw + _i * 8192), 16, 0, 0); } while (0)
; #define PG8_LDA(dst, b, h) do { _Pragma("unroll") for (int m = 0; m < 4; ++m) _Pragma("unroll") for (int k = 0; k < 2; ++k) dst[m][k] = *(const PG8_LAS bf16x8*)(lds + PG8_SA(b, h) + aoff + m * 2048 + k * 1024); } while (0)
; #define PG8_MMA(ai, bj, At, Bt) do { __builtin_amdgcn_s_setprio(1); _Pragma("unroll") for (int m = 0; m < 4; ++m) _Pragma("unroll") for (int n = 0; n < 2; ++n) _Pragma("unroll") for (int k = 0; k < 2; ++k) \
;         acc[ai][bj][m][n] = __builtin_amdgcn_mfma_f32_16x16x32_bf16(Bt[n][k], At[m][k], acc[ai][bj][m][n], 0, 0, 0); __builtin_amdgcn_s_setprio(0); } while (0)
; #define PG8_WAIT_V(n) asm volatile("s_waitcnt vmcnt(" #n ")" ::: "memory")
; #define PG8_WAIT_L(n) asm volatile("s_waitcnt lgkmcnt(" #n ")" ::: "memory")
; #define PG8_BAR __builtin_amdgcn_s_barrier()
; #define PG8_SCHED __builtin_amdgcn_sched_barrier(0)
; template <class Epi, class Sched, bool ALIGN_EPI = false, bool SP2 = false>
; __device__ __forceinline__ void gemm_phase(PG8_LAS unsigned char* lds, const Gemm g, const Sched& S, const Epi& E) {
;     ...
;             PG8_WAIT_V(8); PG8_WAIT_L(0); PG8_BAR; PG8_MMA(0, 0, At, B0); PG8_MMA(0, 1, At, B1); PG8_BAR; PG8_SCHED;
;             PG8_LDA(At, 1, 1); PG8_STAGE(PG8_SB(1, 0), b3, voffB); PG8_STAGE(PG8_SB(1, 1), b3 + hstep, voffB); PG8_STAGE(PG8_SA(1, 0), a3, voffA);
;             PG8_WAIT_V(8); PG8_WAIT_L(0); PG8_BAR; PG8_MMA(1, 0, At, B0); PG8_MMA(1, 1, At, B1); PG8_BAR; PG8_SCHED;
;     ...
;         if constexpr (ALIGN_EPI) { if (wr == 0) PG8_BAR; }
	s_setprio 1
	s_waitcnt lgkmcnt(0)
	v_mfma_f32_16x16x32_bf16 v[124:127], v[146:149], v[188:191], v[124:127]
	v_mfma_f32_16x16x32_bf16 v[120:123], v[154:157], v[188:191], v[120:123]
	v_mfma_f32_16x16x32_bf16 v[108:111], v[146:149], v[198:201], v[108:111]
	v_mfma_f32_16x16x32_bf16 v[104:107], v[154:157], v[198:201], v[104:107]
	v_mfma_f32_16x16x32_bf16 v[92:95], v[146:149], v[206:209], v[92:95]
	v_mfma_f32_16x16x32_bf16 v[88:91], v[154:157], v[206:209], v[88:91]
	v_mfma_f32_16x16x32_bf16 v[76:79], v[146:149], v[214:217], v[76:79]
	v_mfma_f32_16x16x32_bf16 v[72:75], v[154:157], v[214:217], v[72:75]
	v_mfma_f32_16x16x32_bf16 v[124:127], v[150:153], v[192:195], v[124:127]
	v_mfma_f32_16x16x32_bf16 v[120:123], v[168:171], v[192:195], v[120:123]
	v_mfma_f32_16x16x32_bf16 v[108:111], v[150:153], v[202:205], v[108:111]
	v_mfma_f32_16x16x32_bf16 v[104:107], v[168:171], v[202:205], v[104:107]
	v_mfma_f32_16x16x32_bf16 v[92:95], v[150:153], v[210:213], v[92:95]
	v_mfma_f32_16x16x32_bf16 v[88:91], v[168:171], v[210:213], v[88:91]
	v_mfma_f32_16x16x32_bf16 v[76:79], v[150:153], v[218:221], v[76:79]
	v_mfma_f32_16x16x32_bf16 v[72:75], v[168:171], v[218:221], v[72:75]
	v_mfma_f32_16x16x32_bf16 v[116:119], v[172:175], v[188:191], v[116:119]
	v_mfma_f32_16x16x32_bf16 v[112:115], v[180:183], v[188:191], v[112:115]
	v_mfma_f32_16x16x32_bf16 v[100:103], v[172:175], v[198:201], v[100:103]
	v_mfma_f32_16x16x32_bf16 v[96:99], v[180:183], v[198:201], v[96:99]
	v_mfma_f32_16x16x32_bf16 v[84:87], v[172:175], v[206:209], v[84:87]
	v_mfma_f32_16x16x32_bf16 v[80:83], v[180:183], v[206:209], v[80:83]
	v_mfma_f32_16x16x32_bf16 v[68:71], v[172:175], v[214:217], v[68:71]
	v_mfma_f32_16x16x32_bf16 v[64:67], v[180:183], v[214:217], v[64:67]
	v_mfma_f32_16x16x32_bf16 v[116:119], v[176:179], v[192:195], v[116:119]
	v_mfma_f32_16x16x32_bf16 v[112:115], v[184:187], v[192:195], v[112:115]
	v_mfma_f32_16x16x32_bf16 v[100:103], v[176:179], v[202:205], v[100:103]
	v_mfma_f32_16x16x32_bf16 v[96:99], v[184:187], v[202:205], v[96:99]
	v_mfma_f32_16x16x32_bf16 v[84:87], v[176:179], v[210:213], v[84:87]
	v_mfma_f32_16x16x32_bf16 v[80:83], v[184:187], v[210:213], v[80:83]
	v_mfma_f32_16x16x32_bf16 v[68:71], v[176:179], v[218:221], v[68:71]
	v_mfma_f32_16x16x32_bf16 v[64:67], v[184:187], v[218:221], v[64:67]
	s_setprio 0
	s_barrier
	s_add_i32 s54, s85, s63
	s_mov_b32 m0, s54
	ds_read_b128 v[188:191], v167 offset:49152
	ds_read_b128 v[192:195], v167 offset:50176
	ds_read_b128 v[198:201], v167 offset:51200
	ds_read_b128 v[202:205], v167 offset:52224
	ds_read_b128 v[206:209], v167 offset:53248
	ds_read_b128 v[210:213], v167 offset:54272
	ds_read_b128 v[214:217], v167 offset:55296
	ds_read_b128 v[218:221], v167 offset:56320
	global_load_lds_dwordx4 v132, s[98:99]
	s_add_i32 m0, s54, 0x2000
	s_add_u32 s52, s52, 0x40080
	s_addc_u32 s53, s53, 0
	s_add_i32 s54, s86, s63
	global_load_lds_dwordx4 v128, s[98:99]
	s_mov_b32 m0, s54
	s_nop 0
	global_load_lds_dwordx4 v132, s[52:53]
	s_add_i32 m0, s54, 0x2000
	s_nop 0
	global_load_lds_dwordx4 v128, s[52:53]
	s_mov_b32 m0, s69
	s_nop 0
	global_load_lds_dwordx4 v134, s[100:101]
	s_mov_b32 m0, s70
	s_nop 0
	global_load_lds_dwordx4 v130, s[100:101]
	s_waitcnt vmcnt(8)
	s_waitcnt lgkmcnt(0)
	s_barrier
	s_setprio 1
	s_waitcnt lgkmcnt(0)
	v_mfma_f32_16x16x32_bf16 v[60:63], v[146:149], v[188:191], v[60:63]
	v_mfma_f32_16x16x32_bf16 v[56:59], v[154:157], v[188:191], v[56:59]
	v_mfma_f32_16x16x32_bf16 v[44:47], v[146:149], v[198:201], v[44:47]
	v_mfma_f32_16x16x32_bf16 v[40:43], v[154:157], v[198:201], v[40:43]
	v_mfma_f32_16x16x32_bf16 v[28:31], v[146:149], v[206:209], v[28:31]
	v_mfma_f32_16x16x32_bf16 v[24:27], v[154:157], v[206:209], v[24:27]
	v_mfma_f32_16x16x32_bf16 v[12:15], v[146:149], v[214:217], v[12:15]
	v_mfma_f32_16x16x32_bf16 v[8:11], v[154:157], v[214:217], v[8:11]
	v_mfma_f32_16x16x32_bf16 v[60:63], v[150:153], v[192:195], v[60:63]
	v_mfma_f32_16x16x32_bf16 v[56:59], v[168:171], v[192:195], v[56:59]
	v_mfma_f32_16x16x32_bf16 v[44:47], v[150:153], v[202:205], v[44:47]
	v_mfma_f32_16x16x32_bf16 v[40:43], v[168:171], v[202:205], v[40:43]
	v_mfma_f32_16x16x32_bf16 v[28:31], v[150:153], v[210:213], v[28:31]
	v_mfma_f32_16x16x32_bf16 v[24:27], v[168:171], v[210:213], v[24:27]
	v_mfma_f32_16x16x32_bf16 v[12:15], v[150:153], v[218:221], v[12:15]
	v_mfma_f32_16x16x32_bf16 v[8:11], v[168:171], v[218:221], v[8:11]
	v_mfma_f32_16x16x32_bf16 v[52:55], v[172:175], v[188:191], v[52:55]
	v_mfma_f32_16x16x32_bf16 v[48:51], v[180:183], v[188:191], v[48:51]
	v_mfma_f32_16x16x32_bf16 v[36:39], v[172:175], v[198:201], v[36:39]
	v_mfma_f32_16x16x32_bf16 v[32:35], v[180:183], v[198:201], v[32:35]
	v_mfma_f32_16x16x32_bf16 v[20:23], v[172:175], v[206:209], v[20:23]
	v_mfma_f32_16x16x32_bf16 v[16:19], v[180:183], v[206:209], v[16:19]
	v_mfma_f32_16x16x32_bf16 v[4:7], v[172:175], v[214:217], v[4:7]
	v_mfma_f32_16x16x32_bf16 v[0:3], v[180:183], v[214:217], v[0:3]
	v_mfma_f32_16x16x32_bf16 v[52:55], v[176:179], v[192:195], v[52:55]
	v_mfma_f32_16x16x32_bf16 v[48:51], v[184:187], v[192:195], v[48:51]
	v_mfma_f32_16x16x32_bf16 v[36:39], v[176:179], v[202:205], v[36:39]
	v_mfma_f32_16x16x32_bf16 v[32:35], v[184:187], v[202:205], v[32:35]
	v_mfma_f32_16x16x32_bf16 v[20:23], v[176:179], v[210:213], v[20:23]
	v_mfma_f32_16x16x32_bf16 v[16:19], v[184:187], v[210:213], v[16:19]
	v_mfma_f32_16x16x32_bf16 v[4:7], v[176:179], v[218:221], v[4:7]
	v_mfma_f32_16x16x32_bf16 v[0:3], v[184:187], v[218:221], v[0:3]
	s_setprio 0
	s_barrier
	s_add_i32 s84, s84, 2
	s_add_u32 s20, s20, 0x100
	s_addc_u32 s21, s21, 0
	s_add_u32 s80, s80, 0x100
	s_addc_u32 s81, s81, 0
	s_cmp_gt_u32 s84, 13
	s_cbranch_scc0 .LBB0_414
	s_and_b64 vcc, exec, s[10:11]
	s_cbranch_vccz .LBB0_417
	s_barrier

; #define PG8_STAGE(bufoff, gbase, voff) do { _Pragma("unroll") for (int _i = 0; _i < 2; ++_i) \
;         __builtin_amdgcn_global_load_lds((const unsigned*)((const char*)(gbase) + (voff)[_i]), (PG8_LAS unsigned*)(lds + (bufoff) + ldsw + _i * 8192), 16, 0, 0); } while (0)
; #define PG8_LDA(dst, b, h) do { _Pragma("unroll") for (int m = 0; m < 4; ++m) _Pragma("unroll") for (int k = 0; k < 2; ++k) dst[m][k] = *(const PG8_LAS bf16x8*)(lds + PG8_SA(b, h) + aoff + m * 2048 + k * 1024); } while (0)
; #define PG8_LDB(dst, b, h) do { _Pragma("unroll") for (int n = 0; n < 2; ++n) _Pragma("unroll") for (int k = 0; k < 2; ++k) dst[n][k] = *(const PG8_LAS bf16x8*)(lds + PG8_SB(b, h) + boff + n * 2048 + k * 1024); } while (0)
; #define PG8_MMA(ai, bj, At, Bt) do { __builtin_amdgcn_s_setprio(1); _Pragma("unroll") for (int m = 0; m < 4; ++m) _Pragma("unroll") for (int n = 0; n < 2; ++n) _Pragma("unroll") for (int k = 0; k < 2; ++k) \
;         acc[ai][bj][m][n] = __builtin_amdgcn_mfma_f32_16x16x32_bf16(Bt[n][k], At[m][k], acc[ai][bj][m][n], 0, 0, 0); __builtin_amdgcn_s_setprio(0); } while (0)
; #define PG8_BAR __builtin_amdgcn_s_barrier()
; template <class Epi, class Sched, bool ALIGN_EPI = false, bool SP2 = false>
; __device__ __forceinline__ void gemm_phase(PG8_LAS unsigned char* lds, const Gemm g, const Sched& S, const Epi& E) {
;     ...
;         const bool has_next = S.next(ui + 1, nxt);
;         const char* nA = has_next ? (const char*)g.A + (size_t)nxt.pm * tstep : cA; const char* nB = has_next ? (const char*)g.Bt + (size_t)nxt.pn * tstep : cB;
;         for (int t = 0; t < nt; t += 2) {
;             const bool last = (t == nt - 2);
;             const char* a1 = cA + (size_t)(t + 1) * kstep;
;             const char* a2 = last ? nA : cA + (size_t)(t + 2) * kstep; const char* b2 = last ? nB : cB + (size_t)(t + 2) * kstep;
;             const char* a3 = a2 + kstep; const char* b3 = b2 + kstep;
;             if (last && has_next) S.a_ready(nxt);
;             if constexpr (SP2) {
;             PG8_LDB(B0, 0, 0); PG8_LDB(B1, 0, 1); PG8_SCHED; PG8_LDA(At, 0, 0); PG8_STAGE(PG8_SA(1, 1), a1 + hstep, voffA);
;             PG8_WAIT_V(8); PG8_WAIT_L(0); PG8_BAR; PG8_MMA(0, 0, At, B0); PG8_MMA(0, 1, At, B1); PG8_BAR; PG8_SCHED;
;             PG8_LDA(At, 0, 1); PG8_STAGE(PG8_SB(0, 0), b2, voffB); PG8_STAGE(PG8_SB(0, 1), b2 + hstep, voffB); PG8_STAGE(PG8_SA(0, 0), a2, voffA);
.LBB0_623:
	s_ashr_i32 s17, s16, 31
	s_lshl_b64 s[18:19], s[16:17], 18
	s_add_u32 s18, s0, s18
	s_addc_u32 s19, s1, s19
	s_and_b64 s[38:39], s[4:5], exec
	s_cselect_b32 s17, s19, s21
	s_cselect_b32 s63, s18, s20
	s_ashr_i32 s15, s14, 31
	s_lshl_b64 s[38:39], s[14:15], 18
	s_add_u32 s38, s33, s38
	s_addc_u32 s39, s50, s39
	s_and_b64 s[48:49], s[4:5], exec
	s_cselect_b32 s15, s39, s47
	s_cselect_b32 s64, s38, s46
	s_add_u32 s20, s20, 0x20080
	s_addc_u32 s21, s21, 0
	s_add_u32 s65, s46, 0x100
	s_addc_u32 s66, s47, 0
	s_mov_b32 s67, -2
	ds_read_b128 v[112:115], v167
	ds_read_b128 v[116:119], v167 offset:1024
	ds_read_b128 v[152:155], v167 offset:2048
	ds_read_b128 v[156:159], v167 offset:3072
	ds_read_b128 v[160:163], v168
	ds_read_b128 v[170:173], v168 offset:1024
	ds_read_b128 v[174:177], v168 offset:2048
	ds_read_b128 v[178:181], v168 offset:3072
	s_add_u32 s46, s20, 0xfffe0080
	s_addc_u32 s47, s21, -1
	s_cmp_eq_u32 s67, 4
	s_cselect_b32 s49, s17, s47
	s_cselect_b32 s48, s63, s46
	s_cselect_b32 s47, s15, s66
	s_cselect_b32 s46, s64, s65
	s_add_i32 m0, s35, 0xc000
	ds_read_b128 v[182:185], v169
	ds_read_b128 v[186:189], v169 offset:1024
	ds_read_b128 v[190:193], v169 offset:2048
	ds_read_b128 v[198:201], v169 offset:3072
	ds_read_b128 v[202:205], v169 offset:4096
	ds_read_b128 v[206:209], v169 offset:5120
	ds_read_b128 v[210:213], v169 offset:6144
	ds_read_b128 v[214:217], v169 offset:7168
	global_load_lds_dwordx4 v144, s[20:21]
	s_add_i32 m0, s35, 0xe000
	s_nop 0
	global_load_lds_dwordx4 v146, s[20:21]
	s_waitcnt vmcnt(8)
	s_waitcnt lgkmcnt(0)
	s_barrier
	s_setprio 1
	s_waitcnt lgkmcnt(0)
	v_mfma_f32_16x16x32_bf16 v[132:135], v[112:115], v[182:185], 0
	v_mfma_f32_16x16x32_bf16 v[128:131], v[152:155], v[182:185], 0
	v_mfma_f32_16x16x32_bf16 v[124:127], v[112:115], v[190:193], 0
	v_mfma_f32_16x16x32_bf16 v[120:123], v[152:155], v[190:193], 0
	v_mfma_f32_16x16x32_bf16 v[108:111], v[112:115], v[202:205], 0
	v_mfma_f32_16x16x32_bf16 v[104:107], v[152:155], v[202:205], 0
	v_mfma_f32_16x16x32_bf16 v[100:103], v[112:115], v[210:213], 0
	v_mfma_f32_16x16x32_bf16 v[96:99], v[152:155], v[210:213], 0
	v_mfma_f32_16x16x32_bf16 v[132:135], v[116:119], v[186:189], v[132:135]
	v_mfma_f32_16x16x32_bf16 v[128:131], v[156:159], v[186:189], v[128:131]
	v_mfma_f32_16x16x32_bf16 v[124:127], v[116:119], v[198:201], v[124:127]
	v_mfma_f32_16x16x32_bf16 v[120:123], v[156:159], v[198:201], v[120:123]
	v_mfma_f32_16x16x32_bf16 v[108:111], v[116:119], v[206:209], v[108:111]
	v_mfma_f32_16x16x32_bf16 v[104:107], v[156:159], v[206:209], v[104:107]
	v_mfma_f32_16x16x32_bf16 v[100:103], v[116:119], v[214:217], v[100:103]
	v_mfma_f32_16x16x32_bf16 v[96:99], v[156:159], v[214:217], v[96:99]
	v_mfma_f32_16x16x32_bf16 v[60:63], v[160:163], v[182:185], 0
	v_mfma_f32_16x16x32_bf16 v[56:59], v[174:177], v[182:185], 0
	v_mfma_f32_16x16x32_bf16 v[52:55], v[160:163], v[190:193], 0
	v_mfma_f32_16x16x32_bf16 v[48:51], v[174:177], v[190:193], 0
	v_mfma_f32_16x16x32_bf16 v[44:47], v[160:163], v[202:205], 0
	v_mfma_f32_16x16x32_bf16 v[40:43], v[174:177], v[202:205], 0
	v_mfma_f32_16x16x32_bf16 v[36:39], v[160:163], v[210:213], 0
	v_mfma_f32_16x16x32_bf16 v[32:35], v[174:177], v[210:213], 0
	v_mfma_f32_16x16x32_bf16 v[60:63], v[170:173], v[186:189], v[60:63]
	v_mfma_f32_16x16x32_bf16 v[56:59], v[178:181], v[186:189], v[56:59]
	v_mfma_f32_16x16x32_bf16 v[52:55], v[170:173], v[198:201], v[52:55]
	v_mfma_f32_16x16x32_bf16 v[48:51], v[178:181], v[198:201], v[48:51]
	v_mfma_f32_16x16x32_bf16 v[44:47], v[170:173], v[206:209], v[44:47]
	v_mfma_f32_16x16x32_bf16 v[40:43], v[178:181], v[206:209], v[40:43]
	v_mfma_f32_16x16x32_bf16 v[36:39], v[170:173], v[214:217], v[36:39]
	v_mfma_f32_16x16x32_bf16 v[32:35], v[178:181], v[214:217], v[32:35]
	s_setprio 0
	s_barrier
	s_add_i32 s68, s60, s51
	s_add_u32 s98, s46, s10
	s_addc_u32 s99, s47, s11
	s_add_u32 s100, s48, s10
	s_addc_u32 s101, s49, s11
	s_mov_b32 m0, s68
	ds_read_b128 v[182:185], v169 offset:16384
	ds_read_b128 v[186:189], v169 offset:17408
	ds_read_b128 v[190:193], v169 offset:18432
	ds_read_b128 v[198:201], v169 offset:19456
	ds_read_b128 v[202:205], v169 offset:20480
	ds_read_b128 v[206:209], v169 offset:21504
	ds_read_b128 v[210:213], v169 offset:22528
	ds_read_b128 v[214:217], v169 offset:23552
	global_load_lds_dwordx4 v138, s[46:47]
	s_add_i32 m0, s68, 0x2000
	s_add_u32 s68, s46, 0x20000
	s_addc_u32 s69, s47, 0
	s_add_i32 s70, s61, s51
	global_load_lds_dwordx4 v142, s[46:47]
	s_mov_b32 m0, s70
	s_nop 0
	global_load_lds_dwordx4 v138, s[68:69]
	s_add_i32 m0, s70, 0x2000
	s_nop 0
	global_load_lds_dwordx4 v142, s[68:69]
	s_mov_b32 m0, s35
	s_nop 0
	global_load_lds_dwordx4 v136, s[48:49]
	s_mov_b32 m0, s52
	s_nop 0
	global_load_lds_dwordx4 v140, s[48:49]
	s_waitcnt vmcnt(8)
	s_waitcnt lgkmcnt(0)
	s_barrier
; #define PG8_STAGE(bufoff, gbase, voff) do { _Pragma("unroll") for (int _i = 0; _i < 2; ++_i) \
;         __builtin_amdgcn_global_load_lds((const unsigned*)((const char*)(gbase) + (voff)[_i]), (PG8_LAS unsigned*)(lds + (bufoff) + ldsw + _i * 8192), 16, 0, 0); } while (0)
; #define PG8_LDA(dst, b, h) do { _Pragma("unroll") for (int m = 0; m < 4; ++m) _Pragma("unroll") for (int k = 0; k < 2; ++k) dst[m][k] = *(const PG8_LAS bf16x8*)(lds + PG8_SA(b, h) + aoff + m * 2048 + k * 1024); } while (0)
; #define PG8_LDB(dst, b, h) do { _Pragma("unroll") for (int n = 0; n < 2; ++n) _Pragma("unroll") for (int k = 0; k < 2; ++k) dst[n][k] = *(const PG8_LAS bf16x8*)(lds + PG8_SB(b, h) + boff + n * 2048 + k * 1024); } while (0)
; #define PG8_MMA(ai, bj, At, Bt) do { __builtin_amdgcn_s_setprio(1); _Pragma("unroll") for (int m = 0; m < 4; ++m) _Pragma("unroll") for (int n = 0; n < 2; ++n) _Pragma("unroll") for (int k = 0; k < 2; ++k) \
;         acc[ai][bj][m][n] = __builtin_amdgcn_mfma_f32_16x16x32_bf16(Bt[n][k], At[m][k], acc[ai][bj][m][n], 0, 0, 0); __builtin_amdgcn_s_setprio(0); } while (0)
; #define PG8_WAIT_V(n) asm volatile("s_waitcnt vmcnt(" #n ")" ::: "memory")
; #define PG8_WAIT_L(n) asm volatile("s_waitcnt lgkmcnt(" #n ")" ::: "memory")
; #define PG8_BAR __builtin_amdgcn_s_barrier()
; #define PG8_SCHED __builtin_amdgcn_sched_barrier(0)
; template <class Epi, class Sched, bool ALIGN_EPI = false, bool SP2 = false>
; __device__ __forceinline__ void gemm_phase(PG8_LAS unsigned char* lds, const Gemm g, const Sched& S, const Epi& E) {
;     ...
;             PG8_WAIT_V(8); PG8_WAIT_L(0); PG8_BAR; PG8_MMA(1, 0, At, B0); PG8_MMA(1, 1, At, B1); PG8_BAR; PG8_SCHED;
;             PG8_LDB(B0, 1, 0); PG8_LDB(B1, 1, 1); PG8_SCHED; PG8_LDA(At, 1, 0); PG8_STAGE(PG8_SA(0, 1), a2 + hstep, voffA);
;             PG8_WAIT_V(8); PG8_WAIT_L(0); PG8_BAR; PG8_MMA(0, 0, At, B0); PG8_MMA(0, 1, At, B1); PG8_BAR; PG8_SCHED;
	s_setprio 1
	s_waitcnt lgkmcnt(0)
	v_mfma_f32_16x16x32_bf16 v[92:95], v[112:115], v[182:185], 0
	v_mfma_f32_16x16x32_bf16 v[88:91], v[152:155], v[182:185], 0
	v_mfma_f32_16x16x32_bf16 v[84:87], v[112:115], v[190:193], 0
	v_mfma_f32_16x16x32_bf16 v[80:83], v[152:155], v[190:193], 0
	v_mfma_f32_16x16x32_bf16 v[76:79], v[112:115], v[202:205], 0
	v_mfma_f32_16x16x32_bf16 v[72:75], v[152:155], v[202:205], 0
	v_mfma_f32_16x16x32_bf16 v[68:71], v[112:115], v[210:213], 0
	v_mfma_f32_16x16x32_bf16 v[64:67], v[152:155], v[210:213], 0
	v_mfma_f32_16x16x32_bf16 v[92:95], v[116:119], v[186:189], v[92:95]
	v_mfma_f32_16x16x32_bf16 v[88:91], v[156:159], v[186:189], v[88:91]
	v_mfma_f32_16x16x32_bf16 v[84:87], v[116:119], v[198:201], v[84:87]
	v_mfma_f32_16x16x32_bf16 v[80:83], v[156:159], v[198:201], v[80:83]
	v_mfma_f32_16x16x32_bf16 v[76:79], v[116:119], v[206:209], v[76:79]
	v_mfma_f32_16x16x32_bf16 v[72:75], v[156:159], v[206:209], v[72:75]
	v_mfma_f32_16x16x32_bf16 v[68:71], v[116:119], v[214:217], v[68:71]
	v_mfma_f32_16x16x32_bf16 v[64:67], v[156:159], v[214:217], v[64:67]
	v_mfma_f32_16x16x32_bf16 v[28:31], v[160:163], v[182:185], 0
	v_mfma_f32_16x16x32_bf16 v[24:27], v[174:177], v[182:185], 0
	v_mfma_f32_16x16x32_bf16 v[20:23], v[160:163], v[190:193], 0
	v_mfma_f32_16x16x32_bf16 v[16:19], v[174:177], v[190:193], 0
	v_mfma_f32_16x16x32_bf16 v[12:15], v[160:163], v[202:205], 0
	v_mfma_f32_16x16x32_bf16 v[8:11], v[174:177], v[202:205], 0
	v_mfma_f32_16x16x32_bf16 v[4:7], v[160:163], v[210:213], 0
	v_mfma_f32_16x16x32_bf16 v[0:3], v[174:177], v[210:213], 0
	v_mfma_f32_16x16x32_bf16 v[28:31], v[170:173], v[186:189], v[28:31]
	v_mfma_f32_16x16x32_bf16 v[24:27], v[178:181], v[186:189], v[24:27]
	v_mfma_f32_16x16x32_bf16 v[20:23], v[170:173], v[198:201], v[20:23]
	v_mfma_f32_16x16x32_bf16 v[16:19], v[178:181], v[198:201], v[16:19]
	v_mfma_f32_16x16x32_bf16 v[12:15], v[170:173], v[206:209], v[12:15]
	v_mfma_f32_16x16x32_bf16 v[8:11], v[178:181], v[206:209], v[8:11]
	v_mfma_f32_16x16x32_bf16 v[4:7], v[170:173], v[214:217], v[4:7]
	v_mfma_f32_16x16x32_bf16 v[0:3], v[178:181], v[214:217], v[0:3]
	s_setprio 0
	s_barrier
	s_add_i32 s68, 0, 0x18000
	s_add_i32 s69, 0, 0x1c000
	v_add_u32_e32 v156, s68, v165
	v_add_u32_e32 v178, s69, v165
	ds_read_b128 v[112:115], v156
	ds_read_b128 v[116:119], v156 offset:1024
	ds_read_b128 v[152:155], v156 offset:2048
	ds_read_b128 v[156:159], v156 offset:3072
	ds_read_b128 v[160:163], v178
	ds_read_b128 v[170:173], v178 offset:1024
	ds_read_b128 v[174:177], v178 offset:2048
	ds_read_b128 v[178:181], v178 offset:3072
	s_add_u32 s48, s48, 0x20000
	s_addc_u32 s49, s49, 0
	s_mov_b32 m0, s53
	ds_read_b128 v[182:185], v169 offset:32768
	ds_read_b128 v[186:189], v169 offset:33792
	ds_read_b128 v[190:193], v169 offset:34816
	ds_read_b128 v[198:201], v169 offset:35840
	ds_read_b128 v[202:205], v169 offset:36864
	ds_read_b128 v[206:209], v169 offset:37888
	ds_read_b128 v[210:213], v169 offset:38912
	ds_read_b128 v[214:217], v169 offset:39936
	global_load_lds_dwordx4 v136, s[48:49]
	s_mov_b32 m0, s54
	s_nop 0
	global_load_lds_dwordx4 v140, s[48:49]
	s_waitcnt vmcnt(8)
	s_waitcnt lgkmcnt(0)
	s_barrier
	s_setprio 1
	s_waitcnt lgkmcnt(0)
	v_mfma_f32_16x16x32_bf16 v[132:135], v[112:115], v[182:185], v[132:135]
	v_mfma_f32_16x16x32_bf16 v[128:131], v[152:155], v[182:185], v[128:131]
	v_mfma_f32_16x16x32_bf16 v[124:127], v[112:115], v[190:193], v[124:127]
	v_mfma_f32_16x16x32_bf16 v[120:123], v[152:155], v[190:193], v[120:123]
	v_mfma_f32_16x16x32_bf16 v[108:111], v[112:115], v[202:205], v[108:111]
	v_mfma_f32_16x16x32_bf16 v[104:107], v[152:155], v[202:205], v[104:107]
	v_mfma_f32_16x16x32_bf16 v[100:103], v[112:115], v[210:213], v[100:103]
	v_mfma_f32_16x16x32_bf16 v[96:99], v[152:155], v[210:213], v[96:99]
	v_mfma_f32_16x16x32_bf16 v[132:135], v[116:119], v[186:189], v[132:135]
	v_mfma_f32_16x16x32_bf16 v[128:131], v[156:159], v[186:189], v[128:131]
	v_mfma_f32_16x16x32_bf16 v[124:127], v[116:119], v[198:201], v[124:127]
	v_mfma_f32_16x16x32_bf16 v[120:123], v[156:159], v[198:201], v[120:123]
	v_mfma_f32_16x16x32_bf16 v[108:111], v[116:119], v[206:209], v[108:111]
	v_mfma_f32_16x16x32_bf16 v[104:107], v[156:159], v[206:209], v[104:107]
	v_mfma_f32_16x16x32_bf16 v[100:103], v[116:119], v[214:217], v[100:103]
	v_mfma_f32_16x16x32_bf16 v[96:99], v[156:159], v[214:217], v[96:99]
	v_mfma_f32_16x16x32_bf16 v[60:63], v[160:163], v[182:185], v[60:63]
	v_mfma_f32_16x16x32_bf16 v[56:59], v[174:177], v[182:185], v[56:59]
	v_mfma_f32_16x16x32_bf16 v[52:55], v[160:163], v[190:193], v[52:55]
	v_mfma_f32_16x16x32_bf16 v[48:51], v[174:177], v[190:193], v[48:51]
	v_mfma_f32_16x16x32_bf16 v[44:47], v[160:163], v[202:205], v[44:47]
	v_mfma_f32_16x16x32_bf16 v[40:43], v[174:177], v[202:205], v[40:43]
	v_mfma_f32_16x16x32_bf16 v[36:39], v[160:163], v[210:213], v[36:39]
	v_mfma_f32_16x16x32_bf16 v[32:35], v[174:177], v[210:213], v[32:35]
	v_mfma_f32_16x16x32_bf16 v[60:63], v[170:173], v[186:189], v[60:63]
	v_mfma_f32_16x16x32_bf16 v[56:59], v[178:181], v[186:189], v[56:59]
	v_mfma_f32_16x16x32_bf16 v[52:55], v[170:173], v[198:201], v[52:55]
	v_mfma_f32_16x16x32_bf16 v[48:51], v[178:181], v[198:201], v[48:51]
	v_mfma_f32_16x16x32_bf16 v[44:47], v[170:173], v[206:209], v[44:47]
	v_mfma_f32_16x16x32_bf16 v[40:43], v[178:181], v[206:209], v[40:43]
	v_mfma_f32_16x16x32_bf16 v[36:39], v[170:173], v[214:217], v[36:39]
	v_mfma_f32_16x16x32_bf16 v[32:35], v[178:181], v[214:217], v[32:35]
	s_setprio 0
	s_barrier
; #define PG8_STAGE(bufoff, gbase, voff) do { _Pragma("unroll") for (int _i = 0; _i < 2; ++_i) \
;         __builtin_amdgcn_global_load_lds((const unsigned*)((const char*)(gbase) + (voff)[_i]), (PG8_LAS unsigned*)(lds + (bufoff) + ldsw + _i * 8192), 16, 0, 0); } while (0)
; #define PG8_LDA(dst, b, h) do { _Pragma("unroll") for (int m = 0; m < 4; ++m) _Pragma("unroll") for (int k = 0; k < 2; ++k) dst[m][k] = *(const PG8_LAS bf16x8*)(lds + PG8_SA(b, h) + aoff + m * 2048 + k * 1024); } while (0)
; #define PG8_LDB(dst, b, h) do { _Pragma("unroll") for (int n = 0; n < 2; ++n) _Pragma("unroll") for (int k = 0; k < 2; ++k) dst[n][k] = *(const PG8_LAS bf16x8*)(lds + PG8_SB(b, h) + boff + n * 2048 + k * 1024); } while (0)
; #define PG8_MMA(ai, bj, At, Bt) do { __builtin_amdgcn_s_setprio(1); _Pragma("unroll") for (int m = 0; m < 4; ++m) _Pragma("unroll") for (int n = 0; n < 2; ++n) _Pragma("unroll") for (int k = 0; k < 2; ++k) \
;         acc[ai][bj][m][n] = __builtin_amdgcn_mfma_f32_16x16x32_bf16(Bt[n][k], At[m][k], acc[ai][bj][m][n], 0, 0, 0); __builtin_amdgcn_s_setprio(0); } while (0)
; #define PG8_WAIT_V(n) asm volatile("s_waitcnt vmcnt(" #n ")" ::: "memory")
; template <class Epi, class Sched, bool ALIGN_EPI = false, bool SP2 = false>
; __device__ __forceinline__ void gemm_phase(PG8_LAS unsigned char* lds, const Gemm g, const Sched& S, const Epi& E) {
;     ...
;             PG8_LDB(B0, 0, 0); PG8_LDB(B1, 0, 1); PG8_SCHED; PG8_LDA(At, 0, 0); PG8_STAGE(PG8_SA(1, 1), a1 + hstep, voffA);
;             PG8_WAIT_V(8); PG8_WAIT_L(0); PG8_BAR; PG8_MMA(0, 0, At, B0); PG8_MMA(0, 1, At, B1); PG8_BAR; PG8_SCHED;
;             PG8_LDA(At, 0, 1); PG8_STAGE(PG8_SB(0, 0), b2, voffB); PG8_STAGE(PG8_SB(0, 1), b2 + hstep, voffB); PG8_STAGE(PG8_SA(0, 0), a2, voffA);
;             PG8_WAIT_V(8); PG8_WAIT_L(0); PG8_BAR; PG8_MMA(1, 0, At, B0); PG8_MMA(1, 1, At, B1); PG8_BAR; PG8_SCHED;
;             PG8_LDB(B0, 1, 0); PG8_LDB(B1, 1, 1); PG8_SCHED; PG8_LDA(At, 1, 0); PG8_STAGE(PG8_SA(0, 1), a2 + hstep, voffA);
;             PG8_WAIT_V(8); PG8_WAIT_L(0); PG8_BAR; PG8_MMA(0, 0, At, B0); PG8_MMA(0, 1, At, B1); PG8_BAR; PG8_SCHED;
;             PG8_LDA(At, 1, 1); PG8_STAGE(PG8_SB(1, 0), b3, voffB); PG8_STAGE(PG8_SB(1, 1), b3 + hstep, voffB); PG8_STAGE(PG8_SA(1, 0), a3, voffA);
;             PG8_WAIT_V(8); PG8_WAIT_L(0); PG8_BAR; PG8_MMA(1, 0, At, B0); PG8_MMA(1, 1, At, B1); PG8_BAR; PG8_SCHED;
	s_add_i32 s48, s68, s51
	s_mov_b32 m0, s48
	ds_read_b128 v[182:185], v169 offset:49152
	ds_read_b128 v[186:189], v169 offset:50176
	ds_read_b128 v[190:193], v169 offset:51200
	ds_read_b128 v[198:201], v169 offset:52224
	ds_read_b128 v[202:205], v169 offset:53248
	ds_read_b128 v[206:209], v169 offset:54272
	ds_read_b128 v[210:213], v169 offset:55296
	ds_read_b128 v[214:217], v169 offset:56320
	global_load_lds_dwordx4 v138, s[98:99]
	s_add_i32 m0, s48, 0x2000
	s_add_u32 s46, s46, 0x20080
	s_addc_u32 s47, s47, 0
	s_add_i32 s48, s69, s51
	global_load_lds_dwordx4 v142, s[98:99]
	s_mov_b32 m0, s48
	s_nop 0
	global_load_lds_dwordx4 v138, s[46:47]
	s_add_i32 m0, s48, 0x2000
	s_nop 0
	global_load_lds_dwordx4 v142, s[46:47]
	s_mov_b32 m0, s56
	s_nop 0
	global_load_lds_dwordx4 v136, s[100:101]
	s_mov_b32 m0, s57
	s_nop 0
	global_load_lds_dwordx4 v140, s[100:101]
	s_waitcnt vmcnt(8)
	s_waitcnt lgkmcnt(0)
	s_barrier
	s_setprio 1
	s_waitcnt lgkmcnt(0)
	v_mfma_f32_16x16x32_bf16 v[92:95], v[112:115], v[182:185], v[92:95]
	v_mfma_f32_16x16x32_bf16 v[88:91], v[152:155], v[182:185], v[88:91]
	v_mfma_f32_16x16x32_bf16 v[84:87], v[112:115], v[190:193], v[84:87]
	v_mfma_f32_16x16x32_bf16 v[80:83], v[152:155], v[190:193], v[80:83]
	v_mfma_f32_16x16x32_bf16 v[76:79], v[112:115], v[202:205], v[76:79]
	v_mfma_f32_16x16x32_bf16 v[72:75], v[152:155], v[202:205], v[72:75]
	v_mfma_f32_16x16x32_bf16 v[68:71], v[112:115], v[210:213], v[68:71]
	v_mfma_f32_16x16x32_bf16 v[64:67], v[152:155], v[210:213], v[64:67]
	v_mfma_f32_16x16x32_bf16 v[92:95], v[116:119], v[186:189], v[92:95]
	v_mfma_f32_16x16x32_bf16 v[88:91], v[156:159], v[186:189], v[88:91]
	v_mfma_f32_16x16x32_bf16 v[84:87], v[116:119], v[198:201], v[84:87]
	v_mfma_f32_16x16x32_bf16 v[80:83], v[156:159], v[198:201], v[80:83]
	v_mfma_f32_16x16x32_bf16 v[76:79], v[116:119], v[206:209], v[76:79]
	v_mfma_f32_16x16x32_bf16 v[72:75], v[156:159], v[206:209], v[72:75]
	v_mfma_f32_16x16x32_bf16 v[68:71], v[116:119], v[214:217], v[68:71]
	v_mfma_f32_16x16x32_bf16 v[64:67], v[156:159], v[214:217], v[64:67]
	v_mfma_f32_16x16x32_bf16 v[28:31], v[160:163], v[182:185], v[28:31]
	v_mfma_f32_16x16x32_bf16 v[24:27], v[174:177], v[182:185], v[24:27]
	v_mfma_f32_16x16x32_bf16 v[20:23], v[160:163], v[190:193], v[20:23]
	v_mfma_f32_16x16x32_bf16 v[16:19], v[174:177], v[190:193], v[16:19]
	v_mfma_f32_16x16x32_bf16 v[12:15], v[160:163], v[202:205], v[12:15]
	v_mfma_f32_16x16x32_bf16 v[8:11], v[174:177], v[202:205], v[8:11]
	v_mfma_f32_16x16x32_bf16 v[4:7], v[160:163], v[210:213], v[4:7]
	v_mfma_f32_16x16x32_bf16 v[0:3], v[174:177], v[210:213], v[0:3]
	v_mfma_f32_16x16x32_bf16 v[28:31], v[170:173], v[186:189], v[28:31]
	v_mfma_f32_16x16x32_bf16 v[24:27], v[178:181], v[186:189], v[24:27]
	v_mfma_f32_16x16x32_bf16 v[20:23], v[170:173], v[198:201], v[20:23]
	v_mfma_f32_16x16x32_bf16 v[16:19], v[178:181], v[198:201], v[16:19]
	v_mfma_f32_16x16x32_bf16 v[12:15], v[170:173], v[206:209], v[12:15]
	v_mfma_f32_16x16x32_bf16 v[8:11], v[178:181], v[206:209], v[8:11]
	v_mfma_f32_16x16x32_bf16 v[4:7], v[170:173], v[214:217], v[4:7]
	v_mfma_f32_16x16x32_bf16 v[0:3], v[178:181], v[214:217], v[0:3]
	s_setprio 0
	s_barrier
	s_add_i32 s67, s67, 2
	s_add_u32 s20, s20, 0x100
	s_addc_u32 s21, s21, 0
	s_add_u32 s65, s65, 0x100
	s_addc_u32 s66, s66, 0
	s_cmp_gt_u32 s67, 5
.LBB0_624:
	ds_read_b128 v[112:115], v167
	ds_read_b128 v[116:119], v167 offset:1024
	ds_read_b128 v[152:155], v167 offset:2048
	ds_read_b128 v[156:159], v167 offset:3072
	ds_read_b128 v[160:163], v168
	ds_read_b128 v[170:173], v168 offset:1024
	ds_read_b128 v[174:177], v168 offset:2048
	ds_read_b128 v[178:181], v168 offset:3072
	s_add_u32 s46, s20, 0xfffe0080
	s_addc_u32 s47, s21, -1
	s_cmp_eq_u32 s67, 4
	s_cselect_b32 s49, s17, s47
	s_cselect_b32 s48, s63, s46
	s_cselect_b32 s47, s15, s66
	s_cselect_b32 s46, s64, s65
	s_add_i32 m0, s35, 0xc000
	ds_read_b128 v[182:185], v169
	ds_read_b128 v[186:189], v169 offset:1024
	ds_read_b128 v[190:193], v169 offset:2048
	ds_read_b128 v[198:201], v169 offset:3072
	ds_read_b128 v[202:205], v169 offset:4096
	ds_read_b128 v[206:209], v169 offset:5120
	ds_read_b128 v[210:213], v169 offset:6144
	ds_read_b128 v[214:217], v169 offset:7168
	global_load_lds_dwordx4 v144, s[20:21]
	s_add_i32 m0, s35, 0xe000
	s_nop 0
	global_load_lds_dwordx4 v146, s[20:21]
	s_waitcnt vmcnt(8)
	s_waitcnt lgkmcnt(0)
	s_barrier
	s_setprio 1
	s_waitcnt lgkmcnt(0)
	v_mfma_f32_16x16x32_bf16 v[132:135], v[112:115], v[182:185], v[132:135]
	v_mfma_f32_16x16x32_bf16 v[128:131], v[152:155], v[182:185], v[128:131]
	v_mfma_f32_16x16x32_bf16 v[124:127], v[112:115], v[190:193], v[124:127]
	v_mfma_f32_16x16x32_bf16 v[120:123], v[152:155], v[190:193], v[120:123]
	v_mfma_f32_16x16x32_bf16 v[108:111], v[112:115], v[202:205], v[108:111]
	v_mfma_f32_16x16x32_bf16 v[104:107], v[152:155], v[202:205], v[104:107]
	v_mfma_f32_16x16x32_bf16 v[100:103], v[112:115], v[210:213], v[100:103]
	v_mfma_f32_16x16x32_bf16 v[96:99], v[152:155], v[210:213], v[96:99]
	v_mfma_f32_16x16x32_bf16 v[132:135], v[116:119], v[186:189], v[132:135]
	v_mfma_f32_16x16x32_bf16 v[128:131], v[156:159], v[186:189], v[128:131]
	v_mfma_f32_16x16x32_bf16 v[124:127], v[116:119], v[198:201], v[124:127]
	v_mfma_f32_16x16x32_bf16 v[120:123], v[156:159], v[198:201], v[120:123]
	v_mfma_f32_16x16x32_bf16 v[108:111], v[116:119], v[206:209], v[108:111]
	v_mfma_f32_16x16x32_bf16 v[104:107], v[156:159], v[206:209], v[104:107]
	v_mfma_f32_16x16x32_bf16 v[100:103], v[116:119], v[214:217], v[100:103]
	v_mfma_f32_16x16x32_bf16 v[96:99], v[156:159], v[214:217], v[96:99]
	v_mfma_f32_16x16x32_bf16 v[60:63], v[160:163], v[182:185], v[60:63]
	v_mfma_f32_16x16x32_bf16 v[56:59], v[174:177], v[182:185], v[56:59]
	v_mfma_f32_16x16x32_bf16 v[52:55], v[160:163], v[190:193], v[52:55]
	v_mfma_f32_16x16x32_bf16 v[48:51], v[174:177], v[190:193], v[48:51]
	v_mfma_f32_16x16x32_bf16 v[44:47], v[160:163], v[202:205], v[44:47]
	v_mfma_f32_16x16x32_bf16 v[40:43], v[174:177], v[202:205], v[40:43]
	v_mfma_f32_16x16x32_bf16 v[36:39], v[160:163], v[210:213], v[36:39]
	v_mfma_f32_16x16x32_bf16 v[32:35], v[174:177], v[210:213], v[32:35]
	v_mfma_f32_16x16x32_bf16 v[60:63], v[170:173], v[186:189], v[60:63]
	v_mfma_f32_16x16x32_bf16 v[56:59], v[178:181], v[186:189], v[56:59]
	v_mfma_f32_16x16x32_bf16 v[52:55], v[170:173], v[198:201], v[52:55]
	v_mfma_f32_16x16x32_bf16 v[48:51], v[178:181], v[198:201], v[48:51]
	v_mfma_f32_16x16x32_bf16 v[44:47], v[170:173], v[206:209], v[44:47]
	v_mfma_f32_16x16x32_bf16 v[40:43], v[178:181], v[206:209], v[40:43]
	v_mfma_f32_16x16x32_bf16 v[36:39], v[170:173], v[214:217], v[36:39]
	v_mfma_f32_16x16x32_bf16 v[32:35], v[178:181], v[214:217], v[32:35]
	s_setprio 0
	s_barrier
; #define PG8_STAGE(bufoff, gbase, voff) do { _Pragma("unroll") for (int _i = 0; _i < 2; ++_i) \
;         __builtin_amdgcn_global_load_lds((const unsigned*)((const char*)(gbase) + (voff)[_i]), (PG8_LAS unsigned*)(lds + (bufoff) + ldsw + _i * 8192), 16, 0, 0); } while (0)
; #define PG8_LDA(dst, b, h) do { _Pragma("unroll") for (int m = 0; m < 4; ++m) _Pragma("unroll") for (int k = 0; k < 2; ++k) dst[m][k] = *(const PG8_LAS bf16x8*)(lds + PG8_SA(b, h) + aoff + m * 2048 + k * 1024); } while (0)
; #define PG8_LDB(dst, b, h) do { _Pragma("unroll") for (int n = 0; n < 2; ++n) _Pragma("unroll") for (int k = 0; k < 2; ++k) dst[n][k] = *(const PG8_LAS bf16x8*)(lds + PG8_SB(b, h) + boff + n * 2048 + k * 1024); } while (0)
; #define PG8_MMA(ai, bj, At, Bt) do { __builtin_amdgcn_s_setprio(1); _Pragma("unroll") for (int m = 0; m < 4; ++m) _Pragma("unroll") for (int n = 0; n < 2; ++n) _Pragma("unroll") for (int k = 0; k < 2; ++k) \
;         acc[ai][bj][m][n] = __builtin_amdgcn_mfma_f32_16x16x32_bf16(Bt[n][k], At[m][k], acc[ai][bj][m][n], 0, 0, 0); __builtin_amdgcn_s_setprio(0); } while (0)
; #define PG8_WAIT_V(n) asm volatile("s_waitcnt vmcnt(" #n ")" ::: "memory")
; #define PG8_WAIT_L(n) asm volatile("s_waitcnt lgkmcnt(" #n ")" ::: "memory")
; #define PG8_BAR __builtin_amdgcn_s_barrier()
; #define PG8_SCHED __builtin_amdgcn_sched_barrier(0)
; template <class Epi, class Sched, bool ALIGN_EPI = false, bool SP2 = false>
; __device__ __forceinline__ void gemm_phase(PG8_LAS unsigned char* lds, const Gemm g, const Sched& S, const Epi& E) {
;     ...
;             PG8_LDA(At, 0, 1); PG8_STAGE(PG8_SB(0, 0), b2, voffB); PG8_STAGE(PG8_SB(0, 1), b2 + hstep, voffB); PG8_STAGE(PG8_SA(0, 0), a2, voffA);
;             PG8_WAIT_V(8); PG8_WAIT_L(0); PG8_BAR; PG8_MMA(1, 0, At, B0); PG8_MMA(1, 1, At, B1); PG8_BAR; PG8_SCHED;
;             PG8_LDB(B0, 1, 0); PG8_LDB(B1, 1, 1); PG8_SCHED; PG8_LDA(At, 1, 0); PG8_STAGE(PG8_SA(0, 1), a2 + hstep, voffA);
	s_add_i32 s68, s60, s51
	s_add_u32 s98, s46, s10
	s_addc_u32 s99, s47, s11
	s_add_u32 s100, s48, s10
	s_addc_u32 s101, s49, s11
	s_mov_b32 m0, s68
	ds_read_b128 v[182:185], v169 offset:16384
	ds_read_b128 v[186:189], v169 offset:17408
	ds_read_b128 v[190:193], v169 offset:18432
	ds_read_b128 v[198:201], v169 offset:19456
	ds_read_b128 v[202:205], v169 offset:20480
	ds_read_b128 v[206:209], v169 offset:21504
	ds_read_b128 v[210:213], v169 offset:22528
	ds_read_b128 v[214:217], v169 offset:23552
	global_load_lds_dwordx4 v138, s[46:47]
	s_add_i32 m0, s68, 0x2000
	s_add_u32 s68, s46, 0x20000
	s_addc_u32 s69, s47, 0
	s_add_i32 s70, s61, s51
	global_load_lds_dwordx4 v142, s[46:47]
	s_mov_b32 m0, s70
	s_nop 0
	global_load_lds_dwordx4 v138, s[68:69]
	s_add_i32 m0, s70, 0x2000
	s_nop 0
	global_load_lds_dwordx4 v142, s[68:69]
	s_mov_b32 m0, s35
	s_nop 0
	global_load_lds_dwordx4 v136, s[48:49]
	s_mov_b32 m0, s52
	s_nop 0
	global_load_lds_dwordx4 v140, s[48:49]
	s_waitcnt vmcnt(8)
	s_waitcnt lgkmcnt(0)
	s_barrier
	s_setprio 1
	s_waitcnt lgkmcnt(0)
	v_mfma_f32_16x16x32_bf16 v[92:95], v[112:115], v[182:185], v[92:95]
	v_mfma_f32_16x16x32_bf16 v[88:91], v[152:155], v[182:185], v[88:91]
	v_mfma_f32_16x16x32_bf16 v[84:87], v[112:115], v[190:193], v[84:87]
	v_mfma_f32_16x16x32_bf16 v[80:83], v[152:155], v[190:193], v[80:83]
	v_mfma_f32_16x16x32_bf16 v[76:79], v[112:115], v[202:205], v[76:79]
	v_mfma_f32_16x16x32_bf16 v[72:75], v[152:155], v[202:205], v[72:75]
	v_mfma_f32_16x16x32_bf16 v[68:71], v[112:115], v[210:213], v[68:71]
	v_mfma_f32_16x16x32_bf16 v[64:67], v[152:155], v[210:213], v[64:67]
	v_mfma_f32_16x16x32_bf16 v[92:95], v[116:119], v[186:189], v[92:95]
	v_mfma_f32_16x16x32_bf16 v[88:91], v[156:159], v[186:189], v[88:91]
	v_mfma_f32_16x16x32_bf16 v[84:87], v[116:119], v[198:201], v[84:87]
	v_mfma_f32_16x16x32_bf16 v[80:83], v[156:159], v[198:201], v[80:83]
	v_mfma_f32_16x16x32_bf16 v[76:79], v[116:119], v[206:209], v[76:79]
	v_mfma_f32_16x16x32_bf16 v[72:75], v[156:159], v[206:209], v[72:75]
	v_mfma_f32_16x16x32_bf16 v[68:71], v[116:119], v[214:217], v[68:71]
	v_mfma_f32_16x16x32_bf16 v[64:67], v[156:159], v[214:217], v[64:67]
	v_mfma_f32_16x16x32_bf16 v[28:31], v[160:163], v[182:185], v[28:31]
	v_mfma_f32_16x16x32_bf16 v[24:27], v[174:177], v[182:185], v[24:27]
	v_mfma_f32_16x16x32_bf16 v[20:23], v[160:163], v[190:193], v[20:23]
	v_mfma_f32_16x16x32_bf16 v[16:19], v[174:177], v[190:193], v[16:19]
	v_mfma_f32_16x16x32_bf16 v[12:15], v[160:163], v[202:205], v[12:15]
	v_mfma_f32_16x16x32_bf16 v[8:11], v[174:177], v[202:205], v[8:11]
	v_mfma_f32_16x16x32_bf16 v[4:7], v[160:163], v[210:213], v[4:7]
	v_mfma_f32_16x16x32_bf16 v[0:3], v[174:177], v[210:213], v[0:3]
	v_mfma_f32_16x16x32_bf16 v[28:31], v[170:173], v[186:189], v[28:31]
	v_mfma_f32_16x16x32_bf16 v[24:27], v[178:181], v[186:189], v[24:27]
	v_mfma_f32_16x16x32_bf16 v[20:23], v[170:173], v[198:201], v[20:23]
	v_mfma_f32_16x16x32_bf16 v[16:19], v[178:181], v[198:201], v[16:19]
	v_mfma_f32_16x16x32_bf16 v[12:15], v[170:173], v[206:209], v[12:15]
	v_mfma_f32_16x16x32_bf16 v[8:11], v[178:181], v[206:209], v[8:11]
	v_mfma_f32_16x16x32_bf16 v[4:7], v[170:173], v[214:217], v[4:7]
	v_mfma_f32_16x16x32_bf16 v[0:3], v[178:181], v[214:217], v[0:3]
	s_setprio 0
	s_barrier
	s_add_i32 s68, 0, 0x18000
	s_add_i32 s69, 0, 0x1c000
	v_add_u32_e32 v156, s68, v165
	v_add_u32_e32 v178, s69, v165
	ds_read_b128 v[112:115], v156
	ds_read_b128 v[116:119], v156 offset:1024
	ds_read_b128 v[152:155], v156 offset:2048
	ds_read_b128 v[156:159], v156 offset:3072
	ds_read_b128 v[160:163], v178
	ds_read_b128 v[170:173], v178 offset:1024
	ds_read_b128 v[174:177], v178 offset:2048
	ds_read_b128 v[178:181], v178 offset:3072
	s_add_u32 s48, s48, 0x20000
	s_addc_u32 s49, s49, 0
	s_mov_b32 m0, s53
	ds_read_b128 v[182:185], v169 offset:32768
	ds_read_b128 v[186:189], v169 offset:33792
	ds_read_b128 v[190:193], v169 offset:34816
	ds_read_b128 v[198:201], v169 offset:35840
	ds_read_b128 v[202:205], v169 offset:36864
	ds_read_b128 v[206:209], v169 offset:37888
	ds_read_b128 v[210:213], v169 offset:38912
	ds_read_b128 v[214:217], v169 offset:39936
	global_load_lds_dwordx4 v136, s[48:49]
	s_mov_b32 m0, s54
	s_nop 0
	global_load_lds_dwordx4 v140, s[48:49]
	s_waitcnt vmcnt(8)
	s_waitcnt lgkmcnt(0)
	s_barrier
; #define PG8_STAGE(bufoff, gbase, voff) do { _Pragma("unroll") for (int _i = 0; _i < 2; ++_i) \
;         __builtin_amdgcn_global_load_lds((const unsigned*)((const char*)(gbase) + (voff)[_i]), (PG8_LAS unsigned*)(lds + (bufoff) + ldsw + _i * 8192), 16, 0, 0); } while (0)
; #define PG8_LDA(dst, b, h) do { _Pragma("unroll") for (int m = 0; m < 4; ++m) _Pragma("unroll") for (int k = 0; k < 2; ++k) dst[m][k] = *(const PG8_LAS bf16x8*)(lds + PG8_SA(b, h) + aoff + m * 2048 + k * 1024); } while (0)
; #define PG8_MMA(ai, bj, At, Bt) do { __builtin_amdgcn_s_setprio(1); _Pragma("unroll") for (int m = 0; m < 4; ++m) _Pragma("unroll") for (int n = 0; n < 2; ++n) _Pragma("unroll") for (int k = 0; k < 2; ++k) \
;         acc[ai][bj][m][n] = __builtin_amdgcn_mfma_f32_16x16x32_bf16(Bt[n][k], At[m][k], acc[ai][bj][m][n], 0, 0, 0); __builtin_amdgcn_s_setprio(0); } while (0)
; #define PG8_WAIT_V(n) asm volatile("s_waitcnt vmcnt(" #n ")" ::: "memory")
; #define PG8_WAIT_L(n) asm volatile("s_waitcnt lgkmcnt(" #n ")" ::: "memory")
; #define PG8_BAR __builtin_amdgcn_s_barrier()
; #define PG8_SCHED __builtin_amdgcn_sched_barrier(0)
; template <class Epi, class Sched, bool ALIGN_EPI = false, bool SP2 = false>
; __device__ __forceinline__ void gemm_phase(PG8_LAS unsigned char* lds, const Gemm g, const Sched& S, const Epi& E) {
;     ...
;             PG8_WAIT_V(8); PG8_WAIT_L(0); PG8_BAR; PG8_MMA(0, 0, At, B0); PG8_MMA(0, 1, At, B1); PG8_BAR; PG8_SCHED;
;             PG8_LDA(At, 1, 1); PG8_STAGE(PG8_SB(1, 0), b3, voffB); PG8_STAGE(PG8_SB(1, 1), b3 + hstep, voffB); PG8_STAGE(PG8_SA(1, 0), a3, voffA);
;             PG8_WAIT_V(8); PG8_WAIT_L(0); PG8_BAR; PG8_MMA(1, 0, At, B0); PG8_MMA(1, 1, At, B1); PG8_BAR; PG8_SCHED;
;     ...
;         if constexpr (ALIGN_EPI) { if (wr == 0) PG8_BAR; }
	s_setprio 1
	s_waitcnt lgkmcnt(0)
	v_mfma_f32_16x16x32_bf16 v[132:135], v[112:115], v[182:185], v[132:135]
	v_mfma_f32_16x16x32_bf16 v[128:131], v[152:155], v[182:185], v[128:131]
	v_mfma_f32_16x16x32_bf16 v[124:127], v[112:115], v[190:193], v[124:127]
	v_mfma_f32_16x16x32_bf16 v[120:123], v[152:155], v[190:193], v[120:123]
	v_mfma_f32_16x16x32_bf16 v[108:111], v[112:115], v[202:205], v[108:111]
	v_mfma_f32_16x16x32_bf16 v[104:107], v[152:155], v[202:205], v[104:107]
	v_mfma_f32_16x16x32_bf16 v[100:103], v[112:115], v[210:213], v[100:103]
	v_mfma_f32_16x16x32_bf16 v[96:99], v[152:155], v[210:213], v[96:99]
	v_mfma_f32_16x16x32_bf16 v[132:135], v[116:119], v[186:189], v[132:135]
	v_mfma_f32_16x16x32_bf16 v[128:131], v[156:159], v[186:189], v[128:131]
	v_mfma_f32_16x16x32_bf16 v[124:127], v[116:119], v[198:201], v[124:127]
	v_mfma_f32_16x16x32_bf16 v[120:123], v[156:159], v[198:201], v[120:123]
	v_mfma_f32_16x16x32_bf16 v[108:111], v[116:119], v[206:209], v[108:111]
	v_mfma_f32_16x16x32_bf16 v[104:107], v[156:159], v[206:209], v[104:107]
	v_mfma_f32_16x16x32_bf16 v[100:103], v[116:119], v[214:217], v[100:103]
	v_mfma_f32_16x16x32_bf16 v[96:99], v[156:159], v[214:217], v[96:99]
	v_mfma_f32_16x16x32_bf16 v[60:63], v[160:163], v[182:185], v[60:63]
	v_mfma_f32_16x16x32_bf16 v[56:59], v[174:177], v[182:185], v[56:59]
	v_mfma_f32_16x16x32_bf16 v[52:55], v[160:163], v[190:193], v[52:55]
	v_mfma_f32_16x16x32_bf16 v[48:51], v[174:177], v[190:193], v[48:51]
	v_mfma_f32_16x16x32_bf16 v[44:47], v[160:163], v[202:205], v[44:47]
	v_mfma_f32_16x16x32_bf16 v[40:43], v[174:177], v[202:205], v[40:43]
	v_mfma_f32_16x16x32_bf16 v[36:39], v[160:163], v[210:213], v[36:39]
	v_mfma_f32_16x16x32_bf16 v[32:35], v[174:177], v[210:213], v[32:35]
	v_mfma_f32_16x16x32_bf16 v[60:63], v[170:173], v[186:189], v[60:63]
	v_mfma_f32_16x16x32_bf16 v[56:59], v[178:181], v[186:189], v[56:59]
	v_mfma_f32_16x16x32_bf16 v[52:55], v[170:173], v[198:201], v[52:55]
	v_mfma_f32_16x16x32_bf16 v[48:51], v[178:181], v[198:201], v[48:51]
	v_mfma_f32_16x16x32_bf16 v[44:47], v[170:173], v[206:209], v[44:47]
	v_mfma_f32_16x16x32_bf16 v[40:43], v[178:181], v[206:209], v[40:43]
	v_mfma_f32_16x16x32_bf16 v[36:39], v[170:173], v[214:217], v[36:39]
	v_mfma_f32_16x16x32_bf16 v[32:35], v[178:181], v[214:217], v[32:35]
	s_setprio 0
	s_barrier
	s_add_i32 s48, s68, s51
	s_mov_b32 m0, s48
	ds_read_b128 v[182:185], v169 offset:49152
	ds_read_b128 v[186:189], v169 offset:50176
	ds_read_b128 v[190:193], v169 offset:51200
	ds_read_b128 v[198:201], v169 offset:52224
	ds_read_b128 v[202:205], v169 offset:53248
	ds_read_b128 v[206:209], v169 offset:54272
	ds_read_b128 v[210:213], v169 offset:55296
	ds_read_b128 v[214:217], v169 offset:56320
	global_load_lds_dwordx4 v138, s[98:99]
	s_add_i32 m0, s48, 0x2000
	s_add_u32 s46, s46, 0x20080
	s_addc_u32 s47, s47, 0
	s_add_i32 s48, s69, s51
	global_load_lds_dwordx4 v142, s[98:99]
	s_mov_b32 m0, s48
	s_nop 0
	global_load_lds_dwordx4 v138, s[46:47]
	s_add_i32 m0, s48, 0x2000
	s_nop 0
	global_load_lds_dwordx4 v142, s[46:47]
	s_mov_b32 m0, s56
	s_nop 0
	global_load_lds_dwordx4 v136, s[100:101]
	s_mov_b32 m0, s57
	s_nop 0
	global_load_lds_dwordx4 v140, s[100:101]
	s_waitcnt vmcnt(8)
	s_waitcnt lgkmcnt(0)
	s_barrier
	s_setprio 1
	s_waitcnt lgkmcnt(0)
	v_mfma_f32_16x16x32_bf16 v[92:95], v[112:115], v[182:185], v[92:95]
	v_mfma_f32_16x16x32_bf16 v[88:91], v[152:155], v[182:185], v[88:91]
	v_mfma_f32_16x16x32_bf16 v[84:87], v[112:115], v[190:193], v[84:87]
	v_mfma_f32_16x16x32_bf16 v[80:83], v[152:155], v[190:193], v[80:83]
	v_mfma_f32_16x16x32_bf16 v[76:79], v[112:115], v[202:205], v[76:79]
	v_mfma_f32_16x16x32_bf16 v[72:75], v[152:155], v[202:205], v[72:75]
	v_mfma_f32_16x16x32_bf16 v[68:71], v[112:115], v[210:213], v[68:71]
	v_mfma_f32_16x16x32_bf16 v[64:67], v[152:155], v[210:213], v[64:67]
	v_mfma_f32_16x16x32_bf16 v[92:95], v[116:119], v[186:189], v[92:95]
	v_mfma_f32_16x16x32_bf16 v[88:91], v[156:159], v[186:189], v[88:91]
	v_mfma_f32_16x16x32_bf16 v[84:87], v[116:119], v[198:201], v[84:87]
	v_mfma_f32_16x16x32_bf16 v[80:83], v[156:159], v[198:201], v[80:83]
	v_mfma_f32_16x16x32_bf16 v[76:79], v[116:119], v[206:209], v[76:79]
	v_mfma_f32_16x16x32_bf16 v[72:75], v[156:159], v[206:209], v[72:75]
	v_mfma_f32_16x16x32_bf16 v[68:71], v[116:119], v[214:217], v[68:71]
	v_mfma_f32_16x16x32_bf16 v[64:67], v[156:159], v[214:217], v[64:67]
	v_mfma_f32_16x16x32_bf16 v[28:31], v[160:163], v[182:185], v[28:31]
	v_mfma_f32_16x16x32_bf16 v[24:27], v[174:177], v[182:185], v[24:27]
	v_mfma_f32_16x16x32_bf16 v[20:23], v[160:163], v[190:193], v[20:23]
	v_mfma_f32_16x16x32_bf16 v[16:19], v[174:177], v[190:193], v[16:19]
	v_mfma_f32_16x16x32_bf16 v[12:15], v[160:163], v[202:205], v[12:15]
	v_mfma_f32_16x16x32_bf16 v[8:11], v[174:177], v[202:205], v[8:11]
	v_mfma_f32_16x16x32_bf16 v[4:7], v[160:163], v[210:213], v[4:7]
	v_mfma_f32_16x16x32_bf16 v[0:3], v[174:177], v[210:213], v[0:3]
	v_mfma_f32_16x16x32_bf16 v[28:31], v[170:173], v[186:189], v[28:31]
	v_mfma_f32_16x16x32_bf16 v[24:27], v[178:181], v[186:189], v[24:27]
	v_mfma_f32_16x16x32_bf16 v[20:23], v[170:173], v[198:201], v[20:23]
	v_mfma_f32_16x16x32_bf16 v[16:19], v[178:181], v[198:201], v[16:19]
	v_mfma_f32_16x16x32_bf16 v[12:15], v[170:173], v[206:209], v[12:15]
	v_mfma_f32_16x16x32_bf16 v[8:11], v[178:181], v[206:209], v[8:11]
	v_mfma_f32_16x16x32_bf16 v[4:7], v[170:173], v[214:217], v[4:7]
	v_mfma_f32_16x16x32_bf16 v[0:3], v[178:181], v[214:217], v[0:3]
	s_setprio 0
	s_barrier
	s_add_i32 s67, s67, 2
	s_add_u32 s20, s20, 0x100
	s_addc_u32 s21, s21, 0
	s_add_u32 s65, s65, 0x100
	s_addc_u32 s66, s66, 0
	s_cmp_gt_u32 s67, 5
	s_cbranch_scc0 .LBB0_624
	s_and_b64 vcc, exec, s[12:13]
	s_cbranch_vccz .LBB0_627
	s_barrier

; #define PG8_STAGE(bufoff, gbase, voff) do { _Pragma("unroll") for (int _i = 0; _i < 2; ++_i) \
;         __builtin_amdgcn_global_load_lds((const unsigned*)((const char*)(gbase) + (voff)[_i]), (PG8_LAS unsigned*)(lds + (bufoff) + ldsw + _i * 8192), 16, 0, 0); } while (0)
; #define PG8_LDA(dst, b, h) do { _Pragma("unroll") for (int m = 0; m < 4; ++m) _Pragma("unroll") for (int k = 0; k < 2; ++k) dst[m][k] = *(const PG8_LAS bf16x8*)(lds + PG8_SA(b, h) + aoff + m * 2048 + k * 1024); } while (0)
; #define PG8_LDB(dst, b, h) do { _Pragma("unroll") for (int n = 0; n < 2; ++n) _Pragma("unroll") for (int k = 0; k < 2; ++k) dst[n][k] = *(const PG8_LAS bf16x8*)(lds + PG8_SB(b, h) + boff + n * 2048 + k * 1024); } while (0)
; #define PG8_MMA(ai, bj, At, Bt) do { __builtin_amdgcn_s_setprio(1); _Pragma("unroll") for (int m = 0; m < 4; ++m) _Pragma("unroll") for (int n = 0; n < 2; ++n) _Pragma("unroll") for (int k = 0; k < 2; ++k) \
;         acc[ai][bj][m][n] = __builtin_amdgcn_mfma_f32_16x16x32_bf16(Bt[n][k], At[m][k], acc[ai][bj][m][n], 0, 0, 0); __builtin_amdgcn_s_setprio(0); } while (0)
; #define PG8_BAR __builtin_amdgcn_s_barrier()
; template <class Epi, class Sched, bool ALIGN_EPI = false, bool SP2 = false>
; __device__ __forceinline__ void gemm_phase(PG8_LAS unsigned char* lds, const Gemm g, const Sched& S, const Epi& E) {
;     ...
;         const bool has_next = S.next(ui + 1, nxt);
;         const char* nA = has_next ? (const char*)g.A + (size_t)nxt.pm * tstep : cA; const char* nB = has_next ? (const char*)g.Bt + (size_t)nxt.pn * tstep : cB;
;         for (int t = 0; t < nt; t += 2) {
;             const bool last = (t == nt - 2);
;             const char* a1 = cA + (size_t)(t + 1) * kstep;
;             const char* a2 = last ? nA : cA + (size_t)(t + 2) * kstep; const char* b2 = last ? nB : cB + (size_t)(t + 2) * kstep;
;             const char* a3 = a2 + kstep; const char* b3 = b2 + kstep;
;             if (last && has_next) S.a_ready(nxt);
;             if constexpr (SP2) {
;             PG8_LDB(B0, 0, 0); PG8_LDB(B1, 0, 1); PG8_SCHED; PG8_LDA(At, 0, 0); PG8_STAGE(PG8_SA(1, 1), a1 + hstep, voffA);
;             PG8_WAIT_V(8); PG8_WAIT_L(0); PG8_BAR; PG8_MMA(0, 0, At, B0); PG8_MMA(0, 1, At, B1); PG8_BAR; PG8_SCHED;
;             PG8_LDA(At, 0, 1); PG8_STAGE(PG8_SB(0, 0), b2, voffB); PG8_STAGE(PG8_SB(0, 1), b2 + hstep, voffB); PG8_STAGE(PG8_SA(0, 0), a2, voffA);
.LBB0_704:
	s_ashr_i32 s47, s46, 31
	s_lshl_b64 s[48:49], s[46:47], 19
	s_add_u32 s48, s42, s48
	s_addc_u32 s49, s43, s49
	s_and_b64 s[50:51], s[6:7], exec
	s_cselect_b32 s35, s49, s21
	s_cselect_b32 s47, s48, s20
	s_ashr_i32 s45, s44, 31
	s_lshl_b64 s[50:51], s[44:45], 19
	s_add_u32 s50, s3, s50
	s_addc_u32 s51, s33, s51
	s_and_b64 s[56:57], s[6:7], exec
	s_cselect_b32 s45, s51, s55
	s_cselect_b32 s73, s50, s54
	s_add_u32 s20, s20, 0x40080
	s_addc_u32 s21, s21, 0
	s_add_u32 s74, s54, 0x100
	s_addc_u32 s75, s55, 0
	s_mov_b32 s76, -2
	s_waitcnt lgkmcnt(0)
	ds_read_b128 v[96:99], v223
	ds_read_b128 v[108:111], v223 offset:1024
	ds_read_b128 v[120:123], v223 offset:2048
	ds_read_b128 v[128:131], v223 offset:3072
	ds_read_b128 v[144:147], v224
	ds_read_b128 v[148:151], v224 offset:1024
	ds_read_b128 v[152:155], v224 offset:2048
	ds_read_b128 v[156:159], v224 offset:3072
	s_add_u32 s54, s20, 0xfffc0080
	s_addc_u32 s55, s21, -1
	s_cmp_eq_u32 s76, 12
	s_cselect_b32 s57, s35, s55
	s_cselect_b32 s56, s47, s54
	s_cselect_b32 s55, s45, s75
	s_cselect_b32 s54, s73, s74
	s_add_i32 m0, s53, 0xc000
	ds_read_b128 v[160:163], v225
	ds_read_b128 v[164:167], v225 offset:1024
	ds_read_b128 v[168:171], v225 offset:2048
	ds_read_b128 v[172:175], v225 offset:3072
	ds_read_b128 v[176:179], v225 offset:4096
	ds_read_b128 v[180:183], v225 offset:5120
	ds_read_b128 v[202:205], v225 offset:6144
	ds_read_b128 v[206:209], v225 offset:7168
	global_load_lds_dwordx4 v192, s[20:21]
	s_add_i32 m0, s53, 0xe000
	s_nop 0
	global_load_lds_dwordx4 v194, s[20:21]
	s_waitcnt vmcnt(8)
	s_waitcnt lgkmcnt(0)
	s_barrier
	s_setprio 1
	s_waitcnt lgkmcnt(0)
	v_mfma_f32_16x16x32_bf16 v[140:143], v[96:99], v[160:163], 0
	v_mfma_f32_16x16x32_bf16 v[136:139], v[120:123], v[160:163], 0
	v_mfma_f32_16x16x32_bf16 v[116:119], v[96:99], v[168:171], 0
	v_mfma_f32_16x16x32_bf16 v[112:115], v[120:123], v[168:171], 0
	v_mfma_f32_16x16x32_bf16 v[92:95], v[96:99], v[176:179], 0
	v_mfma_f32_16x16x32_bf16 v[88:91], v[120:123], v[176:179], 0
	v_mfma_f32_16x16x32_bf16 v[76:79], v[96:99], v[202:205], 0
	v_mfma_f32_16x16x32_bf16 v[72:75], v[120:123], v[202:205], 0
	v_mfma_f32_16x16x32_bf16 v[140:143], v[108:111], v[164:167], v[140:143]
	v_mfma_f32_16x16x32_bf16 v[136:139], v[128:131], v[164:167], v[136:139]
	v_mfma_f32_16x16x32_bf16 v[116:119], v[108:111], v[172:175], v[116:119]
	v_mfma_f32_16x16x32_bf16 v[112:115], v[128:131], v[172:175], v[112:115]
	v_mfma_f32_16x16x32_bf16 v[92:95], v[108:111], v[180:183], v[92:95]
	v_mfma_f32_16x16x32_bf16 v[88:91], v[128:131], v[180:183], v[88:91]
	v_mfma_f32_16x16x32_bf16 v[76:79], v[108:111], v[206:209], v[76:79]
	v_mfma_f32_16x16x32_bf16 v[72:75], v[128:131], v[206:209], v[72:75]
	v_mfma_f32_16x16x32_bf16 v[132:135], v[144:147], v[160:163], 0
	v_mfma_f32_16x16x32_bf16 v[124:127], v[152:155], v[160:163], 0
	v_mfma_f32_16x16x32_bf16 v[104:107], v[144:147], v[168:171], 0
	v_mfma_f32_16x16x32_bf16 v[100:103], v[152:155], v[168:171], 0
	v_mfma_f32_16x16x32_bf16 v[84:87], v[144:147], v[176:179], 0
	v_mfma_f32_16x16x32_bf16 v[80:83], v[152:155], v[176:179], 0
	v_mfma_f32_16x16x32_bf16 v[68:71], v[144:147], v[202:205], 0
	v_mfma_f32_16x16x32_bf16 v[64:67], v[152:155], v[202:205], 0
	v_mfma_f32_16x16x32_bf16 v[132:135], v[148:151], v[164:167], v[132:135]
	v_mfma_f32_16x16x32_bf16 v[124:127], v[156:159], v[164:167], v[124:127]
	v_mfma_f32_16x16x32_bf16 v[104:107], v[148:151], v[172:175], v[104:107]
	v_mfma_f32_16x16x32_bf16 v[100:103], v[156:159], v[172:175], v[100:103]
	v_mfma_f32_16x16x32_bf16 v[84:87], v[148:151], v[180:183], v[84:87]
	v_mfma_f32_16x16x32_bf16 v[80:83], v[156:159], v[180:183], v[80:83]
	v_mfma_f32_16x16x32_bf16 v[68:71], v[148:151], v[206:209], v[68:71]
	v_mfma_f32_16x16x32_bf16 v[64:67], v[156:159], v[206:209], v[64:67]
	s_setprio 0
	s_barrier
	s_add_i32 s77, s71, s58
	s_add_u32 s98, s54, s12
	s_addc_u32 s99, s55, s13
	s_add_u32 s100, s56, s12
	s_addc_u32 s101, s57, s13
	s_mov_b32 m0, s77
	ds_read_b128 v[160:163], v225 offset:16384
	ds_read_b128 v[164:167], v225 offset:17408
	ds_read_b128 v[168:171], v225 offset:18432
	ds_read_b128 v[172:175], v225 offset:19456
	ds_read_b128 v[176:179], v225 offset:20480
	ds_read_b128 v[180:183], v225 offset:21504
	ds_read_b128 v[202:205], v225 offset:22528
	ds_read_b128 v[206:209], v225 offset:23552
	global_load_lds_dwordx4 v186, s[54:55]
	s_add_i32 m0, s77, 0x2000
	s_add_u32 s78, s54, 0x40000
	s_addc_u32 s79, s55, 0
	s_add_i32 s77, s72, s58
	global_load_lds_dwordx4 v190, s[54:55]
	s_mov_b32 m0, s77
	s_nop 0
	global_load_lds_dwordx4 v186, s[78:79]
	s_add_i32 m0, s77, 0x2000
	s_nop 0
	global_load_lds_dwordx4 v190, s[78:79]
	s_mov_b32 m0, s53
	s_nop 0
	global_load_lds_dwordx4 v184, s[56:57]
	s_mov_b32 m0, s59
	s_nop 0
	global_load_lds_dwordx4 v188, s[56:57]
	s_waitcnt vmcnt(8)
	s_waitcnt lgkmcnt(0)
	s_barrier
; #define PG8_STAGE(bufoff, gbase, voff) do { _Pragma("unroll") for (int _i = 0; _i < 2; ++_i) \
;         __builtin_amdgcn_global_load_lds((const unsigned*)((const char*)(gbase) + (voff)[_i]), (PG8_LAS unsigned*)(lds + (bufoff) + ldsw + _i * 8192), 16, 0, 0); } while (0)
; #define PG8_LDA(dst, b, h) do { _Pragma("unroll") for (int m = 0; m < 4; ++m) _Pragma("unroll") for (int k = 0; k < 2; ++k) dst[m][k] = *(const PG8_LAS bf16x8*)(lds + PG8_SA(b, h) + aoff + m * 2048 + k * 1024); } while (0)
; #define PG8_LDB(dst, b, h) do { _Pragma("unroll") for (int n = 0; n < 2; ++n) _Pragma("unroll") for (int k = 0; k < 2; ++k) dst[n][k] = *(const PG8_LAS bf16x8*)(lds + PG8_SB(b, h) + boff + n * 2048 + k * 1024); } while (0)
; #define PG8_MMA(ai, bj, At, Bt) do { __builtin_amdgcn_s_setprio(1); _Pragma("unroll") for (int m = 0; m < 4; ++m) _Pragma("unroll") for (int n = 0; n < 2; ++n) _Pragma("unroll") for (int k = 0; k < 2; ++k) \
;         acc[ai][bj][m][n] = __builtin_amdgcn_mfma_f32_16x16x32_bf16(Bt[n][k], At[m][k], acc[ai][bj][m][n], 0, 0, 0); __builtin_amdgcn_s_setprio(0); } while (0)
; #define PG8_WAIT_V(n) asm volatile("s_waitcnt vmcnt(" #n ")" ::: "memory")
; #define PG8_WAIT_L(n) asm volatile("s_waitcnt lgkmcnt(" #n ")" ::: "memory")
; #define PG8_BAR __builtin_amdgcn_s_barrier()
; #define PG8_SCHED __builtin_amdgcn_sched_barrier(0)
; template <class Epi, class Sched, bool ALIGN_EPI = false, bool SP2 = false>
; __device__ __forceinline__ void gemm_phase(PG8_LAS unsigned char* lds, const Gemm g, const Sched& S, const Epi& E) {
;     ...
;             PG8_WAIT_V(8); PG8_WAIT_L(0); PG8_BAR; PG8_MMA(1, 0, At, B0); PG8_MMA(1, 1, At, B1); PG8_BAR; PG8_SCHED;
;             PG8_LDB(B0, 1, 0); PG8_LDB(B1, 1, 1); PG8_SCHED; PG8_LDA(At, 1, 0); PG8_STAGE(PG8_SA(0, 1), a2 + hstep, voffA);
;             PG8_WAIT_V(8); PG8_WAIT_L(0); PG8_BAR; PG8_MMA(0, 0, At, B0); PG8_MMA(0, 1, At, B1); PG8_BAR; PG8_SCHED;
	s_setprio 1
	s_waitcnt lgkmcnt(0)
	v_mfma_f32_16x16x32_bf16 v[60:63], v[96:99], v[160:163], 0
	v_mfma_f32_16x16x32_bf16 v[56:59], v[120:123], v[160:163], 0
	v_mfma_f32_16x16x32_bf16 v[44:47], v[96:99], v[168:171], 0
	v_mfma_f32_16x16x32_bf16 v[40:43], v[120:123], v[168:171], 0
	v_mfma_f32_16x16x32_bf16 v[28:31], v[96:99], v[176:179], 0
	v_mfma_f32_16x16x32_bf16 v[24:27], v[120:123], v[176:179], 0
	v_mfma_f32_16x16x32_bf16 v[12:15], v[96:99], v[202:205], 0
	v_mfma_f32_16x16x32_bf16 v[8:11], v[120:123], v[202:205], 0
	v_mfma_f32_16x16x32_bf16 v[60:63], v[108:111], v[164:167], v[60:63]
	v_mfma_f32_16x16x32_bf16 v[56:59], v[128:131], v[164:167], v[56:59]
	v_mfma_f32_16x16x32_bf16 v[44:47], v[108:111], v[172:175], v[44:47]
	v_mfma_f32_16x16x32_bf16 v[40:43], v[128:131], v[172:175], v[40:43]
	v_mfma_f32_16x16x32_bf16 v[28:31], v[108:111], v[180:183], v[28:31]
	v_mfma_f32_16x16x32_bf16 v[24:27], v[128:131], v[180:183], v[24:27]
	v_mfma_f32_16x16x32_bf16 v[12:15], v[108:111], v[206:209], v[12:15]
	v_mfma_f32_16x16x32_bf16 v[8:11], v[128:131], v[206:209], v[8:11]
	v_mfma_f32_16x16x32_bf16 v[52:55], v[144:147], v[160:163], 0
	v_mfma_f32_16x16x32_bf16 v[48:51], v[152:155], v[160:163], 0
	v_mfma_f32_16x16x32_bf16 v[36:39], v[144:147], v[168:171], 0
	v_mfma_f32_16x16x32_bf16 v[32:35], v[152:155], v[168:171], 0
	v_mfma_f32_16x16x32_bf16 v[20:23], v[144:147], v[176:179], 0
	v_mfma_f32_16x16x32_bf16 v[16:19], v[152:155], v[176:179], 0
	v_mfma_f32_16x16x32_bf16 v[4:7], v[144:147], v[202:205], 0
	v_mfma_f32_16x16x32_bf16 v[0:3], v[152:155], v[202:205], 0
	v_mfma_f32_16x16x32_bf16 v[52:55], v[148:151], v[164:167], v[52:55]
	v_mfma_f32_16x16x32_bf16 v[48:51], v[156:159], v[164:167], v[48:51]
	v_mfma_f32_16x16x32_bf16 v[36:39], v[148:151], v[172:175], v[36:39]
	v_mfma_f32_16x16x32_bf16 v[32:35], v[156:159], v[172:175], v[32:35]
	v_mfma_f32_16x16x32_bf16 v[20:23], v[148:151], v[180:183], v[20:23]
	v_mfma_f32_16x16x32_bf16 v[16:19], v[156:159], v[180:183], v[16:19]
	v_mfma_f32_16x16x32_bf16 v[4:7], v[148:151], v[206:209], v[4:7]
	v_mfma_f32_16x16x32_bf16 v[0:3], v[156:159], v[206:209], v[0:3]
	s_setprio 0
	s_barrier
	s_add_i32 s77, 0, 0x18000
	s_add_i32 s78, 0, 0x1c000
	v_add_u32_e32 v128, s77, v221
	v_add_u32_e32 v156, s78, v221
	ds_read_b128 v[96:99], v128
	ds_read_b128 v[108:111], v128 offset:1024
	ds_read_b128 v[120:123], v128 offset:2048
	ds_read_b128 v[128:131], v128 offset:3072
	ds_read_b128 v[144:147], v156
	ds_read_b128 v[148:151], v156 offset:1024
	ds_read_b128 v[152:155], v156 offset:2048
	ds_read_b128 v[156:159], v156 offset:3072
	s_add_u32 s56, s56, 0x40000
	s_addc_u32 s57, s57, 0
	s_mov_b32 m0, s60
	ds_read_b128 v[160:163], v225 offset:32768
	ds_read_b128 v[164:167], v225 offset:33792
	ds_read_b128 v[168:171], v225 offset:34816
	ds_read_b128 v[172:175], v225 offset:35840
	ds_read_b128 v[176:179], v225 offset:36864
	ds_read_b128 v[180:183], v225 offset:37888
	ds_read_b128 v[202:205], v225 offset:38912
	ds_read_b128 v[206:209], v225 offset:39936
	global_load_lds_dwordx4 v184, s[56:57]
	s_mov_b32 m0, s61
	s_nop 0
	global_load_lds_dwordx4 v188, s[56:57]
	s_waitcnt vmcnt(8)
	s_waitcnt lgkmcnt(0)
	s_barrier
	s_setprio 1
	s_waitcnt lgkmcnt(0)
	v_mfma_f32_16x16x32_bf16 v[140:143], v[96:99], v[160:163], v[140:143]
	v_mfma_f32_16x16x32_bf16 v[136:139], v[120:123], v[160:163], v[136:139]
	v_mfma_f32_16x16x32_bf16 v[116:119], v[96:99], v[168:171], v[116:119]
	v_mfma_f32_16x16x32_bf16 v[112:115], v[120:123], v[168:171], v[112:115]
	v_mfma_f32_16x16x32_bf16 v[92:95], v[96:99], v[176:179], v[92:95]
	v_mfma_f32_16x16x32_bf16 v[88:91], v[120:123], v[176:179], v[88:91]
	v_mfma_f32_16x16x32_bf16 v[76:79], v[96:99], v[202:205], v[76:79]
	v_mfma_f32_16x16x32_bf16 v[72:75], v[120:123], v[202:205], v[72:75]
	v_mfma_f32_16x16x32_bf16 v[140:143], v[108:111], v[164:167], v[140:143]
	v_mfma_f32_16x16x32_bf16 v[136:139], v[128:131], v[164:167], v[136:139]
	v_mfma_f32_16x16x32_bf16 v[116:119], v[108:111], v[172:175], v[116:119]
	v_mfma_f32_16x16x32_bf16 v[112:115], v[128:131], v[172:175], v[112:115]
	v_mfma_f32_16x16x32_bf16 v[92:95], v[108:111], v[180:183], v[92:95]
	v_mfma_f32_16x16x32_bf16 v[88:91], v[128:131], v[180:183], v[88:91]
	v_mfma_f32_16x16x32_bf16 v[76:79], v[108:111], v[206:209], v[76:79]
	v_mfma_f32_16x16x32_bf16 v[72:75], v[128:131], v[206:209], v[72:75]
	v_mfma_f32_16x16x32_bf16 v[132:135], v[144:147], v[160:163], v[132:135]
	v_mfma_f32_16x16x32_bf16 v[124:127], v[152:155], v[160:163], v[124:127]
	v_mfma_f32_16x16x32_bf16 v[104:107], v[144:147], v[168:171], v[104:107]
	v_mfma_f32_16x16x32_bf16 v[100:103], v[152:155], v[168:171], v[100:103]
	v_mfma_f32_16x16x32_bf16 v[84:87], v[144:147], v[176:179], v[84:87]
	v_mfma_f32_16x16x32_bf16 v[80:83], v[152:155], v[176:179], v[80:83]
	v_mfma_f32_16x16x32_bf16 v[68:71], v[144:147], v[202:205], v[68:71]
	v_mfma_f32_16x16x32_bf16 v[64:67], v[152:155], v[202:205], v[64:67]
	v_mfma_f32_16x16x32_bf16 v[132:135], v[148:151], v[164:167], v[132:135]
	v_mfma_f32_16x16x32_bf16 v[124:127], v[156:159], v[164:167], v[124:127]
	v_mfma_f32_16x16x32_bf16 v[104:107], v[148:151], v[172:175], v[104:107]
	v_mfma_f32_16x16x32_bf16 v[100:103], v[156:159], v[172:175], v[100:103]
	v_mfma_f32_16x16x32_bf16 v[84:87], v[148:151], v[180:183], v[84:87]
	v_mfma_f32_16x16x32_bf16 v[80:83], v[156:159], v[180:183], v[80:83]
	v_mfma_f32_16x16x32_bf16 v[68:71], v[148:151], v[206:209], v[68:71]
	v_mfma_f32_16x16x32_bf16 v[64:67], v[156:159], v[206:209], v[64:67]
	s_setprio 0
	s_barrier
; #define PG8_STAGE(bufoff, gbase, voff) do { _Pragma("unroll") for (int _i = 0; _i < 2; ++_i) \
;         __builtin_amdgcn_global_load_lds((const unsigned*)((const char*)(gbase) + (voff)[_i]), (PG8_LAS unsigned*)(lds + (bufoff) + ldsw + _i * 8192), 16, 0, 0); } while (0)
; #define PG8_LDA(dst, b, h) do { _Pragma("unroll") for (int m = 0; m < 4; ++m) _Pragma("unroll") for (int k = 0; k < 2; ++k) dst[m][k] = *(const PG8_LAS bf16x8*)(lds + PG8_SA(b, h) + aoff + m * 2048 + k * 1024); } while (0)
; #define PG8_LDB(dst, b, h) do { _Pragma("unroll") for (int n = 0; n < 2; ++n) _Pragma("unroll") for (int k = 0; k < 2; ++k) dst[n][k] = *(const PG8_LAS bf16x8*)(lds + PG8_SB(b, h) + boff + n * 2048 + k * 1024); } while (0)
; #define PG8_MMA(ai, bj, At, Bt) do { __builtin_amdgcn_s_setprio(1); _Pragma("unroll") for (int m = 0; m < 4; ++m) _Pragma("unroll") for (int n = 0; n < 2; ++n) _Pragma("unroll") for (int k = 0; k < 2; ++k) \
;         acc[ai][bj][m][n] = __builtin_amdgcn_mfma_f32_16x16x32_bf16(Bt[n][k], At[m][k], acc[ai][bj][m][n], 0, 0, 0); __builtin_amdgcn_s_setprio(0); } while (0)
; #define PG8_WAIT_V(n) asm volatile("s_waitcnt vmcnt(" #n ")" ::: "memory")
; template <class Epi, class Sched, bool ALIGN_EPI = false, bool SP2 = false>
; __device__ __forceinline__ void gemm_phase(PG8_LAS unsigned char* lds, const Gemm g, const Sched& S, const Epi& E) {
;     ...
;             PG8_LDB(B0, 0, 0); PG8_LDB(B1, 0, 1); PG8_SCHED; PG8_LDA(At, 0, 0); PG8_STAGE(PG8_SA(1, 1), a1 + hstep, voffA);
;             PG8_WAIT_V(8); PG8_WAIT_L(0); PG8_BAR; PG8_MMA(0, 0, At, B0); PG8_MMA(0, 1, At, B1); PG8_BAR; PG8_SCHED;
;             PG8_LDA(At, 0, 1); PG8_STAGE(PG8_SB(0, 0), b2, voffB); PG8_STAGE(PG8_SB(0, 1), b2 + hstep, voffB); PG8_STAGE(PG8_SA(0, 0), a2, voffA);
;             PG8_WAIT_V(8); PG8_WAIT_L(0); PG8_BAR; PG8_MMA(1, 0, At, B0); PG8_MMA(1, 1, At, B1); PG8_BAR; PG8_SCHED;
;             PG8_LDB(B0, 1, 0); PG8_LDB(B1, 1, 1); PG8_SCHED; PG8_LDA(At, 1, 0); PG8_STAGE(PG8_SA(0, 1), a2 + hstep, voffA);
;             PG8_WAIT_V(8); PG8_WAIT_L(0); PG8_BAR; PG8_MMA(0, 0, At, B0); PG8_MMA(0, 1, At, B1); PG8_BAR; PG8_SCHED;
;             PG8_LDA(At, 1, 1); PG8_STAGE(PG8_SB(1, 0), b3, voffB); PG8_STAGE(PG8_SB(1, 1), b3 + hstep, voffB); PG8_STAGE(PG8_SA(1, 0), a3, voffA);
;             PG8_WAIT_V(8); PG8_WAIT_L(0); PG8_BAR; PG8_MMA(1, 0, At, B0); PG8_MMA(1, 1, At, B1); PG8_BAR; PG8_SCHED;
	s_add_i32 s56, s77, s58
	s_mov_b32 m0, s56
	ds_read_b128 v[160:163], v225 offset:49152
	ds_read_b128 v[164:167], v225 offset:50176
	ds_read_b128 v[168:171], v225 offset:51200
	ds_read_b128 v[172:175], v225 offset:52224
	ds_read_b128 v[176:179], v225 offset:53248
	ds_read_b128 v[180:183], v225 offset:54272
	ds_read_b128 v[202:205], v225 offset:55296
	ds_read_b128 v[206:209], v225 offset:56320
	global_load_lds_dwordx4 v186, s[98:99]
	s_add_i32 m0, s56, 0x2000
	s_add_u32 s54, s54, 0x40080
	s_addc_u32 s55, s55, 0
	s_add_i32 s56, s78, s58
	global_load_lds_dwordx4 v190, s[98:99]
	s_mov_b32 m0, s56
	s_nop 0
	global_load_lds_dwordx4 v186, s[54:55]
	s_add_i32 m0, s56, 0x2000
	s_nop 0
	global_load_lds_dwordx4 v190, s[54:55]
	s_mov_b32 m0, s66
	s_nop 0
	global_load_lds_dwordx4 v184, s[100:101]
	s_mov_b32 m0, s67
	s_nop 0
	global_load_lds_dwordx4 v188, s[100:101]
	s_waitcnt vmcnt(8)
	s_waitcnt lgkmcnt(0)
	s_barrier
	s_setprio 1
	s_waitcnt lgkmcnt(0)
	v_mfma_f32_16x16x32_bf16 v[60:63], v[96:99], v[160:163], v[60:63]
	v_mfma_f32_16x16x32_bf16 v[56:59], v[120:123], v[160:163], v[56:59]
	v_mfma_f32_16x16x32_bf16 v[44:47], v[96:99], v[168:171], v[44:47]
	v_mfma_f32_16x16x32_bf16 v[40:43], v[120:123], v[168:171], v[40:43]
	v_mfma_f32_16x16x32_bf16 v[28:31], v[96:99], v[176:179], v[28:31]
	v_mfma_f32_16x16x32_bf16 v[24:27], v[120:123], v[176:179], v[24:27]
	v_mfma_f32_16x16x32_bf16 v[12:15], v[96:99], v[202:205], v[12:15]
	v_mfma_f32_16x16x32_bf16 v[8:11], v[120:123], v[202:205], v[8:11]
	v_mfma_f32_16x16x32_bf16 v[60:63], v[108:111], v[164:167], v[60:63]
	v_mfma_f32_16x16x32_bf16 v[56:59], v[128:131], v[164:167], v[56:59]
	v_mfma_f32_16x16x32_bf16 v[44:47], v[108:111], v[172:175], v[44:47]
	v_mfma_f32_16x16x32_bf16 v[40:43], v[128:131], v[172:175], v[40:43]
	v_mfma_f32_16x16x32_bf16 v[28:31], v[108:111], v[180:183], v[28:31]
	v_mfma_f32_16x16x32_bf16 v[24:27], v[128:131], v[180:183], v[24:27]
	v_mfma_f32_16x16x32_bf16 v[12:15], v[108:111], v[206:209], v[12:15]
	v_mfma_f32_16x16x32_bf16 v[8:11], v[128:131], v[206:209], v[8:11]
	v_mfma_f32_16x16x32_bf16 v[52:55], v[144:147], v[160:163], v[52:55]
	v_mfma_f32_16x16x32_bf16 v[48:51], v[152:155], v[160:163], v[48:51]
	v_mfma_f32_16x16x32_bf16 v[36:39], v[144:147], v[168:171], v[36:39]
	v_mfma_f32_16x16x32_bf16 v[32:35], v[152:155], v[168:171], v[32:35]
	v_mfma_f32_16x16x32_bf16 v[20:23], v[144:147], v[176:179], v[20:23]
	v_mfma_f32_16x16x32_bf16 v[16:19], v[152:155], v[176:179], v[16:19]
	v_mfma_f32_16x16x32_bf16 v[4:7], v[144:147], v[202:205], v[4:7]
	v_mfma_f32_16x16x32_bf16 v[0:3], v[152:155], v[202:205], v[0:3]
	v_mfma_f32_16x16x32_bf16 v[52:55], v[148:151], v[164:167], v[52:55]
	v_mfma_f32_16x16x32_bf16 v[48:51], v[156:159], v[164:167], v[48:51]
	v_mfma_f32_16x16x32_bf16 v[36:39], v[148:151], v[172:175], v[36:39]
	v_mfma_f32_16x16x32_bf16 v[32:35], v[156:159], v[172:175], v[32:35]
	v_mfma_f32_16x16x32_bf16 v[20:23], v[148:151], v[180:183], v[20:23]
	v_mfma_f32_16x16x32_bf16 v[16:19], v[156:159], v[180:183], v[16:19]
	v_mfma_f32_16x16x32_bf16 v[4:7], v[148:151], v[206:209], v[4:7]
	v_mfma_f32_16x16x32_bf16 v[0:3], v[156:159], v[206:209], v[0:3]
	s_setprio 0
	s_barrier
	s_add_i32 s76, s76, 2
	s_add_u32 s20, s20, 0x100
	s_addc_u32 s21, s21, 0
	s_add_u32 s74, s74, 0x100
	s_addc_u32 s75, s75, 0
	s_cmp_gt_u32 s76, 13
.LBB0_705:
	ds_read_b128 v[96:99], v223
	ds_read_b128 v[108:111], v223 offset:1024
	ds_read_b128 v[120:123], v223 offset:2048
	ds_read_b128 v[128:131], v223 offset:3072
	ds_read_b128 v[144:147], v224
	ds_read_b128 v[148:151], v224 offset:1024
	ds_read_b128 v[152:155], v224 offset:2048
	ds_read_b128 v[156:159], v224 offset:3072
	s_add_u32 s54, s20, 0xfffc0080
	s_addc_u32 s55, s21, -1
	s_cmp_eq_u32 s76, 12
	s_cselect_b32 s57, s35, s55
	s_cselect_b32 s56, s47, s54
	s_cselect_b32 s55, s45, s75
	s_cselect_b32 s54, s73, s74
	s_add_i32 m0, s53, 0xc000
	ds_read_b128 v[160:163], v225
	ds_read_b128 v[164:167], v225 offset:1024
	ds_read_b128 v[168:171], v225 offset:2048
	ds_read_b128 v[172:175], v225 offset:3072
	ds_read_b128 v[176:179], v225 offset:4096
	ds_read_b128 v[180:183], v225 offset:5120
	ds_read_b128 v[202:205], v225 offset:6144
	ds_read_b128 v[206:209], v225 offset:7168
	global_load_lds_dwordx4 v192, s[20:21]
	s_add_i32 m0, s53, 0xe000
	s_nop 0
	global_load_lds_dwordx4 v194, s[20:21]
	s_waitcnt vmcnt(8)
	s_waitcnt lgkmcnt(0)
	s_barrier
	s_setprio 1
	s_waitcnt lgkmcnt(0)
	v_mfma_f32_16x16x32_bf16 v[140:143], v[96:99], v[160:163], v[140:143]
	v_mfma_f32_16x16x32_bf16 v[136:139], v[120:123], v[160:163], v[136:139]
	v_mfma_f32_16x16x32_bf16 v[116:119], v[96:99], v[168:171], v[116:119]
	v_mfma_f32_16x16x32_bf16 v[112:115], v[120:123], v[168:171], v[112:115]
	v_mfma_f32_16x16x32_bf16 v[92:95], v[96:99], v[176:179], v[92:95]
	v_mfma_f32_16x16x32_bf16 v[88:91], v[120:123], v[176:179], v[88:91]
	v_mfma_f32_16x16x32_bf16 v[76:79], v[96:99], v[202:205], v[76:79]
	v_mfma_f32_16x16x32_bf16 v[72:75], v[120:123], v[202:205], v[72:75]
	v_mfma_f32_16x16x32_bf16 v[140:143], v[108:111], v[164:167], v[140:143]
	v_mfma_f32_16x16x32_bf16 v[136:139], v[128:131], v[164:167], v[136:139]
	v_mfma_f32_16x16x32_bf16 v[116:119], v[108:111], v[172:175], v[116:119]
	v_mfma_f32_16x16x32_bf16 v[112:115], v[128:131], v[172:175], v[112:115]
	v_mfma_f32_16x16x32_bf16 v[92:95], v[108:111], v[180:183], v[92:95]
	v_mfma_f32_16x16x32_bf16 v[88:91], v[128:131], v[180:183], v[88:91]
	v_mfma_f32_16x16x32_bf16 v[76:79], v[108:111], v[206:209], v[76:79]
	v_mfma_f32_16x16x32_bf16 v[72:75], v[128:131], v[206:209], v[72:75]
	v_mfma_f32_16x16x32_bf16 v[132:135], v[144:147], v[160:163], v[132:135]
	v_mfma_f32_16x16x32_bf16 v[124:127], v[152:155], v[160:163], v[124:127]
	v_mfma_f32_16x16x32_bf16 v[104:107], v[144:147], v[168:171], v[104:107]
	v_mfma_f32_16x16x32_bf16 v[100:103], v[152:155], v[168:171], v[100:103]
	v_mfma_f32_16x16x32_bf16 v[84:87], v[144:147], v[176:179], v[84:87]
	v_mfma_f32_16x16x32_bf16 v[80:83], v[152:155], v[176:179], v[80:83]
	v_mfma_f32_16x16x32_bf16 v[68:71], v[144:147], v[202:205], v[68:71]
	v_mfma_f32_16x16x32_bf16 v[64:67], v[152:155], v[202:205], v[64:67]
	v_mfma_f32_16x16x32_bf16 v[132:135], v[148:151], v[164:167], v[132:135]
	v_mfma_f32_16x16x32_bf16 v[124:127], v[156:159], v[164:167], v[124:127]
	v_mfma_f32_16x16x32_bf16 v[104:107], v[148:151], v[172:175], v[104:107]
	v_mfma_f32_16x16x32_bf16 v[100:103], v[156:159], v[172:175], v[100:103]
	v_mfma_f32_16x16x32_bf16 v[84:87], v[148:151], v[180:183], v[84:87]
	v_mfma_f32_16x16x32_bf16 v[80:83], v[156:159], v[180:183], v[80:83]
	v_mfma_f32_16x16x32_bf16 v[68:71], v[148:151], v[206:209], v[68:71]
	v_mfma_f32_16x16x32_bf16 v[64:67], v[156:159], v[206:209], v[64:67]
	s_setprio 0
	s_barrier
; #define PG8_STAGE(bufoff, gbase, voff) do { _Pragma("unroll") for (int _i = 0; _i < 2; ++_i) \
;         __builtin_amdgcn_global_load_lds((const unsigned*)((const char*)(gbase) + (voff)[_i]), (PG8_LAS unsigned*)(lds + (bufoff) + ldsw + _i * 8192), 16, 0, 0); } while (0)
; #define PG8_LDA(dst, b, h) do { _Pragma("unroll") for (int m = 0; m < 4; ++m) _Pragma("unroll") for (int k = 0; k < 2; ++k) dst[m][k] = *(const PG8_LAS bf16x8*)(lds + PG8_SA(b, h) + aoff + m * 2048 + k * 1024); } while (0)
; #define PG8_LDB(dst, b, h) do { _Pragma("unroll") for (int n = 0; n < 2; ++n) _Pragma("unroll") for (int k = 0; k < 2; ++k) dst[n][k] = *(const PG8_LAS bf16x8*)(lds + PG8_SB(b, h) + boff + n * 2048 + k * 1024); } while (0)
; #define PG8_MMA(ai, bj, At, Bt) do { __builtin_amdgcn_s_setprio(1); _Pragma("unroll") for (int m = 0; m < 4; ++m) _Pragma("unroll") for (int n = 0; n < 2; ++n) _Pragma("unroll") for (int k = 0; k < 2; ++k) \
;         acc[ai][bj][m][n] = __builtin_amdgcn_mfma_f32_16x16x32_bf16(Bt[n][k], At[m][k], acc[ai][bj][m][n], 0, 0, 0); __builtin_amdgcn_s_setprio(0); } while (0)
; #define PG8_WAIT_V(n) asm volatile("s_waitcnt vmcnt(" #n ")" ::: "memory")
; #define PG8_WAIT_L(n) asm volatile("s_waitcnt lgkmcnt(" #n ")" ::: "memory")
; #define PG8_BAR __builtin_amdgcn_s_barrier()
; #define PG8_SCHED __builtin_amdgcn_sched_barrier(0)
; template <class Epi, class Sched, bool ALIGN_EPI = false, bool SP2 = false>
; __device__ __forceinline__ void gemm_phase(PG8_LAS unsigned char* lds, const Gemm g, const Sched& S, const Epi& E) {
;     ...
;             PG8_LDA(At, 0, 1); PG8_STAGE(PG8_SB(0, 0), b2, voffB); PG8_STAGE(PG8_SB(0, 1), b2 + hstep, voffB); PG8_STAGE(PG8_SA(0, 0), a2, voffA);
;             PG8_WAIT_V(8); PG8_WAIT_L(0); PG8_BAR; PG8_MMA(1, 0, At, B0); PG8_MMA(1, 1, At, B1); PG8_BAR; PG8_SCHED;
;             PG8_LDB(B0, 1, 0); PG8_LDB(B1, 1, 1); PG8_SCHED; PG8_LDA(At, 1, 0); PG8_STAGE(PG8_SA(0, 1), a2 + hstep, voffA);
	s_add_i32 s77, s71, s58
	s_add_u32 s98, s54, s12
	s_addc_u32 s99, s55, s13
	s_add_u32 s100, s56, s12
	s_addc_u32 s101, s57, s13
	s_mov_b32 m0, s77
	ds_read_b128 v[160:163], v225 offset:16384
	ds_read_b128 v[164:167], v225 offset:17408
	ds_read_b128 v[168:171], v225 offset:18432
	ds_read_b128 v[172:175], v225 offset:19456
	ds_read_b128 v[176:179], v225 offset:20480
	ds_read_b128 v[180:183], v225 offset:21504
	ds_read_b128 v[202:205], v225 offset:22528
	ds_read_b128 v[206:209], v225 offset:23552
	global_load_lds_dwordx4 v186, s[54:55]
	s_add_i32 m0, s77, 0x2000
	s_add_u32 s78, s54, 0x40000
	s_addc_u32 s79, s55, 0
	s_add_i32 s77, s72, s58
	global_load_lds_dwordx4 v190, s[54:55]
	s_mov_b32 m0, s77
	s_nop 0
	global_load_lds_dwordx4 v186, s[78:79]
	s_add_i32 m0, s77, 0x2000
	s_nop 0
	global_load_lds_dwordx4 v190, s[78:79]
	s_mov_b32 m0, s53
	s_nop 0
	global_load_lds_dwordx4 v184, s[56:57]
	s_mov_b32 m0, s59
	s_nop 0
	global_load_lds_dwordx4 v188, s[56:57]
	s_waitcnt vmcnt(8)
	s_waitcnt lgkmcnt(0)
	s_barrier
	s_setprio 1
	s_waitcnt lgkmcnt(0)
	v_mfma_f32_16x16x32_bf16 v[60:63], v[96:99], v[160:163], v[60:63]
	v_mfma_f32_16x16x32_bf16 v[56:59], v[120:123], v[160:163], v[56:59]
	v_mfma_f32_16x16x32_bf16 v[44:47], v[96:99], v[168:171], v[44:47]
	v_mfma_f32_16x16x32_bf16 v[40:43], v[120:123], v[168:171], v[40:43]
	v_mfma_f32_16x16x32_bf16 v[28:31], v[96:99], v[176:179], v[28:31]
	v_mfma_f32_16x16x32_bf16 v[24:27], v[120:123], v[176:179], v[24:27]
	v_mfma_f32_16x16x32_bf16 v[12:15], v[96:99], v[202:205], v[12:15]
	v_mfma_f32_16x16x32_bf16 v[8:11], v[120:123], v[202:205], v[8:11]
	v_mfma_f32_16x16x32_bf16 v[60:63], v[108:111], v[164:167], v[60:63]
	v_mfma_f32_16x16x32_bf16 v[56:59], v[128:131], v[164:167], v[56:59]
	v_mfma_f32_16x16x32_bf16 v[44:47], v[108:111], v[172:175], v[44:47]
	v_mfma_f32_16x16x32_bf16 v[40:43], v[128:131], v[172:175], v[40:43]
	v_mfma_f32_16x16x32_bf16 v[28:31], v[108:111], v[180:183], v[28:31]
	v_mfma_f32_16x16x32_bf16 v[24:27], v[128:131], v[180:183], v[24:27]
	v_mfma_f32_16x16x32_bf16 v[12:15], v[108:111], v[206:209], v[12:15]
	v_mfma_f32_16x16x32_bf16 v[8:11], v[128:131], v[206:209], v[8:11]
	v_mfma_f32_16x16x32_bf16 v[52:55], v[144:147], v[160:163], v[52:55]
	v_mfma_f32_16x16x32_bf16 v[48:51], v[152:155], v[160:163], v[48:51]
	v_mfma_f32_16x16x32_bf16 v[36:39], v[144:147], v[168:171], v[36:39]
	v_mfma_f32_16x16x32_bf16 v[32:35], v[152:155], v[168:171], v[32:35]
	v_mfma_f32_16x16x32_bf16 v[20:23], v[144:147], v[176:179], v[20:23]
	v_mfma_f32_16x16x32_bf16 v[16:19], v[152:155], v[176:179], v[16:19]
	v_mfma_f32_16x16x32_bf16 v[4:7], v[144:147], v[202:205], v[4:7]
	v_mfma_f32_16x16x32_bf16 v[0:3], v[152:155], v[202:205], v[0:3]
	v_mfma_f32_16x16x32_bf16 v[52:55], v[148:151], v[164:167], v[52:55]
	v_mfma_f32_16x16x32_bf16 v[48:51], v[156:159], v[164:167], v[48:51]
	v_mfma_f32_16x16x32_bf16 v[36:39], v[148:151], v[172:175], v[36:39]
	v_mfma_f32_16x16x32_bf16 v[32:35], v[156:159], v[172:175], v[32:35]
	v_mfma_f32_16x16x32_bf16 v[20:23], v[148:151], v[180:183], v[20:23]
	v_mfma_f32_16x16x32_bf16 v[16:19], v[156:159], v[180:183], v[16:19]
	v_mfma_f32_16x16x32_bf16 v[4:7], v[148:151], v[206:209], v[4:7]
	v_mfma_f32_16x16x32_bf16 v[0:3], v[156:159], v[206:209], v[0:3]
	s_setprio 0
	s_barrier
	s_add_i32 s77, 0, 0x18000
	s_add_i32 s78, 0, 0x1c000
	v_add_u32_e32 v128, s77, v221
	v_add_u32_e32 v156, s78, v221
	ds_read_b128 v[96:99], v128
	ds_read_b128 v[108:111], v128 offset:1024
	ds_read_b128 v[120:123], v128 offset:2048
	ds_read_b128 v[128:131], v128 offset:3072
	ds_read_b128 v[144:147], v156
	ds_read_b128 v[148:151], v156 offset:1024
	ds_read_b128 v[152:155], v156 offset:2048
	ds_read_b128 v[156:159], v156 offset:3072
	s_add_u32 s56, s56, 0x40000
	s_addc_u32 s57, s57, 0
	s_mov_b32 m0, s60
	ds_read_b128 v[160:163], v225 offset:32768
	ds_read_b128 v[164:167], v225 offset:33792
	ds_read_b128 v[168:171], v225 offset:34816
	ds_read_b128 v[172:175], v225 offset:35840
	ds_read_b128 v[176:179], v225 offset:36864
	ds_read_b128 v[180:183], v225 offset:37888
	ds_read_b128 v[202:205], v225 offset:38912
	ds_read_b128 v[206:209], v225 offset:39936
	global_load_lds_dwordx4 v184, s[56:57]
	s_mov_b32 m0, s61
	s_nop 0
	global_load_lds_dwordx4 v188, s[56:57]
	s_waitcnt vmcnt(8)
	s_waitcnt lgkmcnt(0)
	s_barrier
; #define PG8_STAGE(bufoff, gbase, voff) do { _Pragma("unroll") for (int _i = 0; _i < 2; ++_i) \
;         __builtin_amdgcn_global_load_lds((const unsigned*)((const char*)(gbase) + (voff)[_i]), (PG8_LAS unsigned*)(lds + (bufoff) + ldsw + _i * 8192), 16, 0, 0); } while (0)
; #define PG8_LDA(dst, b, h) do { _Pragma("unroll") for (int m = 0; m < 4; ++m) _Pragma("unroll") for (int k = 0; k < 2; ++k) dst[m][k] = *(const PG8_LAS bf16x8*)(lds + PG8_SA(b, h) + aoff + m * 2048 + k * 1024); } while (0)
; #define PG8_MMA(ai, bj, At, Bt) do { __builtin_amdgcn_s_setprio(1); _Pragma("unroll") for (int m = 0; m < 4; ++m) _Pragma("unroll") for (int n = 0; n < 2; ++n) _Pragma("unroll") for (int k = 0; k < 2; ++k) \
;         acc[ai][bj][m][n] = __builtin_amdgcn_mfma_f32_16x16x32_bf16(Bt[n][k], At[m][k], acc[ai][bj][m][n], 0, 0, 0); __builtin_amdgcn_s_setprio(0); } while (0)
; #define PG8_WAIT_V(n) asm volatile("s_waitcnt vmcnt(" #n ")" ::: "memory")
; #define PG8_WAIT_L(n) asm volatile("s_waitcnt lgkmcnt(" #n ")" ::: "memory")
; #define PG8_BAR __builtin_amdgcn_s_barrier()
; #define PG8_SCHED __builtin_amdgcn_sched_barrier(0)
; template <class Epi, class Sched, bool ALIGN_EPI = false, bool SP2 = false>
; __device__ __forceinline__ void gemm_phase(PG8_LAS unsigned char* lds, const Gemm g, const Sched& S, const Epi& E) {
;     ...
;             PG8_WAIT_V(8); PG8_WAIT_L(0); PG8_BAR; PG8_MMA(0, 0, At, B0); PG8_MMA(0, 1, At, B1); PG8_BAR; PG8_SCHED;
;             PG8_LDA(At, 1, 1); PG8_STAGE(PG8_SB(1, 0), b3, voffB); PG8_STAGE(PG8_SB(1, 1), b3 + hstep, voffB); PG8_STAGE(PG8_SA(1, 0), a3, voffA);
;             PG8_WAIT_V(8); PG8_WAIT_L(0); PG8_BAR; PG8_MMA(1, 0, At, B0); PG8_MMA(1, 1, At, B1); PG8_BAR; PG8_SCHED;
;     ...
;         if constexpr (ALIGN_EPI) { if (wr == 0) PG8_BAR; }
	s_setprio 1
	s_waitcnt lgkmcnt(0)
	v_mfma_f32_16x16x32_bf16 v[140:143], v[96:99], v[160:163], v[140:143]
	v_mfma_f32_16x16x32_bf16 v[136:139], v[120:123], v[160:163], v[136:139]
	v_mfma_f32_16x16x32_bf16 v[116:119], v[96:99], v[168:171], v[116:119]
	v_mfma_f32_16x16x32_bf16 v[112:115], v[120:123], v[168:171], v[112:115]
	v_mfma_f32_16x16x32_bf16 v[92:95], v[96:99], v[176:179], v[92:95]
	v_mfma_f32_16x16x32_bf16 v[88:91], v[120:123], v[176:179], v[88:91]
	v_mfma_f32_16x16x32_bf16 v[76:79], v[96:99], v[202:205], v[76:79]
	v_mfma_f32_16x16x32_bf16 v[72:75], v[120:123], v[202:205], v[72:75]
	v_mfma_f32_16x16x32_bf16 v[140:143], v[108:111], v[164:167], v[140:143]
	v_mfma_f32_16x16x32_bf16 v[136:139], v[128:131], v[164:167], v[136:139]
	v_mfma_f32_16x16x32_bf16 v[116:119], v[108:111], v[172:175], v[116:119]
	v_mfma_f32_16x16x32_bf16 v[112:115], v[128:131], v[172:175], v[112:115]
	v_mfma_f32_16x16x32_bf16 v[92:95], v[108:111], v[180:183], v[92:95]
	v_mfma_f32_16x16x32_bf16 v[88:91], v[128:131], v[180:183], v[88:91]
	v_mfma_f32_16x16x32_bf16 v[76:79], v[108:111], v[206:209], v[76:79]
	v_mfma_f32_16x16x32_bf16 v[72:75], v[128:131], v[206:209], v[72:75]
	v_mfma_f32_16x16x32_bf16 v[132:135], v[144:147], v[160:163], v[132:135]
	v_mfma_f32_16x16x32_bf16 v[124:127], v[152:155], v[160:163], v[124:127]
	v_mfma_f32_16x16x32_bf16 v[104:107], v[144:147], v[168:171], v[104:107]
	v_mfma_f32_16x16x32_bf16 v[100:103], v[152:155], v[168:171], v[100:103]
	v_mfma_f32_16x16x32_bf16 v[84:87], v[144:147], v[176:179], v[84:87]
	v_mfma_f32_16x16x32_bf16 v[80:83], v[152:155], v[176:179], v[80:83]
	v_mfma_f32_16x16x32_bf16 v[68:71], v[144:147], v[202:205], v[68:71]
	v_mfma_f32_16x16x32_bf16 v[64:67], v[152:155], v[202:205], v[64:67]
	v_mfma_f32_16x16x32_bf16 v[132:135], v[148:151], v[164:167], v[132:135]
	v_mfma_f32_16x16x32_bf16 v[124:127], v[156:159], v[164:167], v[124:127]
	v_mfma_f32_16x16x32_bf16 v[104:107], v[148:151], v[172:175], v[104:107]
	v_mfma_f32_16x16x32_bf16 v[100:103], v[156:159], v[172:175], v[100:103]
	v_mfma_f32_16x16x32_bf16 v[84:87], v[148:151], v[180:183], v[84:87]
	v_mfma_f32_16x16x32_bf16 v[80:83], v[156:159], v[180:183], v[80:83]
	v_mfma_f32_16x16x32_bf16 v[68:71], v[148:151], v[206:209], v[68:71]
	v_mfma_f32_16x16x32_bf16 v[64:67], v[156:159], v[206:209], v[64:67]
	s_setprio 0
	s_barrier
	s_add_i32 s56, s77, s58
	s_mov_b32 m0, s56
	ds_read_b128 v[160:163], v225 offset:49152
	ds_read_b128 v[164:167], v225 offset:50176
	ds_read_b128 v[168:171], v225 offset:51200
	ds_read_b128 v[172:175], v225 offset:52224
	ds_read_b128 v[176:179], v225 offset:53248
	ds_read_b128 v[180:183], v225 offset:54272
	ds_read_b128 v[202:205], v225 offset:55296
	ds_read_b128 v[206:209], v225 offset:56320
	global_load_lds_dwordx4 v186, s[98:99]
	s_add_i32 m0, s56, 0x2000
	s_add_u32 s54, s54, 0x40080
	s_addc_u32 s55, s55, 0
	s_add_i32 s56, s78, s58
	global_load_lds_dwordx4 v190, s[98:99]
	s_mov_b32 m0, s56
	s_nop 0
	global_load_lds_dwordx4 v186, s[54:55]
	s_add_i32 m0, s56, 0x2000
	s_nop 0
	global_load_lds_dwordx4 v190, s[54:55]
	s_mov_b32 m0, s66
	s_nop 0
	global_load_lds_dwordx4 v184, s[100:101]
	s_mov_b32 m0, s67
	s_nop 0
	global_load_lds_dwordx4 v188, s[100:101]
	s_waitcnt vmcnt(8)
	s_waitcnt lgkmcnt(0)
	s_barrier
	s_setprio 1
	s_waitcnt lgkmcnt(0)
	v_mfma_f32_16x16x32_bf16 v[60:63], v[96:99], v[160:163], v[60:63]
	v_mfma_f32_16x16x32_bf16 v[56:59], v[120:123], v[160:163], v[56:59]
	v_mfma_f32_16x16x32_bf16 v[44:47], v[96:99], v[168:171], v[44:47]
	v_mfma_f32_16x16x32_bf16 v[40:43], v[120:123], v[168:171], v[40:43]
	v_mfma_f32_16x16x32_bf16 v[28:31], v[96:99], v[176:179], v[28:31]
	v_mfma_f32_16x16x32_bf16 v[24:27], v[120:123], v[176:179], v[24:27]
	v_mfma_f32_16x16x32_bf16 v[12:15], v[96:99], v[202:205], v[12:15]
	v_mfma_f32_16x16x32_bf16 v[8:11], v[120:123], v[202:205], v[8:11]
	v_mfma_f32_16x16x32_bf16 v[60:63], v[108:111], v[164:167], v[60:63]
	v_mfma_f32_16x16x32_bf16 v[56:59], v[128:131], v[164:167], v[56:59]
	v_mfma_f32_16x16x32_bf16 v[44:47], v[108:111], v[172:175], v[44:47]
	v_mfma_f32_16x16x32_bf16 v[40:43], v[128:131], v[172:175], v[40:43]
	v_mfma_f32_16x16x32_bf16 v[28:31], v[108:111], v[180:183], v[28:31]
	v_mfma_f32_16x16x32_bf16 v[24:27], v[128:131], v[180:183], v[24:27]
	v_mfma_f32_16x16x32_bf16 v[12:15], v[108:111], v[206:209], v[12:15]
	v_mfma_f32_16x16x32_bf16 v[8:11], v[128:131], v[206:209], v[8:11]
	v_mfma_f32_16x16x32_bf16 v[52:55], v[144:147], v[160:163], v[52:55]
	v_mfma_f32_16x16x32_bf16 v[48:51], v[152:155], v[160:163], v[48:51]
	v_mfma_f32_16x16x32_bf16 v[36:39], v[144:147], v[168:171], v[36:39]
	v_mfma_f32_16x16x32_bf16 v[32:35], v[152:155], v[168:171], v[32:35]
	v_mfma_f32_16x16x32_bf16 v[20:23], v[144:147], v[176:179], v[20:23]
	v_mfma_f32_16x16x32_bf16 v[16:19], v[152:155], v[176:179], v[16:19]
	v_mfma_f32_16x16x32_bf16 v[4:7], v[144:147], v[202:205], v[4:7]
	v_mfma_f32_16x16x32_bf16 v[0:3], v[152:155], v[202:205], v[0:3]
	v_mfma_f32_16x16x32_bf16 v[52:55], v[148:151], v[164:167], v[52:55]
	v_mfma_f32_16x16x32_bf16 v[48:51], v[156:159], v[164:167], v[48:51]
	v_mfma_f32_16x16x32_bf16 v[36:39], v[148:151], v[172:175], v[36:39]
	v_mfma_f32_16x16x32_bf16 v[32:35], v[156:159], v[172:175], v[32:35]
	v_mfma_f32_16x16x32_bf16 v[20:23], v[148:151], v[180:183], v[20:23]
	v_mfma_f32_16x16x32_bf16 v[16:19], v[156:159], v[180:183], v[16:19]
	v_mfma_f32_16x16x32_bf16 v[4:7], v[148:151], v[206:209], v[4:7]
	v_mfma_f32_16x16x32_bf16 v[0:3], v[156:159], v[206:209], v[0:3]
	s_setprio 0
	s_barrier
	s_add_i32 s76, s76, 2
	s_add_u32 s20, s20, 0x100
	s_addc_u32 s21, s21, 0
	s_add_u32 s74, s74, 0x100
	s_addc_u32 s75, s75, 0
	s_cmp_gt_u32 s76, 13
	s_cbranch_scc0 .LBB0_705
	s_and_b64 vcc, exec, s[14:15]
	s_cbranch_vccz .LBB0_708
	s_barrier

; #define PG8_STAGE(bufoff, gbase, voff) do { _Pragma("unroll") for (int _i = 0; _i < 2; ++_i) \
;         __builtin_amdgcn_global_load_lds((const unsigned*)((const char*)(gbase) + (voff)[_i]), (PG8_LAS unsigned*)(lds + (bufoff) + ldsw + _i * 8192), 16, 0, 0); } while (0)
; #define PG8_LDA(dst, b, h) do { _Pragma("unroll") for (int m = 0; m < 4; ++m) _Pragma("unroll") for (int k = 0; k < 2; ++k) dst[m][k] = *(const PG8_LAS bf16x8*)(lds + PG8_SA(b, h) + aoff + m * 2048 + k * 1024); } while (0)
; #define PG8_LDB(dst, b, h) do { _Pragma("unroll") for (int n = 0; n < 2; ++n) _Pragma("unroll") for (int k = 0; k < 2; ++k) dst[n][k] = *(const PG8_LAS bf16x8*)(lds + PG8_SB(b, h) + boff + n * 2048 + k * 1024); } while (0)
; #define PG8_MMA(ai, bj, At, Bt) do { __builtin_amdgcn_s_setprio(1); _Pragma("unroll") for (int m = 0; m < 4; ++m) _Pragma("unroll") for (int n = 0; n < 2; ++n) _Pragma("unroll") for (int k = 0; k < 2; ++k) \
;         acc[ai][bj][m][n] = __builtin_amdgcn_mfma_f32_16x16x32_bf16(Bt[n][k], At[m][k], acc[ai][bj][m][n], 0, 0, 0); __builtin_amdgcn_s_setprio(0); } while (0)
; #define PG8_BAR __builtin_amdgcn_s_barrier()
; template <class Epi, class Sched, bool ALIGN_EPI = false, bool SP2 = false>
; __device__ __forceinline__ void gemm_phase(PG8_LAS unsigned char* lds, const Gemm g, const Sched& S, const Epi& E) {
;     ...
;         const bool has_next = S.next(ui + 1, nxt);
;         const char* nA = has_next ? (const char*)g.A + (size_t)nxt.pm * tstep : cA; const char* nB = has_next ? (const char*)g.Bt + (size_t)nxt.pn * tstep : cB;
;         for (int t = 0; t < nt; t += 2) {
;             const bool last = (t == nt - 2);
;             const char* a1 = cA + (size_t)(t + 1) * kstep;
;             const char* a2 = last ? nA : cA + (size_t)(t + 2) * kstep; const char* b2 = last ? nB : cB + (size_t)(t + 2) * kstep;
;             const char* a3 = a2 + kstep; const char* b3 = b2 + kstep;
;             if (last && has_next) S.a_ready(nxt);
;             if constexpr (SP2) {
;             PG8_LDB(B0, 0, 0); PG8_LDB(B1, 0, 1); PG8_SCHED; PG8_LDA(At, 0, 0); PG8_STAGE(PG8_SA(1, 1), a1 + hstep, voffA);
;             PG8_WAIT_V(8); PG8_WAIT_L(0); PG8_BAR; PG8_MMA(0, 0, At, B0); PG8_MMA(0, 1, At, B1); PG8_BAR; PG8_SCHED;
;             PG8_LDA(At, 0, 1); PG8_STAGE(PG8_SB(0, 0), b2, voffB); PG8_STAGE(PG8_SB(0, 1), b2 + hstep, voffB); PG8_STAGE(PG8_SA(0, 0), a2, voffA);
.LBB0_809:
	s_ashr_i32 s15, s14, 31
	s_lshl_b64 s[16:17], s[14:15], 19
	s_add_u32 s16, s36, s16
	s_addc_u32 s17, s37, s17
	s_and_b64 s[18:19], s[4:5], exec
	s_cselect_b32 s15, s17, s21
	s_cselect_b32 s65, s16, s20
	s_ashr_i32 s13, s12, 31
	s_lshl_b64 s[18:19], s[12:13], 19
	s_add_u32 s18, s50, s18
	s_addc_u32 s19, s51, s19
	s_and_b64 s[44:45], s[4:5], exec
	s_cselect_b32 s13, s19, s39
	s_cselect_b32 s66, s18, s38
	s_add_u32 s20, s20, 0x40080
	s_addc_u32 s21, s21, 0
	s_add_u32 s67, s38, 0x100
	s_addc_u32 s68, s39, 0
	s_mov_b32 s69, -2
	ds_read_b128 v[154:157], v150
	ds_read_b128 v[158:161], v150 offset:1024
	ds_read_b128 v[162:165], v150 offset:2048
	ds_read_b128 v[166:169], v150 offset:3072
	ds_read_b128 v[170:173], v151
	ds_read_b128 v[174:177], v151 offset:1024
	ds_read_b128 v[178:181], v151 offset:2048
	ds_read_b128 v[182:185], v151 offset:3072
	s_add_u32 s38, s20, 0xfffc0080
	s_addc_u32 s39, s21, -1
	s_cmp_eq_u32 s69, 12
	s_cselect_b32 s45, s15, s39
	s_cselect_b32 s44, s65, s38
	s_cselect_b32 s39, s13, s68
	s_cselect_b32 s38, s66, s67
	s_add_i32 m0, s35, 0xc000
	ds_read_b128 v[186:189], v152
	ds_read_b128 v[190:193], v152 offset:1024
	ds_read_b128 v[198:201], v152 offset:2048
	ds_read_b128 v[202:205], v152 offset:3072
	ds_read_b128 v[206:209], v152 offset:4096
	ds_read_b128 v[210:213], v152 offset:5120
	ds_read_b128 v[214:217], v152 offset:6144
	ds_read_b128 v[218:221], v152 offset:7168
	global_load_lds_dwordx4 v136, s[20:21]
	s_add_i32 m0, s35, 0xe000
	s_nop 0
	global_load_lds_dwordx4 v138, s[20:21]
	s_waitcnt vmcnt(8)
	s_waitcnt lgkmcnt(0)
	s_barrier
	s_setprio 1
	s_waitcnt lgkmcnt(0)
	v_mfma_f32_16x16x32_bf16 v[124:127], v[154:157], v[186:189], 0
	v_mfma_f32_16x16x32_bf16 v[116:119], v[162:165], v[186:189], 0
	v_mfma_f32_16x16x32_bf16 v[108:111], v[154:157], v[198:201], 0
	v_mfma_f32_16x16x32_bf16 v[100:103], v[162:165], v[198:201], 0
	v_mfma_f32_16x16x32_bf16 v[92:95], v[154:157], v[206:209], 0
	v_mfma_f32_16x16x32_bf16 v[84:87], v[162:165], v[206:209], 0
	v_mfma_f32_16x16x32_bf16 v[76:79], v[154:157], v[214:217], 0
	v_mfma_f32_16x16x32_bf16 v[68:71], v[162:165], v[214:217], 0
	v_mfma_f32_16x16x32_bf16 v[124:127], v[158:161], v[190:193], v[124:127]
	v_mfma_f32_16x16x32_bf16 v[116:119], v[166:169], v[190:193], v[116:119]
	v_mfma_f32_16x16x32_bf16 v[108:111], v[158:161], v[202:205], v[108:111]
	v_mfma_f32_16x16x32_bf16 v[100:103], v[166:169], v[202:205], v[100:103]
	v_mfma_f32_16x16x32_bf16 v[92:95], v[158:161], v[210:213], v[92:95]
	v_mfma_f32_16x16x32_bf16 v[84:87], v[166:169], v[210:213], v[84:87]
	v_mfma_f32_16x16x32_bf16 v[76:79], v[158:161], v[218:221], v[76:79]
	v_mfma_f32_16x16x32_bf16 v[68:71], v[166:169], v[218:221], v[68:71]
	v_mfma_f32_16x16x32_bf16 v[120:123], v[170:173], v[186:189], 0
	v_mfma_f32_16x16x32_bf16 v[112:115], v[178:181], v[186:189], 0
	v_mfma_f32_16x16x32_bf16 v[104:107], v[170:173], v[198:201], 0
	v_mfma_f32_16x16x32_bf16 v[96:99], v[178:181], v[198:201], 0
	v_mfma_f32_16x16x32_bf16 v[88:91], v[170:173], v[206:209], 0
	v_mfma_f32_16x16x32_bf16 v[80:83], v[178:181], v[206:209], 0
	v_mfma_f32_16x16x32_bf16 v[72:75], v[170:173], v[214:217], 0
	v_mfma_f32_16x16x32_bf16 v[64:67], v[178:181], v[214:217], 0
	v_mfma_f32_16x16x32_bf16 v[120:123], v[174:177], v[190:193], v[120:123]
	v_mfma_f32_16x16x32_bf16 v[112:115], v[182:185], v[190:193], v[112:115]
	v_mfma_f32_16x16x32_bf16 v[104:107], v[174:177], v[202:205], v[104:107]
	v_mfma_f32_16x16x32_bf16 v[96:99], v[182:185], v[202:205], v[96:99]
	v_mfma_f32_16x16x32_bf16 v[88:91], v[174:177], v[210:213], v[88:91]
	v_mfma_f32_16x16x32_bf16 v[80:83], v[182:185], v[210:213], v[80:83]
	v_mfma_f32_16x16x32_bf16 v[72:75], v[174:177], v[218:221], v[72:75]
	v_mfma_f32_16x16x32_bf16 v[64:67], v[182:185], v[218:221], v[64:67]
	s_setprio 0
	s_barrier
	s_add_i32 s70, s60, s52
	s_add_u32 s98, s38, s8
	s_addc_u32 s99, s39, s9
	s_add_u32 s100, s44, s8
	s_addc_u32 s101, s45, s9
	s_mov_b32 m0, s70
	ds_read_b128 v[186:189], v152 offset:16384
	ds_read_b128 v[190:193], v152 offset:17408
	ds_read_b128 v[198:201], v152 offset:18432
	ds_read_b128 v[202:205], v152 offset:19456
	ds_read_b128 v[206:209], v152 offset:20480
	ds_read_b128 v[210:213], v152 offset:21504
	ds_read_b128 v[214:217], v152 offset:22528
	ds_read_b128 v[218:221], v152 offset:23552
	global_load_lds_dwordx4 v132, s[38:39]
	s_add_i32 m0, s70, 0x2000
	s_add_u32 s70, s38, 0x40000
	s_addc_u32 s71, s39, 0
	s_add_i32 s72, s61, s52
	global_load_lds_dwordx4 v128, s[38:39]
	s_mov_b32 m0, s72
	s_nop 0
	global_load_lds_dwordx4 v132, s[70:71]
	s_add_i32 m0, s72, 0x2000
	s_nop 0
	global_load_lds_dwordx4 v128, s[70:71]
	s_mov_b32 m0, s35
	s_nop 0
	global_load_lds_dwordx4 v134, s[44:45]
	s_mov_b32 m0, s54
	s_nop 0
	global_load_lds_dwordx4 v130, s[44:45]
	s_waitcnt vmcnt(8)
	s_waitcnt lgkmcnt(0)
	s_barrier
; #define PG8_STAGE(bufoff, gbase, voff) do { _Pragma("unroll") for (int _i = 0; _i < 2; ++_i) \
;         __builtin_amdgcn_global_load_lds((const unsigned*)((const char*)(gbase) + (voff)[_i]), (PG8_LAS unsigned*)(lds + (bufoff) + ldsw + _i * 8192), 16, 0, 0); } while (0)
; #define PG8_LDA(dst, b, h) do { _Pragma("unroll") for (int m = 0; m < 4; ++m) _Pragma("unroll") for (int k = 0; k < 2; ++k) dst[m][k] = *(const PG8_LAS bf16x8*)(lds + PG8_SA(b, h) + aoff + m * 2048 + k * 1024); } while (0)
; #define PG8_LDB(dst, b, h) do { _Pragma("unroll") for (int n = 0; n < 2; ++n) _Pragma("unroll") for (int k = 0; k < 2; ++k) dst[n][k] = *(const PG8_LAS bf16x8*)(lds + PG8_SB(b, h) + boff + n * 2048 + k * 1024); } while (0)
; #define PG8_MMA(ai, bj, At, Bt) do { __builtin_amdgcn_s_setprio(1); _Pragma("unroll") for (int m = 0; m < 4; ++m) _Pragma("unroll") for (int n = 0; n < 2; ++n) _Pragma("unroll") for (int k = 0; k < 2; ++k) \
;         acc[ai][bj][m][n] = __builtin_amdgcn_mfma_f32_16x16x32_bf16(Bt[n][k], At[m][k], acc[ai][bj][m][n], 0, 0, 0); __builtin_amdgcn_s_setprio(0); } while (0)
; #define PG8_WAIT_V(n) asm volatile("s_waitcnt vmcnt(" #n ")" ::: "memory")
; #define PG8_WAIT_L(n) asm volatile("s_waitcnt lgkmcnt(" #n ")" ::: "memory")
; #define PG8_BAR __builtin_amdgcn_s_barrier()
; #define PG8_SCHED __builtin_amdgcn_sched_barrier(0)
; template <class Epi, class Sched, bool ALIGN_EPI = false, bool SP2 = false>
; __device__ __forceinline__ void gemm_phase(PG8_LAS unsigned char* lds, const Gemm g, const Sched& S, const Epi& E) {
;     ...
;             PG8_WAIT_V(8); PG8_WAIT_L(0); PG8_BAR; PG8_MMA(1, 0, At, B0); PG8_MMA(1, 1, At, B1); PG8_BAR; PG8_SCHED;
;             PG8_LDB(B0, 1, 0); PG8_LDB(B1, 1, 1); PG8_SCHED; PG8_LDA(At, 1, 0); PG8_STAGE(PG8_SA(0, 1), a2 + hstep, voffA);
;             PG8_WAIT_V(8); PG8_WAIT_L(0); PG8_BAR; PG8_MMA(0, 0, At, B0); PG8_MMA(0, 1, At, B1); PG8_BAR; PG8_SCHED;
	s_setprio 1
	s_waitcnt lgkmcnt(0)
	v_mfma_f32_16x16x32_bf16 v[60:63], v[154:157], v[186:189], 0
	v_mfma_f32_16x16x32_bf16 v[52:55], v[162:165], v[186:189], 0
	v_mfma_f32_16x16x32_bf16 v[44:47], v[154:157], v[198:201], 0
	v_mfma_f32_16x16x32_bf16 v[36:39], v[162:165], v[198:201], 0
	v_mfma_f32_16x16x32_bf16 v[28:31], v[154:157], v[206:209], 0
	v_mfma_f32_16x16x32_bf16 v[20:23], v[162:165], v[206:209], 0
	v_mfma_f32_16x16x32_bf16 v[12:15], v[154:157], v[214:217], 0
	v_mfma_f32_16x16x32_bf16 v[4:7], v[162:165], v[214:217], 0
	v_mfma_f32_16x16x32_bf16 v[60:63], v[158:161], v[190:193], v[60:63]
	v_mfma_f32_16x16x32_bf16 v[52:55], v[166:169], v[190:193], v[52:55]
	v_mfma_f32_16x16x32_bf16 v[44:47], v[158:161], v[202:205], v[44:47]
	v_mfma_f32_16x16x32_bf16 v[36:39], v[166:169], v[202:205], v[36:39]
	v_mfma_f32_16x16x32_bf16 v[28:31], v[158:161], v[210:213], v[28:31]
	v_mfma_f32_16x16x32_bf16 v[20:23], v[166:169], v[210:213], v[20:23]
	v_mfma_f32_16x16x32_bf16 v[12:15], v[158:161], v[218:221], v[12:15]
	v_mfma_f32_16x16x32_bf16 v[4:7], v[166:169], v[218:221], v[4:7]
	v_mfma_f32_16x16x32_bf16 v[56:59], v[170:173], v[186:189], 0
	v_mfma_f32_16x16x32_bf16 v[48:51], v[178:181], v[186:189], 0
	v_mfma_f32_16x16x32_bf16 v[40:43], v[170:173], v[198:201], 0
	v_mfma_f32_16x16x32_bf16 v[32:35], v[178:181], v[198:201], 0
	v_mfma_f32_16x16x32_bf16 v[24:27], v[170:173], v[206:209], 0
	v_mfma_f32_16x16x32_bf16 v[16:19], v[178:181], v[206:209], 0
	v_mfma_f32_16x16x32_bf16 v[8:11], v[170:173], v[214:217], 0
	v_mfma_f32_16x16x32_bf16 v[0:3], v[178:181], v[214:217], 0
	v_mfma_f32_16x16x32_bf16 v[56:59], v[174:177], v[190:193], v[56:59]
	v_mfma_f32_16x16x32_bf16 v[48:51], v[182:185], v[190:193], v[48:51]
	v_mfma_f32_16x16x32_bf16 v[40:43], v[174:177], v[202:205], v[40:43]
	v_mfma_f32_16x16x32_bf16 v[32:35], v[182:185], v[202:205], v[32:35]
	v_mfma_f32_16x16x32_bf16 v[24:27], v[174:177], v[210:213], v[24:27]
	v_mfma_f32_16x16x32_bf16 v[16:19], v[182:185], v[210:213], v[16:19]
	v_mfma_f32_16x16x32_bf16 v[8:11], v[174:177], v[218:221], v[8:11]
	v_mfma_f32_16x16x32_bf16 v[0:3], v[182:185], v[218:221], v[0:3]
	s_setprio 0
	s_barrier
	s_add_i32 s70, 0, 0x18000
	v_add_u32_e32 v153, s70, v147
	s_add_i32 s71, 0, 0x1c000
	ds_read_b128 v[154:157], v153
	ds_read_b128 v[158:161], v153 offset:1024
	ds_read_b128 v[162:165], v153 offset:2048
	ds_read_b128 v[166:169], v153 offset:3072
	v_add_u32_e32 v153, s71, v147
	ds_read_b128 v[170:173], v153
	ds_read_b128 v[174:177], v153 offset:1024
	ds_read_b128 v[178:181], v153 offset:2048
	ds_read_b128 v[182:185], v153 offset:3072
	s_add_u32 s44, s44, 0x40000
	s_addc_u32 s45, s45, 0
	s_mov_b32 m0, s55
	ds_read_b128 v[186:189], v152 offset:32768
	ds_read_b128 v[190:193], v152 offset:33792
	ds_read_b128 v[198:201], v152 offset:34816
	ds_read_b128 v[202:205], v152 offset:35840
	ds_read_b128 v[206:209], v152 offset:36864
	ds_read_b128 v[210:213], v152 offset:37888
	ds_read_b128 v[214:217], v152 offset:38912
	ds_read_b128 v[218:221], v152 offset:39936
	global_load_lds_dwordx4 v134, s[44:45]
	s_mov_b32 m0, s56
	s_nop 0
	global_load_lds_dwordx4 v130, s[44:45]
	s_waitcnt vmcnt(8)
	s_waitcnt lgkmcnt(0)
	s_barrier
	s_setprio 1
	s_waitcnt lgkmcnt(0)
	v_mfma_f32_16x16x32_bf16 v[124:127], v[154:157], v[186:189], v[124:127]
	v_mfma_f32_16x16x32_bf16 v[116:119], v[162:165], v[186:189], v[116:119]
	v_mfma_f32_16x16x32_bf16 v[108:111], v[154:157], v[198:201], v[108:111]
	v_mfma_f32_16x16x32_bf16 v[100:103], v[162:165], v[198:201], v[100:103]
	v_mfma_f32_16x16x32_bf16 v[92:95], v[154:157], v[206:209], v[92:95]
	v_mfma_f32_16x16x32_bf16 v[84:87], v[162:165], v[206:209], v[84:87]
	v_mfma_f32_16x16x32_bf16 v[76:79], v[154:157], v[214:217], v[76:79]
	v_mfma_f32_16x16x32_bf16 v[68:71], v[162:165], v[214:217], v[68:71]
	v_mfma_f32_16x16x32_bf16 v[124:127], v[158:161], v[190:193], v[124:127]
	v_mfma_f32_16x16x32_bf16 v[116:119], v[166:169], v[190:193], v[116:119]
	v_mfma_f32_16x16x32_bf16 v[108:111], v[158:161], v[202:205], v[108:111]
	v_mfma_f32_16x16x32_bf16 v[100:103], v[166:169], v[202:205], v[100:103]
	v_mfma_f32_16x16x32_bf16 v[92:95], v[158:161], v[210:213], v[92:95]
	v_mfma_f32_16x16x32_bf16 v[84:87], v[166:169], v[210:213], v[84:87]
	v_mfma_f32_16x16x32_bf16 v[76:79], v[158:161], v[218:221], v[76:79]
	v_mfma_f32_16x16x32_bf16 v[68:71], v[166:169], v[218:221], v[68:71]
	v_mfma_f32_16x16x32_bf16 v[120:123], v[170:173], v[186:189], v[120:123]
	v_mfma_f32_16x16x32_bf16 v[112:115], v[178:181], v[186:189], v[112:115]
	v_mfma_f32_16x16x32_bf16 v[104:107], v[170:173], v[198:201], v[104:107]
	v_mfma_f32_16x16x32_bf16 v[96:99], v[178:181], v[198:201], v[96:99]
	v_mfma_f32_16x16x32_bf16 v[88:91], v[170:173], v[206:209], v[88:91]
	v_mfma_f32_16x16x32_bf16 v[80:83], v[178:181], v[206:209], v[80:83]
	v_mfma_f32_16x16x32_bf16 v[72:75], v[170:173], v[214:217], v[72:75]
	v_mfma_f32_16x16x32_bf16 v[64:67], v[178:181], v[214:217], v[64:67]
	v_mfma_f32_16x16x32_bf16 v[120:123], v[174:177], v[190:193], v[120:123]
	v_mfma_f32_16x16x32_bf16 v[112:115], v[182:185], v[190:193], v[112:115]
	v_mfma_f32_16x16x32_bf16 v[104:107], v[174:177], v[202:205], v[104:107]
	v_mfma_f32_16x16x32_bf16 v[96:99], v[182:185], v[202:205], v[96:99]
	v_mfma_f32_16x16x32_bf16 v[88:91], v[174:177], v[210:213], v[88:91]
	v_mfma_f32_16x16x32_bf16 v[80:83], v[182:185], v[210:213], v[80:83]
	v_mfma_f32_16x16x32_bf16 v[72:75], v[174:177], v[218:221], v[72:75]
	v_mfma_f32_16x16x32_bf16 v[64:67], v[182:185], v[218:221], v[64:67]
	s_setprio 0
	s_barrier
; #define PG8_STAGE(bufoff, gbase, voff) do { _Pragma("unroll") for (int _i = 0; _i < 2; ++_i) \
;         __builtin_amdgcn_global_load_lds((const unsigned*)((const char*)(gbase) + (voff)[_i]), (PG8_LAS unsigned*)(lds + (bufoff) + ldsw + _i * 8192), 16, 0, 0); } while (0)
; #define PG8_LDA(dst, b, h) do { _Pragma("unroll") for (int m = 0; m < 4; ++m) _Pragma("unroll") for (int k = 0; k < 2; ++k) dst[m][k] = *(const PG8_LAS bf16x8*)(lds + PG8_SA(b, h) + aoff + m * 2048 + k * 1024); } while (0)
; #define PG8_LDB(dst, b, h) do { _Pragma("unroll") for (int n = 0; n < 2; ++n) _Pragma("unroll") for (int k = 0; k < 2; ++k) dst[n][k] = *(const PG8_LAS bf16x8*)(lds + PG8_SB(b, h) + boff + n * 2048 + k * 1024); } while (0)
; #define PG8_MMA(ai, bj, At, Bt) do { __builtin_amdgcn_s_setprio(1); _Pragma("unroll") for (int m = 0; m < 4; ++m) _Pragma("unroll") for (int n = 0; n < 2; ++n) _Pragma("unroll") for (int k = 0; k < 2; ++k) \
;         acc[ai][bj][m][n] = __builtin_amdgcn_mfma_f32_16x16x32_bf16(Bt[n][k], At[m][k], acc[ai][bj][m][n], 0, 0, 0); __builtin_amdgcn_s_setprio(0); } while (0)
; #define PG8_WAIT_V(n) asm volatile("s_waitcnt vmcnt(" #n ")" ::: "memory")
; template <class Epi, class Sched, bool ALIGN_EPI = false, bool SP2 = false>
; __device__ __forceinline__ void gemm_phase(PG8_LAS unsigned char* lds, const Gemm g, const Sched& S, const Epi& E) {
;     ...
;             PG8_LDB(B0, 0, 0); PG8_LDB(B1, 0, 1); PG8_SCHED; PG8_LDA(At, 0, 0); PG8_STAGE(PG8_SA(1, 1), a1 + hstep, voffA);
;             PG8_WAIT_V(8); PG8_WAIT_L(0); PG8_BAR; PG8_MMA(0, 0, At, B0); PG8_MMA(0, 1, At, B1); PG8_BAR; PG8_SCHED;
;             PG8_LDA(At, 0, 1); PG8_STAGE(PG8_SB(0, 0), b2, voffB); PG8_STAGE(PG8_SB(0, 1), b2 + hstep, voffB); PG8_STAGE(PG8_SA(0, 0), a2, voffA);
;             PG8_WAIT_V(8); PG8_WAIT_L(0); PG8_BAR; PG8_MMA(1, 0, At, B0); PG8_MMA(1, 1, At, B1); PG8_BAR; PG8_SCHED;
;             PG8_LDB(B0, 1, 0); PG8_LDB(B1, 1, 1); PG8_SCHED; PG8_LDA(At, 1, 0); PG8_STAGE(PG8_SA(0, 1), a2 + hstep, voffA);
;             PG8_WAIT_V(8); PG8_WAIT_L(0); PG8_BAR; PG8_MMA(0, 0, At, B0); PG8_MMA(0, 1, At, B1); PG8_BAR; PG8_SCHED;
;             PG8_LDA(At, 1, 1); PG8_STAGE(PG8_SB(1, 0), b3, voffB); PG8_STAGE(PG8_SB(1, 1), b3 + hstep, voffB); PG8_STAGE(PG8_SA(1, 0), a3, voffA);
;             PG8_WAIT_V(8); PG8_WAIT_L(0); PG8_BAR; PG8_MMA(1, 0, At, B0); PG8_MMA(1, 1, At, B1); PG8_BAR; PG8_SCHED;
	s_add_i32 s44, s70, s52
	s_mov_b32 m0, s44
	ds_read_b128 v[186:189], v152 offset:49152
	ds_read_b128 v[190:193], v152 offset:50176
	ds_read_b128 v[198:201], v152 offset:51200
	ds_read_b128 v[202:205], v152 offset:52224
	ds_read_b128 v[206:209], v152 offset:53248
	ds_read_b128 v[210:213], v152 offset:54272
	ds_read_b128 v[214:217], v152 offset:55296
	ds_read_b128 v[218:221], v152 offset:56320
	global_load_lds_dwordx4 v132, s[98:99]
	s_add_i32 m0, s44, 0x2000
	s_add_u32 s38, s38, 0x40080
	s_addc_u32 s39, s39, 0
	s_add_i32 s44, s71, s52
	global_load_lds_dwordx4 v128, s[98:99]
	s_mov_b32 m0, s44
	s_nop 0
	global_load_lds_dwordx4 v132, s[38:39]
	s_add_i32 m0, s44, 0x2000
	s_nop 0
	global_load_lds_dwordx4 v128, s[38:39]
	s_mov_b32 m0, s58
	s_nop 0
	global_load_lds_dwordx4 v134, s[100:101]
	s_mov_b32 m0, s59
	s_nop 0
	global_load_lds_dwordx4 v130, s[100:101]
	s_waitcnt vmcnt(8)
	s_waitcnt lgkmcnt(0)
	s_barrier
	s_setprio 1
	s_waitcnt lgkmcnt(0)
	v_mfma_f32_16x16x32_bf16 v[60:63], v[154:157], v[186:189], v[60:63]
	v_mfma_f32_16x16x32_bf16 v[52:55], v[162:165], v[186:189], v[52:55]
	v_mfma_f32_16x16x32_bf16 v[44:47], v[154:157], v[198:201], v[44:47]
	v_mfma_f32_16x16x32_bf16 v[36:39], v[162:165], v[198:201], v[36:39]
	v_mfma_f32_16x16x32_bf16 v[28:31], v[154:157], v[206:209], v[28:31]
	v_mfma_f32_16x16x32_bf16 v[20:23], v[162:165], v[206:209], v[20:23]
	v_mfma_f32_16x16x32_bf16 v[12:15], v[154:157], v[214:217], v[12:15]
	v_mfma_f32_16x16x32_bf16 v[4:7], v[162:165], v[214:217], v[4:7]
	v_mfma_f32_16x16x32_bf16 v[60:63], v[158:161], v[190:193], v[60:63]
	v_mfma_f32_16x16x32_bf16 v[52:55], v[166:169], v[190:193], v[52:55]
	v_mfma_f32_16x16x32_bf16 v[44:47], v[158:161], v[202:205], v[44:47]
	v_mfma_f32_16x16x32_bf16 v[36:39], v[166:169], v[202:205], v[36:39]
	v_mfma_f32_16x16x32_bf16 v[28:31], v[158:161], v[210:213], v[28:31]
	v_mfma_f32_16x16x32_bf16 v[20:23], v[166:169], v[210:213], v[20:23]
	v_mfma_f32_16x16x32_bf16 v[12:15], v[158:161], v[218:221], v[12:15]
	v_mfma_f32_16x16x32_bf16 v[4:7], v[166:169], v[218:221], v[4:7]
	v_mfma_f32_16x16x32_bf16 v[56:59], v[170:173], v[186:189], v[56:59]
	v_mfma_f32_16x16x32_bf16 v[48:51], v[178:181], v[186:189], v[48:51]
	v_mfma_f32_16x16x32_bf16 v[40:43], v[170:173], v[198:201], v[40:43]
	v_mfma_f32_16x16x32_bf16 v[32:35], v[178:181], v[198:201], v[32:35]
	v_mfma_f32_16x16x32_bf16 v[24:27], v[170:173], v[206:209], v[24:27]
	v_mfma_f32_16x16x32_bf16 v[16:19], v[178:181], v[206:209], v[16:19]
	v_mfma_f32_16x16x32_bf16 v[8:11], v[170:173], v[214:217], v[8:11]
	v_mfma_f32_16x16x32_bf16 v[0:3], v[178:181], v[214:217], v[0:3]
	v_mfma_f32_16x16x32_bf16 v[56:59], v[174:177], v[190:193], v[56:59]
	v_mfma_f32_16x16x32_bf16 v[48:51], v[182:185], v[190:193], v[48:51]
	v_mfma_f32_16x16x32_bf16 v[40:43], v[174:177], v[202:205], v[40:43]
	v_mfma_f32_16x16x32_bf16 v[32:35], v[182:185], v[202:205], v[32:35]
	v_mfma_f32_16x16x32_bf16 v[24:27], v[174:177], v[210:213], v[24:27]
	v_mfma_f32_16x16x32_bf16 v[16:19], v[182:185], v[210:213], v[16:19]
	v_mfma_f32_16x16x32_bf16 v[8:11], v[174:177], v[218:221], v[8:11]
	v_mfma_f32_16x16x32_bf16 v[0:3], v[182:185], v[218:221], v[0:3]
	s_setprio 0
	s_barrier
	s_add_i32 s69, s69, 2
	s_add_u32 s20, s20, 0x100
	s_addc_u32 s21, s21, 0
	s_add_u32 s67, s67, 0x100
	s_addc_u32 s68, s68, 0
	s_cmp_gt_u32 s69, 13
.LBB0_810:
	ds_read_b128 v[154:157], v150
	ds_read_b128 v[158:161], v150 offset:1024
	ds_read_b128 v[162:165], v150 offset:2048
	ds_read_b128 v[166:169], v150 offset:3072
	ds_read_b128 v[170:173], v151
	ds_read_b128 v[174:177], v151 offset:1024
	ds_read_b128 v[178:181], v151 offset:2048
	ds_read_b128 v[182:185], v151 offset:3072
	s_add_u32 s38, s20, 0xfffc0080
	s_addc_u32 s39, s21, -1
	s_cmp_eq_u32 s69, 12
	s_cselect_b32 s45, s15, s39
	s_cselect_b32 s44, s65, s38
	s_cselect_b32 s39, s13, s68
	s_cselect_b32 s38, s66, s67
	s_add_i32 m0, s35, 0xc000
	ds_read_b128 v[186:189], v152
	ds_read_b128 v[190:193], v152 offset:1024
	ds_read_b128 v[198:201], v152 offset:2048
	ds_read_b128 v[202:205], v152 offset:3072
	ds_read_b128 v[206:209], v152 offset:4096
	ds_read_b128 v[210:213], v152 offset:5120
	ds_read_b128 v[214:217], v152 offset:6144
	ds_read_b128 v[218:221], v152 offset:7168
	global_load_lds_dwordx4 v136, s[20:21]
	s_add_i32 m0, s35, 0xe000
	s_nop 0
	global_load_lds_dwordx4 v138, s[20:21]
	s_waitcnt vmcnt(8)
	s_waitcnt lgkmcnt(0)
	s_barrier
	s_setprio 1
	s_waitcnt lgkmcnt(0)
	v_mfma_f32_16x16x32_bf16 v[124:127], v[154:157], v[186:189], v[124:127]
	v_mfma_f32_16x16x32_bf16 v[116:119], v[162:165], v[186:189], v[116:119]
	v_mfma_f32_16x16x32_bf16 v[108:111], v[154:157], v[198:201], v[108:111]
	v_mfma_f32_16x16x32_bf16 v[100:103], v[162:165], v[198:201], v[100:103]
	v_mfma_f32_16x16x32_bf16 v[92:95], v[154:157], v[206:209], v[92:95]
	v_mfma_f32_16x16x32_bf16 v[84:87], v[162:165], v[206:209], v[84:87]
	v_mfma_f32_16x16x32_bf16 v[76:79], v[154:157], v[214:217], v[76:79]
	v_mfma_f32_16x16x32_bf16 v[68:71], v[162:165], v[214:217], v[68:71]
	v_mfma_f32_16x16x32_bf16 v[124:127], v[158:161], v[190:193], v[124:127]
	v_mfma_f32_16x16x32_bf16 v[116:119], v[166:169], v[190:193], v[116:119]
	v_mfma_f32_16x16x32_bf16 v[108:111], v[158:161], v[202:205], v[108:111]
	v_mfma_f32_16x16x32_bf16 v[100:103], v[166:169], v[202:205], v[100:103]
	v_mfma_f32_16x16x32_bf16 v[92:95], v[158:161], v[210:213], v[92:95]
	v_mfma_f32_16x16x32_bf16 v[84:87], v[166:169], v[210:213], v[84:87]
	v_mfma_f32_16x16x32_bf16 v[76:79], v[158:161], v[218:221], v[76:79]
	v_mfma_f32_16x16x32_bf16 v[68:71], v[166:169], v[218:221], v[68:71]
	v_mfma_f32_16x16x32_bf16 v[120:123], v[170:173], v[186:189], v[120:123]
	v_mfma_f32_16x16x32_bf16 v[112:115], v[178:181], v[186:189], v[112:115]
	v_mfma_f32_16x16x32_bf16 v[104:107], v[170:173], v[198:201], v[104:107]
	v_mfma_f32_16x16x32_bf16 v[96:99], v[178:181], v[198:201], v[96:99]
	v_mfma_f32_16x16x32_bf16 v[88:91], v[170:173], v[206:209], v[88:91]
	v_mfma_f32_16x16x32_bf16 v[80:83], v[178:181], v[206:209], v[80:83]
	v_mfma_f32_16x16x32_bf16 v[72:75], v[170:173], v[214:217], v[72:75]
	v_mfma_f32_16x16x32_bf16 v[64:67], v[178:181], v[214:217], v[64:67]
	v_mfma_f32_16x16x32_bf16 v[120:123], v[174:177], v[190:193], v[120:123]
	v_mfma_f32_16x16x32_bf16 v[112:115], v[182:185], v[190:193], v[112:115]
	v_mfma_f32_16x16x32_bf16 v[104:107], v[174:177], v[202:205], v[104:107]
	v_mfma_f32_16x16x32_bf16 v[96:99], v[182:185], v[202:205], v[96:99]
	v_mfma_f32_16x16x32_bf16 v[88:91], v[174:177], v[210:213], v[88:91]
	v_mfma_f32_16x16x32_bf16 v[80:83], v[182:185], v[210:213], v[80:83]
	v_mfma_f32_16x16x32_bf16 v[72:75], v[174:177], v[218:221], v[72:75]
	v_mfma_f32_16x16x32_bf16 v[64:67], v[182:185], v[218:221], v[64:67]
	s_setprio 0
	s_barrier
; #define PG8_STAGE(bufoff, gbase, voff) do { _Pragma("unroll") for (int _i = 0; _i < 2; ++_i) \
;         __builtin_amdgcn_global_load_lds((const unsigned*)((const char*)(gbase) + (voff)[_i]), (PG8_LAS unsigned*)(lds + (bufoff) + ldsw + _i * 8192), 16, 0, 0); } while (0)
; #define PG8_LDA(dst, b, h) do { _Pragma("unroll") for (int m = 0; m < 4; ++m) _Pragma("unroll") for (int k = 0; k < 2; ++k) dst[m][k] = *(const PG8_LAS bf16x8*)(lds + PG8_SA(b, h) + aoff + m * 2048 + k * 1024); } while (0)
; #define PG8_LDB(dst, b, h) do { _Pragma("unroll") for (int n = 0; n < 2; ++n) _Pragma("unroll") for (int k = 0; k < 2; ++k) dst[n][k] = *(const PG8_LAS bf16x8*)(lds + PG8_SB(b, h) + boff + n * 2048 + k * 1024); } while (0)
; #define PG8_MMA(ai, bj, At, Bt) do { __builtin_amdgcn_s_setprio(1); _Pragma("unroll") for (int m = 0; m < 4; ++m) _Pragma("unroll") for (int n = 0; n < 2; ++n) _Pragma("unroll") for (int k = 0; k < 2; ++k) \
;         acc[ai][bj][m][n] = __builtin_amdgcn_mfma_f32_16x16x32_bf16(Bt[n][k], At[m][k], acc[ai][bj][m][n], 0, 0, 0); __builtin_amdgcn_s_setprio(0); } while (0)
; #define PG8_WAIT_V(n) asm volatile("s_waitcnt vmcnt(" #n ")" ::: "memory")
; #define PG8_WAIT_L(n) asm volatile("s_waitcnt lgkmcnt(" #n ")" ::: "memory")
; #define PG8_BAR __builtin_amdgcn_s_barrier()
; #define PG8_SCHED __builtin_amdgcn_sched_barrier(0)
; template <class Epi, class Sched, bool ALIGN_EPI = false, bool SP2 = false>
; __device__ __forceinline__ void gemm_phase(PG8_LAS unsigned char* lds, const Gemm g, const Sched& S, const Epi& E) {
;     ...
;             PG8_LDA(At, 0, 1); PG8_STAGE(PG8_SB(0, 0), b2, voffB); PG8_STAGE(PG8_SB(0, 1), b2 + hstep, voffB); PG8_STAGE(PG8_SA(0, 0), a2, voffA);
;             PG8_WAIT_V(8); PG8_WAIT_L(0); PG8_BAR; PG8_MMA(1, 0, At, B0); PG8_MMA(1, 1, At, B1); PG8_BAR; PG8_SCHED;
;             PG8_LDB(B0, 1, 0); PG8_LDB(B1, 1, 1); PG8_SCHED; PG8_LDA(At, 1, 0); PG8_STAGE(PG8_SA(0, 1), a2 + hstep, voffA);
	s_add_i32 s70, s60, s52
	s_add_u32 s98, s38, s8
	s_addc_u32 s99, s39, s9
	s_add_u32 s100, s44, s8
	s_addc_u32 s101, s45, s9
	s_mov_b32 m0, s70
	ds_read_b128 v[186:189], v152 offset:16384
	ds_read_b128 v[190:193], v152 offset:17408
	ds_read_b128 v[198:201], v152 offset:18432
	ds_read_b128 v[202:205], v152 offset:19456
	ds_read_b128 v[206:209], v152 offset:20480
	ds_read_b128 v[210:213], v152 offset:21504
	ds_read_b128 v[214:217], v152 offset:22528
	ds_read_b128 v[218:221], v152 offset:23552
	global_load_lds_dwordx4 v132, s[38:39]
	s_add_i32 m0, s70, 0x2000
	s_add_u32 s70, s38, 0x40000
	s_addc_u32 s71, s39, 0
	s_add_i32 s72, s61, s52
	global_load_lds_dwordx4 v128, s[38:39]
	s_mov_b32 m0, s72
	s_nop 0
	global_load_lds_dwordx4 v132, s[70:71]
	s_add_i32 m0, s72, 0x2000
	s_nop 0
	global_load_lds_dwordx4 v128, s[70:71]
	s_mov_b32 m0, s35
	s_nop 0
	global_load_lds_dwordx4 v134, s[44:45]
	s_mov_b32 m0, s54
	s_nop 0
	global_load_lds_dwordx4 v130, s[44:45]
	s_waitcnt vmcnt(8)
	s_waitcnt lgkmcnt(0)
	s_barrier
	s_setprio 1
	s_waitcnt lgkmcnt(0)
	v_mfma_f32_16x16x32_bf16 v[60:63], v[154:157], v[186:189], v[60:63]
	v_mfma_f32_16x16x32_bf16 v[52:55], v[162:165], v[186:189], v[52:55]
	v_mfma_f32_16x16x32_bf16 v[44:47], v[154:157], v[198:201], v[44:47]
	v_mfma_f32_16x16x32_bf16 v[36:39], v[162:165], v[198:201], v[36:39]
	v_mfma_f32_16x16x32_bf16 v[28:31], v[154:157], v[206:209], v[28:31]
	v_mfma_f32_16x16x32_bf16 v[20:23], v[162:165], v[206:209], v[20:23]
	v_mfma_f32_16x16x32_bf16 v[12:15], v[154:157], v[214:217], v[12:15]
	v_mfma_f32_16x16x32_bf16 v[4:7], v[162:165], v[214:217], v[4:7]
	v_mfma_f32_16x16x32_bf16 v[60:63], v[158:161], v[190:193], v[60:63]
	v_mfma_f32_16x16x32_bf16 v[52:55], v[166:169], v[190:193], v[52:55]
	v_mfma_f32_16x16x32_bf16 v[44:47], v[158:161], v[202:205], v[44:47]
	v_mfma_f32_16x16x32_bf16 v[36:39], v[166:169], v[202:205], v[36:39]
	v_mfma_f32_16x16x32_bf16 v[28:31], v[158:161], v[210:213], v[28:31]
	v_mfma_f32_16x16x32_bf16 v[20:23], v[166:169], v[210:213], v[20:23]
	v_mfma_f32_16x16x32_bf16 v[12:15], v[158:161], v[218:221], v[12:15]
	v_mfma_f32_16x16x32_bf16 v[4:7], v[166:169], v[218:221], v[4:7]
	v_mfma_f32_16x16x32_bf16 v[56:59], v[170:173], v[186:189], v[56:59]
	v_mfma_f32_16x16x32_bf16 v[48:51], v[178:181], v[186:189], v[48:51]
	v_mfma_f32_16x16x32_bf16 v[40:43], v[170:173], v[198:201], v[40:43]
	v_mfma_f32_16x16x32_bf16 v[32:35], v[178:181], v[198:201], v[32:35]
	v_mfma_f32_16x16x32_bf16 v[24:27], v[170:173], v[206:209], v[24:27]
	v_mfma_f32_16x16x32_bf16 v[16:19], v[178:181], v[206:209], v[16:19]
	v_mfma_f32_16x16x32_bf16 v[8:11], v[170:173], v[214:217], v[8:11]
	v_mfma_f32_16x16x32_bf16 v[0:3], v[178:181], v[214:217], v[0:3]
	v_mfma_f32_16x16x32_bf16 v[56:59], v[174:177], v[190:193], v[56:59]
	v_mfma_f32_16x16x32_bf16 v[48:51], v[182:185], v[190:193], v[48:51]
	v_mfma_f32_16x16x32_bf16 v[40:43], v[174:177], v[202:205], v[40:43]
	v_mfma_f32_16x16x32_bf16 v[32:35], v[182:185], v[202:205], v[32:35]
	v_mfma_f32_16x16x32_bf16 v[24:27], v[174:177], v[210:213], v[24:27]
	v_mfma_f32_16x16x32_bf16 v[16:19], v[182:185], v[210:213], v[16:19]
	v_mfma_f32_16x16x32_bf16 v[8:11], v[174:177], v[218:221], v[8:11]
	v_mfma_f32_16x16x32_bf16 v[0:3], v[182:185], v[218:221], v[0:3]
	s_setprio 0
	s_barrier
	s_add_i32 s70, 0, 0x18000
	v_add_u32_e32 v153, s70, v147
	s_add_i32 s71, 0, 0x1c000
	ds_read_b128 v[154:157], v153
	ds_read_b128 v[158:161], v153 offset:1024
	ds_read_b128 v[162:165], v153 offset:2048
	ds_read_b128 v[166:169], v153 offset:3072
	v_add_u32_e32 v153, s71, v147
	ds_read_b128 v[170:173], v153
	ds_read_b128 v[174:177], v153 offset:1024
	ds_read_b128 v[178:181], v153 offset:2048
	ds_read_b128 v[182:185], v153 offset:3072
	s_add_u32 s44, s44, 0x40000
	s_addc_u32 s45, s45, 0
	s_mov_b32 m0, s55
	ds_read_b128 v[186:189], v152 offset:32768
	ds_read_b128 v[190:193], v152 offset:33792
	ds_read_b128 v[198:201], v152 offset:34816
	ds_read_b128 v[202:205], v152 offset:35840
	ds_read_b128 v[206:209], v152 offset:36864
	ds_read_b128 v[210:213], v152 offset:37888
	ds_read_b128 v[214:217], v152 offset:38912
	ds_read_b128 v[218:221], v152 offset:39936
	global_load_lds_dwordx4 v134, s[44:45]
	s_mov_b32 m0, s56
	s_nop 0
	global_load_lds_dwordx4 v130, s[44:45]
	s_waitcnt vmcnt(8)
	s_waitcnt lgkmcnt(0)
	s_barrier
; #define PG8_STAGE(bufoff, gbase, voff) do { _Pragma("unroll") for (int _i = 0; _i < 2; ++_i) \
;         __builtin_amdgcn_global_load_lds((const unsigned*)((const char*)(gbase) + (voff)[_i]), (PG8_LAS unsigned*)(lds + (bufoff) + ldsw + _i * 8192), 16, 0, 0); } while (0)
; #define PG8_LDA(dst, b, h) do { _Pragma("unroll") for (int m = 0; m < 4; ++m) _Pragma("unroll") for (int k = 0; k < 2; ++k) dst[m][k] = *(const PG8_LAS bf16x8*)(lds + PG8_SA(b, h) + aoff + m * 2048 + k * 1024); } while (0)
; #define PG8_MMA(ai, bj, At, Bt) do { __builtin_amdgcn_s_setprio(1); _Pragma("unroll") for (int m = 0; m < 4; ++m) _Pragma("unroll") for (int n = 0; n < 2; ++n) _Pragma("unroll") for (int k = 0; k < 2; ++k) \
;         acc[ai][bj][m][n] = __builtin_amdgcn_mfma_f32_16x16x32_bf16(Bt[n][k], At[m][k], acc[ai][bj][m][n], 0, 0, 0); __builtin_amdgcn_s_setprio(0); } while (0)
; #define PG8_WAIT_V(n) asm volatile("s_waitcnt vmcnt(" #n ")" ::: "memory")
; #define PG8_WAIT_L(n) asm volatile("s_waitcnt lgkmcnt(" #n ")" ::: "memory")
; #define PG8_BAR __builtin_amdgcn_s_barrier()
; #define PG8_SCHED __builtin_amdgcn_sched_barrier(0)
; template <class Epi, class Sched, bool ALIGN_EPI = false, bool SP2 = false>
; __device__ __forceinline__ void gemm_phase(PG8_LAS unsigned char* lds, const Gemm g, const Sched& S, const Epi& E) {
;     ...
;             PG8_WAIT_V(8); PG8_WAIT_L(0); PG8_BAR; PG8_MMA(0, 0, At, B0); PG8_MMA(0, 1, At, B1); PG8_BAR; PG8_SCHED;
;             PG8_LDA(At, 1, 1); PG8_STAGE(PG8_SB(1, 0), b3, voffB); PG8_STAGE(PG8_SB(1, 1), b3 + hstep, voffB); PG8_STAGE(PG8_SA(1, 0), a3, voffA);
;             PG8_WAIT_V(8); PG8_WAIT_L(0); PG8_BAR; PG8_MMA(1, 0, At, B0); PG8_MMA(1, 1, At, B1); PG8_BAR; PG8_SCHED;
;     ...
;         if constexpr (ALIGN_EPI) { if (wr == 0) PG8_BAR; }
	s_setprio 1
	s_waitcnt lgkmcnt(0)
	v_mfma_f32_16x16x32_bf16 v[124:127], v[154:157], v[186:189], v[124:127]
	v_mfma_f32_16x16x32_bf16 v[116:119], v[162:165], v[186:189], v[116:119]
	v_mfma_f32_16x16x32_bf16 v[108:111], v[154:157], v[198:201], v[108:111]
	v_mfma_f32_16x16x32_bf16 v[100:103], v[162:165], v[198:201], v[100:103]
	v_mfma_f32_16x16x32_bf16 v[92:95], v[154:157], v[206:209], v[92:95]
	v_mfma_f32_16x16x32_bf16 v[84:87], v[162:165], v[206:209], v[84:87]
	v_mfma_f32_16x16x32_bf16 v[76:79], v[154:157], v[214:217], v[76:79]
	v_mfma_f32_16x16x32_bf16 v[68:71], v[162:165], v[214:217], v[68:71]
	v_mfma_f32_16x16x32_bf16 v[124:127], v[158:161], v[190:193], v[124:127]
	v_mfma_f32_16x16x32_bf16 v[116:119], v[166:169], v[190:193], v[116:119]
	v_mfma_f32_16x16x32_bf16 v[108:111], v[158:161], v[202:205], v[108:111]
	v_mfma_f32_16x16x32_bf16 v[100:103], v[166:169], v[202:205], v[100:103]
	v_mfma_f32_16x16x32_bf16 v[92:95], v[158:161], v[210:213], v[92:95]
	v_mfma_f32_16x16x32_bf16 v[84:87], v[166:169], v[210:213], v[84:87]
	v_mfma_f32_16x16x32_bf16 v[76:79], v[158:161], v[218:221], v[76:79]
	v_mfma_f32_16x16x32_bf16 v[68:71], v[166:169], v[218:221], v[68:71]
	v_mfma_f32_16x16x32_bf16 v[120:123], v[170:173], v[186:189], v[120:123]
	v_mfma_f32_16x16x32_bf16 v[112:115], v[178:181], v[186:189], v[112:115]
	v_mfma_f32_16x16x32_bf16 v[104:107], v[170:173], v[198:201], v[104:107]
	v_mfma_f32_16x16x32_bf16 v[96:99], v[178:181], v[198:201], v[96:99]
	v_mfma_f32_16x16x32_bf16 v[88:91], v[170:173], v[206:209], v[88:91]
	v_mfma_f32_16x16x32_bf16 v[80:83], v[178:181], v[206:209], v[80:83]
	v_mfma_f32_16x16x32_bf16 v[72:75], v[170:173], v[214:217], v[72:75]
	v_mfma_f32_16x16x32_bf16 v[64:67], v[178:181], v[214:217], v[64:67]
	v_mfma_f32_16x16x32_bf16 v[120:123], v[174:177], v[190:193], v[120:123]
	v_mfma_f32_16x16x32_bf16 v[112:115], v[182:185], v[190:193], v[112:115]
	v_mfma_f32_16x16x32_bf16 v[104:107], v[174:177], v[202:205], v[104:107]
	v_mfma_f32_16x16x32_bf16 v[96:99], v[182:185], v[202:205], v[96:99]
	v_mfma_f32_16x16x32_bf16 v[88:91], v[174:177], v[210:213], v[88:91]
	v_mfma_f32_16x16x32_bf16 v[80:83], v[182:185], v[210:213], v[80:83]
	v_mfma_f32_16x16x32_bf16 v[72:75], v[174:177], v[218:221], v[72:75]
	v_mfma_f32_16x16x32_bf16 v[64:67], v[182:185], v[218:221], v[64:67]
	s_setprio 0
	s_barrier
	s_add_i32 s44, s70, s52
	s_mov_b32 m0, s44
	ds_read_b128 v[186:189], v152 offset:49152
	ds_read_b128 v[190:193], v152 offset:50176
	ds_read_b128 v[198:201], v152 offset:51200
	ds_read_b128 v[202:205], v152 offset:52224
	ds_read_b128 v[206:209], v152 offset:53248
	ds_read_b128 v[210:213], v152 offset:54272
	ds_read_b128 v[214:217], v152 offset:55296
	ds_read_b128 v[218:221], v152 offset:56320
	global_load_lds_dwordx4 v132, s[98:99]
	s_add_i32 m0, s44, 0x2000
	s_add_u32 s38, s38, 0x40080
	s_addc_u32 s39, s39, 0
	s_add_i32 s44, s71, s52
	global_load_lds_dwordx4 v128, s[98:99]
	s_mov_b32 m0, s44
	s_nop 0
	global_load_lds_dwordx4 v132, s[38:39]
	s_add_i32 m0, s44, 0x2000
	s_nop 0
	global_load_lds_dwordx4 v128, s[38:39]
	s_mov_b32 m0, s58
	s_nop 0
	global_load_lds_dwordx4 v134, s[100:101]
	s_mov_b32 m0, s59
	s_nop 0
	global_load_lds_dwordx4 v130, s[100:101]
	s_waitcnt vmcnt(8)
	s_waitcnt lgkmcnt(0)
	s_barrier
	s_setprio 1
	s_waitcnt lgkmcnt(0)
	v_mfma_f32_16x16x32_bf16 v[60:63], v[154:157], v[186:189], v[60:63]
	v_mfma_f32_16x16x32_bf16 v[52:55], v[162:165], v[186:189], v[52:55]
	v_mfma_f32_16x16x32_bf16 v[44:47], v[154:157], v[198:201], v[44:47]
	v_mfma_f32_16x16x32_bf16 v[36:39], v[162:165], v[198:201], v[36:39]
	v_mfma_f32_16x16x32_bf16 v[28:31], v[154:157], v[206:209], v[28:31]
	v_mfma_f32_16x16x32_bf16 v[20:23], v[162:165], v[206:209], v[20:23]
	v_mfma_f32_16x16x32_bf16 v[12:15], v[154:157], v[214:217], v[12:15]
	v_mfma_f32_16x16x32_bf16 v[4:7], v[162:165], v[214:217], v[4:7]
	v_mfma_f32_16x16x32_bf16 v[60:63], v[158:161], v[190:193], v[60:63]
	v_mfma_f32_16x16x32_bf16 v[52:55], v[166:169], v[190:193], v[52:55]
	v_mfma_f32_16x16x32_bf16 v[44:47], v[158:161], v[202:205], v[44:47]
	v_mfma_f32_16x16x32_bf16 v[36:39], v[166:169], v[202:205], v[36:39]
	v_mfma_f32_16x16x32_bf16 v[28:31], v[158:161], v[210:213], v[28:31]
	v_mfma_f32_16x16x32_bf16 v[20:23], v[166:169], v[210:213], v[20:23]
	v_mfma_f32_16x16x32_bf16 v[12:15], v[158:161], v[218:221], v[12:15]
	v_mfma_f32_16x16x32_bf16 v[4:7], v[166:169], v[218:221], v[4:7]
	v_mfma_f32_16x16x32_bf16 v[56:59], v[170:173], v[186:189], v[56:59]
	v_mfma_f32_16x16x32_bf16 v[48:51], v[178:181], v[186:189], v[48:51]
	v_mfma_f32_16x16x32_bf16 v[40:43], v[170:173], v[198:201], v[40:43]
	v_mfma_f32_16x16x32_bf16 v[32:35], v[178:181], v[198:201], v[32:35]
	v_mfma_f32_16x16x32_bf16 v[24:27], v[170:173], v[206:209], v[24:27]
	v_mfma_f32_16x16x32_bf16 v[16:19], v[178:181], v[206:209], v[16:19]
	v_mfma_f32_16x16x32_bf16 v[8:11], v[170:173], v[214:217], v[8:11]
	v_mfma_f32_16x16x32_bf16 v[0:3], v[178:181], v[214:217], v[0:3]
	v_mfma_f32_16x16x32_bf16 v[56:59], v[174:177], v[190:193], v[56:59]
	v_mfma_f32_16x16x32_bf16 v[48:51], v[182:185], v[190:193], v[48:51]
	v_mfma_f32_16x16x32_bf16 v[40:43], v[174:177], v[202:205], v[40:43]
	v_mfma_f32_16x16x32_bf16 v[32:35], v[182:185], v[202:205], v[32:35]
	v_mfma_f32_16x16x32_bf16 v[24:27], v[174:177], v[210:213], v[24:27]
	v_mfma_f32_16x16x32_bf16 v[16:19], v[182:185], v[210:213], v[16:19]
	v_mfma_f32_16x16x32_bf16 v[8:11], v[174:177], v[218:221], v[8:11]
	v_mfma_f32_16x16x32_bf16 v[0:3], v[182:185], v[218:221], v[0:3]
	s_setprio 0
	s_barrier
	s_add_i32 s69, s69, 2
	s_add_u32 s20, s20, 0x100
	s_addc_u32 s21, s21, 0
	s_add_u32 s67, s67, 0x100
	s_addc_u32 s68, s68, 0
	s_cmp_gt_u32 s69, 13
	s_cbranch_scc0 .LBB0_810
	s_and_b64 vcc, exec, s[10:11]
	s_cbranch_vccz .LBB0_813
	s_barrier

; #define PG8_STAGE(bufoff, gbase, voff) do { _Pragma("unroll") for (int _i = 0; _i < 2; ++_i) \
;         __builtin_amdgcn_global_load_lds((const unsigned*)((const char*)(gbase) + (voff)[_i]), (PG8_LAS unsigned*)(lds + (bufoff) + ldsw + _i * 8192), 16, 0, 0); } while (0)
; #define PG8_LDA(dst, b, h) do { _Pragma("unroll") for (int m = 0; m < 4; ++m) _Pragma("unroll") for (int k = 0; k < 2; ++k) dst[m][k] = *(const PG8_LAS bf16x8*)(lds + PG8_SA(b, h) + aoff + m * 2048 + k * 1024); } while (0)
; #define PG8_LDB(dst, b, h) do { _Pragma("unroll") for (int n = 0; n < 2; ++n) _Pragma("unroll") for (int k = 0; k < 2; ++k) dst[n][k] = *(const PG8_LAS bf16x8*)(lds + PG8_SB(b, h) + boff + n * 2048 + k * 1024); } while (0)
; #define PG8_MMA(ai, bj, At, Bt) do { __builtin_amdgcn_s_setprio(1); _Pragma("unroll") for (int m = 0; m < 4; ++m) _Pragma("unroll") for (int n = 0; n < 2; ++n) _Pragma("unroll") for (int k = 0; k < 2; ++k) \
;         acc[ai][bj][m][n] = __builtin_amdgcn_mfma_f32_16x16x32_bf16(Bt[n][k], At[m][k], acc[ai][bj][m][n], 0, 0, 0); __builtin_amdgcn_s_setprio(0); } while (0)
; #define PG8_WAIT_V(n) asm volatile("s_waitcnt vmcnt(" #n ")" ::: "memory")
; #define PG8_BAR __builtin_amdgcn_s_barrier()
; template <class Epi, class Sched, bool ALIGN_EPI = false, bool SP2 = false>
; __device__ __forceinline__ void gemm_phase(PG8_LAS unsigned char* lds, const Gemm g, const Sched& S, const Epi& E) {
;     ...
;         for (int t = 0; t < nt; t += 2) {
;             const bool last = (t == nt - 2);
;             const char* a1 = cA + (size_t)(t + 1) * kstep;
;             const char* a2 = last ? nA : cA + (size_t)(t + 2) * kstep; const char* b2 = last ? nB : cB + (size_t)(t + 2) * kstep;
;             const char* a3 = a2 + kstep; const char* b3 = b2 + kstep;
;             if (last && has_next) S.a_ready(nxt);
;             if constexpr (SP2) {
;             PG8_LDB(B0, 0, 0); PG8_LDB(B1, 0, 1); PG8_SCHED; PG8_LDA(At, 0, 0); PG8_STAGE(PG8_SA(1, 1), a1 + hstep, voffA);
;             PG8_WAIT_V(8); PG8_WAIT_L(0); PG8_BAR; PG8_MMA(0, 0, At, B0); PG8_MMA(0, 1, At, B1); PG8_BAR; PG8_SCHED;
;             PG8_LDA(At, 0, 1); PG8_STAGE(PG8_SB(0, 0), b2, voffB); PG8_STAGE(PG8_SB(0, 1), b2 + hstep, voffB); PG8_STAGE(PG8_SA(0, 0), a2, voffA);
;             PG8_WAIT_V(8); PG8_WAIT_L(0); PG8_BAR; PG8_MMA(1, 0, At, B0); PG8_MMA(1, 1, At, B1); PG8_BAR; PG8_SCHED;
.LBB0_894:
	s_add_u32 s20, s20, 0xb0080
	s_addc_u32 s21, s21, 0
	s_add_u32 s70, s34, 0x100
	s_addc_u32 s71, s35, 0
	s_mov_b32 s72, -2
	s_waitcnt lgkmcnt(0)
	ds_read_b128 v[96:99], v223
	ds_read_b128 v[108:111], v223 offset:1024
	ds_read_b128 v[120:123], v223 offset:2048
	ds_read_b128 v[128:131], v223 offset:3072
	ds_read_b128 v[144:147], v224
	ds_read_b128 v[148:151], v224 offset:1024
	ds_read_b128 v[152:155], v224 offset:2048
	ds_read_b128 v[156:159], v224 offset:3072
	s_add_u32 s34, s20, 0xfff50080
	s_addc_u32 s35, s21, -1
	s_cmp_eq_u32 s72, 40
	s_cselect_b32 s49, s1, s35
	s_cselect_b32 s48, s0, s34
	s_cselect_b32 s35, s47, s71
	s_cselect_b32 s34, s46, s70
	s_add_i32 m0, s51, 0xc000
	ds_read_b128 v[160:163], v225
	ds_read_b128 v[164:167], v225 offset:1024
	ds_read_b128 v[168:171], v225 offset:2048
	ds_read_b128 v[172:175], v225 offset:3072
	ds_read_b128 v[176:179], v225 offset:4096
	ds_read_b128 v[180:183], v225 offset:5120
	ds_read_b128 v[202:205], v225 offset:6144
	ds_read_b128 v[206:209], v225 offset:7168
	global_load_lds_dwordx4 v192, s[20:21]
	s_add_i32 m0, s51, 0xe000
	s_nop 0
	global_load_lds_dwordx4 v194, s[20:21]
	s_waitcnt vmcnt(8)
	s_waitcnt lgkmcnt(0)
	s_barrier
	s_setprio 1
	s_waitcnt lgkmcnt(0)
	v_mfma_f32_16x16x32_bf16 v[140:143], v[96:99], v[160:163], 0
	v_mfma_f32_16x16x32_bf16 v[136:139], v[120:123], v[160:163], 0
	v_mfma_f32_16x16x32_bf16 v[116:119], v[96:99], v[168:171], 0
	v_mfma_f32_16x16x32_bf16 v[112:115], v[120:123], v[168:171], 0
	v_mfma_f32_16x16x32_bf16 v[92:95], v[96:99], v[176:179], 0
	v_mfma_f32_16x16x32_bf16 v[88:91], v[120:123], v[176:179], 0
	v_mfma_f32_16x16x32_bf16 v[76:79], v[96:99], v[202:205], 0
	v_mfma_f32_16x16x32_bf16 v[72:75], v[120:123], v[202:205], 0
	v_mfma_f32_16x16x32_bf16 v[140:143], v[108:111], v[164:167], v[140:143]
	v_mfma_f32_16x16x32_bf16 v[136:139], v[128:131], v[164:167], v[136:139]
	v_mfma_f32_16x16x32_bf16 v[116:119], v[108:111], v[172:175], v[116:119]
	v_mfma_f32_16x16x32_bf16 v[112:115], v[128:131], v[172:175], v[112:115]
	v_mfma_f32_16x16x32_bf16 v[92:95], v[108:111], v[180:183], v[92:95]
	v_mfma_f32_16x16x32_bf16 v[88:91], v[128:131], v[180:183], v[88:91]
	v_mfma_f32_16x16x32_bf16 v[76:79], v[108:111], v[206:209], v[76:79]
	v_mfma_f32_16x16x32_bf16 v[72:75], v[128:131], v[206:209], v[72:75]
	v_mfma_f32_16x16x32_bf16 v[132:135], v[144:147], v[160:163], 0
	v_mfma_f32_16x16x32_bf16 v[124:127], v[152:155], v[160:163], 0
	v_mfma_f32_16x16x32_bf16 v[104:107], v[144:147], v[168:171], 0
	v_mfma_f32_16x16x32_bf16 v[100:103], v[152:155], v[168:171], 0
	v_mfma_f32_16x16x32_bf16 v[84:87], v[144:147], v[176:179], 0
	v_mfma_f32_16x16x32_bf16 v[80:83], v[152:155], v[176:179], 0
	v_mfma_f32_16x16x32_bf16 v[68:71], v[144:147], v[202:205], 0
	v_mfma_f32_16x16x32_bf16 v[64:67], v[152:155], v[202:205], 0
	v_mfma_f32_16x16x32_bf16 v[132:135], v[148:151], v[164:167], v[132:135]
	v_mfma_f32_16x16x32_bf16 v[124:127], v[156:159], v[164:167], v[124:127]
	v_mfma_f32_16x16x32_bf16 v[104:107], v[148:151], v[172:175], v[104:107]
	v_mfma_f32_16x16x32_bf16 v[100:103], v[156:159], v[172:175], v[100:103]
	v_mfma_f32_16x16x32_bf16 v[84:87], v[148:151], v[180:183], v[84:87]
	v_mfma_f32_16x16x32_bf16 v[80:83], v[156:159], v[180:183], v[80:83]
	v_mfma_f32_16x16x32_bf16 v[68:71], v[148:151], v[206:209], v[68:71]
	v_mfma_f32_16x16x32_bf16 v[64:67], v[156:159], v[206:209], v[64:67]
	s_setprio 0
	s_barrier
	s_add_i32 s73, s64, s50
	s_add_u32 s98, s34, s12
	s_addc_u32 s99, s35, s13
	s_add_u32 s100, s48, s12
	s_addc_u32 s101, s49, s13
	s_mov_b32 m0, s73
	ds_read_b128 v[160:163], v225 offset:16384
	ds_read_b128 v[164:167], v225 offset:17408
	ds_read_b128 v[168:171], v225 offset:18432
	ds_read_b128 v[172:175], v225 offset:19456
	ds_read_b128 v[176:179], v225 offset:20480
	ds_read_b128 v[180:183], v225 offset:21504
	ds_read_b128 v[202:205], v225 offset:22528
	ds_read_b128 v[206:209], v225 offset:23552
	global_load_lds_dwordx4 v186, s[34:35]
	s_add_i32 m0, s73, 0x2000
	s_add_u32 s74, s34, 0xb0000
	s_addc_u32 s75, s35, 0
	s_add_i32 s73, s65, s50
	global_load_lds_dwordx4 v190, s[34:35]
	s_mov_b32 m0, s73
	s_nop 0
	global_load_lds_dwordx4 v186, s[74:75]
	s_add_i32 m0, s73, 0x2000
	s_nop 0
	global_load_lds_dwordx4 v190, s[74:75]
	s_mov_b32 m0, s51
	s_nop 0
	global_load_lds_dwordx4 v184, s[48:49]
	s_mov_b32 m0, s52
	s_nop 0
	global_load_lds_dwordx4 v188, s[48:49]
	s_waitcnt vmcnt(8)
	s_waitcnt lgkmcnt(0)
	s_barrier
	s_setprio 1
	s_waitcnt lgkmcnt(0)
	v_mfma_f32_16x16x32_bf16 v[60:63], v[96:99], v[160:163], 0
	v_mfma_f32_16x16x32_bf16 v[56:59], v[120:123], v[160:163], 0
	v_mfma_f32_16x16x32_bf16 v[44:47], v[96:99], v[168:171], 0
	v_mfma_f32_16x16x32_bf16 v[40:43], v[120:123], v[168:171], 0
	v_mfma_f32_16x16x32_bf16 v[28:31], v[96:99], v[176:179], 0
	v_mfma_f32_16x16x32_bf16 v[24:27], v[120:123], v[176:179], 0
	v_mfma_f32_16x16x32_bf16 v[12:15], v[96:99], v[202:205], 0
	v_mfma_f32_16x16x32_bf16 v[8:11], v[120:123], v[202:205], 0
	v_mfma_f32_16x16x32_bf16 v[60:63], v[108:111], v[164:167], v[60:63]
	v_mfma_f32_16x16x32_bf16 v[56:59], v[128:131], v[164:167], v[56:59]
	v_mfma_f32_16x16x32_bf16 v[44:47], v[108:111], v[172:175], v[44:47]
	v_mfma_f32_16x16x32_bf16 v[40:43], v[128:131], v[172:175], v[40:43]
	v_mfma_f32_16x16x32_bf16 v[28:31], v[108:111], v[180:183], v[28:31]
	v_mfma_f32_16x16x32_bf16 v[24:27], v[128:131], v[180:183], v[24:27]
	v_mfma_f32_16x16x32_bf16 v[12:15], v[108:111], v[206:209], v[12:15]
	v_mfma_f32_16x16x32_bf16 v[8:11], v[128:131], v[206:209], v[8:11]
	v_mfma_f32_16x16x32_bf16 v[52:55], v[144:147], v[160:163], 0
	v_mfma_f32_16x16x32_bf16 v[48:51], v[152:155], v[160:163], 0
	v_mfma_f32_16x16x32_bf16 v[36:39], v[144:147], v[168:171], 0
	v_mfma_f32_16x16x32_bf16 v[32:35], v[152:155], v[168:171], 0
	v_mfma_f32_16x16x32_bf16 v[20:23], v[144:147], v[176:179], 0
	v_mfma_f32_16x16x32_bf16 v[16:19], v[152:155], v[176:179], 0
	v_mfma_f32_16x16x32_bf16 v[4:7], v[144:147], v[202:205], 0
	v_mfma_f32_16x16x32_bf16 v[0:3], v[152:155], v[202:205], 0
	v_mfma_f32_16x16x32_bf16 v[52:55], v[148:151], v[164:167], v[52:55]
	v_mfma_f32_16x16x32_bf16 v[48:51], v[156:159], v[164:167], v[48:51]
	v_mfma_f32_16x16x32_bf16 v[36:39], v[148:151], v[172:175], v[36:39]
	v_mfma_f32_16x16x32_bf16 v[32:35], v[156:159], v[172:175], v[32:35]
	v_mfma_f32_16x16x32_bf16 v[20:23], v[148:151], v[180:183], v[20:23]
	v_mfma_f32_16x16x32_bf16 v[16:19], v[156:159], v[180:183], v[16:19]
	v_mfma_f32_16x16x32_bf16 v[4:7], v[148:151], v[206:209], v[4:7]
	v_mfma_f32_16x16x32_bf16 v[0:3], v[156:159], v[206:209], v[0:3]
	s_setprio 0
	s_barrier
; #define PG8_STAGE(bufoff, gbase, voff) do { _Pragma("unroll") for (int _i = 0; _i < 2; ++_i) \
;         __builtin_amdgcn_global_load_lds((const unsigned*)((const char*)(gbase) + (voff)[_i]), (PG8_LAS unsigned*)(lds + (bufoff) + ldsw + _i * 8192), 16, 0, 0); } while (0)
; #define PG8_LDA(dst, b, h) do { _Pragma("unroll") for (int m = 0; m < 4; ++m) _Pragma("unroll") for (int k = 0; k < 2; ++k) dst[m][k] = *(const PG8_LAS bf16x8*)(lds + PG8_SA(b, h) + aoff + m * 2048 + k * 1024); } while (0)
; #define PG8_LDB(dst, b, h) do { _Pragma("unroll") for (int n = 0; n < 2; ++n) _Pragma("unroll") for (int k = 0; k < 2; ++k) dst[n][k] = *(const PG8_LAS bf16x8*)(lds + PG8_SB(b, h) + boff + n * 2048 + k * 1024); } while (0)
; #define PG8_MMA(ai, bj, At, Bt) do { __builtin_amdgcn_s_setprio(1); _Pragma("unroll") for (int m = 0; m < 4; ++m) _Pragma("unroll") for (int n = 0; n < 2; ++n) _Pragma("unroll") for (int k = 0; k < 2; ++k) \
;         acc[ai][bj][m][n] = __builtin_amdgcn_mfma_f32_16x16x32_bf16(Bt[n][k], At[m][k], acc[ai][bj][m][n], 0, 0, 0); __builtin_amdgcn_s_setprio(0); } while (0)
; #define PG8_WAIT_V(n) asm volatile("s_waitcnt vmcnt(" #n ")" ::: "memory")
; #define PG8_WAIT_L(n) asm volatile("s_waitcnt lgkmcnt(" #n ")" ::: "memory")
; #define PG8_BAR __builtin_amdgcn_s_barrier()
; #define PG8_SCHED __builtin_amdgcn_sched_barrier(0)
; template <class Epi, class Sched, bool ALIGN_EPI = false, bool SP2 = false>
; __device__ __forceinline__ void gemm_phase(PG8_LAS unsigned char* lds, const Gemm g, const Sched& S, const Epi& E) {
;     ...
;             PG8_LDB(B0, 1, 0); PG8_LDB(B1, 1, 1); PG8_SCHED; PG8_LDA(At, 1, 0); PG8_STAGE(PG8_SA(0, 1), a2 + hstep, voffA);
;             PG8_WAIT_V(8); PG8_WAIT_L(0); PG8_BAR; PG8_MMA(0, 0, At, B0); PG8_MMA(0, 1, At, B1); PG8_BAR; PG8_SCHED;
;             PG8_LDA(At, 1, 1); PG8_STAGE(PG8_SB(1, 0), b3, voffB); PG8_STAGE(PG8_SB(1, 1), b3 + hstep, voffB); PG8_STAGE(PG8_SA(1, 0), a3, voffA);
;             PG8_WAIT_V(8); PG8_WAIT_L(0); PG8_BAR; PG8_MMA(1, 0, At, B0); PG8_MMA(1, 1, At, B1); PG8_BAR; PG8_SCHED;
	s_add_i32 s73, 0, 0x18000
	s_add_i32 s74, 0, 0x1c000
	v_add_u32_e32 v128, s73, v221
	v_add_u32_e32 v156, s74, v221
	ds_read_b128 v[96:99], v128
	ds_read_b128 v[108:111], v128 offset:1024
	ds_read_b128 v[120:123], v128 offset:2048
	ds_read_b128 v[128:131], v128 offset:3072
	ds_read_b128 v[144:147], v156
	ds_read_b128 v[148:151], v156 offset:1024
	ds_read_b128 v[152:155], v156 offset:2048
	ds_read_b128 v[156:159], v156 offset:3072
	s_add_u32 s48, s48, 0xb0000
	s_addc_u32 s49, s49, 0
	s_mov_b32 m0, s53
	ds_read_b128 v[160:163], v225 offset:32768
	ds_read_b128 v[164:167], v225 offset:33792
	ds_read_b128 v[168:171], v225 offset:34816
	ds_read_b128 v[172:175], v225 offset:35840
	ds_read_b128 v[176:179], v225 offset:36864
	ds_read_b128 v[180:183], v225 offset:37888
	ds_read_b128 v[202:205], v225 offset:38912
	ds_read_b128 v[206:209], v225 offset:39936
	global_load_lds_dwordx4 v184, s[48:49]
	s_mov_b32 m0, s54
	s_nop 0
	global_load_lds_dwordx4 v188, s[48:49]
	s_waitcnt vmcnt(8)
	s_waitcnt lgkmcnt(0)
	s_barrier
	s_setprio 1
	s_waitcnt lgkmcnt(0)
	v_mfma_f32_16x16x32_bf16 v[140:143], v[96:99], v[160:163], v[140:143]
	v_mfma_f32_16x16x32_bf16 v[136:139], v[120:123], v[160:163], v[136:139]
	v_mfma_f32_16x16x32_bf16 v[116:119], v[96:99], v[168:171], v[116:119]
	v_mfma_f32_16x16x32_bf16 v[112:115], v[120:123], v[168:171], v[112:115]
	v_mfma_f32_16x16x32_bf16 v[92:95], v[96:99], v[176:179], v[92:95]
	v_mfma_f32_16x16x32_bf16 v[88:91], v[120:123], v[176:179], v[88:91]
	v_mfma_f32_16x16x32_bf16 v[76:79], v[96:99], v[202:205], v[76:79]
	v_mfma_f32_16x16x32_bf16 v[72:75], v[120:123], v[202:205], v[72:75]
	v_mfma_f32_16x16x32_bf16 v[140:143], v[108:111], v[164:167], v[140:143]
	v_mfma_f32_16x16x32_bf16 v[136:139], v[128:131], v[164:167], v[136:139]
	v_mfma_f32_16x16x32_bf16 v[116:119], v[108:111], v[172:175], v[116:119]
	v_mfma_f32_16x16x32_bf16 v[112:115], v[128:131], v[172:175], v[112:115]
	v_mfma_f32_16x16x32_bf16 v[92:95], v[108:111], v[180:183], v[92:95]
	v_mfma_f32_16x16x32_bf16 v[88:91], v[128:131], v[180:183], v[88:91]
	v_mfma_f32_16x16x32_bf16 v[76:79], v[108:111], v[206:209], v[76:79]
	v_mfma_f32_16x16x32_bf16 v[72:75], v[128:131], v[206:209], v[72:75]
	v_mfma_f32_16x16x32_bf16 v[132:135], v[144:147], v[160:163], v[132:135]
	v_mfma_f32_16x16x32_bf16 v[124:127], v[152:155], v[160:163], v[124:127]
	v_mfma_f32_16x16x32_bf16 v[104:107], v[144:147], v[168:171], v[104:107]
	v_mfma_f32_16x16x32_bf16 v[100:103], v[152:155], v[168:171], v[100:103]
	v_mfma_f32_16x16x32_bf16 v[84:87], v[144:147], v[176:179], v[84:87]
	v_mfma_f32_16x16x32_bf16 v[80:83], v[152:155], v[176:179], v[80:83]
	v_mfma_f32_16x16x32_bf16 v[68:71], v[144:147], v[202:205], v[68:71]
	v_mfma_f32_16x16x32_bf16 v[64:67], v[152:155], v[202:205], v[64:67]
	v_mfma_f32_16x16x32_bf16 v[132:135], v[148:151], v[164:167], v[132:135]
	v_mfma_f32_16x16x32_bf16 v[124:127], v[156:159], v[164:167], v[124:127]
	v_mfma_f32_16x16x32_bf16 v[104:107], v[148:151], v[172:175], v[104:107]
	v_mfma_f32_16x16x32_bf16 v[100:103], v[156:159], v[172:175], v[100:103]
	v_mfma_f32_16x16x32_bf16 v[84:87], v[148:151], v[180:183], v[84:87]
	v_mfma_f32_16x16x32_bf16 v[80:83], v[156:159], v[180:183], v[80:83]
	v_mfma_f32_16x16x32_bf16 v[68:71], v[148:151], v[206:209], v[68:71]
	v_mfma_f32_16x16x32_bf16 v[64:67], v[156:159], v[206:209], v[64:67]
	s_setprio 0
	s_barrier
	s_add_i32 s48, s73, s50
	s_mov_b32 m0, s48
	ds_read_b128 v[160:163], v225 offset:49152
	ds_read_b128 v[164:167], v225 offset:50176
	ds_read_b128 v[168:171], v225 offset:51200
	ds_read_b128 v[172:175], v225 offset:52224
	ds_read_b128 v[176:179], v225 offset:53248
	ds_read_b128 v[180:183], v225 offset:54272
	ds_read_b128 v[202:205], v225 offset:55296
	ds_read_b128 v[206:209], v225 offset:56320
	global_load_lds_dwordx4 v186, s[98:99]
	s_add_i32 m0, s48, 0x2000
	s_add_u32 s34, s34, 0xb0080
	s_addc_u32 s35, s35, 0
	s_add_i32 s48, s74, s50
	global_load_lds_dwordx4 v190, s[98:99]
	s_mov_b32 m0, s48
	s_nop 0
	global_load_lds_dwordx4 v186, s[34:35]
	s_add_i32 m0, s48, 0x2000
	s_nop 0
	global_load_lds_dwordx4 v190, s[34:35]
	s_mov_b32 m0, s59
	s_nop 0
	global_load_lds_dwordx4 v184, s[100:101]
	s_mov_b32 m0, s60
	s_nop 0
	global_load_lds_dwordx4 v188, s[100:101]
	s_waitcnt vmcnt(8)
	s_waitcnt lgkmcnt(0)
	s_barrier
	s_setprio 1
	s_waitcnt lgkmcnt(0)
	v_mfma_f32_16x16x32_bf16 v[60:63], v[96:99], v[160:163], v[60:63]
	v_mfma_f32_16x16x32_bf16 v[56:59], v[120:123], v[160:163], v[56:59]
	v_mfma_f32_16x16x32_bf16 v[44:47], v[96:99], v[168:171], v[44:47]
	v_mfma_f32_16x16x32_bf16 v[40:43], v[120:123], v[168:171], v[40:43]
	v_mfma_f32_16x16x32_bf16 v[28:31], v[96:99], v[176:179], v[28:31]
	v_mfma_f32_16x16x32_bf16 v[24:27], v[120:123], v[176:179], v[24:27]
	v_mfma_f32_16x16x32_bf16 v[12:15], v[96:99], v[202:205], v[12:15]
	v_mfma_f32_16x16x32_bf16 v[8:11], v[120:123], v[202:205], v[8:11]
	v_mfma_f32_16x16x32_bf16 v[60:63], v[108:111], v[164:167], v[60:63]
	v_mfma_f32_16x16x32_bf16 v[56:59], v[128:131], v[164:167], v[56:59]
	v_mfma_f32_16x16x32_bf16 v[44:47], v[108:111], v[172:175], v[44:47]
	v_mfma_f32_16x16x32_bf16 v[40:43], v[128:131], v[172:175], v[40:43]
	v_mfma_f32_16x16x32_bf16 v[28:31], v[108:111], v[180:183], v[28:31]
	v_mfma_f32_16x16x32_bf16 v[24:27], v[128:131], v[180:183], v[24:27]
	v_mfma_f32_16x16x32_bf16 v[12:15], v[108:111], v[206:209], v[12:15]
	v_mfma_f32_16x16x32_bf16 v[8:11], v[128:131], v[206:209], v[8:11]
	v_mfma_f32_16x16x32_bf16 v[52:55], v[144:147], v[160:163], v[52:55]
	v_mfma_f32_16x16x32_bf16 v[48:51], v[152:155], v[160:163], v[48:51]
	v_mfma_f32_16x16x32_bf16 v[36:39], v[144:147], v[168:171], v[36:39]
	v_mfma_f32_16x16x32_bf16 v[32:35], v[152:155], v[168:171], v[32:35]
	v_mfma_f32_16x16x32_bf16 v[20:23], v[144:147], v[176:179], v[20:23]
	v_mfma_f32_16x16x32_bf16 v[16:19], v[152:155], v[176:179], v[16:19]
	v_mfma_f32_16x16x32_bf16 v[4:7], v[144:147], v[202:205], v[4:7]
	v_mfma_f32_16x16x32_bf16 v[0:3], v[152:155], v[202:205], v[0:3]
	v_mfma_f32_16x16x32_bf16 v[52:55], v[148:151], v[164:167], v[52:55]
	v_mfma_f32_16x16x32_bf16 v[48:51], v[156:159], v[164:167], v[48:51]
	v_mfma_f32_16x16x32_bf16 v[36:39], v[148:151], v[172:175], v[36:39]
	v_mfma_f32_16x16x32_bf16 v[32:35], v[156:159], v[172:175], v[32:35]
	v_mfma_f32_16x16x32_bf16 v[20:23], v[148:151], v[180:183], v[20:23]
	v_mfma_f32_16x16x32_bf16 v[16:19], v[156:159], v[180:183], v[16:19]
	v_mfma_f32_16x16x32_bf16 v[4:7], v[148:151], v[206:209], v[4:7]
	v_mfma_f32_16x16x32_bf16 v[0:3], v[156:159], v[206:209], v[0:3]
	s_setprio 0
	s_barrier
	s_add_i32 s72, s72, 2
	s_add_u32 s20, s20, 0x100
	s_addc_u32 s21, s21, 0
	s_add_u32 s70, s70, 0x100
	s_addc_u32 s71, s71, 0
	s_cmp_gt_u32 s72, 41
; #define PG8_STAGE(bufoff, gbase, voff) do { _Pragma("unroll") for (int _i = 0; _i < 2; ++_i) \
;         __builtin_amdgcn_global_load_lds((const unsigned*)((const char*)(gbase) + (voff)[_i]), (PG8_LAS unsigned*)(lds + (bufoff) + ldsw + _i * 8192), 16, 0, 0); } while (0)
; #define PG8_LDA(dst, b, h) do { _Pragma("unroll") for (int m = 0; m < 4; ++m) _Pragma("unroll") for (int k = 0; k < 2; ++k) dst[m][k] = *(const PG8_LAS bf16x8*)(lds + PG8_SA(b, h) + aoff + m * 2048 + k * 1024); } while (0)
; #define PG8_LDB(dst, b, h) do { _Pragma("unroll") for (int n = 0; n < 2; ++n) _Pragma("unroll") for (int k = 0; k < 2; ++k) dst[n][k] = *(const PG8_LAS bf16x8*)(lds + PG8_SB(b, h) + boff + n * 2048 + k * 1024); } while (0)
; #define PG8_MMA(ai, bj, At, Bt) do { __builtin_amdgcn_s_setprio(1); _Pragma("unroll") for (int m = 0; m < 4; ++m) _Pragma("unroll") for (int n = 0; n < 2; ++n) _Pragma("unroll") for (int k = 0; k < 2; ++k) \
;         acc[ai][bj][m][n] = __builtin_amdgcn_mfma_f32_16x16x32_bf16(Bt[n][k], At[m][k], acc[ai][bj][m][n], 0, 0, 0); __builtin_amdgcn_s_setprio(0); } while (0)
; #define PG8_WAIT_V(n) asm volatile("s_waitcnt vmcnt(" #n ")" ::: "memory")
; #define PG8_WAIT_L(n) asm volatile("s_waitcnt lgkmcnt(" #n ")" ::: "memory")
; template <class Epi, class Sched, bool ALIGN_EPI = false, bool SP2 = false>
; __device__ __forceinline__ void gemm_phase(PG8_LAS unsigned char* lds, const Gemm g, const Sched& S, const Epi& E) {
;     ...
;             const bool last = (t == nt - 2);
;             const char* a1 = cA + (size_t)(t + 1) * kstep;
;             const char* a2 = last ? nA : cA + (size_t)(t + 2) * kstep; const char* b2 = last ? nB : cB + (size_t)(t + 2) * kstep;
;             const char* a3 = a2 + kstep; const char* b3 = b2 + kstep;
;             if (last && has_next) S.a_ready(nxt);
;             if constexpr (SP2) {
;             PG8_LDB(B0, 0, 0); PG8_LDB(B1, 0, 1); PG8_SCHED; PG8_LDA(At, 0, 0); PG8_STAGE(PG8_SA(1, 1), a1 + hstep, voffA);
;             PG8_WAIT_V(8); PG8_WAIT_L(0); PG8_BAR; PG8_MMA(0, 0, At, B0); PG8_MMA(0, 1, At, B1); PG8_BAR; PG8_SCHED;
;             PG8_LDA(At, 0, 1); PG8_STAGE(PG8_SB(0, 0), b2, voffB); PG8_STAGE(PG8_SB(0, 1), b2 + hstep, voffB); PG8_STAGE(PG8_SA(0, 0), a2, voffA);
;             PG8_WAIT_V(8); PG8_WAIT_L(0); PG8_BAR; PG8_MMA(1, 0, At, B0); PG8_MMA(1, 1, At, B1); PG8_BAR; PG8_SCHED;
.LBB0_895:
	ds_read_b128 v[96:99], v223
	ds_read_b128 v[108:111], v223 offset:1024
	ds_read_b128 v[120:123], v223 offset:2048
	ds_read_b128 v[128:131], v223 offset:3072
	ds_read_b128 v[144:147], v224
	ds_read_b128 v[148:151], v224 offset:1024
	ds_read_b128 v[152:155], v224 offset:2048
	ds_read_b128 v[156:159], v224 offset:3072
	s_add_u32 s34, s20, 0xfff50080
	s_addc_u32 s35, s21, -1
	s_cmp_eq_u32 s72, 40
	s_cselect_b32 s49, s1, s35
	s_cselect_b32 s48, s0, s34
	s_cselect_b32 s35, s47, s71
	s_cselect_b32 s34, s46, s70
	s_add_i32 m0, s51, 0xc000
	ds_read_b128 v[160:163], v225
	ds_read_b128 v[164:167], v225 offset:1024
	ds_read_b128 v[168:171], v225 offset:2048
	ds_read_b128 v[172:175], v225 offset:3072
	ds_read_b128 v[176:179], v225 offset:4096
	ds_read_b128 v[180:183], v225 offset:5120
	ds_read_b128 v[202:205], v225 offset:6144
	ds_read_b128 v[206:209], v225 offset:7168
	global_load_lds_dwordx4 v192, s[20:21]
	s_add_i32 m0, s51, 0xe000
	s_nop 0
	global_load_lds_dwordx4 v194, s[20:21]
	s_waitcnt vmcnt(8)
	s_waitcnt lgkmcnt(0)
	s_barrier
	s_setprio 1
	s_waitcnt lgkmcnt(0)
	v_mfma_f32_16x16x32_bf16 v[140:143], v[96:99], v[160:163], v[140:143]
	v_mfma_f32_16x16x32_bf16 v[136:139], v[120:123], v[160:163], v[136:139]
	v_mfma_f32_16x16x32_bf16 v[116:119], v[96:99], v[168:171], v[116:119]
	v_mfma_f32_16x16x32_bf16 v[112:115], v[120:123], v[168:171], v[112:115]
	v_mfma_f32_16x16x32_bf16 v[92:95], v[96:99], v[176:179], v[92:95]
	v_mfma_f32_16x16x32_bf16 v[88:91], v[120:123], v[176:179], v[88:91]
	v_mfma_f32_16x16x32_bf16 v[76:79], v[96:99], v[202:205], v[76:79]
	v_mfma_f32_16x16x32_bf16 v[72:75], v[120:123], v[202:205], v[72:75]
	v_mfma_f32_16x16x32_bf16 v[140:143], v[108:111], v[164:167], v[140:143]
	v_mfma_f32_16x16x32_bf16 v[136:139], v[128:131], v[164:167], v[136:139]
	v_mfma_f32_16x16x32_bf16 v[116:119], v[108:111], v[172:175], v[116:119]
	v_mfma_f32_16x16x32_bf16 v[112:115], v[128:131], v[172:175], v[112:115]
	v_mfma_f32_16x16x32_bf16 v[92:95], v[108:111], v[180:183], v[92:95]
	v_mfma_f32_16x16x32_bf16 v[88:91], v[128:131], v[180:183], v[88:91]
	v_mfma_f32_16x16x32_bf16 v[76:79], v[108:111], v[206:209], v[76:79]
	v_mfma_f32_16x16x32_bf16 v[72:75], v[128:131], v[206:209], v[72:75]
	v_mfma_f32_16x16x32_bf16 v[132:135], v[144:147], v[160:163], v[132:135]
	v_mfma_f32_16x16x32_bf16 v[124:127], v[152:155], v[160:163], v[124:127]
	v_mfma_f32_16x16x32_bf16 v[104:107], v[144:147], v[168:171], v[104:107]
	v_mfma_f32_16x16x32_bf16 v[100:103], v[152:155], v[168:171], v[100:103]
	v_mfma_f32_16x16x32_bf16 v[84:87], v[144:147], v[176:179], v[84:87]
	v_mfma_f32_16x16x32_bf16 v[80:83], v[152:155], v[176:179], v[80:83]
	v_mfma_f32_16x16x32_bf16 v[68:71], v[144:147], v[202:205], v[68:71]
	v_mfma_f32_16x16x32_bf16 v[64:67], v[152:155], v[202:205], v[64:67]
	v_mfma_f32_16x16x32_bf16 v[132:135], v[148:151], v[164:167], v[132:135]
	v_mfma_f32_16x16x32_bf16 v[124:127], v[156:159], v[164:167], v[124:127]
	v_mfma_f32_16x16x32_bf16 v[104:107], v[148:151], v[172:175], v[104:107]
	v_mfma_f32_16x16x32_bf16 v[100:103], v[156:159], v[172:175], v[100:103]
	v_mfma_f32_16x16x32_bf16 v[84:87], v[148:151], v[180:183], v[84:87]
	v_mfma_f32_16x16x32_bf16 v[80:83], v[156:159], v[180:183], v[80:83]
	v_mfma_f32_16x16x32_bf16 v[68:71], v[148:151], v[206:209], v[68:71]
	v_mfma_f32_16x16x32_bf16 v[64:67], v[156:159], v[206:209], v[64:67]
	s_setprio 0
	s_barrier
	s_add_i32 s73, s64, s50
	s_add_u32 s98, s34, s12
	s_addc_u32 s99, s35, s13
	s_add_u32 s100, s48, s12
	s_addc_u32 s101, s49, s13
	s_mov_b32 m0, s73
	ds_read_b128 v[160:163], v225 offset:16384
	ds_read_b128 v[164:167], v225 offset:17408
	ds_read_b128 v[168:171], v225 offset:18432
	ds_read_b128 v[172:175], v225 offset:19456
	ds_read_b128 v[176:179], v225 offset:20480
	ds_read_b128 v[180:183], v225 offset:21504
	ds_read_b128 v[202:205], v225 offset:22528
	ds_read_b128 v[206:209], v225 offset:23552
	global_load_lds_dwordx4 v186, s[34:35]
	s_add_i32 m0, s73, 0x2000
	s_add_u32 s74, s34, 0xb0000
	s_addc_u32 s75, s35, 0
	s_add_i32 s73, s65, s50
	global_load_lds_dwordx4 v190, s[34:35]
	s_mov_b32 m0, s73
	s_nop 0
	global_load_lds_dwordx4 v186, s[74:75]
	s_add_i32 m0, s73, 0x2000
	s_nop 0
	global_load_lds_dwordx4 v190, s[74:75]
	s_mov_b32 m0, s51
	s_nop 0
	global_load_lds_dwordx4 v184, s[48:49]
	s_mov_b32 m0, s52
	s_nop 0
	global_load_lds_dwordx4 v188, s[48:49]
	s_waitcnt vmcnt(8)
	s_waitcnt lgkmcnt(0)
	s_barrier
	s_setprio 1
	s_waitcnt lgkmcnt(0)
	v_mfma_f32_16x16x32_bf16 v[60:63], v[96:99], v[160:163], v[60:63]
	v_mfma_f32_16x16x32_bf16 v[56:59], v[120:123], v[160:163], v[56:59]
	v_mfma_f32_16x16x32_bf16 v[44:47], v[96:99], v[168:171], v[44:47]
	v_mfma_f32_16x16x32_bf16 v[40:43], v[120:123], v[168:171], v[40:43]
	v_mfma_f32_16x16x32_bf16 v[28:31], v[96:99], v[176:179], v[28:31]
	v_mfma_f32_16x16x32_bf16 v[24:27], v[120:123], v[176:179], v[24:27]
	v_mfma_f32_16x16x32_bf16 v[12:15], v[96:99], v[202:205], v[12:15]
	v_mfma_f32_16x16x32_bf16 v[8:11], v[120:123], v[202:205], v[8:11]
	v_mfma_f32_16x16x32_bf16 v[60:63], v[108:111], v[164:167], v[60:63]
	v_mfma_f32_16x16x32_bf16 v[56:59], v[128:131], v[164:167], v[56:59]
	v_mfma_f32_16x16x32_bf16 v[44:47], v[108:111], v[172:175], v[44:47]
	v_mfma_f32_16x16x32_bf16 v[40:43], v[128:131], v[172:175], v[40:43]
	v_mfma_f32_16x16x32_bf16 v[28:31], v[108:111], v[180:183], v[28:31]
	v_mfma_f32_16x16x32_bf16 v[24:27], v[128:131], v[180:183], v[24:27]
	v_mfma_f32_16x16x32_bf16 v[12:15], v[108:111], v[206:209], v[12:15]
	v_mfma_f32_16x16x32_bf16 v[8:11], v[128:131], v[206:209], v[8:11]
	v_mfma_f32_16x16x32_bf16 v[52:55], v[144:147], v[160:163], v[52:55]
	v_mfma_f32_16x16x32_bf16 v[48:51], v[152:155], v[160:163], v[48:51]
	v_mfma_f32_16x16x32_bf16 v[36:39], v[144:147], v[168:171], v[36:39]
	v_mfma_f32_16x16x32_bf16 v[32:35], v[152:155], v[168:171], v[32:35]
	v_mfma_f32_16x16x32_bf16 v[20:23], v[144:147], v[176:179], v[20:23]
	v_mfma_f32_16x16x32_bf16 v[16:19], v[152:155], v[176:179], v[16:19]
	v_mfma_f32_16x16x32_bf16 v[4:7], v[144:147], v[202:205], v[4:7]
	v_mfma_f32_16x16x32_bf16 v[0:3], v[152:155], v[202:205], v[0:3]
	v_mfma_f32_16x16x32_bf16 v[52:55], v[148:151], v[164:167], v[52:55]
	v_mfma_f32_16x16x32_bf16 v[48:51], v[156:159], v[164:167], v[48:51]
	v_mfma_f32_16x16x32_bf16 v[36:39], v[148:151], v[172:175], v[36:39]
	v_mfma_f32_16x16x32_bf16 v[32:35], v[156:159], v[172:175], v[32:35]
	v_mfma_f32_16x16x32_bf16 v[20:23], v[148:151], v[180:183], v[20:23]
	v_mfma_f32_16x16x32_bf16 v[16:19], v[156:159], v[180:183], v[16:19]
	v_mfma_f32_16x16x32_bf16 v[4:7], v[148:151], v[206:209], v[4:7]
	v_mfma_f32_16x16x32_bf16 v[0:3], v[156:159], v[206:209], v[0:3]
	s_setprio 0
	s_barrier
; #define PG8_STAGE(bufoff, gbase, voff) do { _Pragma("unroll") for (int _i = 0; _i < 2; ++_i) \
;         __builtin_amdgcn_global_load_lds((const unsigned*)((const char*)(gbase) + (voff)[_i]), (PG8_LAS unsigned*)(lds + (bufoff) + ldsw + _i * 8192), 16, 0, 0); } while (0)
; #define PG8_LDA(dst, b, h) do { _Pragma("unroll") for (int m = 0; m < 4; ++m) _Pragma("unroll") for (int k = 0; k < 2; ++k) dst[m][k] = *(const PG8_LAS bf16x8*)(lds + PG8_SA(b, h) + aoff + m * 2048 + k * 1024); } while (0)
; #define PG8_LDB(dst, b, h) do { _Pragma("unroll") for (int n = 0; n < 2; ++n) _Pragma("unroll") for (int k = 0; k < 2; ++k) dst[n][k] = *(const PG8_LAS bf16x8*)(lds + PG8_SB(b, h) + boff + n * 2048 + k * 1024); } while (0)
; #define PG8_MMA(ai, bj, At, Bt) do { __builtin_amdgcn_s_setprio(1); _Pragma("unroll") for (int m = 0; m < 4; ++m) _Pragma("unroll") for (int n = 0; n < 2; ++n) _Pragma("unroll") for (int k = 0; k < 2; ++k) \
;         acc[ai][bj][m][n] = __builtin_amdgcn_mfma_f32_16x16x32_bf16(Bt[n][k], At[m][k], acc[ai][bj][m][n], 0, 0, 0); __builtin_amdgcn_s_setprio(0); } while (0)
; #define PG8_WAIT_V(n) asm volatile("s_waitcnt vmcnt(" #n ")" ::: "memory")
; #define PG8_WAIT_L(n) asm volatile("s_waitcnt lgkmcnt(" #n ")" ::: "memory")
; #define PG8_BAR __builtin_amdgcn_s_barrier()
; #define PG8_SCHED __builtin_amdgcn_sched_barrier(0)
; template <class Epi, class Sched, bool ALIGN_EPI = false, bool SP2 = false>
; __device__ __forceinline__ void gemm_phase(PG8_LAS unsigned char* lds, const Gemm g, const Sched& S, const Epi& E) {
;     ...
;             PG8_LDB(B0, 1, 0); PG8_LDB(B1, 1, 1); PG8_SCHED; PG8_LDA(At, 1, 0); PG8_STAGE(PG8_SA(0, 1), a2 + hstep, voffA);
;             PG8_WAIT_V(8); PG8_WAIT_L(0); PG8_BAR; PG8_MMA(0, 0, At, B0); PG8_MMA(0, 1, At, B1); PG8_BAR; PG8_SCHED;
;             PG8_LDA(At, 1, 1); PG8_STAGE(PG8_SB(1, 0), b3, voffB); PG8_STAGE(PG8_SB(1, 1), b3 + hstep, voffB); PG8_STAGE(PG8_SA(1, 0), a3, voffA);
;             PG8_WAIT_V(8); PG8_WAIT_L(0); PG8_BAR; PG8_MMA(1, 0, At, B0); PG8_MMA(1, 1, At, B1); PG8_BAR; PG8_SCHED;
	s_add_i32 s73, 0, 0x18000
	s_add_i32 s74, 0, 0x1c000
	v_add_u32_e32 v128, s73, v221
	v_add_u32_e32 v156, s74, v221
	ds_read_b128 v[96:99], v128
	ds_read_b128 v[108:111], v128 offset:1024
	ds_read_b128 v[120:123], v128 offset:2048
	ds_read_b128 v[128:131], v128 offset:3072
	ds_read_b128 v[144:147], v156
	ds_read_b128 v[148:151], v156 offset:1024
	ds_read_b128 v[152:155], v156 offset:2048
	ds_read_b128 v[156:159], v156 offset:3072
	s_add_u32 s48, s48, 0xb0000
	s_addc_u32 s49, s49, 0
	s_mov_b32 m0, s53
	ds_read_b128 v[160:163], v225 offset:32768
	ds_read_b128 v[164:167], v225 offset:33792
	ds_read_b128 v[168:171], v225 offset:34816
	ds_read_b128 v[172:175], v225 offset:35840
	ds_read_b128 v[176:179], v225 offset:36864
	ds_read_b128 v[180:183], v225 offset:37888
	ds_read_b128 v[202:205], v225 offset:38912
	ds_read_b128 v[206:209], v225 offset:39936
	global_load_lds_dwordx4 v184, s[48:49]
	s_mov_b32 m0, s54
	s_nop 0
	global_load_lds_dwordx4 v188, s[48:49]
	s_waitcnt vmcnt(8)
	s_waitcnt lgkmcnt(0)
	s_barrier
	s_setprio 1
	s_waitcnt lgkmcnt(0)
	v_mfma_f32_16x16x32_bf16 v[140:143], v[96:99], v[160:163], v[140:143]
	v_mfma_f32_16x16x32_bf16 v[136:139], v[120:123], v[160:163], v[136:139]
	v_mfma_f32_16x16x32_bf16 v[116:119], v[96:99], v[168:171], v[116:119]
	v_mfma_f32_16x16x32_bf16 v[112:115], v[120:123], v[168:171], v[112:115]
	v_mfma_f32_16x16x32_bf16 v[92:95], v[96:99], v[176:179], v[92:95]
	v_mfma_f32_16x16x32_bf16 v[88:91], v[120:123], v[176:179], v[88:91]
	v_mfma_f32_16x16x32_bf16 v[76:79], v[96:99], v[202:205], v[76:79]
	v_mfma_f32_16x16x32_bf16 v[72:75], v[120:123], v[202:205], v[72:75]
	v_mfma_f32_16x16x32_bf16 v[140:143], v[108:111], v[164:167], v[140:143]
	v_mfma_f32_16x16x32_bf16 v[136:139], v[128:131], v[164:167], v[136:139]
	v_mfma_f32_16x16x32_bf16 v[116:119], v[108:111], v[172:175], v[116:119]
	v_mfma_f32_16x16x32_bf16 v[112:115], v[128:131], v[172:175], v[112:115]
	v_mfma_f32_16x16x32_bf16 v[92:95], v[108:111], v[180:183], v[92:95]
	v_mfma_f32_16x16x32_bf16 v[88:91], v[128:131], v[180:183], v[88:91]
	v_mfma_f32_16x16x32_bf16 v[76:79], v[108:111], v[206:209], v[76:79]
	v_mfma_f32_16x16x32_bf16 v[72:75], v[128:131], v[206:209], v[72:75]
	v_mfma_f32_16x16x32_bf16 v[132:135], v[144:147], v[160:163], v[132:135]
	v_mfma_f32_16x16x32_bf16 v[124:127], v[152:155], v[160:163], v[124:127]
	v_mfma_f32_16x16x32_bf16 v[104:107], v[144:147], v[168:171], v[104:107]
	v_mfma_f32_16x16x32_bf16 v[100:103], v[152:155], v[168:171], v[100:103]
	v_mfma_f32_16x16x32_bf16 v[84:87], v[144:147], v[176:179], v[84:87]
	v_mfma_f32_16x16x32_bf16 v[80:83], v[152:155], v[176:179], v[80:83]
	v_mfma_f32_16x16x32_bf16 v[68:71], v[144:147], v[202:205], v[68:71]
	v_mfma_f32_16x16x32_bf16 v[64:67], v[152:155], v[202:205], v[64:67]
	v_mfma_f32_16x16x32_bf16 v[132:135], v[148:151], v[164:167], v[132:135]
	v_mfma_f32_16x16x32_bf16 v[124:127], v[156:159], v[164:167], v[124:127]
	v_mfma_f32_16x16x32_bf16 v[104:107], v[148:151], v[172:175], v[104:107]
	v_mfma_f32_16x16x32_bf16 v[100:103], v[156:159], v[172:175], v[100:103]
	v_mfma_f32_16x16x32_bf16 v[84:87], v[148:151], v[180:183], v[84:87]
	v_mfma_f32_16x16x32_bf16 v[80:83], v[156:159], v[180:183], v[80:83]
	v_mfma_f32_16x16x32_bf16 v[68:71], v[148:151], v[206:209], v[68:71]
	v_mfma_f32_16x16x32_bf16 v[64:67], v[156:159], v[206:209], v[64:67]
	s_setprio 0
	s_barrier
	s_add_i32 s48, s73, s50
	s_mov_b32 m0, s48
	ds_read_b128 v[160:163], v225 offset:49152
	ds_read_b128 v[164:167], v225 offset:50176
	ds_read_b128 v[168:171], v225 offset:51200
	ds_read_b128 v[172:175], v225 offset:52224
	ds_read_b128 v[176:179], v225 offset:53248
	ds_read_b128 v[180:183], v225 offset:54272
	ds_read_b128 v[202:205], v225 offset:55296
	ds_read_b128 v[206:209], v225 offset:56320
	global_load_lds_dwordx4 v186, s[98:99]
	s_add_i32 m0, s48, 0x2000
	s_add_u32 s34, s34, 0xb0080
	s_addc_u32 s35, s35, 0
	s_add_i32 s48, s74, s50
	global_load_lds_dwordx4 v190, s[98:99]
	s_mov_b32 m0, s48
	s_nop 0
	global_load_lds_dwordx4 v186, s[34:35]
	s_add_i32 m0, s48, 0x2000
	s_nop 0
	global_load_lds_dwordx4 v190, s[34:35]
	s_mov_b32 m0, s59
	s_nop 0
	global_load_lds_dwordx4 v184, s[100:101]
	s_mov_b32 m0, s60
	s_nop 0
	global_load_lds_dwordx4 v188, s[100:101]
	s_waitcnt vmcnt(8)
	s_waitcnt lgkmcnt(0)
	s_barrier
	s_setprio 1
	s_waitcnt lgkmcnt(0)
	v_mfma_f32_16x16x32_bf16 v[60:63], v[96:99], v[160:163], v[60:63]
	v_mfma_f32_16x16x32_bf16 v[56:59], v[120:123], v[160:163], v[56:59]
	v_mfma_f32_16x16x32_bf16 v[44:47], v[96:99], v[168:171], v[44:47]
	v_mfma_f32_16x16x32_bf16 v[40:43], v[120:123], v[168:171], v[40:43]
	v_mfma_f32_16x16x32_bf16 v[28:31], v[96:99], v[176:179], v[28:31]
	v_mfma_f32_16x16x32_bf16 v[24:27], v[120:123], v[176:179], v[24:27]
	v_mfma_f32_16x16x32_bf16 v[12:15], v[96:99], v[202:205], v[12:15]
	v_mfma_f32_16x16x32_bf16 v[8:11], v[120:123], v[202:205], v[8:11]
	v_mfma_f32_16x16x32_bf16 v[60:63], v[108:111], v[164:167], v[60:63]
	v_mfma_f32_16x16x32_bf16 v[56:59], v[128:131], v[164:167], v[56:59]
	v_mfma_f32_16x16x32_bf16 v[44:47], v[108:111], v[172:175], v[44:47]
	v_mfma_f32_16x16x32_bf16 v[40:43], v[128:131], v[172:175], v[40:43]
	v_mfma_f32_16x16x32_bf16 v[28:31], v[108:111], v[180:183], v[28:31]
	v_mfma_f32_16x16x32_bf16 v[24:27], v[128:131], v[180:183], v[24:27]
	v_mfma_f32_16x16x32_bf16 v[12:15], v[108:111], v[206:209], v[12:15]
	v_mfma_f32_16x16x32_bf16 v[8:11], v[128:131], v[206:209], v[8:11]
	v_mfma_f32_16x16x32_bf16 v[52:55], v[144:147], v[160:163], v[52:55]
	v_mfma_f32_16x16x32_bf16 v[48:51], v[152:155], v[160:163], v[48:51]
	v_mfma_f32_16x16x32_bf16 v[36:39], v[144:147], v[168:171], v[36:39]
	v_mfma_f32_16x16x32_bf16 v[32:35], v[152:155], v[168:171], v[32:35]
	v_mfma_f32_16x16x32_bf16 v[20:23], v[144:147], v[176:179], v[20:23]
	v_mfma_f32_16x16x32_bf16 v[16:19], v[152:155], v[176:179], v[16:19]
	v_mfma_f32_16x16x32_bf16 v[4:7], v[144:147], v[202:205], v[4:7]
	v_mfma_f32_16x16x32_bf16 v[0:3], v[152:155], v[202:205], v[0:3]
	v_mfma_f32_16x16x32_bf16 v[52:55], v[148:151], v[164:167], v[52:55]
	v_mfma_f32_16x16x32_bf16 v[48:51], v[156:159], v[164:167], v[48:51]
	v_mfma_f32_16x16x32_bf16 v[36:39], v[148:151], v[172:175], v[36:39]
	v_mfma_f32_16x16x32_bf16 v[32:35], v[156:159], v[172:175], v[32:35]
	v_mfma_f32_16x16x32_bf16 v[20:23], v[148:151], v[180:183], v[20:23]
	v_mfma_f32_16x16x32_bf16 v[16:19], v[156:159], v[180:183], v[16:19]
	v_mfma_f32_16x16x32_bf16 v[4:7], v[148:151], v[206:209], v[4:7]
	v_mfma_f32_16x16x32_bf16 v[0:3], v[156:159], v[206:209], v[0:3]
	s_setprio 0
	s_barrier
	s_add_i32 s72, s72, 2
	s_add_u32 s20, s20, 0x100
	s_addc_u32 s21, s21, 0
	s_add_u32 s70, s70, 0x100
	s_addc_u32 s71, s71, 0
	s_cmp_gt_u32 s72, 41
	s_cbranch_scc0 .LBB0_895
	s_and_b64 vcc, exec, s[14:15]
	s_cbranch_vccz .LBB0_898
	s_barrier

; #define PG8_STAGE(bufoff, gbase, voff) do { _Pragma("unroll") for (int _i = 0; _i < 2; ++_i) \
;         __builtin_amdgcn_global_load_lds((const unsigned*)((const char*)(gbase) + (voff)[_i]), (PG8_LAS unsigned*)(lds + (bufoff) + ldsw + _i * 8192), 16, 0, 0); } while (0)
; #define PG8_LDA(dst, b, h) do { _Pragma("unroll") for (int m = 0; m < 4; ++m) _Pragma("unroll") for (int k = 0; k < 2; ++k) dst[m][k] = *(const PG8_LAS bf16x8*)(lds + PG8_SA(b, h) + aoff + m * 2048 + k * 1024); } while (0)
; #define PG8_LDB(dst, b, h) do { _Pragma("unroll") for (int n = 0; n < 2; ++n) _Pragma("unroll") for (int k = 0; k < 2; ++k) dst[n][k] = *(const PG8_LAS bf16x8*)(lds + PG8_SB(b, h) + boff + n * 2048 + k * 1024); } while (0)
; #define PG8_MMA(ai, bj, At, Bt) do { __builtin_amdgcn_s_setprio(1); _Pragma("unroll") for (int m = 0; m < 4; ++m) _Pragma("unroll") for (int n = 0; n < 2; ++n) _Pragma("unroll") for (int k = 0; k < 2; ++k) \
;         acc[ai][bj][m][n] = __builtin_amdgcn_mfma_f32_16x16x32_bf16(Bt[n][k], At[m][k], acc[ai][bj][m][n], 0, 0, 0); __builtin_amdgcn_s_setprio(0); } while (0)
; #define PG8_WAIT_V(n) asm volatile("s_waitcnt vmcnt(" #n ")" ::: "memory")
; template <class Epi, class Sched, bool ALIGN_EPI = false, bool SP2 = false>
; __device__ __forceinline__ void gemm_phase(PG8_LAS unsigned char* lds, const Gemm g, const Sched& S, const Epi& E) {
;     ...
;         const char* nA = has_next ? (const char*)g.A + (size_t)nxt.pm * tstep : cA; const char* nB = has_next ? (const char*)g.Bt + (size_t)nxt.pn * tstep : cB;
;         for (int t = 0; t < nt; t += 2) {
;             const bool last = (t == nt - 2);
;             const char* a1 = cA + (size_t)(t + 1) * kstep;
;             const char* a2 = last ? nA : cA + (size_t)(t + 2) * kstep; const char* b2 = last ? nB : cB + (size_t)(t + 2) * kstep;
;             const char* a3 = a2 + kstep; const char* b3 = b2 + kstep;
;             if (last && has_next) S.a_ready(nxt);
;             if constexpr (SP2) {
;             PG8_LDB(B0, 0, 0); PG8_LDB(B1, 0, 1); PG8_SCHED; PG8_LDA(At, 0, 0); PG8_STAGE(PG8_SA(1, 1), a1 + hstep, voffA);
;             PG8_WAIT_V(8); PG8_WAIT_L(0); PG8_BAR; PG8_MMA(0, 0, At, B0); PG8_MMA(0, 1, At, B1); PG8_BAR; PG8_SCHED;
;             PG8_LDA(At, 0, 1); PG8_STAGE(PG8_SB(0, 0), b2, voffB); PG8_STAGE(PG8_SB(0, 1), b2 + hstep, voffB); PG8_STAGE(PG8_SA(0, 0), a2, voffA);
.LBB0_1199:
	s_ashr_i32 s57, s56, 31
	s_lshl_b64 s[58:59], s[56:57], 19
	s_add_u32 s58, s36, s58
	s_addc_u32 s59, s37, s59
	s_and_b64 s[60:61], s[8:9], exec
	s_cselect_b32 s1, s59, s21
	s_cselect_b32 s57, s58, s20
	s_ashr_i32 s55, s54, 31
	s_lshl_b64 s[60:61], s[54:55], 19
	s_add_u32 s60, s68, s60
	s_addc_u32 s61, s69, s61
	s_and_b64 s[62:63], s[8:9], exec
	s_cselect_b32 s55, s61, s35
	s_cselect_b32 s85, s60, s34
	s_add_u32 s20, s20, 0x40080
	s_addc_u32 s21, s21, 0
	s_add_u32 s86, s34, 0x100
	s_addc_u32 s87, s35, 0
	s_mov_b32 s88, -2
	s_waitcnt lgkmcnt(0)
	ds_read_b128 v[140:143], v163
	ds_read_b128 v[168:171], v163 offset:1024
	ds_read_b128 v[172:175], v163 offset:2048
	ds_read_b128 v[176:179], v163 offset:3072
	ds_read_b128 v[180:183], v164
	ds_read_b128 v[184:187], v164 offset:1024
	ds_read_b128 v[188:191], v164 offset:2048
	ds_read_b128 v[192:195], v164 offset:3072
	s_add_u32 s34, s20, 0xfffc0080
	s_addc_u32 s35, s21, -1
	s_cmp_eq_u32 s88, 12
	s_cselect_b32 s63, s1, s35
	s_cselect_b32 s62, s57, s34
	s_cselect_b32 s35, s55, s87
	s_cselect_b32 s34, s85, s86
	s_add_i32 m0, s71, 0xc000
	ds_read_b128 v[198:201], v165
	ds_read_b128 v[202:205], v165 offset:1024
	ds_read_b128 v[206:209], v165 offset:2048
	ds_read_b128 v[210:213], v165 offset:3072
	ds_read_b128 v[214:217], v165 offset:4096
	ds_read_b128 v[218:221], v165 offset:5120
	ds_read_b128 v[222:225], v165 offset:6144
	ds_read_b128 v[226:229], v165 offset:7168
	global_load_lds_dwordx4 v132, s[20:21]
	s_add_i32 m0, s71, 0xe000
	s_nop 0
	global_load_lds_dwordx4 v134, s[20:21]
	s_waitcnt vmcnt(8)
	s_waitcnt lgkmcnt(0)
	s_barrier
	s_setprio 1
	s_waitcnt lgkmcnt(0)
	v_mfma_f32_16x16x32_bf16 v[124:127], v[140:143], v[198:201], 0
	v_mfma_f32_16x16x32_bf16 v[120:123], v[172:175], v[198:201], 0
	v_mfma_f32_16x16x32_bf16 v[108:111], v[140:143], v[206:209], 0
	v_mfma_f32_16x16x32_bf16 v[104:107], v[172:175], v[206:209], 0
	v_mfma_f32_16x16x32_bf16 v[92:95], v[140:143], v[214:217], 0
	v_mfma_f32_16x16x32_bf16 v[88:91], v[172:175], v[214:217], 0
	v_mfma_f32_16x16x32_bf16 v[76:79], v[140:143], v[222:225], 0
	v_mfma_f32_16x16x32_bf16 v[72:75], v[172:175], v[222:225], 0
	v_mfma_f32_16x16x32_bf16 v[124:127], v[168:171], v[202:205], v[124:127]
	v_mfma_f32_16x16x32_bf16 v[120:123], v[176:179], v[202:205], v[120:123]
	v_mfma_f32_16x16x32_bf16 v[108:111], v[168:171], v[210:213], v[108:111]
	v_mfma_f32_16x16x32_bf16 v[104:107], v[176:179], v[210:213], v[104:107]
	v_mfma_f32_16x16x32_bf16 v[92:95], v[168:171], v[218:221], v[92:95]
	v_mfma_f32_16x16x32_bf16 v[88:91], v[176:179], v[218:221], v[88:91]
	v_mfma_f32_16x16x32_bf16 v[76:79], v[168:171], v[226:229], v[76:79]
	v_mfma_f32_16x16x32_bf16 v[72:75], v[176:179], v[226:229], v[72:75]
	v_mfma_f32_16x16x32_bf16 v[116:119], v[180:183], v[198:201], 0
	v_mfma_f32_16x16x32_bf16 v[112:115], v[188:191], v[198:201], 0
	v_mfma_f32_16x16x32_bf16 v[100:103], v[180:183], v[206:209], 0
	v_mfma_f32_16x16x32_bf16 v[96:99], v[188:191], v[206:209], 0
	v_mfma_f32_16x16x32_bf16 v[84:87], v[180:183], v[214:217], 0
	v_mfma_f32_16x16x32_bf16 v[80:83], v[188:191], v[214:217], 0
	v_mfma_f32_16x16x32_bf16 v[68:71], v[180:183], v[222:225], 0
	v_mfma_f32_16x16x32_bf16 v[64:67], v[188:191], v[222:225], 0
	v_mfma_f32_16x16x32_bf16 v[116:119], v[184:187], v[202:205], v[116:119]
	v_mfma_f32_16x16x32_bf16 v[112:115], v[192:195], v[202:205], v[112:115]
	v_mfma_f32_16x16x32_bf16 v[100:103], v[184:187], v[210:213], v[100:103]
	v_mfma_f32_16x16x32_bf16 v[96:99], v[192:195], v[210:213], v[96:99]
	v_mfma_f32_16x16x32_bf16 v[84:87], v[184:187], v[218:221], v[84:87]
	v_mfma_f32_16x16x32_bf16 v[80:83], v[192:195], v[218:221], v[80:83]
	v_mfma_f32_16x16x32_bf16 v[68:71], v[184:187], v[226:229], v[68:71]
	v_mfma_f32_16x16x32_bf16 v[64:67], v[192:195], v[226:229], v[64:67]
	s_setprio 0
	s_barrier
	s_add_i32 s89, s77, s70
	s_add_u32 s98, s34, s18
	s_addc_u32 s99, s35, s19
	s_add_u32 s100, s62, s18
	s_addc_u32 s101, s63, s19
	s_mov_b32 m0, s89
	ds_read_b128 v[198:201], v165 offset:16384
	ds_read_b128 v[202:205], v165 offset:17408
	ds_read_b128 v[206:209], v165 offset:18432
	ds_read_b128 v[210:213], v165 offset:19456
	ds_read_b128 v[214:217], v165 offset:20480
	ds_read_b128 v[218:221], v165 offset:21504
	ds_read_b128 v[222:225], v165 offset:22528
	ds_read_b128 v[226:229], v165 offset:23552
	global_load_lds_dwordx4 v146, s[34:35]
	s_add_i32 m0, s89, 0x2000
	s_add_u32 s90, s34, 0x40000
	s_addc_u32 s91, s35, 0
	s_add_i32 s89, s78, s70
	global_load_lds_dwordx4 v150, s[34:35]
	s_mov_b32 m0, s89
	s_nop 0
	global_load_lds_dwordx4 v146, s[90:91]
	s_add_i32 m0, s89, 0x2000
	s_nop 0
	global_load_lds_dwordx4 v150, s[90:91]
	s_mov_b32 m0, s71
	s_nop 0
	global_load_lds_dwordx4 v144, s[62:63]
	s_mov_b32 m0, s72
	s_nop 0
	global_load_lds_dwordx4 v148, s[62:63]
	s_waitcnt vmcnt(8)
	s_waitcnt lgkmcnt(0)
	s_barrier
; #define PG8_STAGE(bufoff, gbase, voff) do { _Pragma("unroll") for (int _i = 0; _i < 2; ++_i) \
;         __builtin_amdgcn_global_load_lds((const unsigned*)((const char*)(gbase) + (voff)[_i]), (PG8_LAS unsigned*)(lds + (bufoff) + ldsw + _i * 8192), 16, 0, 0); } while (0)
; #define PG8_LDA(dst, b, h) do { _Pragma("unroll") for (int m = 0; m < 4; ++m) _Pragma("unroll") for (int k = 0; k < 2; ++k) dst[m][k] = *(const PG8_LAS bf16x8*)(lds + PG8_SA(b, h) + aoff + m * 2048 + k * 1024); } while (0)
; #define PG8_LDB(dst, b, h) do { _Pragma("unroll") for (int n = 0; n < 2; ++n) _Pragma("unroll") for (int k = 0; k < 2; ++k) dst[n][k] = *(const PG8_LAS bf16x8*)(lds + PG8_SB(b, h) + boff + n * 2048 + k * 1024); } while (0)
; #define PG8_MMA(ai, bj, At, Bt) do { __builtin_amdgcn_s_setprio(1); _Pragma("unroll") for (int m = 0; m < 4; ++m) _Pragma("unroll") for (int n = 0; n < 2; ++n) _Pragma("unroll") for (int k = 0; k < 2; ++k) \
;         acc[ai][bj][m][n] = __builtin_amdgcn_mfma_f32_16x16x32_bf16(Bt[n][k], At[m][k], acc[ai][bj][m][n], 0, 0, 0); __builtin_amdgcn_s_setprio(0); } while (0)
; #define PG8_WAIT_V(n) asm volatile("s_waitcnt vmcnt(" #n ")" ::: "memory")
; #define PG8_WAIT_L(n) asm volatile("s_waitcnt lgkmcnt(" #n ")" ::: "memory")
; #define PG8_BAR __builtin_amdgcn_s_barrier()
; #define PG8_SCHED __builtin_amdgcn_sched_barrier(0)
; template <class Epi, class Sched, bool ALIGN_EPI = false, bool SP2 = false>
; __device__ __forceinline__ void gemm_phase(PG8_LAS unsigned char* lds, const Gemm g, const Sched& S, const Epi& E) {
;     ...
;             PG8_WAIT_V(8); PG8_WAIT_L(0); PG8_BAR; PG8_MMA(1, 0, At, B0); PG8_MMA(1, 1, At, B1); PG8_BAR; PG8_SCHED;
;             PG8_LDB(B0, 1, 0); PG8_LDB(B1, 1, 1); PG8_SCHED; PG8_LDA(At, 1, 0); PG8_STAGE(PG8_SA(0, 1), a2 + hstep, voffA);
;             PG8_WAIT_V(8); PG8_WAIT_L(0); PG8_BAR; PG8_MMA(0, 0, At, B0); PG8_MMA(0, 1, At, B1); PG8_BAR; PG8_SCHED;
	s_setprio 1
	s_waitcnt lgkmcnt(0)
	v_mfma_f32_16x16x32_bf16 v[60:63], v[140:143], v[198:201], 0
	v_mfma_f32_16x16x32_bf16 v[56:59], v[172:175], v[198:201], 0
	v_mfma_f32_16x16x32_bf16 v[48:51], v[140:143], v[206:209], 0
	v_mfma_f32_16x16x32_bf16 v[40:43], v[172:175], v[206:209], 0
	v_mfma_f32_16x16x32_bf16 v[32:35], v[140:143], v[214:217], 0
	v_mfma_f32_16x16x32_bf16 v[24:27], v[172:175], v[214:217], 0
	v_mfma_f32_16x16x32_bf16 v[16:19], v[140:143], v[222:225], 0
	v_mfma_f32_16x16x32_bf16 v[8:11], v[172:175], v[222:225], 0
	v_mfma_f32_16x16x32_bf16 v[60:63], v[168:171], v[202:205], v[60:63]
	v_mfma_f32_16x16x32_bf16 v[56:59], v[176:179], v[202:205], v[56:59]
	v_mfma_f32_16x16x32_bf16 v[48:51], v[168:171], v[210:213], v[48:51]
	v_mfma_f32_16x16x32_bf16 v[40:43], v[176:179], v[210:213], v[40:43]
	v_mfma_f32_16x16x32_bf16 v[32:35], v[168:171], v[218:221], v[32:35]
	v_mfma_f32_16x16x32_bf16 v[24:27], v[176:179], v[218:221], v[24:27]
	v_mfma_f32_16x16x32_bf16 v[16:19], v[168:171], v[226:229], v[16:19]
	v_mfma_f32_16x16x32_bf16 v[8:11], v[176:179], v[226:229], v[8:11]
	v_mfma_f32_16x16x32_bf16 v[52:55], v[180:183], v[198:201], 0
	v_mfma_f32_16x16x32_bf16 v[44:47], v[188:191], v[198:201], 0
	v_mfma_f32_16x16x32_bf16 v[36:39], v[180:183], v[206:209], 0
	v_mfma_f32_16x16x32_bf16 v[28:31], v[188:191], v[206:209], 0
	v_mfma_f32_16x16x32_bf16 v[20:23], v[180:183], v[214:217], 0
	v_mfma_f32_16x16x32_bf16 v[12:15], v[188:191], v[214:217], 0
	v_mfma_f32_16x16x32_bf16 v[4:7], v[180:183], v[222:225], 0
	v_mfma_f32_16x16x32_bf16 v[0:3], v[188:191], v[222:225], 0
	v_mfma_f32_16x16x32_bf16 v[52:55], v[184:187], v[202:205], v[52:55]
	v_mfma_f32_16x16x32_bf16 v[44:47], v[192:195], v[202:205], v[44:47]
	v_mfma_f32_16x16x32_bf16 v[36:39], v[184:187], v[210:213], v[36:39]
	v_mfma_f32_16x16x32_bf16 v[28:31], v[192:195], v[210:213], v[28:31]
	v_mfma_f32_16x16x32_bf16 v[20:23], v[184:187], v[218:221], v[20:23]
	v_mfma_f32_16x16x32_bf16 v[12:15], v[192:195], v[218:221], v[12:15]
	v_mfma_f32_16x16x32_bf16 v[4:7], v[184:187], v[226:229], v[4:7]
	v_mfma_f32_16x16x32_bf16 v[0:3], v[192:195], v[226:229], v[0:3]
	s_setprio 0
	s_barrier
	s_add_i32 s89, 0, 0x18000
	v_add_u32_e32 v128, s89, v161
	s_add_i32 s90, 0, 0x1c000
	ds_read_b128 v[140:143], v128
	ds_read_b128 v[168:171], v128 offset:1024
	ds_read_b128 v[172:175], v128 offset:2048
	ds_read_b128 v[176:179], v128 offset:3072
	v_add_u32_e32 v128, s90, v161
	ds_read_b128 v[180:183], v128
	ds_read_b128 v[184:187], v128 offset:1024
	ds_read_b128 v[188:191], v128 offset:2048
	ds_read_b128 v[192:195], v128 offset:3072
	s_add_u32 s62, s62, 0x40000
	s_addc_u32 s63, s63, 0
	s_mov_b32 m0, s73
	ds_read_b128 v[198:201], v165 offset:32768
	ds_read_b128 v[202:205], v165 offset:33792
	ds_read_b128 v[206:209], v165 offset:34816
	ds_read_b128 v[210:213], v165 offset:35840
	ds_read_b128 v[214:217], v165 offset:36864
	ds_read_b128 v[218:221], v165 offset:37888
	ds_read_b128 v[222:225], v165 offset:38912
	ds_read_b128 v[226:229], v165 offset:39936
	global_load_lds_dwordx4 v144, s[62:63]
	s_mov_b32 m0, s74
	s_nop 0
	global_load_lds_dwordx4 v148, s[62:63]
	s_waitcnt vmcnt(8)
	s_waitcnt lgkmcnt(0)
	s_barrier
	s_setprio 1
	s_waitcnt lgkmcnt(0)
	v_mfma_f32_16x16x32_bf16 v[124:127], v[140:143], v[198:201], v[124:127]
	v_mfma_f32_16x16x32_bf16 v[120:123], v[172:175], v[198:201], v[120:123]
	v_mfma_f32_16x16x32_bf16 v[108:111], v[140:143], v[206:209], v[108:111]
	v_mfma_f32_16x16x32_bf16 v[104:107], v[172:175], v[206:209], v[104:107]
	v_mfma_f32_16x16x32_bf16 v[92:95], v[140:143], v[214:217], v[92:95]
	v_mfma_f32_16x16x32_bf16 v[88:91], v[172:175], v[214:217], v[88:91]
	v_mfma_f32_16x16x32_bf16 v[76:79], v[140:143], v[222:225], v[76:79]
	v_mfma_f32_16x16x32_bf16 v[72:75], v[172:175], v[222:225], v[72:75]
	v_mfma_f32_16x16x32_bf16 v[124:127], v[168:171], v[202:205], v[124:127]
	v_mfma_f32_16x16x32_bf16 v[120:123], v[176:179], v[202:205], v[120:123]
	v_mfma_f32_16x16x32_bf16 v[108:111], v[168:171], v[210:213], v[108:111]
	v_mfma_f32_16x16x32_bf16 v[104:107], v[176:179], v[210:213], v[104:107]
	v_mfma_f32_16x16x32_bf16 v[92:95], v[168:171], v[218:221], v[92:95]
	v_mfma_f32_16x16x32_bf16 v[88:91], v[176:179], v[218:221], v[88:91]
	v_mfma_f32_16x16x32_bf16 v[76:79], v[168:171], v[226:229], v[76:79]
	v_mfma_f32_16x16x32_bf16 v[72:75], v[176:179], v[226:229], v[72:75]
	v_mfma_f32_16x16x32_bf16 v[116:119], v[180:183], v[198:201], v[116:119]
	v_mfma_f32_16x16x32_bf16 v[112:115], v[188:191], v[198:201], v[112:115]
	v_mfma_f32_16x16x32_bf16 v[100:103], v[180:183], v[206:209], v[100:103]
	v_mfma_f32_16x16x32_bf16 v[96:99], v[188:191], v[206:209], v[96:99]
	v_mfma_f32_16x16x32_bf16 v[84:87], v[180:183], v[214:217], v[84:87]
	v_mfma_f32_16x16x32_bf16 v[80:83], v[188:191], v[214:217], v[80:83]
	v_mfma_f32_16x16x32_bf16 v[68:71], v[180:183], v[222:225], v[68:71]
	v_mfma_f32_16x16x32_bf16 v[64:67], v[188:191], v[222:225], v[64:67]
	v_mfma_f32_16x16x32_bf16 v[116:119], v[184:187], v[202:205], v[116:119]
	v_mfma_f32_16x16x32_bf16 v[112:115], v[192:195], v[202:205], v[112:115]
	v_mfma_f32_16x16x32_bf16 v[100:103], v[184:187], v[210:213], v[100:103]
	v_mfma_f32_16x16x32_bf16 v[96:99], v[192:195], v[210:213], v[96:99]
	v_mfma_f32_16x16x32_bf16 v[84:87], v[184:187], v[218:221], v[84:87]
	v_mfma_f32_16x16x32_bf16 v[80:83], v[192:195], v[218:221], v[80:83]
	v_mfma_f32_16x16x32_bf16 v[68:71], v[184:187], v[226:229], v[68:71]
	v_mfma_f32_16x16x32_bf16 v[64:67], v[192:195], v[226:229], v[64:67]
	s_setprio 0
	s_barrier
; #define PG8_STAGE(bufoff, gbase, voff) do { _Pragma("unroll") for (int _i = 0; _i < 2; ++_i) \
;         __builtin_amdgcn_global_load_lds((const unsigned*)((const char*)(gbase) + (voff)[_i]), (PG8_LAS unsigned*)(lds + (bufoff) + ldsw + _i * 8192), 16, 0, 0); } while (0)
; #define PG8_LDA(dst, b, h) do { _Pragma("unroll") for (int m = 0; m < 4; ++m) _Pragma("unroll") for (int k = 0; k < 2; ++k) dst[m][k] = *(const PG8_LAS bf16x8*)(lds + PG8_SA(b, h) + aoff + m * 2048 + k * 1024); } while (0)
; #define PG8_LDB(dst, b, h) do { _Pragma("unroll") for (int n = 0; n < 2; ++n) _Pragma("unroll") for (int k = 0; k < 2; ++k) dst[n][k] = *(const PG8_LAS bf16x8*)(lds + PG8_SB(b, h) + boff + n * 2048 + k * 1024); } while (0)
; #define PG8_MMA(ai, bj, At, Bt) do { __builtin_amdgcn_s_setprio(1); _Pragma("unroll") for (int m = 0; m < 4; ++m) _Pragma("unroll") for (int n = 0; n < 2; ++n) _Pragma("unroll") for (int k = 0; k < 2; ++k) \
;         acc[ai][bj][m][n] = __builtin_amdgcn_mfma_f32_16x16x32_bf16(Bt[n][k], At[m][k], acc[ai][bj][m][n], 0, 0, 0); __builtin_amdgcn_s_setprio(0); } while (0)
; #define PG8_WAIT_V(n) asm volatile("s_waitcnt vmcnt(" #n ")" ::: "memory")
; template <class Epi, class Sched, bool ALIGN_EPI = false, bool SP2 = false>
; __device__ __forceinline__ void gemm_phase(PG8_LAS unsigned char* lds, const Gemm g, const Sched& S, const Epi& E) {
;     ...
;             PG8_LDB(B0, 0, 0); PG8_LDB(B1, 0, 1); PG8_SCHED; PG8_LDA(At, 0, 0); PG8_STAGE(PG8_SA(1, 1), a1 + hstep, voffA);
;             PG8_WAIT_V(8); PG8_WAIT_L(0); PG8_BAR; PG8_MMA(0, 0, At, B0); PG8_MMA(0, 1, At, B1); PG8_BAR; PG8_SCHED;
;             PG8_LDA(At, 0, 1); PG8_STAGE(PG8_SB(0, 0), b2, voffB); PG8_STAGE(PG8_SB(0, 1), b2 + hstep, voffB); PG8_STAGE(PG8_SA(0, 0), a2, voffA);
;             PG8_WAIT_V(8); PG8_WAIT_L(0); PG8_BAR; PG8_MMA(1, 0, At, B0); PG8_MMA(1, 1, At, B1); PG8_BAR; PG8_SCHED;
;             PG8_LDB(B0, 1, 0); PG8_LDB(B1, 1, 1); PG8_SCHED; PG8_LDA(At, 1, 0); PG8_STAGE(PG8_SA(0, 1), a2 + hstep, voffA);
;             PG8_WAIT_V(8); PG8_WAIT_L(0); PG8_BAR; PG8_MMA(0, 0, At, B0); PG8_MMA(0, 1, At, B1); PG8_BAR; PG8_SCHED;
;             PG8_LDA(At, 1, 1); PG8_STAGE(PG8_SB(1, 0), b3, voffB); PG8_STAGE(PG8_SB(1, 1), b3 + hstep, voffB); PG8_STAGE(PG8_SA(1, 0), a3, voffA);
;             PG8_WAIT_V(8); PG8_WAIT_L(0); PG8_BAR; PG8_MMA(1, 0, At, B0); PG8_MMA(1, 1, At, B1); PG8_BAR; PG8_SCHED;
	s_add_i32 s62, s89, s70
	s_mov_b32 m0, s62
	ds_read_b128 v[198:201], v165 offset:49152
	ds_read_b128 v[202:205], v165 offset:50176
	ds_read_b128 v[206:209], v165 offset:51200
	ds_read_b128 v[210:213], v165 offset:52224
	ds_read_b128 v[214:217], v165 offset:53248
	ds_read_b128 v[218:221], v165 offset:54272
	ds_read_b128 v[222:225], v165 offset:55296
	ds_read_b128 v[226:229], v165 offset:56320
	global_load_lds_dwordx4 v146, s[98:99]
	s_add_i32 m0, s62, 0x2000
	s_add_u32 s34, s34, 0x40080
	s_addc_u32 s35, s35, 0
	s_add_i32 s62, s90, s70
	global_load_lds_dwordx4 v150, s[98:99]
	s_mov_b32 m0, s62
	s_nop 0
	global_load_lds_dwordx4 v146, s[34:35]
	s_add_i32 m0, s62, 0x2000
	s_nop 0
	global_load_lds_dwordx4 v150, s[34:35]
	s_mov_b32 m0, s75
	s_nop 0
	global_load_lds_dwordx4 v144, s[100:101]
	s_mov_b32 m0, s76
	s_nop 0
	global_load_lds_dwordx4 v148, s[100:101]
	s_waitcnt vmcnt(8)
	s_waitcnt lgkmcnt(0)
	s_barrier
	s_setprio 1
	s_waitcnt lgkmcnt(0)
	v_mfma_f32_16x16x32_bf16 v[60:63], v[140:143], v[198:201], v[60:63]
	v_mfma_f32_16x16x32_bf16 v[56:59], v[172:175], v[198:201], v[56:59]
	v_mfma_f32_16x16x32_bf16 v[48:51], v[140:143], v[206:209], v[48:51]
	v_mfma_f32_16x16x32_bf16 v[40:43], v[172:175], v[206:209], v[40:43]
	v_mfma_f32_16x16x32_bf16 v[32:35], v[140:143], v[214:217], v[32:35]
	v_mfma_f32_16x16x32_bf16 v[24:27], v[172:175], v[214:217], v[24:27]
	v_mfma_f32_16x16x32_bf16 v[16:19], v[140:143], v[222:225], v[16:19]
	v_mfma_f32_16x16x32_bf16 v[8:11], v[172:175], v[222:225], v[8:11]
	v_mfma_f32_16x16x32_bf16 v[60:63], v[168:171], v[202:205], v[60:63]
	v_mfma_f32_16x16x32_bf16 v[56:59], v[176:179], v[202:205], v[56:59]
	v_mfma_f32_16x16x32_bf16 v[48:51], v[168:171], v[210:213], v[48:51]
	v_mfma_f32_16x16x32_bf16 v[40:43], v[176:179], v[210:213], v[40:43]
	v_mfma_f32_16x16x32_bf16 v[32:35], v[168:171], v[218:221], v[32:35]
	v_mfma_f32_16x16x32_bf16 v[24:27], v[176:179], v[218:221], v[24:27]
	v_mfma_f32_16x16x32_bf16 v[16:19], v[168:171], v[226:229], v[16:19]
	v_mfma_f32_16x16x32_bf16 v[8:11], v[176:179], v[226:229], v[8:11]
	v_mfma_f32_16x16x32_bf16 v[52:55], v[180:183], v[198:201], v[52:55]
	v_mfma_f32_16x16x32_bf16 v[44:47], v[188:191], v[198:201], v[44:47]
	v_mfma_f32_16x16x32_bf16 v[36:39], v[180:183], v[206:209], v[36:39]
	v_mfma_f32_16x16x32_bf16 v[28:31], v[188:191], v[206:209], v[28:31]
	v_mfma_f32_16x16x32_bf16 v[20:23], v[180:183], v[214:217], v[20:23]
	v_mfma_f32_16x16x32_bf16 v[12:15], v[188:191], v[214:217], v[12:15]
	v_mfma_f32_16x16x32_bf16 v[4:7], v[180:183], v[222:225], v[4:7]
	v_mfma_f32_16x16x32_bf16 v[0:3], v[188:191], v[222:225], v[0:3]
	v_mfma_f32_16x16x32_bf16 v[52:55], v[184:187], v[202:205], v[52:55]
	v_mfma_f32_16x16x32_bf16 v[44:47], v[192:195], v[202:205], v[44:47]
	v_mfma_f32_16x16x32_bf16 v[36:39], v[184:187], v[210:213], v[36:39]
	v_mfma_f32_16x16x32_bf16 v[28:31], v[192:195], v[210:213], v[28:31]
	v_mfma_f32_16x16x32_bf16 v[20:23], v[184:187], v[218:221], v[20:23]
	v_mfma_f32_16x16x32_bf16 v[12:15], v[192:195], v[218:221], v[12:15]
	v_mfma_f32_16x16x32_bf16 v[4:7], v[184:187], v[226:229], v[4:7]
	v_mfma_f32_16x16x32_bf16 v[0:3], v[192:195], v[226:229], v[0:3]
	s_setprio 0
	s_barrier
	s_add_i32 s88, s88, 2
	s_add_u32 s20, s20, 0x100
	s_addc_u32 s21, s21, 0
	s_add_u32 s86, s86, 0x100
	s_addc_u32 s87, s87, 0
	s_cmp_gt_u32 s88, 13
.LBB0_1200:
	ds_read_b128 v[140:143], v163
	ds_read_b128 v[168:171], v163 offset:1024
	ds_read_b128 v[172:175], v163 offset:2048
	ds_read_b128 v[176:179], v163 offset:3072
	ds_read_b128 v[180:183], v164
	ds_read_b128 v[184:187], v164 offset:1024
	ds_read_b128 v[188:191], v164 offset:2048
	ds_read_b128 v[192:195], v164 offset:3072
	s_add_u32 s34, s20, 0xfffc0080
	s_addc_u32 s35, s21, -1
	s_cmp_eq_u32 s88, 12
	s_cselect_b32 s63, s1, s35
	s_cselect_b32 s62, s57, s34
	s_cselect_b32 s35, s55, s87
	s_cselect_b32 s34, s85, s86
	s_add_i32 m0, s71, 0xc000
	ds_read_b128 v[198:201], v165
	ds_read_b128 v[202:205], v165 offset:1024
	ds_read_b128 v[206:209], v165 offset:2048
	ds_read_b128 v[210:213], v165 offset:3072
	ds_read_b128 v[214:217], v165 offset:4096
	ds_read_b128 v[218:221], v165 offset:5120
	ds_read_b128 v[222:225], v165 offset:6144
	ds_read_b128 v[226:229], v165 offset:7168
	global_load_lds_dwordx4 v132, s[20:21]
	s_add_i32 m0, s71, 0xe000
	s_nop 0
	global_load_lds_dwordx4 v134, s[20:21]
	s_waitcnt vmcnt(8)
	s_waitcnt lgkmcnt(0)
	s_barrier
	s_setprio 1
	s_waitcnt lgkmcnt(0)
	v_mfma_f32_16x16x32_bf16 v[124:127], v[140:143], v[198:201], v[124:127]
	v_mfma_f32_16x16x32_bf16 v[120:123], v[172:175], v[198:201], v[120:123]
	v_mfma_f32_16x16x32_bf16 v[108:111], v[140:143], v[206:209], v[108:111]
	v_mfma_f32_16x16x32_bf16 v[104:107], v[172:175], v[206:209], v[104:107]
	v_mfma_f32_16x16x32_bf16 v[92:95], v[140:143], v[214:217], v[92:95]
	v_mfma_f32_16x16x32_bf16 v[88:91], v[172:175], v[214:217], v[88:91]
	v_mfma_f32_16x16x32_bf16 v[76:79], v[140:143], v[222:225], v[76:79]
	v_mfma_f32_16x16x32_bf16 v[72:75], v[172:175], v[222:225], v[72:75]
	v_mfma_f32_16x16x32_bf16 v[124:127], v[168:171], v[202:205], v[124:127]
	v_mfma_f32_16x16x32_bf16 v[120:123], v[176:179], v[202:205], v[120:123]
	v_mfma_f32_16x16x32_bf16 v[108:111], v[168:171], v[210:213], v[108:111]
	v_mfma_f32_16x16x32_bf16 v[104:107], v[176:179], v[210:213], v[104:107]
	v_mfma_f32_16x16x32_bf16 v[92:95], v[168:171], v[218:221], v[92:95]
	v_mfma_f32_16x16x32_bf16 v[88:91], v[176:179], v[218:221], v[88:91]
	v_mfma_f32_16x16x32_bf16 v[76:79], v[168:171], v[226:229], v[76:79]
	v_mfma_f32_16x16x32_bf16 v[72:75], v[176:179], v[226:229], v[72:75]
	v_mfma_f32_16x16x32_bf16 v[116:119], v[180:183], v[198:201], v[116:119]
	v_mfma_f32_16x16x32_bf16 v[112:115], v[188:191], v[198:201], v[112:115]
	v_mfma_f32_16x16x32_bf16 v[100:103], v[180:183], v[206:209], v[100:103]
	v_mfma_f32_16x16x32_bf16 v[96:99], v[188:191], v[206:209], v[96:99]
	v_mfma_f32_16x16x32_bf16 v[84:87], v[180:183], v[214:217], v[84:87]
	v_mfma_f32_16x16x32_bf16 v[80:83], v[188:191], v[214:217], v[80:83]
	v_mfma_f32_16x16x32_bf16 v[68:71], v[180:183], v[222:225], v[68:71]
	v_mfma_f32_16x16x32_bf16 v[64:67], v[188:191], v[222:225], v[64:67]
	v_mfma_f32_16x16x32_bf16 v[116:119], v[184:187], v[202:205], v[116:119]
	v_mfma_f32_16x16x32_bf16 v[112:115], v[192:195], v[202:205], v[112:115]
	v_mfma_f32_16x16x32_bf16 v[100:103], v[184:187], v[210:213], v[100:103]
	v_mfma_f32_16x16x32_bf16 v[96:99], v[192:195], v[210:213], v[96:99]
	v_mfma_f32_16x16x32_bf16 v[84:87], v[184:187], v[218:221], v[84:87]
	v_mfma_f32_16x16x32_bf16 v[80:83], v[192:195], v[218:221], v[80:83]
	v_mfma_f32_16x16x32_bf16 v[68:71], v[184:187], v[226:229], v[68:71]
	v_mfma_f32_16x16x32_bf16 v[64:67], v[192:195], v[226:229], v[64:67]
	s_setprio 0
	s_barrier
; #define PG8_STAGE(bufoff, gbase, voff) do { _Pragma("unroll") for (int _i = 0; _i < 2; ++_i) \
;         __builtin_amdgcn_global_load_lds((const unsigned*)((const char*)(gbase) + (voff)[_i]), (PG8_LAS unsigned*)(lds + (bufoff) + ldsw + _i * 8192), 16, 0, 0); } while (0)
; #define PG8_LDA(dst, b, h) do { _Pragma("unroll") for (int m = 0; m < 4; ++m) _Pragma("unroll") for (int k = 0; k < 2; ++k) dst[m][k] = *(const PG8_LAS bf16x8*)(lds + PG8_SA(b, h) + aoff + m * 2048 + k * 1024); } while (0)
; #define PG8_LDB(dst, b, h) do { _Pragma("unroll") for (int n = 0; n < 2; ++n) _Pragma("unroll") for (int k = 0; k < 2; ++k) dst[n][k] = *(const PG8_LAS bf16x8*)(lds + PG8_SB(b, h) + boff + n * 2048 + k * 1024); } while (0)
; #define PG8_MMA(ai, bj, At, Bt) do { __builtin_amdgcn_s_setprio(1); _Pragma("unroll") for (int m = 0; m < 4; ++m) _Pragma("unroll") for (int n = 0; n < 2; ++n) _Pragma("unroll") for (int k = 0; k < 2; ++k) \
;         acc[ai][bj][m][n] = __builtin_amdgcn_mfma_f32_16x16x32_bf16(Bt[n][k], At[m][k], acc[ai][bj][m][n], 0, 0, 0); __builtin_amdgcn_s_setprio(0); } while (0)
; #define PG8_WAIT_V(n) asm volatile("s_waitcnt vmcnt(" #n ")" ::: "memory")
; #define PG8_WAIT_L(n) asm volatile("s_waitcnt lgkmcnt(" #n ")" ::: "memory")
; #define PG8_BAR __builtin_amdgcn_s_barrier()
; #define PG8_SCHED __builtin_amdgcn_sched_barrier(0)
; template <class Epi, class Sched, bool ALIGN_EPI = false, bool SP2 = false>
; __device__ __forceinline__ void gemm_phase(PG8_LAS unsigned char* lds, const Gemm g, const Sched& S, const Epi& E) {
;     ...
;             PG8_LDA(At, 0, 1); PG8_STAGE(PG8_SB(0, 0), b2, voffB); PG8_STAGE(PG8_SB(0, 1), b2 + hstep, voffB); PG8_STAGE(PG8_SA(0, 0), a2, voffA);
;             PG8_WAIT_V(8); PG8_WAIT_L(0); PG8_BAR; PG8_MMA(1, 0, At, B0); PG8_MMA(1, 1, At, B1); PG8_BAR; PG8_SCHED;
;             PG8_LDB(B0, 1, 0); PG8_LDB(B1, 1, 1); PG8_SCHED; PG8_LDA(At, 1, 0); PG8_STAGE(PG8_SA(0, 1), a2 + hstep, voffA);
;             PG8_WAIT_V(8); PG8_WAIT_L(0); PG8_BAR; PG8_MMA(0, 0, At, B0); PG8_MMA(0, 1, At, B1); PG8_BAR; PG8_SCHED;
	s_add_i32 s89, s77, s70
	s_add_u32 s98, s34, s18
	s_addc_u32 s99, s35, s19
	s_add_u32 s100, s62, s18
	s_addc_u32 s101, s63, s19
	s_mov_b32 m0, s89
	ds_read_b128 v[198:201], v165 offset:16384
	ds_read_b128 v[202:205], v165 offset:17408
	ds_read_b128 v[206:209], v165 offset:18432
	ds_read_b128 v[210:213], v165 offset:19456
	ds_read_b128 v[214:217], v165 offset:20480
	ds_read_b128 v[218:221], v165 offset:21504
	ds_read_b128 v[222:225], v165 offset:22528
	ds_read_b128 v[226:229], v165 offset:23552
	global_load_lds_dwordx4 v146, s[34:35]
	s_add_i32 m0, s89, 0x2000
	s_add_u32 s90, s34, 0x40000
	s_addc_u32 s91, s35, 0
	s_add_i32 s89, s78, s70
	global_load_lds_dwordx4 v150, s[34:35]
	s_mov_b32 m0, s89
	s_nop 0
	global_load_lds_dwordx4 v146, s[90:91]
	s_add_i32 m0, s89, 0x2000
	s_nop 0
	global_load_lds_dwordx4 v150, s[90:91]
	s_mov_b32 m0, s71
	s_nop 0
	global_load_lds_dwordx4 v144, s[62:63]
	s_mov_b32 m0, s72
	s_nop 0
	global_load_lds_dwordx4 v148, s[62:63]
	s_waitcnt vmcnt(8)
	s_waitcnt lgkmcnt(0)
	s_barrier
	s_setprio 1
	s_waitcnt lgkmcnt(0)
	v_mfma_f32_16x16x32_bf16 v[60:63], v[140:143], v[198:201], v[60:63]
	v_mfma_f32_16x16x32_bf16 v[56:59], v[172:175], v[198:201], v[56:59]
	v_mfma_f32_16x16x32_bf16 v[48:51], v[140:143], v[206:209], v[48:51]
	v_mfma_f32_16x16x32_bf16 v[40:43], v[172:175], v[206:209], v[40:43]
	v_mfma_f32_16x16x32_bf16 v[32:35], v[140:143], v[214:217], v[32:35]
	v_mfma_f32_16x16x32_bf16 v[24:27], v[172:175], v[214:217], v[24:27]
	v_mfma_f32_16x16x32_bf16 v[16:19], v[140:143], v[222:225], v[16:19]
	v_mfma_f32_16x16x32_bf16 v[8:11], v[172:175], v[222:225], v[8:11]
	v_mfma_f32_16x16x32_bf16 v[60:63], v[168:171], v[202:205], v[60:63]
	v_mfma_f32_16x16x32_bf16 v[56:59], v[176:179], v[202:205], v[56:59]
	v_mfma_f32_16x16x32_bf16 v[48:51], v[168:171], v[210:213], v[48:51]
	v_mfma_f32_16x16x32_bf16 v[40:43], v[176:179], v[210:213], v[40:43]
	v_mfma_f32_16x16x32_bf16 v[32:35], v[168:171], v[218:221], v[32:35]
	v_mfma_f32_16x16x32_bf16 v[24:27], v[176:179], v[218:221], v[24:27]
	v_mfma_f32_16x16x32_bf16 v[16:19], v[168:171], v[226:229], v[16:19]
	v_mfma_f32_16x16x32_bf16 v[8:11], v[176:179], v[226:229], v[8:11]
	v_mfma_f32_16x16x32_bf16 v[52:55], v[180:183], v[198:201], v[52:55]
	v_mfma_f32_16x16x32_bf16 v[44:47], v[188:191], v[198:201], v[44:47]
	v_mfma_f32_16x16x32_bf16 v[36:39], v[180:183], v[206:209], v[36:39]
	v_mfma_f32_16x16x32_bf16 v[28:31], v[188:191], v[206:209], v[28:31]
	v_mfma_f32_16x16x32_bf16 v[20:23], v[180:183], v[214:217], v[20:23]
	v_mfma_f32_16x16x32_bf16 v[12:15], v[188:191], v[214:217], v[12:15]
	v_mfma_f32_16x16x32_bf16 v[4:7], v[180:183], v[222:225], v[4:7]
	v_mfma_f32_16x16x32_bf16 v[0:3], v[188:191], v[222:225], v[0:3]
	v_mfma_f32_16x16x32_bf16 v[52:55], v[184:187], v[202:205], v[52:55]
	v_mfma_f32_16x16x32_bf16 v[44:47], v[192:195], v[202:205], v[44:47]
	v_mfma_f32_16x16x32_bf16 v[36:39], v[184:187], v[210:213], v[36:39]
	v_mfma_f32_16x16x32_bf16 v[28:31], v[192:195], v[210:213], v[28:31]
	v_mfma_f32_16x16x32_bf16 v[20:23], v[184:187], v[218:221], v[20:23]
	v_mfma_f32_16x16x32_bf16 v[12:15], v[192:195], v[218:221], v[12:15]
	v_mfma_f32_16x16x32_bf16 v[4:7], v[184:187], v[226:229], v[4:7]
	v_mfma_f32_16x16x32_bf16 v[0:3], v[192:195], v[226:229], v[0:3]
	s_setprio 0
	s_barrier
	s_add_i32 s89, 0, 0x18000
	v_add_u32_e32 v128, s89, v161
	s_add_i32 s90, 0, 0x1c000
	ds_read_b128 v[140:143], v128
	ds_read_b128 v[168:171], v128 offset:1024
	ds_read_b128 v[172:175], v128 offset:2048
	ds_read_b128 v[176:179], v128 offset:3072
	v_add_u32_e32 v128, s90, v161
	ds_read_b128 v[180:183], v128
	ds_read_b128 v[184:187], v128 offset:1024
	ds_read_b128 v[188:191], v128 offset:2048
	ds_read_b128 v[192:195], v128 offset:3072
	s_add_u32 s62, s62, 0x40000
	s_addc_u32 s63, s63, 0
	s_mov_b32 m0, s73
	ds_read_b128 v[198:201], v165 offset:32768
	ds_read_b128 v[202:205], v165 offset:33792
	ds_read_b128 v[206:209], v165 offset:34816
	ds_read_b128 v[210:213], v165 offset:35840
	ds_read_b128 v[214:217], v165 offset:36864
	ds_read_b128 v[218:221], v165 offset:37888
	ds_read_b128 v[222:225], v165 offset:38912
	ds_read_b128 v[226:229], v165 offset:39936
	global_load_lds_dwordx4 v144, s[62:63]
	s_mov_b32 m0, s74
	s_nop 0
	global_load_lds_dwordx4 v148, s[62:63]
	s_waitcnt vmcnt(8)
	s_waitcnt lgkmcnt(0)
	s_barrier
; #define PG8_STAGE(bufoff, gbase, voff) do { _Pragma("unroll") for (int _i = 0; _i < 2; ++_i) \
;         __builtin_amdgcn_global_load_lds((const unsigned*)((const char*)(gbase) + (voff)[_i]), (PG8_LAS unsigned*)(lds + (bufoff) + ldsw + _i * 8192), 16, 0, 0); } while (0)
; #define PG8_LDA(dst, b, h) do { _Pragma("unroll") for (int m = 0; m < 4; ++m) _Pragma("unroll") for (int k = 0; k < 2; ++k) dst[m][k] = *(const PG8_LAS bf16x8*)(lds + PG8_SA(b, h) + aoff + m * 2048 + k * 1024); } while (0)
; #define PG8_MMA(ai, bj, At, Bt) do { __builtin_amdgcn_s_setprio(1); _Pragma("unroll") for (int m = 0; m < 4; ++m) _Pragma("unroll") for (int n = 0; n < 2; ++n) _Pragma("unroll") for (int k = 0; k < 2; ++k) \
;         acc[ai][bj][m][n] = __builtin_amdgcn_mfma_f32_16x16x32_bf16(Bt[n][k], At[m][k], acc[ai][bj][m][n], 0, 0, 0); __builtin_amdgcn_s_setprio(0); } while (0)
; #define PG8_WAIT_V(n) asm volatile("s_waitcnt vmcnt(" #n ")" ::: "memory")
; #define PG8_WAIT_L(n) asm volatile("s_waitcnt lgkmcnt(" #n ")" ::: "memory")
; #define PG8_BAR __builtin_amdgcn_s_barrier()
; #define PG8_SCHED __builtin_amdgcn_sched_barrier(0)
; template <class Epi, class Sched, bool ALIGN_EPI = false, bool SP2 = false>
; __device__ __forceinline__ void gemm_phase(PG8_LAS unsigned char* lds, const Gemm g, const Sched& S, const Epi& E) {
;     ...
;             PG8_WAIT_V(8); PG8_WAIT_L(0); PG8_BAR; PG8_MMA(0, 0, At, B0); PG8_MMA(0, 1, At, B1); PG8_BAR; PG8_SCHED;
;             PG8_LDA(At, 1, 1); PG8_STAGE(PG8_SB(1, 0), b3, voffB); PG8_STAGE(PG8_SB(1, 1), b3 + hstep, voffB); PG8_STAGE(PG8_SA(1, 0), a3, voffA);
;             PG8_WAIT_V(8); PG8_WAIT_L(0); PG8_BAR; PG8_MMA(1, 0, At, B0); PG8_MMA(1, 1, At, B1); PG8_BAR; PG8_SCHED;
	s_setprio 1
	s_waitcnt lgkmcnt(0)
	v_mfma_f32_16x16x32_bf16 v[124:127], v[140:143], v[198:201], v[124:127]
	v_mfma_f32_16x16x32_bf16 v[120:123], v[172:175], v[198:201], v[120:123]
	v_mfma_f32_16x16x32_bf16 v[108:111], v[140:143], v[206:209], v[108:111]
	v_mfma_f32_16x16x32_bf16 v[104:107], v[172:175], v[206:209], v[104:107]
	v_mfma_f32_16x16x32_bf16 v[92:95], v[140:143], v[214:217], v[92:95]
	v_mfma_f32_16x16x32_bf16 v[88:91], v[172:175], v[214:217], v[88:91]
	v_mfma_f32_16x16x32_bf16 v[76:79], v[140:143], v[222:225], v[76:79]
	v_mfma_f32_16x16x32_bf16 v[72:75], v[172:175], v[222:225], v[72:75]
	v_mfma_f32_16x16x32_bf16 v[124:127], v[168:171], v[202:205], v[124:127]
	v_mfma_f32_16x16x32_bf16 v[120:123], v[176:179], v[202:205], v[120:123]
	v_mfma_f32_16x16x32_bf16 v[108:111], v[168:171], v[210:213], v[108:111]
	v_mfma_f32_16x16x32_bf16 v[104:107], v[176:179], v[210:213], v[104:107]
	v_mfma_f32_16x16x32_bf16 v[92:95], v[168:171], v[218:221], v[92:95]
	v_mfma_f32_16x16x32_bf16 v[88:91], v[176:179], v[218:221], v[88:91]
	v_mfma_f32_16x16x32_bf16 v[76:79], v[168:171], v[226:229], v[76:79]
	v_mfma_f32_16x16x32_bf16 v[72:75], v[176:179], v[226:229], v[72:75]
	v_mfma_f32_16x16x32_bf16 v[116:119], v[180:183], v[198:201], v[116:119]
	v_mfma_f32_16x16x32_bf16 v[112:115], v[188:191], v[198:201], v[112:115]
	v_mfma_f32_16x16x32_bf16 v[100:103], v[180:183], v[206:209], v[100:103]
	v_mfma_f32_16x16x32_bf16 v[96:99], v[188:191], v[206:209], v[96:99]
	v_mfma_f32_16x16x32_bf16 v[84:87], v[180:183], v[214:217], v[84:87]
	v_mfma_f32_16x16x32_bf16 v[80:83], v[188:191], v[214:217], v[80:83]
	v_mfma_f32_16x16x32_bf16 v[68:71], v[180:183], v[222:225], v[68:71]
	v_mfma_f32_16x16x32_bf16 v[64:67], v[188:191], v[222:225], v[64:67]
	v_mfma_f32_16x16x32_bf16 v[116:119], v[184:187], v[202:205], v[116:119]
	v_mfma_f32_16x16x32_bf16 v[112:115], v[192:195], v[202:205], v[112:115]
	v_mfma_f32_16x16x32_bf16 v[100:103], v[184:187], v[210:213], v[100:103]
	v_mfma_f32_16x16x32_bf16 v[96:99], v[192:195], v[210:213], v[96:99]
	v_mfma_f32_16x16x32_bf16 v[84:87], v[184:187], v[218:221], v[84:87]
	v_mfma_f32_16x16x32_bf16 v[80:83], v[192:195], v[218:221], v[80:83]
	v_mfma_f32_16x16x32_bf16 v[68:71], v[184:187], v[226:229], v[68:71]
	v_mfma_f32_16x16x32_bf16 v[64:67], v[192:195], v[226:229], v[64:67]
	s_setprio 0
	s_barrier
	s_add_i32 s62, s89, s70
	s_mov_b32 m0, s62
	ds_read_b128 v[198:201], v165 offset:49152
	ds_read_b128 v[202:205], v165 offset:50176
	ds_read_b128 v[206:209], v165 offset:51200
	ds_read_b128 v[210:213], v165 offset:52224
	ds_read_b128 v[214:217], v165 offset:53248
	ds_read_b128 v[218:221], v165 offset:54272
	ds_read_b128 v[222:225], v165 offset:55296
	ds_read_b128 v[226:229], v165 offset:56320
	global_load_lds_dwordx4 v146, s[98:99]
	s_add_i32 m0, s62, 0x2000
	s_add_u32 s34, s34, 0x40080
	s_addc_u32 s35, s35, 0
	s_add_i32 s62, s90, s70
	global_load_lds_dwordx4 v150, s[98:99]
	s_mov_b32 m0, s62
	s_nop 0
	global_load_lds_dwordx4 v146, s[34:35]
	s_add_i32 m0, s62, 0x2000
	s_nop 0
	global_load_lds_dwordx4 v150, s[34:35]
	s_mov_b32 m0, s75
	s_nop 0
	global_load_lds_dwordx4 v144, s[100:101]
	s_mov_b32 m0, s76
	s_nop 0
	global_load_lds_dwordx4 v148, s[100:101]
	s_waitcnt vmcnt(8)
	s_waitcnt lgkmcnt(0)
	s_barrier
	s_setprio 1
	s_waitcnt lgkmcnt(0)
	v_mfma_f32_16x16x32_bf16 v[60:63], v[140:143], v[198:201], v[60:63]
	v_mfma_f32_16x16x32_bf16 v[56:59], v[172:175], v[198:201], v[56:59]
	v_mfma_f32_16x16x32_bf16 v[48:51], v[140:143], v[206:209], v[48:51]
	v_mfma_f32_16x16x32_bf16 v[40:43], v[172:175], v[206:209], v[40:43]
	v_mfma_f32_16x16x32_bf16 v[32:35], v[140:143], v[214:217], v[32:35]
	v_mfma_f32_16x16x32_bf16 v[24:27], v[172:175], v[214:217], v[24:27]
	v_mfma_f32_16x16x32_bf16 v[16:19], v[140:143], v[222:225], v[16:19]
	v_mfma_f32_16x16x32_bf16 v[8:11], v[172:175], v[222:225], v[8:11]
	v_mfma_f32_16x16x32_bf16 v[60:63], v[168:171], v[202:205], v[60:63]
	v_mfma_f32_16x16x32_bf16 v[56:59], v[176:179], v[202:205], v[56:59]
	v_mfma_f32_16x16x32_bf16 v[48:51], v[168:171], v[210:213], v[48:51]
	v_mfma_f32_16x16x32_bf16 v[40:43], v[176:179], v[210:213], v[40:43]
	v_mfma_f32_16x16x32_bf16 v[32:35], v[168:171], v[218:221], v[32:35]
	v_mfma_f32_16x16x32_bf16 v[24:27], v[176:179], v[218:221], v[24:27]
	v_mfma_f32_16x16x32_bf16 v[16:19], v[168:171], v[226:229], v[16:19]
	v_mfma_f32_16x16x32_bf16 v[8:11], v[176:179], v[226:229], v[8:11]
	v_mfma_f32_16x16x32_bf16 v[52:55], v[180:183], v[198:201], v[52:55]
	v_mfma_f32_16x16x32_bf16 v[44:47], v[188:191], v[198:201], v[44:47]
	v_mfma_f32_16x16x32_bf16 v[36:39], v[180:183], v[206:209], v[36:39]
	v_mfma_f32_16x16x32_bf16 v[28:31], v[188:191], v[206:209], v[28:31]
	v_mfma_f32_16x16x32_bf16 v[20:23], v[180:183], v[214:217], v[20:23]
	v_mfma_f32_16x16x32_bf16 v[12:15], v[188:191], v[214:217], v[12:15]
	v_mfma_f32_16x16x32_bf16 v[4:7], v[180:183], v[222:225], v[4:7]
	v_mfma_f32_16x16x32_bf16 v[0:3], v[188:191], v[222:225], v[0:3]
	v_mfma_f32_16x16x32_bf16 v[52:55], v[184:187], v[202:205], v[52:55]
	v_mfma_f32_16x16x32_bf16 v[44:47], v[192:195], v[202:205], v[44:47]
	v_mfma_f32_16x16x32_bf16 v[36:39], v[184:187], v[210:213], v[36:39]
	v_mfma_f32_16x16x32_bf16 v[28:31], v[192:195], v[210:213], v[28:31]
	v_mfma_f32_16x16x32_bf16 v[20:23], v[184:187], v[218:221], v[20:23]
	v_mfma_f32_16x16x32_bf16 v[12:15], v[192:195], v[218:221], v[12:15]
	v_mfma_f32_16x16x32_bf16 v[4:7], v[184:187], v[226:229], v[4:7]
	v_mfma_f32_16x16x32_bf16 v[0:3], v[192:195], v[226:229], v[0:3]
	s_setprio 0
	s_barrier
	s_add_i32 s88, s88, 2
	s_add_u32 s20, s20, 0x100
	s_addc_u32 s21, s21, 0
	s_add_u32 s86, s86, 0x100
	s_addc_u32 s87, s87, 0
	s_cmp_gt_u32 s88, 13
	s_cbranch_scc0 .LBB0_1200
	s_and_b64 vcc, exec, s[38:39]
	s_cbranch_vccz .LBB0_1203
	s_barrier

; #define PG8_STAGE(bufoff, gbase, voff) do { _Pragma("unroll") for (int _i = 0; _i < 2; ++_i) \
;         __builtin_amdgcn_global_load_lds((const unsigned*)((const char*)(gbase) + (voff)[_i]), (PG8_LAS unsigned*)(lds + (bufoff) + ldsw + _i * 8192), 16, 0, 0); } while (0)
; #define PG8_LDA(dst, b, h) do { _Pragma("unroll") for (int m = 0; m < 4; ++m) _Pragma("unroll") for (int k = 0; k < 2; ++k) dst[m][k] = *(const PG8_LAS bf16x8*)(lds + PG8_SA(b, h) + aoff + m * 2048 + k * 1024); } while (0)
; #define PG8_LDB(dst, b, h) do { _Pragma("unroll") for (int n = 0; n < 2; ++n) _Pragma("unroll") for (int k = 0; k < 2; ++k) dst[n][k] = *(const PG8_LAS bf16x8*)(lds + PG8_SB(b, h) + boff + n * 2048 + k * 1024); } while (0)
; #define PG8_MMA(ai, bj, At, Bt) do { __builtin_amdgcn_s_setprio(1); _Pragma("unroll") for (int m = 0; m < 4; ++m) _Pragma("unroll") for (int n = 0; n < 2; ++n) _Pragma("unroll") for (int k = 0; k < 2; ++k) \
;         acc[ai][bj][m][n] = __builtin_amdgcn_mfma_f32_16x16x32_bf16(Bt[n][k], At[m][k], acc[ai][bj][m][n], 0, 0, 0); __builtin_amdgcn_s_setprio(0); } while (0)
; #define PG8_WAIT_V(n) asm volatile("s_waitcnt vmcnt(" #n ")" ::: "memory")
; template <class Epi, class Sched, bool ALIGN_EPI = false, bool SP2 = false>
; __device__ __forceinline__ void gemm_phase(PG8_LAS unsigned char* lds, const Gemm g, const Sched& S, const Epi& E) {
;     ...
;         const char* nA = has_next ? (const char*)g.A + (size_t)nxt.pm * tstep : cA; const char* nB = has_next ? (const char*)g.Bt + (size_t)nxt.pn * tstep : cB;
;         for (int t = 0; t < nt; t += 2) {
;             const bool last = (t == nt - 2);
;             const char* a1 = cA + (size_t)(t + 1) * kstep;
;             const char* a2 = last ? nA : cA + (size_t)(t + 2) * kstep; const char* b2 = last ? nB : cB + (size_t)(t + 2) * kstep;
;             const char* a3 = a2 + kstep; const char* b3 = b2 + kstep;
;             if (last && has_next) S.a_ready(nxt);
;             if constexpr (SP2) {
;             PG8_LDB(B0, 0, 0); PG8_LDB(B1, 0, 1); PG8_SCHED; PG8_LDA(At, 0, 0); PG8_STAGE(PG8_SA(1, 1), a1 + hstep, voffA);
;             PG8_WAIT_V(8); PG8_WAIT_L(0); PG8_BAR; PG8_MMA(0, 0, At, B0); PG8_MMA(0, 1, At, B1); PG8_BAR; PG8_SCHED;
;             PG8_LDA(At, 0, 1); PG8_STAGE(PG8_SB(0, 0), b2, voffB); PG8_STAGE(PG8_SB(0, 1), b2 + hstep, voffB); PG8_STAGE(PG8_SA(0, 0), a2, voffA);
.LBB0_1445:
	s_ashr_i32 s15, s14, 31
	s_lshl_b64 s[16:17], s[14:15], 19
	s_add_u32 s16, s49, s16
	s_addc_u32 s17, s50, s17
	s_and_b64 s[18:19], s[4:5], exec
	s_cselect_b32 s15, s17, s21
	s_cselect_b32 s65, s16, s20
	s_ashr_i32 s13, s12, 31
	s_lshl_b64 s[18:19], s[12:13], 19
	s_add_u32 s18, s36, s18
	s_addc_u32 s19, s37, s19
	s_and_b64 s[44:45], s[4:5], exec
	s_cselect_b32 s13, s19, s39
	s_cselect_b32 s66, s18, s38
	s_add_u32 s20, s20, 0x40080
	s_addc_u32 s21, s21, 0
	s_add_u32 s67, s38, 0x100
	s_addc_u32 s68, s39, 0
	s_mov_b32 s69, -2
	ds_read_b128 v[128:131], v153
	ds_read_b128 v[132:135], v153 offset:1024
	ds_read_b128 v[136:139], v153 offset:2048
	ds_read_b128 v[140:143], v153 offset:3072
	ds_read_b128 v[172:175], v155
	ds_read_b128 v[176:179], v155 offset:1024
	ds_read_b128 v[180:183], v155 offset:2048
	ds_read_b128 v[184:187], v155 offset:3072
	s_add_u32 s38, s20, 0xfffc0080
	s_addc_u32 s39, s21, -1
	s_cmp_eq_u32 s69, 12
	s_cselect_b32 s45, s15, s39
	s_cselect_b32 s44, s65, s38
	s_cselect_b32 s39, s13, s68
	s_cselect_b32 s38, s66, s67
	s_add_i32 m0, s35, 0xc000
	ds_read_b128 v[188:191], v157
	ds_read_b128 v[192:195], v157 offset:1024
	ds_read_b128 v[198:201], v157 offset:2048
	ds_read_b128 v[202:205], v157 offset:3072
	ds_read_b128 v[206:209], v157 offset:4096
	ds_read_b128 v[210:213], v157 offset:5120
	ds_read_b128 v[214:217], v157 offset:6144
	ds_read_b128 v[218:221], v157 offset:7168
	global_load_lds_dwordx4 v162, s[20:21]
	s_add_i32 m0, s35, 0xe000
	s_nop 0
	global_load_lds_dwordx4 v164, s[20:21]
	s_waitcnt vmcnt(8)
	s_waitcnt lgkmcnt(0)
	s_barrier
	s_setprio 1
	s_waitcnt lgkmcnt(0)
	v_mfma_f32_16x16x32_bf16 v[124:127], v[128:131], v[188:191], 0
	v_mfma_f32_16x16x32_bf16 v[120:123], v[136:139], v[188:191], 0
	v_mfma_f32_16x16x32_bf16 v[108:111], v[128:131], v[198:201], 0
	v_mfma_f32_16x16x32_bf16 v[104:107], v[136:139], v[198:201], 0
	v_mfma_f32_16x16x32_bf16 v[96:99], v[128:131], v[206:209], 0
	v_mfma_f32_16x16x32_bf16 v[88:91], v[136:139], v[206:209], 0
	v_mfma_f32_16x16x32_bf16 v[80:83], v[128:131], v[214:217], 0
	v_mfma_f32_16x16x32_bf16 v[72:75], v[136:139], v[214:217], 0
	v_mfma_f32_16x16x32_bf16 v[124:127], v[132:135], v[192:195], v[124:127]
	v_mfma_f32_16x16x32_bf16 v[120:123], v[140:143], v[192:195], v[120:123]
	v_mfma_f32_16x16x32_bf16 v[108:111], v[132:135], v[202:205], v[108:111]
	v_mfma_f32_16x16x32_bf16 v[104:107], v[140:143], v[202:205], v[104:107]
	v_mfma_f32_16x16x32_bf16 v[96:99], v[132:135], v[210:213], v[96:99]
	v_mfma_f32_16x16x32_bf16 v[88:91], v[140:143], v[210:213], v[88:91]
	v_mfma_f32_16x16x32_bf16 v[80:83], v[132:135], v[218:221], v[80:83]
	v_mfma_f32_16x16x32_bf16 v[72:75], v[140:143], v[218:221], v[72:75]
	v_mfma_f32_16x16x32_bf16 v[116:119], v[172:175], v[188:191], 0
	v_mfma_f32_16x16x32_bf16 v[112:115], v[180:183], v[188:191], 0
	v_mfma_f32_16x16x32_bf16 v[100:103], v[172:175], v[198:201], 0
	v_mfma_f32_16x16x32_bf16 v[92:95], v[180:183], v[198:201], 0
	v_mfma_f32_16x16x32_bf16 v[84:87], v[172:175], v[206:209], 0
	v_mfma_f32_16x16x32_bf16 v[76:79], v[180:183], v[206:209], 0
	v_mfma_f32_16x16x32_bf16 v[68:71], v[172:175], v[214:217], 0
	v_mfma_f32_16x16x32_bf16 v[64:67], v[180:183], v[214:217], 0
	v_mfma_f32_16x16x32_bf16 v[116:119], v[176:179], v[192:195], v[116:119]
	v_mfma_f32_16x16x32_bf16 v[112:115], v[184:187], v[192:195], v[112:115]
	v_mfma_f32_16x16x32_bf16 v[100:103], v[176:179], v[202:205], v[100:103]
	v_mfma_f32_16x16x32_bf16 v[92:95], v[184:187], v[202:205], v[92:95]
	v_mfma_f32_16x16x32_bf16 v[84:87], v[176:179], v[210:213], v[84:87]
	v_mfma_f32_16x16x32_bf16 v[76:79], v[184:187], v[210:213], v[76:79]
	v_mfma_f32_16x16x32_bf16 v[68:71], v[176:179], v[218:221], v[68:71]
	v_mfma_f32_16x16x32_bf16 v[64:67], v[184:187], v[218:221], v[64:67]
	s_setprio 0
	s_barrier
	s_add_i32 s70, s60, s51
	s_add_u32 s98, s38, s6
	s_addc_u32 s99, s39, s7
	s_add_u32 s100, s44, s6
	s_addc_u32 s101, s45, s7
	s_mov_b32 m0, s70
	ds_read_b128 v[188:191], v157 offset:16384
	ds_read_b128 v[192:195], v157 offset:17408
	ds_read_b128 v[198:201], v157 offset:18432
	ds_read_b128 v[202:205], v157 offset:19456
	ds_read_b128 v[206:209], v157 offset:20480
	ds_read_b128 v[210:213], v157 offset:21504
	ds_read_b128 v[214:217], v157 offset:22528
	ds_read_b128 v[218:221], v157 offset:23552
	global_load_lds_dwordx4 v146, s[38:39]
	s_add_i32 m0, s70, 0x2000
	s_add_u32 s70, s38, 0x40000
	s_addc_u32 s71, s39, 0
	s_add_i32 s72, s61, s51
	global_load_lds_dwordx4 v150, s[38:39]
	s_mov_b32 m0, s72
	s_nop 0
	global_load_lds_dwordx4 v146, s[70:71]
	s_add_i32 m0, s72, 0x2000
	s_nop 0
	global_load_lds_dwordx4 v150, s[70:71]
	s_mov_b32 m0, s35
	s_nop 0
	global_load_lds_dwordx4 v144, s[44:45]
	s_mov_b32 m0, s52
	s_nop 0
	global_load_lds_dwordx4 v148, s[44:45]
	s_waitcnt vmcnt(8)
	s_waitcnt lgkmcnt(0)
	s_barrier
; #define PG8_STAGE(bufoff, gbase, voff) do { _Pragma("unroll") for (int _i = 0; _i < 2; ++_i) \
;         __builtin_amdgcn_global_load_lds((const unsigned*)((const char*)(gbase) + (voff)[_i]), (PG8_LAS unsigned*)(lds + (bufoff) + ldsw + _i * 8192), 16, 0, 0); } while (0)
; #define PG8_LDA(dst, b, h) do { _Pragma("unroll") for (int m = 0; m < 4; ++m) _Pragma("unroll") for (int k = 0; k < 2; ++k) dst[m][k] = *(const PG8_LAS bf16x8*)(lds + PG8_SA(b, h) + aoff + m * 2048 + k * 1024); } while (0)
; #define PG8_LDB(dst, b, h) do { _Pragma("unroll") for (int n = 0; n < 2; ++n) _Pragma("unroll") for (int k = 0; k < 2; ++k) dst[n][k] = *(const PG8_LAS bf16x8*)(lds + PG8_SB(b, h) + boff + n * 2048 + k * 1024); } while (0)
; #define PG8_MMA(ai, bj, At, Bt) do { __builtin_amdgcn_s_setprio(1); _Pragma("unroll") for (int m = 0; m < 4; ++m) _Pragma("unroll") for (int n = 0; n < 2; ++n) _Pragma("unroll") for (int k = 0; k < 2; ++k) \
;         acc[ai][bj][m][n] = __builtin_amdgcn_mfma_f32_16x16x32_bf16(Bt[n][k], At[m][k], acc[ai][bj][m][n], 0, 0, 0); __builtin_amdgcn_s_setprio(0); } while (0)
; #define PG8_WAIT_V(n) asm volatile("s_waitcnt vmcnt(" #n ")" ::: "memory")
; #define PG8_WAIT_L(n) asm volatile("s_waitcnt lgkmcnt(" #n ")" ::: "memory")
; #define PG8_BAR __builtin_amdgcn_s_barrier()
; #define PG8_SCHED __builtin_amdgcn_sched_barrier(0)
; template <class Epi, class Sched, bool ALIGN_EPI = false, bool SP2 = false>
; __device__ __forceinline__ void gemm_phase(PG8_LAS unsigned char* lds, const Gemm g, const Sched& S, const Epi& E) {
;     ...
;             PG8_WAIT_V(8); PG8_WAIT_L(0); PG8_BAR; PG8_MMA(1, 0, At, B0); PG8_MMA(1, 1, At, B1); PG8_BAR; PG8_SCHED;
;             PG8_LDB(B0, 1, 0); PG8_LDB(B1, 1, 1); PG8_SCHED; PG8_LDA(At, 1, 0); PG8_STAGE(PG8_SA(0, 1), a2 + hstep, voffA);
;             PG8_WAIT_V(8); PG8_WAIT_L(0); PG8_BAR; PG8_MMA(0, 0, At, B0); PG8_MMA(0, 1, At, B1); PG8_BAR; PG8_SCHED;
	s_setprio 1
	s_waitcnt lgkmcnt(0)
	v_mfma_f32_16x16x32_bf16 v[60:63], v[128:131], v[188:191], 0
	v_mfma_f32_16x16x32_bf16 v[56:59], v[136:139], v[188:191], 0
	v_mfma_f32_16x16x32_bf16 v[48:51], v[128:131], v[198:201], 0
	v_mfma_f32_16x16x32_bf16 v[40:43], v[136:139], v[198:201], 0
	v_mfma_f32_16x16x32_bf16 v[32:35], v[128:131], v[206:209], 0
	v_mfma_f32_16x16x32_bf16 v[24:27], v[136:139], v[206:209], 0
	v_mfma_f32_16x16x32_bf16 v[16:19], v[128:131], v[214:217], 0
	v_mfma_f32_16x16x32_bf16 v[8:11], v[136:139], v[214:217], 0
	v_mfma_f32_16x16x32_bf16 v[60:63], v[132:135], v[192:195], v[60:63]
	v_mfma_f32_16x16x32_bf16 v[56:59], v[140:143], v[192:195], v[56:59]
	v_mfma_f32_16x16x32_bf16 v[48:51], v[132:135], v[202:205], v[48:51]
	v_mfma_f32_16x16x32_bf16 v[40:43], v[140:143], v[202:205], v[40:43]
	v_mfma_f32_16x16x32_bf16 v[32:35], v[132:135], v[210:213], v[32:35]
	v_mfma_f32_16x16x32_bf16 v[24:27], v[140:143], v[210:213], v[24:27]
	v_mfma_f32_16x16x32_bf16 v[16:19], v[132:135], v[218:221], v[16:19]
	v_mfma_f32_16x16x32_bf16 v[8:11], v[140:143], v[218:221], v[8:11]
	v_mfma_f32_16x16x32_bf16 v[52:55], v[172:175], v[188:191], 0
	v_mfma_f32_16x16x32_bf16 v[44:47], v[180:183], v[188:191], 0
	v_mfma_f32_16x16x32_bf16 v[36:39], v[172:175], v[198:201], 0
	v_mfma_f32_16x16x32_bf16 v[28:31], v[180:183], v[198:201], 0
	v_mfma_f32_16x16x32_bf16 v[20:23], v[172:175], v[206:209], 0
	v_mfma_f32_16x16x32_bf16 v[12:15], v[180:183], v[206:209], 0
	v_mfma_f32_16x16x32_bf16 v[4:7], v[172:175], v[214:217], 0
	v_mfma_f32_16x16x32_bf16 v[0:3], v[180:183], v[214:217], 0
	v_mfma_f32_16x16x32_bf16 v[52:55], v[176:179], v[192:195], v[52:55]
	v_mfma_f32_16x16x32_bf16 v[44:47], v[184:187], v[192:195], v[44:47]
	v_mfma_f32_16x16x32_bf16 v[36:39], v[176:179], v[202:205], v[36:39]
	v_mfma_f32_16x16x32_bf16 v[28:31], v[184:187], v[202:205], v[28:31]
	v_mfma_f32_16x16x32_bf16 v[20:23], v[176:179], v[210:213], v[20:23]
	v_mfma_f32_16x16x32_bf16 v[12:15], v[184:187], v[210:213], v[12:15]
	v_mfma_f32_16x16x32_bf16 v[4:7], v[176:179], v[218:221], v[4:7]
	v_mfma_f32_16x16x32_bf16 v[0:3], v[184:187], v[218:221], v[0:3]
	s_setprio 0
	s_barrier
	s_add_i32 s70, 0, 0x18000
	s_add_i32 s71, 0, 0x1c000
	v_add_u32_e32 v140, s70, v170
	v_add_u32_e32 v159, s71, v170
	ds_read_b128 v[128:131], v140
	ds_read_b128 v[132:135], v140 offset:1024
	ds_read_b128 v[136:139], v140 offset:2048
	ds_read_b128 v[140:143], v140 offset:3072
	ds_read_b128 v[172:175], v159
	ds_read_b128 v[176:179], v159 offset:1024
	ds_read_b128 v[180:183], v159 offset:2048
	ds_read_b128 v[184:187], v159 offset:3072
	s_add_u32 s44, s44, 0x40000
	s_addc_u32 s45, s45, 0
	s_mov_b32 m0, s53
	ds_read_b128 v[188:191], v157 offset:32768
	ds_read_b128 v[192:195], v157 offset:33792
	ds_read_b128 v[198:201], v157 offset:34816
	ds_read_b128 v[202:205], v157 offset:35840
	ds_read_b128 v[206:209], v157 offset:36864
	ds_read_b128 v[210:213], v157 offset:37888
	ds_read_b128 v[214:217], v157 offset:38912
	ds_read_b128 v[218:221], v157 offset:39936
	global_load_lds_dwordx4 v144, s[44:45]
	s_mov_b32 m0, s54
	s_nop 0
	global_load_lds_dwordx4 v148, s[44:45]
	s_waitcnt vmcnt(8)
	s_waitcnt lgkmcnt(0)
	s_barrier
	s_setprio 1
	s_waitcnt lgkmcnt(0)
	v_mfma_f32_16x16x32_bf16 v[124:127], v[128:131], v[188:191], v[124:127]
	v_mfma_f32_16x16x32_bf16 v[120:123], v[136:139], v[188:191], v[120:123]
	v_mfma_f32_16x16x32_bf16 v[108:111], v[128:131], v[198:201], v[108:111]
	v_mfma_f32_16x16x32_bf16 v[104:107], v[136:139], v[198:201], v[104:107]
	v_mfma_f32_16x16x32_bf16 v[96:99], v[128:131], v[206:209], v[96:99]
	v_mfma_f32_16x16x32_bf16 v[88:91], v[136:139], v[206:209], v[88:91]
	v_mfma_f32_16x16x32_bf16 v[80:83], v[128:131], v[214:217], v[80:83]
	v_mfma_f32_16x16x32_bf16 v[72:75], v[136:139], v[214:217], v[72:75]
	v_mfma_f32_16x16x32_bf16 v[124:127], v[132:135], v[192:195], v[124:127]
	v_mfma_f32_16x16x32_bf16 v[120:123], v[140:143], v[192:195], v[120:123]
	v_mfma_f32_16x16x32_bf16 v[108:111], v[132:135], v[202:205], v[108:111]
	v_mfma_f32_16x16x32_bf16 v[104:107], v[140:143], v[202:205], v[104:107]
	v_mfma_f32_16x16x32_bf16 v[96:99], v[132:135], v[210:213], v[96:99]
	v_mfma_f32_16x16x32_bf16 v[88:91], v[140:143], v[210:213], v[88:91]
	v_mfma_f32_16x16x32_bf16 v[80:83], v[132:135], v[218:221], v[80:83]
	v_mfma_f32_16x16x32_bf16 v[72:75], v[140:143], v[218:221], v[72:75]
	v_mfma_f32_16x16x32_bf16 v[116:119], v[172:175], v[188:191], v[116:119]
	v_mfma_f32_16x16x32_bf16 v[112:115], v[180:183], v[188:191], v[112:115]
	v_mfma_f32_16x16x32_bf16 v[100:103], v[172:175], v[198:201], v[100:103]
	v_mfma_f32_16x16x32_bf16 v[92:95], v[180:183], v[198:201], v[92:95]
	v_mfma_f32_16x16x32_bf16 v[84:87], v[172:175], v[206:209], v[84:87]
	v_mfma_f32_16x16x32_bf16 v[76:79], v[180:183], v[206:209], v[76:79]
	v_mfma_f32_16x16x32_bf16 v[68:71], v[172:175], v[214:217], v[68:71]
	v_mfma_f32_16x16x32_bf16 v[64:67], v[180:183], v[214:217], v[64:67]
	v_mfma_f32_16x16x32_bf16 v[116:119], v[176:179], v[192:195], v[116:119]
	v_mfma_f32_16x16x32_bf16 v[112:115], v[184:187], v[192:195], v[112:115]
	v_mfma_f32_16x16x32_bf16 v[100:103], v[176:179], v[202:205], v[100:103]
	v_mfma_f32_16x16x32_bf16 v[92:95], v[184:187], v[202:205], v[92:95]
	v_mfma_f32_16x16x32_bf16 v[84:87], v[176:179], v[210:213], v[84:87]
	v_mfma_f32_16x16x32_bf16 v[76:79], v[184:187], v[210:213], v[76:79]
	v_mfma_f32_16x16x32_bf16 v[68:71], v[176:179], v[218:221], v[68:71]
	v_mfma_f32_16x16x32_bf16 v[64:67], v[184:187], v[218:221], v[64:67]
	s_setprio 0
	s_barrier
; #define PG8_STAGE(bufoff, gbase, voff) do { _Pragma("unroll") for (int _i = 0; _i < 2; ++_i) \
;         __builtin_amdgcn_global_load_lds((const unsigned*)((const char*)(gbase) + (voff)[_i]), (PG8_LAS unsigned*)(lds + (bufoff) + ldsw + _i * 8192), 16, 0, 0); } while (0)
; #define PG8_LDA(dst, b, h) do { _Pragma("unroll") for (int m = 0; m < 4; ++m) _Pragma("unroll") for (int k = 0; k < 2; ++k) dst[m][k] = *(const PG8_LAS bf16x8*)(lds + PG8_SA(b, h) + aoff + m * 2048 + k * 1024); } while (0)
; #define PG8_LDB(dst, b, h) do { _Pragma("unroll") for (int n = 0; n < 2; ++n) _Pragma("unroll") for (int k = 0; k < 2; ++k) dst[n][k] = *(const PG8_LAS bf16x8*)(lds + PG8_SB(b, h) + boff + n * 2048 + k * 1024); } while (0)
; #define PG8_MMA(ai, bj, At, Bt) do { __builtin_amdgcn_s_setprio(1); _Pragma("unroll") for (int m = 0; m < 4; ++m) _Pragma("unroll") for (int n = 0; n < 2; ++n) _Pragma("unroll") for (int k = 0; k < 2; ++k) \
;         acc[ai][bj][m][n] = __builtin_amdgcn_mfma_f32_16x16x32_bf16(Bt[n][k], At[m][k], acc[ai][bj][m][n], 0, 0, 0); __builtin_amdgcn_s_setprio(0); } while (0)
; #define PG8_WAIT_V(n) asm volatile("s_waitcnt vmcnt(" #n ")" ::: "memory")
; template <class Epi, class Sched, bool ALIGN_EPI = false, bool SP2 = false>
; __device__ __forceinline__ void gemm_phase(PG8_LAS unsigned char* lds, const Gemm g, const Sched& S, const Epi& E) {
;     ...
;             PG8_LDB(B0, 0, 0); PG8_LDB(B1, 0, 1); PG8_SCHED; PG8_LDA(At, 0, 0); PG8_STAGE(PG8_SA(1, 1), a1 + hstep, voffA);
;             PG8_WAIT_V(8); PG8_WAIT_L(0); PG8_BAR; PG8_MMA(0, 0, At, B0); PG8_MMA(0, 1, At, B1); PG8_BAR; PG8_SCHED;
;             PG8_LDA(At, 0, 1); PG8_STAGE(PG8_SB(0, 0), b2, voffB); PG8_STAGE(PG8_SB(0, 1), b2 + hstep, voffB); PG8_STAGE(PG8_SA(0, 0), a2, voffA);
;             PG8_WAIT_V(8); PG8_WAIT_L(0); PG8_BAR; PG8_MMA(1, 0, At, B0); PG8_MMA(1, 1, At, B1); PG8_BAR; PG8_SCHED;
;             PG8_LDB(B0, 1, 0); PG8_LDB(B1, 1, 1); PG8_SCHED; PG8_LDA(At, 1, 0); PG8_STAGE(PG8_SA(0, 1), a2 + hstep, voffA);
;             PG8_WAIT_V(8); PG8_WAIT_L(0); PG8_BAR; PG8_MMA(0, 0, At, B0); PG8_MMA(0, 1, At, B1); PG8_BAR; PG8_SCHED;
;             PG8_LDA(At, 1, 1); PG8_STAGE(PG8_SB(1, 0), b3, voffB); PG8_STAGE(PG8_SB(1, 1), b3 + hstep, voffB); PG8_STAGE(PG8_SA(1, 0), a3, voffA);
;             PG8_WAIT_V(8); PG8_WAIT_L(0); PG8_BAR; PG8_MMA(1, 0, At, B0); PG8_MMA(1, 1, At, B1); PG8_BAR; PG8_SCHED;
	s_add_i32 s44, s70, s51
	s_mov_b32 m0, s44
	ds_read_b128 v[188:191], v157 offset:49152
	ds_read_b128 v[192:195], v157 offset:50176
	ds_read_b128 v[198:201], v157 offset:51200
	ds_read_b128 v[202:205], v157 offset:52224
	ds_read_b128 v[206:209], v157 offset:53248
	ds_read_b128 v[210:213], v157 offset:54272
	ds_read_b128 v[214:217], v157 offset:55296
	ds_read_b128 v[218:221], v157 offset:56320
	global_load_lds_dwordx4 v146, s[98:99]
	s_add_i32 m0, s44, 0x2000
	s_add_u32 s38, s38, 0x40080
	s_addc_u32 s39, s39, 0
	s_add_i32 s44, s71, s51
	global_load_lds_dwordx4 v150, s[98:99]
	s_mov_b32 m0, s44
	s_nop 0
	global_load_lds_dwordx4 v146, s[38:39]
	s_add_i32 m0, s44, 0x2000
	s_nop 0
	global_load_lds_dwordx4 v150, s[38:39]
	s_mov_b32 m0, s58
	s_nop 0
	global_load_lds_dwordx4 v144, s[100:101]
	s_mov_b32 m0, s59
	s_nop 0
	global_load_lds_dwordx4 v148, s[100:101]
	s_waitcnt vmcnt(8)
	s_waitcnt lgkmcnt(0)
	s_barrier
	s_setprio 1
	s_waitcnt lgkmcnt(0)
	v_mfma_f32_16x16x32_bf16 v[60:63], v[128:131], v[188:191], v[60:63]
	v_mfma_f32_16x16x32_bf16 v[56:59], v[136:139], v[188:191], v[56:59]
	v_mfma_f32_16x16x32_bf16 v[48:51], v[128:131], v[198:201], v[48:51]
	v_mfma_f32_16x16x32_bf16 v[40:43], v[136:139], v[198:201], v[40:43]
	v_mfma_f32_16x16x32_bf16 v[32:35], v[128:131], v[206:209], v[32:35]
	v_mfma_f32_16x16x32_bf16 v[24:27], v[136:139], v[206:209], v[24:27]
	v_mfma_f32_16x16x32_bf16 v[16:19], v[128:131], v[214:217], v[16:19]
	v_mfma_f32_16x16x32_bf16 v[8:11], v[136:139], v[214:217], v[8:11]
	v_mfma_f32_16x16x32_bf16 v[60:63], v[132:135], v[192:195], v[60:63]
	v_mfma_f32_16x16x32_bf16 v[56:59], v[140:143], v[192:195], v[56:59]
	v_mfma_f32_16x16x32_bf16 v[48:51], v[132:135], v[202:205], v[48:51]
	v_mfma_f32_16x16x32_bf16 v[40:43], v[140:143], v[202:205], v[40:43]
	v_mfma_f32_16x16x32_bf16 v[32:35], v[132:135], v[210:213], v[32:35]
	v_mfma_f32_16x16x32_bf16 v[24:27], v[140:143], v[210:213], v[24:27]
	v_mfma_f32_16x16x32_bf16 v[16:19], v[132:135], v[218:221], v[16:19]
	v_mfma_f32_16x16x32_bf16 v[8:11], v[140:143], v[218:221], v[8:11]
	v_mfma_f32_16x16x32_bf16 v[52:55], v[172:175], v[188:191], v[52:55]
	v_mfma_f32_16x16x32_bf16 v[44:47], v[180:183], v[188:191], v[44:47]
	v_mfma_f32_16x16x32_bf16 v[36:39], v[172:175], v[198:201], v[36:39]
	v_mfma_f32_16x16x32_bf16 v[28:31], v[180:183], v[198:201], v[28:31]
	v_mfma_f32_16x16x32_bf16 v[20:23], v[172:175], v[206:209], v[20:23]
	v_mfma_f32_16x16x32_bf16 v[12:15], v[180:183], v[206:209], v[12:15]
	v_mfma_f32_16x16x32_bf16 v[4:7], v[172:175], v[214:217], v[4:7]
	v_mfma_f32_16x16x32_bf16 v[0:3], v[180:183], v[214:217], v[0:3]
	v_mfma_f32_16x16x32_bf16 v[52:55], v[176:179], v[192:195], v[52:55]
	v_mfma_f32_16x16x32_bf16 v[44:47], v[184:187], v[192:195], v[44:47]
	v_mfma_f32_16x16x32_bf16 v[36:39], v[176:179], v[202:205], v[36:39]
	v_mfma_f32_16x16x32_bf16 v[28:31], v[184:187], v[202:205], v[28:31]
	v_mfma_f32_16x16x32_bf16 v[20:23], v[176:179], v[210:213], v[20:23]
	v_mfma_f32_16x16x32_bf16 v[12:15], v[184:187], v[210:213], v[12:15]
	v_mfma_f32_16x16x32_bf16 v[4:7], v[176:179], v[218:221], v[4:7]
	v_mfma_f32_16x16x32_bf16 v[0:3], v[184:187], v[218:221], v[0:3]
	s_setprio 0
	s_barrier
	s_add_i32 s69, s69, 2
	s_add_u32 s20, s20, 0x100
	s_addc_u32 s21, s21, 0
	s_add_u32 s67, s67, 0x100
	s_addc_u32 s68, s68, 0
	s_cmp_gt_u32 s69, 13
.LBB0_1446:
	ds_read_b128 v[128:131], v153
	ds_read_b128 v[132:135], v153 offset:1024
	ds_read_b128 v[136:139], v153 offset:2048
	ds_read_b128 v[140:143], v153 offset:3072
	ds_read_b128 v[172:175], v155
	ds_read_b128 v[176:179], v155 offset:1024
	ds_read_b128 v[180:183], v155 offset:2048
	ds_read_b128 v[184:187], v155 offset:3072
	s_add_u32 s38, s20, 0xfffc0080
	s_addc_u32 s39, s21, -1
	s_cmp_eq_u32 s69, 12
	s_cselect_b32 s45, s15, s39
	s_cselect_b32 s44, s65, s38
	s_cselect_b32 s39, s13, s68
	s_cselect_b32 s38, s66, s67
	s_add_i32 m0, s35, 0xc000
	ds_read_b128 v[188:191], v157
	ds_read_b128 v[192:195], v157 offset:1024
	ds_read_b128 v[198:201], v157 offset:2048
	ds_read_b128 v[202:205], v157 offset:3072
	ds_read_b128 v[206:209], v157 offset:4096
	ds_read_b128 v[210:213], v157 offset:5120
	ds_read_b128 v[214:217], v157 offset:6144
	ds_read_b128 v[218:221], v157 offset:7168
	global_load_lds_dwordx4 v162, s[20:21]
	s_add_i32 m0, s35, 0xe000
	s_nop 0
	global_load_lds_dwordx4 v164, s[20:21]
	s_waitcnt vmcnt(8)
	s_waitcnt lgkmcnt(0)
	s_barrier
	s_setprio 1
	s_waitcnt lgkmcnt(0)
	v_mfma_f32_16x16x32_bf16 v[124:127], v[128:131], v[188:191], v[124:127]
	v_mfma_f32_16x16x32_bf16 v[120:123], v[136:139], v[188:191], v[120:123]
	v_mfma_f32_16x16x32_bf16 v[108:111], v[128:131], v[198:201], v[108:111]
	v_mfma_f32_16x16x32_bf16 v[104:107], v[136:139], v[198:201], v[104:107]
	v_mfma_f32_16x16x32_bf16 v[96:99], v[128:131], v[206:209], v[96:99]
	v_mfma_f32_16x16x32_bf16 v[88:91], v[136:139], v[206:209], v[88:91]
	v_mfma_f32_16x16x32_bf16 v[80:83], v[128:131], v[214:217], v[80:83]
	v_mfma_f32_16x16x32_bf16 v[72:75], v[136:139], v[214:217], v[72:75]
	v_mfma_f32_16x16x32_bf16 v[124:127], v[132:135], v[192:195], v[124:127]
	v_mfma_f32_16x16x32_bf16 v[120:123], v[140:143], v[192:195], v[120:123]
	v_mfma_f32_16x16x32_bf16 v[108:111], v[132:135], v[202:205], v[108:111]
	v_mfma_f32_16x16x32_bf16 v[104:107], v[140:143], v[202:205], v[104:107]
	v_mfma_f32_16x16x32_bf16 v[96:99], v[132:135], v[210:213], v[96:99]
	v_mfma_f32_16x16x32_bf16 v[88:91], v[140:143], v[210:213], v[88:91]
	v_mfma_f32_16x16x32_bf16 v[80:83], v[132:135], v[218:221], v[80:83]
	v_mfma_f32_16x16x32_bf16 v[72:75], v[140:143], v[218:221], v[72:75]
	v_mfma_f32_16x16x32_bf16 v[116:119], v[172:175], v[188:191], v[116:119]
	v_mfma_f32_16x16x32_bf16 v[112:115], v[180:183], v[188:191], v[112:115]
	v_mfma_f32_16x16x32_bf16 v[100:103], v[172:175], v[198:201], v[100:103]
	v_mfma_f32_16x16x32_bf16 v[92:95], v[180:183], v[198:201], v[92:95]
	v_mfma_f32_16x16x32_bf16 v[84:87], v[172:175], v[206:209], v[84:87]
	v_mfma_f32_16x16x32_bf16 v[76:79], v[180:183], v[206:209], v[76:79]
	v_mfma_f32_16x16x32_bf16 v[68:71], v[172:175], v[214:217], v[68:71]
	v_mfma_f32_16x16x32_bf16 v[64:67], v[180:183], v[214:217], v[64:67]
	v_mfma_f32_16x16x32_bf16 v[116:119], v[176:179], v[192:195], v[116:119]
	v_mfma_f32_16x16x32_bf16 v[112:115], v[184:187], v[192:195], v[112:115]
	v_mfma_f32_16x16x32_bf16 v[100:103], v[176:179], v[202:205], v[100:103]
	v_mfma_f32_16x16x32_bf16 v[92:95], v[184:187], v[202:205], v[92:95]
	v_mfma_f32_16x16x32_bf16 v[84:87], v[176:179], v[210:213], v[84:87]
	v_mfma_f32_16x16x32_bf16 v[76:79], v[184:187], v[210:213], v[76:79]
	v_mfma_f32_16x16x32_bf16 v[68:71], v[176:179], v[218:221], v[68:71]
	v_mfma_f32_16x16x32_bf16 v[64:67], v[184:187], v[218:221], v[64:67]
	s_setprio 0
	s_barrier
; #define PG8_STAGE(bufoff, gbase, voff) do { _Pragma("unroll") for (int _i = 0; _i < 2; ++_i) \
;         __builtin_amdgcn_global_load_lds((const unsigned*)((const char*)(gbase) + (voff)[_i]), (PG8_LAS unsigned*)(lds + (bufoff) + ldsw + _i * 8192), 16, 0, 0); } while (0)
; #define PG8_LDA(dst, b, h) do { _Pragma("unroll") for (int m = 0; m < 4; ++m) _Pragma("unroll") for (int k = 0; k < 2; ++k) dst[m][k] = *(const PG8_LAS bf16x8*)(lds + PG8_SA(b, h) + aoff + m * 2048 + k * 1024); } while (0)
; #define PG8_LDB(dst, b, h) do { _Pragma("unroll") for (int n = 0; n < 2; ++n) _Pragma("unroll") for (int k = 0; k < 2; ++k) dst[n][k] = *(const PG8_LAS bf16x8*)(lds + PG8_SB(b, h) + boff + n * 2048 + k * 1024); } while (0)
; #define PG8_MMA(ai, bj, At, Bt) do { __builtin_amdgcn_s_setprio(1); _Pragma("unroll") for (int m = 0; m < 4; ++m) _Pragma("unroll") for (int n = 0; n < 2; ++n) _Pragma("unroll") for (int k = 0; k < 2; ++k) \
;         acc[ai][bj][m][n] = __builtin_amdgcn_mfma_f32_16x16x32_bf16(Bt[n][k], At[m][k], acc[ai][bj][m][n], 0, 0, 0); __builtin_amdgcn_s_setprio(0); } while (0)
; #define PG8_WAIT_V(n) asm volatile("s_waitcnt vmcnt(" #n ")" ::: "memory")
; #define PG8_WAIT_L(n) asm volatile("s_waitcnt lgkmcnt(" #n ")" ::: "memory")
; #define PG8_BAR __builtin_amdgcn_s_barrier()
; #define PG8_SCHED __builtin_amdgcn_sched_barrier(0)
; template <class Epi, class Sched, bool ALIGN_EPI = false, bool SP2 = false>
; __device__ __forceinline__ void gemm_phase(PG8_LAS unsigned char* lds, const Gemm g, const Sched& S, const Epi& E) {
;     ...
;             PG8_LDA(At, 0, 1); PG8_STAGE(PG8_SB(0, 0), b2, voffB); PG8_STAGE(PG8_SB(0, 1), b2 + hstep, voffB); PG8_STAGE(PG8_SA(0, 0), a2, voffA);
;             PG8_WAIT_V(8); PG8_WAIT_L(0); PG8_BAR; PG8_MMA(1, 0, At, B0); PG8_MMA(1, 1, At, B1); PG8_BAR; PG8_SCHED;
;             PG8_LDB(B0, 1, 0); PG8_LDB(B1, 1, 1); PG8_SCHED; PG8_LDA(At, 1, 0); PG8_STAGE(PG8_SA(0, 1), a2 + hstep, voffA);
;             PG8_WAIT_V(8); PG8_WAIT_L(0); PG8_BAR; PG8_MMA(0, 0, At, B0); PG8_MMA(0, 1, At, B1); PG8_BAR; PG8_SCHED;
	s_add_i32 s70, s60, s51
	s_add_u32 s98, s38, s6
	s_addc_u32 s99, s39, s7
	s_add_u32 s100, s44, s6
	s_addc_u32 s101, s45, s7
	s_mov_b32 m0, s70
	ds_read_b128 v[188:191], v157 offset:16384
	ds_read_b128 v[192:195], v157 offset:17408
	ds_read_b128 v[198:201], v157 offset:18432
	ds_read_b128 v[202:205], v157 offset:19456
	ds_read_b128 v[206:209], v157 offset:20480
	ds_read_b128 v[210:213], v157 offset:21504
	ds_read_b128 v[214:217], v157 offset:22528
	ds_read_b128 v[218:221], v157 offset:23552
	global_load_lds_dwordx4 v146, s[38:39]
	s_add_i32 m0, s70, 0x2000
	s_add_u32 s70, s38, 0x40000
	s_addc_u32 s71, s39, 0
	s_add_i32 s72, s61, s51
	global_load_lds_dwordx4 v150, s[38:39]
	s_mov_b32 m0, s72
	s_nop 0
	global_load_lds_dwordx4 v146, s[70:71]
	s_add_i32 m0, s72, 0x2000
	s_nop 0
	global_load_lds_dwordx4 v150, s[70:71]
	s_mov_b32 m0, s35
	s_nop 0
	global_load_lds_dwordx4 v144, s[44:45]
	s_mov_b32 m0, s52
	s_nop 0
	global_load_lds_dwordx4 v148, s[44:45]
	s_waitcnt vmcnt(8)
	s_waitcnt lgkmcnt(0)
	s_barrier
	s_setprio 1
	s_waitcnt lgkmcnt(0)
	v_mfma_f32_16x16x32_bf16 v[60:63], v[128:131], v[188:191], v[60:63]
	v_mfma_f32_16x16x32_bf16 v[56:59], v[136:139], v[188:191], v[56:59]
	v_mfma_f32_16x16x32_bf16 v[48:51], v[128:131], v[198:201], v[48:51]
	v_mfma_f32_16x16x32_bf16 v[40:43], v[136:139], v[198:201], v[40:43]
	v_mfma_f32_16x16x32_bf16 v[32:35], v[128:131], v[206:209], v[32:35]
	v_mfma_f32_16x16x32_bf16 v[24:27], v[136:139], v[206:209], v[24:27]
	v_mfma_f32_16x16x32_bf16 v[16:19], v[128:131], v[214:217], v[16:19]
	v_mfma_f32_16x16x32_bf16 v[8:11], v[136:139], v[214:217], v[8:11]
	v_mfma_f32_16x16x32_bf16 v[60:63], v[132:135], v[192:195], v[60:63]
	v_mfma_f32_16x16x32_bf16 v[56:59], v[140:143], v[192:195], v[56:59]
	v_mfma_f32_16x16x32_bf16 v[48:51], v[132:135], v[202:205], v[48:51]
	v_mfma_f32_16x16x32_bf16 v[40:43], v[140:143], v[202:205], v[40:43]
	v_mfma_f32_16x16x32_bf16 v[32:35], v[132:135], v[210:213], v[32:35]
	v_mfma_f32_16x16x32_bf16 v[24:27], v[140:143], v[210:213], v[24:27]
	v_mfma_f32_16x16x32_bf16 v[16:19], v[132:135], v[218:221], v[16:19]
	v_mfma_f32_16x16x32_bf16 v[8:11], v[140:143], v[218:221], v[8:11]
	v_mfma_f32_16x16x32_bf16 v[52:55], v[172:175], v[188:191], v[52:55]
	v_mfma_f32_16x16x32_bf16 v[44:47], v[180:183], v[188:191], v[44:47]
	v_mfma_f32_16x16x32_bf16 v[36:39], v[172:175], v[198:201], v[36:39]
	v_mfma_f32_16x16x32_bf16 v[28:31], v[180:183], v[198:201], v[28:31]
	v_mfma_f32_16x16x32_bf16 v[20:23], v[172:175], v[206:209], v[20:23]
	v_mfma_f32_16x16x32_bf16 v[12:15], v[180:183], v[206:209], v[12:15]
	v_mfma_f32_16x16x32_bf16 v[4:7], v[172:175], v[214:217], v[4:7]
	v_mfma_f32_16x16x32_bf16 v[0:3], v[180:183], v[214:217], v[0:3]
	v_mfma_f32_16x16x32_bf16 v[52:55], v[176:179], v[192:195], v[52:55]
	v_mfma_f32_16x16x32_bf16 v[44:47], v[184:187], v[192:195], v[44:47]
	v_mfma_f32_16x16x32_bf16 v[36:39], v[176:179], v[202:205], v[36:39]
	v_mfma_f32_16x16x32_bf16 v[28:31], v[184:187], v[202:205], v[28:31]
	v_mfma_f32_16x16x32_bf16 v[20:23], v[176:179], v[210:213], v[20:23]
	v_mfma_f32_16x16x32_bf16 v[12:15], v[184:187], v[210:213], v[12:15]
	v_mfma_f32_16x16x32_bf16 v[4:7], v[176:179], v[218:221], v[4:7]
	v_mfma_f32_16x16x32_bf16 v[0:3], v[184:187], v[218:221], v[0:3]
	s_setprio 0
	s_barrier
	s_add_i32 s70, 0, 0x18000
	s_add_i32 s71, 0, 0x1c000
	v_add_u32_e32 v140, s70, v170
	v_add_u32_e32 v159, s71, v170
	ds_read_b128 v[128:131], v140
	ds_read_b128 v[132:135], v140 offset:1024
	ds_read_b128 v[136:139], v140 offset:2048
	ds_read_b128 v[140:143], v140 offset:3072
	ds_read_b128 v[172:175], v159
	ds_read_b128 v[176:179], v159 offset:1024
	ds_read_b128 v[180:183], v159 offset:2048
	ds_read_b128 v[184:187], v159 offset:3072
	s_add_u32 s44, s44, 0x40000
	s_addc_u32 s45, s45, 0
	s_mov_b32 m0, s53
	ds_read_b128 v[188:191], v157 offset:32768
	ds_read_b128 v[192:195], v157 offset:33792
	ds_read_b128 v[198:201], v157 offset:34816
	ds_read_b128 v[202:205], v157 offset:35840
	ds_read_b128 v[206:209], v157 offset:36864
	ds_read_b128 v[210:213], v157 offset:37888
	ds_read_b128 v[214:217], v157 offset:38912
	ds_read_b128 v[218:221], v157 offset:39936
	global_load_lds_dwordx4 v144, s[44:45]
	s_mov_b32 m0, s54
	s_nop 0
	global_load_lds_dwordx4 v148, s[44:45]
	s_waitcnt vmcnt(8)
	s_waitcnt lgkmcnt(0)
	s_barrier
; #define PG8_STAGE(bufoff, gbase, voff) do { _Pragma("unroll") for (int _i = 0; _i < 2; ++_i) \
;         __builtin_amdgcn_global_load_lds((const unsigned*)((const char*)(gbase) + (voff)[_i]), (PG8_LAS unsigned*)(lds + (bufoff) + ldsw + _i * 8192), 16, 0, 0); } while (0)
; #define PG8_LDA(dst, b, h) do { _Pragma("unroll") for (int m = 0; m < 4; ++m) _Pragma("unroll") for (int k = 0; k < 2; ++k) dst[m][k] = *(const PG8_LAS bf16x8*)(lds + PG8_SA(b, h) + aoff + m * 2048 + k * 1024); } while (0)
; #define PG8_MMA(ai, bj, At, Bt) do { __builtin_amdgcn_s_setprio(1); _Pragma("unroll") for (int m = 0; m < 4; ++m) _Pragma("unroll") for (int n = 0; n < 2; ++n) _Pragma("unroll") for (int k = 0; k < 2; ++k) \
;         acc[ai][bj][m][n] = __builtin_amdgcn_mfma_f32_16x16x32_bf16(Bt[n][k], At[m][k], acc[ai][bj][m][n], 0, 0, 0); __builtin_amdgcn_s_setprio(0); } while (0)
; #define PG8_WAIT_V(n) asm volatile("s_waitcnt vmcnt(" #n ")" ::: "memory")
; #define PG8_WAIT_L(n) asm volatile("s_waitcnt lgkmcnt(" #n ")" ::: "memory")
; #define PG8_BAR __builtin_amdgcn_s_barrier()
; #define PG8_SCHED __builtin_amdgcn_sched_barrier(0)
; template <class Epi, class Sched, bool ALIGN_EPI = false, bool SP2 = false>
; __device__ __forceinline__ void gemm_phase(PG8_LAS unsigned char* lds, const Gemm g, const Sched& S, const Epi& E) {
;     ...
;             PG8_WAIT_V(8); PG8_WAIT_L(0); PG8_BAR; PG8_MMA(0, 0, At, B0); PG8_MMA(0, 1, At, B1); PG8_BAR; PG8_SCHED;
;             PG8_LDA(At, 1, 1); PG8_STAGE(PG8_SB(1, 0), b3, voffB); PG8_STAGE(PG8_SB(1, 1), b3 + hstep, voffB); PG8_STAGE(PG8_SA(1, 0), a3, voffA);
;             PG8_WAIT_V(8); PG8_WAIT_L(0); PG8_BAR; PG8_MMA(1, 0, At, B0); PG8_MMA(1, 1, At, B1); PG8_BAR; PG8_SCHED;
	s_setprio 1
	s_waitcnt lgkmcnt(0)
	v_mfma_f32_16x16x32_bf16 v[124:127], v[128:131], v[188:191], v[124:127]
	v_mfma_f32_16x16x32_bf16 v[120:123], v[136:139], v[188:191], v[120:123]
	v_mfma_f32_16x16x32_bf16 v[108:111], v[128:131], v[198:201], v[108:111]
	v_mfma_f32_16x16x32_bf16 v[104:107], v[136:139], v[198:201], v[104:107]
	v_mfma_f32_16x16x32_bf16 v[96:99], v[128:131], v[206:209], v[96:99]
	v_mfma_f32_16x16x32_bf16 v[88:91], v[136:139], v[206:209], v[88:91]
	v_mfma_f32_16x16x32_bf16 v[80:83], v[128:131], v[214:217], v[80:83]
	v_mfma_f32_16x16x32_bf16 v[72:75], v[136:139], v[214:217], v[72:75]
	v_mfma_f32_16x16x32_bf16 v[124:127], v[132:135], v[192:195], v[124:127]
	v_mfma_f32_16x16x32_bf16 v[120:123], v[140:143], v[192:195], v[120:123]
	v_mfma_f32_16x16x32_bf16 v[108:111], v[132:135], v[202:205], v[108:111]
	v_mfma_f32_16x16x32_bf16 v[104:107], v[140:143], v[202:205], v[104:107]
	v_mfma_f32_16x16x32_bf16 v[96:99], v[132:135], v[210:213], v[96:99]
	v_mfma_f32_16x16x32_bf16 v[88:91], v[140:143], v[210:213], v[88:91]
	v_mfma_f32_16x16x32_bf16 v[80:83], v[132:135], v[218:221], v[80:83]
	v_mfma_f32_16x16x32_bf16 v[72:75], v[140:143], v[218:221], v[72:75]
	v_mfma_f32_16x16x32_bf16 v[116:119], v[172:175], v[188:191], v[116:119]
	v_mfma_f32_16x16x32_bf16 v[112:115], v[180:183], v[188:191], v[112:115]
	v_mfma_f32_16x16x32_bf16 v[100:103], v[172:175], v[198:201], v[100:103]
	v_mfma_f32_16x16x32_bf16 v[92:95], v[180:183], v[198:201], v[92:95]
	v_mfma_f32_16x16x32_bf16 v[84:87], v[172:175], v[206:209], v[84:87]
	v_mfma_f32_16x16x32_bf16 v[76:79], v[180:183], v[206:209], v[76:79]
	v_mfma_f32_16x16x32_bf16 v[68:71], v[172:175], v[214:217], v[68:71]
	v_mfma_f32_16x16x32_bf16 v[64:67], v[180:183], v[214:217], v[64:67]
	v_mfma_f32_16x16x32_bf16 v[116:119], v[176:179], v[192:195], v[116:119]
	v_mfma_f32_16x16x32_bf16 v[112:115], v[184:187], v[192:195], v[112:115]
	v_mfma_f32_16x16x32_bf16 v[100:103], v[176:179], v[202:205], v[100:103]
	v_mfma_f32_16x16x32_bf16 v[92:95], v[184:187], v[202:205], v[92:95]
	v_mfma_f32_16x16x32_bf16 v[84:87], v[176:179], v[210:213], v[84:87]
	v_mfma_f32_16x16x32_bf16 v[76:79], v[184:187], v[210:213], v[76:79]
	v_mfma_f32_16x16x32_bf16 v[68:71], v[176:179], v[218:221], v[68:71]
	v_mfma_f32_16x16x32_bf16 v[64:67], v[184:187], v[218:221], v[64:67]
	s_setprio 0
	s_barrier
	s_add_i32 s44, s70, s51
	s_mov_b32 m0, s44
	ds_read_b128 v[188:191], v157 offset:49152
	ds_read_b128 v[192:195], v157 offset:50176
	ds_read_b128 v[198:201], v157 offset:51200
	ds_read_b128 v[202:205], v157 offset:52224
	ds_read_b128 v[206:209], v157 offset:53248
	ds_read_b128 v[210:213], v157 offset:54272
	ds_read_b128 v[214:217], v157 offset:55296
	ds_read_b128 v[218:221], v157 offset:56320
	global_load_lds_dwordx4 v146, s[98:99]
	s_add_i32 m0, s44, 0x2000
	s_add_u32 s38, s38, 0x40080
	s_addc_u32 s39, s39, 0
	s_add_i32 s44, s71, s51
	global_load_lds_dwordx4 v150, s[98:99]
	s_mov_b32 m0, s44
	s_nop 0
	global_load_lds_dwordx4 v146, s[38:39]
	s_add_i32 m0, s44, 0x2000
	s_nop 0
	global_load_lds_dwordx4 v150, s[38:39]
	s_mov_b32 m0, s58
	s_nop 0
	global_load_lds_dwordx4 v144, s[100:101]
	s_mov_b32 m0, s59
	s_nop 0
	global_load_lds_dwordx4 v148, s[100:101]
	s_waitcnt vmcnt(8)
	s_waitcnt lgkmcnt(0)
	s_barrier
	s_setprio 1
	s_waitcnt lgkmcnt(0)
	v_mfma_f32_16x16x32_bf16 v[60:63], v[128:131], v[188:191], v[60:63]
	v_mfma_f32_16x16x32_bf16 v[56:59], v[136:139], v[188:191], v[56:59]
	v_mfma_f32_16x16x32_bf16 v[48:51], v[128:131], v[198:201], v[48:51]
	v_mfma_f32_16x16x32_bf16 v[40:43], v[136:139], v[198:201], v[40:43]
	v_mfma_f32_16x16x32_bf16 v[32:35], v[128:131], v[206:209], v[32:35]
	v_mfma_f32_16x16x32_bf16 v[24:27], v[136:139], v[206:209], v[24:27]
	v_mfma_f32_16x16x32_bf16 v[16:19], v[128:131], v[214:217], v[16:19]
	v_mfma_f32_16x16x32_bf16 v[8:11], v[136:139], v[214:217], v[8:11]
	v_mfma_f32_16x16x32_bf16 v[60:63], v[132:135], v[192:195], v[60:63]
	v_mfma_f32_16x16x32_bf16 v[56:59], v[140:143], v[192:195], v[56:59]
	v_mfma_f32_16x16x32_bf16 v[48:51], v[132:135], v[202:205], v[48:51]
	v_mfma_f32_16x16x32_bf16 v[40:43], v[140:143], v[202:205], v[40:43]
	v_mfma_f32_16x16x32_bf16 v[32:35], v[132:135], v[210:213], v[32:35]
	v_mfma_f32_16x16x32_bf16 v[24:27], v[140:143], v[210:213], v[24:27]
	v_mfma_f32_16x16x32_bf16 v[16:19], v[132:135], v[218:221], v[16:19]
	v_mfma_f32_16x16x32_bf16 v[8:11], v[140:143], v[218:221], v[8:11]
	v_mfma_f32_16x16x32_bf16 v[52:55], v[172:175], v[188:191], v[52:55]
	v_mfma_f32_16x16x32_bf16 v[44:47], v[180:183], v[188:191], v[44:47]
	v_mfma_f32_16x16x32_bf16 v[36:39], v[172:175], v[198:201], v[36:39]
	v_mfma_f32_16x16x32_bf16 v[28:31], v[180:183], v[198:201], v[28:31]
	v_mfma_f32_16x16x32_bf16 v[20:23], v[172:175], v[206:209], v[20:23]
	v_mfma_f32_16x16x32_bf16 v[12:15], v[180:183], v[206:209], v[12:15]
	v_mfma_f32_16x16x32_bf16 v[4:7], v[172:175], v[214:217], v[4:7]
	v_mfma_f32_16x16x32_bf16 v[0:3], v[180:183], v[214:217], v[0:3]
	v_mfma_f32_16x16x32_bf16 v[52:55], v[176:179], v[192:195], v[52:55]
	v_mfma_f32_16x16x32_bf16 v[44:47], v[184:187], v[192:195], v[44:47]
	v_mfma_f32_16x16x32_bf16 v[36:39], v[176:179], v[202:205], v[36:39]
	v_mfma_f32_16x16x32_bf16 v[28:31], v[184:187], v[202:205], v[28:31]
	v_mfma_f32_16x16x32_bf16 v[20:23], v[176:179], v[210:213], v[20:23]
	v_mfma_f32_16x16x32_bf16 v[12:15], v[184:187], v[210:213], v[12:15]
	v_mfma_f32_16x16x32_bf16 v[4:7], v[176:179], v[218:221], v[4:7]
	v_mfma_f32_16x16x32_bf16 v[0:3], v[184:187], v[218:221], v[0:3]
	s_setprio 0
	s_barrier
	s_add_i32 s69, s69, 2
	s_add_u32 s20, s20, 0x100
	s_addc_u32 s21, s21, 0
	s_add_u32 s67, s67, 0x100
	s_addc_u32 s68, s68, 0
	s_cmp_gt_u32 s69, 13
	s_cbranch_scc0 .LBB0_1446
	s_and_b64 vcc, exec, s[8:9]
	s_cbranch_vccz .LBB0_1449
	s_barrier

; #define PG8_STAGE(bufoff, gbase, voff) do { _Pragma("unroll") for (int _i = 0; _i < 2; ++_i) \
;         __builtin_amdgcn_global_load_lds((const unsigned*)((const char*)(gbase) + (voff)[_i]), (PG8_LAS unsigned*)(lds + (bufoff) + ldsw + _i * 8192), 16, 0, 0); } while (0)
; #define PG8_LDA(dst, b, h) do { _Pragma("unroll") for (int m = 0; m < 4; ++m) _Pragma("unroll") for (int k = 0; k < 2; ++k) dst[m][k] = *(const PG8_LAS bf16x8*)(lds + PG8_SA(b, h) + aoff + m * 2048 + k * 1024); } while (0)
; #define PG8_LDB(dst, b, h) do { _Pragma("unroll") for (int n = 0; n < 2; ++n) _Pragma("unroll") for (int k = 0; k < 2; ++k) dst[n][k] = *(const PG8_LAS bf16x8*)(lds + PG8_SB(b, h) + boff + n * 2048 + k * 1024); } while (0)
; #define PG8_MMA(ai, bj, At, Bt) do { __builtin_amdgcn_s_setprio(1); _Pragma("unroll") for (int m = 0; m < 4; ++m) _Pragma("unroll") for (int n = 0; n < 2; ++n) _Pragma("unroll") for (int k = 0; k < 2; ++k) \
;         acc[ai][bj][m][n] = __builtin_amdgcn_mfma_f32_16x16x32_bf16(Bt[n][k], At[m][k], acc[ai][bj][m][n], 0, 0, 0); __builtin_amdgcn_s_setprio(0); } while (0)
; #define PG8_WAIT_V(n) asm volatile("s_waitcnt vmcnt(" #n ")" ::: "memory")
; template <class Epi, class Sched, bool ALIGN_EPI = false, bool SP2 = false>
; __device__ __forceinline__ void gemm_phase(PG8_LAS unsigned char* lds, const Gemm g, const Sched& S, const Epi& E) {
;     ...
;         const char* nA = has_next ? (const char*)g.A + (size_t)nxt.pm * tstep : cA; const char* nB = has_next ? (const char*)g.Bt + (size_t)nxt.pn * tstep : cB;
;         for (int t = 0; t < nt; t += 2) {
;             const bool last = (t == nt - 2);
;             const char* a1 = cA + (size_t)(t + 1) * kstep;
;             const char* a2 = last ? nA : cA + (size_t)(t + 2) * kstep; const char* b2 = last ? nB : cB + (size_t)(t + 2) * kstep;
;             const char* a3 = a2 + kstep; const char* b3 = b2 + kstep;
;             if (last && has_next) S.a_ready(nxt);
;             if constexpr (SP2) {
;             PG8_LDB(B0, 0, 0); PG8_LDB(B1, 0, 1); PG8_SCHED; PG8_LDA(At, 0, 0); PG8_STAGE(PG8_SA(1, 1), a1 + hstep, voffA);
;             PG8_WAIT_V(8); PG8_WAIT_L(0); PG8_BAR; PG8_MMA(0, 0, At, B0); PG8_MMA(0, 1, At, B1); PG8_BAR; PG8_SCHED;
;             PG8_LDA(At, 0, 1); PG8_STAGE(PG8_SB(0, 0), b2, voffB); PG8_STAGE(PG8_SB(0, 1), b2 + hstep, voffB); PG8_STAGE(PG8_SA(0, 0), a2, voffA);
.LBB0_1634:
	s_ashr_i32 s47, s46, 31
	s_lshl_b64 s[48:49], s[46:47], 19
	s_add_u32 s48, s18, s48
	s_addc_u32 s49, s19, s49
	s_and_b64 s[50:51], s[6:7], exec
	s_cselect_b32 s35, s49, s21
	s_cselect_b32 s47, s48, s20
	s_ashr_i32 s45, s44, 31
	s_lshl_b64 s[50:51], s[44:45], 19
	s_add_u32 s50, s3, s50
	s_addc_u32 s51, s33, s51
	s_and_b64 s[56:57], s[6:7], exec
	s_cselect_b32 s45, s51, s55
	s_cselect_b32 s73, s50, s54
	s_add_u32 s20, s20, 0x40080
	s_addc_u32 s21, s21, 0
	s_add_u32 s74, s54, 0x100
	s_addc_u32 s75, s55, 0
	s_mov_b32 s76, -2
	s_waitcnt lgkmcnt(0)
	ds_read_b128 v[96:99], v223
	ds_read_b128 v[108:111], v223 offset:1024
	ds_read_b128 v[120:123], v223 offset:2048
	ds_read_b128 v[128:131], v223 offset:3072
	ds_read_b128 v[144:147], v224
	ds_read_b128 v[148:151], v224 offset:1024
	ds_read_b128 v[152:155], v224 offset:2048
	ds_read_b128 v[156:159], v224 offset:3072
	s_add_u32 s54, s20, 0xfffc0080
	s_addc_u32 s55, s21, -1
	s_cmp_eq_u32 s76, 12
	s_cselect_b32 s57, s35, s55
	s_cselect_b32 s56, s47, s54
	s_cselect_b32 s55, s45, s75
	s_cselect_b32 s54, s73, s74
	s_add_i32 m0, s53, 0xc000
	ds_read_b128 v[160:163], v225
	ds_read_b128 v[164:167], v225 offset:1024
	ds_read_b128 v[168:171], v225 offset:2048
	ds_read_b128 v[172:175], v225 offset:3072
	ds_read_b128 v[176:179], v225 offset:4096
	ds_read_b128 v[180:183], v225 offset:5120
	ds_read_b128 v[202:205], v225 offset:6144
	ds_read_b128 v[206:209], v225 offset:7168
	global_load_lds_dwordx4 v192, s[20:21]
	s_add_i32 m0, s53, 0xe000
	s_nop 0
	global_load_lds_dwordx4 v194, s[20:21]
	s_waitcnt vmcnt(8)
	s_waitcnt lgkmcnt(0)
	s_barrier
	s_setprio 1
	s_waitcnt lgkmcnt(0)
	v_mfma_f32_16x16x32_bf16 v[140:143], v[96:99], v[160:163], 0
	v_mfma_f32_16x16x32_bf16 v[136:139], v[120:123], v[160:163], 0
	v_mfma_f32_16x16x32_bf16 v[116:119], v[96:99], v[168:171], 0
	v_mfma_f32_16x16x32_bf16 v[112:115], v[120:123], v[168:171], 0
	v_mfma_f32_16x16x32_bf16 v[92:95], v[96:99], v[176:179], 0
	v_mfma_f32_16x16x32_bf16 v[88:91], v[120:123], v[176:179], 0
	v_mfma_f32_16x16x32_bf16 v[76:79], v[96:99], v[202:205], 0
	v_mfma_f32_16x16x32_bf16 v[72:75], v[120:123], v[202:205], 0
	v_mfma_f32_16x16x32_bf16 v[140:143], v[108:111], v[164:167], v[140:143]
	v_mfma_f32_16x16x32_bf16 v[136:139], v[128:131], v[164:167], v[136:139]
	v_mfma_f32_16x16x32_bf16 v[116:119], v[108:111], v[172:175], v[116:119]
	v_mfma_f32_16x16x32_bf16 v[112:115], v[128:131], v[172:175], v[112:115]
	v_mfma_f32_16x16x32_bf16 v[92:95], v[108:111], v[180:183], v[92:95]
	v_mfma_f32_16x16x32_bf16 v[88:91], v[128:131], v[180:183], v[88:91]
	v_mfma_f32_16x16x32_bf16 v[76:79], v[108:111], v[206:209], v[76:79]
	v_mfma_f32_16x16x32_bf16 v[72:75], v[128:131], v[206:209], v[72:75]
	v_mfma_f32_16x16x32_bf16 v[132:135], v[144:147], v[160:163], 0
	v_mfma_f32_16x16x32_bf16 v[124:127], v[152:155], v[160:163], 0
	v_mfma_f32_16x16x32_bf16 v[104:107], v[144:147], v[168:171], 0
	v_mfma_f32_16x16x32_bf16 v[100:103], v[152:155], v[168:171], 0
	v_mfma_f32_16x16x32_bf16 v[84:87], v[144:147], v[176:179], 0
	v_mfma_f32_16x16x32_bf16 v[80:83], v[152:155], v[176:179], 0
	v_mfma_f32_16x16x32_bf16 v[68:71], v[144:147], v[202:205], 0
	v_mfma_f32_16x16x32_bf16 v[64:67], v[152:155], v[202:205], 0
	v_mfma_f32_16x16x32_bf16 v[132:135], v[148:151], v[164:167], v[132:135]
	v_mfma_f32_16x16x32_bf16 v[124:127], v[156:159], v[164:167], v[124:127]
	v_mfma_f32_16x16x32_bf16 v[104:107], v[148:151], v[172:175], v[104:107]
	v_mfma_f32_16x16x32_bf16 v[100:103], v[156:159], v[172:175], v[100:103]
	v_mfma_f32_16x16x32_bf16 v[84:87], v[148:151], v[180:183], v[84:87]
	v_mfma_f32_16x16x32_bf16 v[80:83], v[156:159], v[180:183], v[80:83]
	v_mfma_f32_16x16x32_bf16 v[68:71], v[148:151], v[206:209], v[68:71]
	v_mfma_f32_16x16x32_bf16 v[64:67], v[156:159], v[206:209], v[64:67]
	s_setprio 0
	s_barrier
	s_add_i32 s77, s71, s58
	s_add_u32 s98, s54, s12
	s_addc_u32 s99, s55, s13
	s_add_u32 s100, s56, s12
	s_addc_u32 s101, s57, s13
	s_mov_b32 m0, s77
	ds_read_b128 v[160:163], v225 offset:16384
	ds_read_b128 v[164:167], v225 offset:17408
	ds_read_b128 v[168:171], v225 offset:18432
	ds_read_b128 v[172:175], v225 offset:19456
	ds_read_b128 v[176:179], v225 offset:20480
	ds_read_b128 v[180:183], v225 offset:21504
	ds_read_b128 v[202:205], v225 offset:22528
	ds_read_b128 v[206:209], v225 offset:23552
	global_load_lds_dwordx4 v186, s[54:55]
	s_add_i32 m0, s77, 0x2000
	s_add_u32 s78, s54, 0x40000
	s_addc_u32 s79, s55, 0
	s_add_i32 s77, s72, s58
	global_load_lds_dwordx4 v190, s[54:55]
	s_mov_b32 m0, s77
	s_nop 0
	global_load_lds_dwordx4 v186, s[78:79]
	s_add_i32 m0, s77, 0x2000
	s_nop 0
	global_load_lds_dwordx4 v190, s[78:79]
	s_mov_b32 m0, s53
	s_nop 0
	global_load_lds_dwordx4 v184, s[56:57]
	s_mov_b32 m0, s59
	s_nop 0
	global_load_lds_dwordx4 v188, s[56:57]
	s_waitcnt vmcnt(8)
	s_waitcnt lgkmcnt(0)
	s_barrier
; #define PG8_STAGE(bufoff, gbase, voff) do { _Pragma("unroll") for (int _i = 0; _i < 2; ++_i) \
;         __builtin_amdgcn_global_load_lds((const unsigned*)((const char*)(gbase) + (voff)[_i]), (PG8_LAS unsigned*)(lds + (bufoff) + ldsw + _i * 8192), 16, 0, 0); } while (0)
; #define PG8_LDA(dst, b, h) do { _Pragma("unroll") for (int m = 0; m < 4; ++m) _Pragma("unroll") for (int k = 0; k < 2; ++k) dst[m][k] = *(const PG8_LAS bf16x8*)(lds + PG8_SA(b, h) + aoff + m * 2048 + k * 1024); } while (0)
; #define PG8_LDB(dst, b, h) do { _Pragma("unroll") for (int n = 0; n < 2; ++n) _Pragma("unroll") for (int k = 0; k < 2; ++k) dst[n][k] = *(const PG8_LAS bf16x8*)(lds + PG8_SB(b, h) + boff + n * 2048 + k * 1024); } while (0)
; #define PG8_MMA(ai, bj, At, Bt) do { __builtin_amdgcn_s_setprio(1); _Pragma("unroll") for (int m = 0; m < 4; ++m) _Pragma("unroll") for (int n = 0; n < 2; ++n) _Pragma("unroll") for (int k = 0; k < 2; ++k) \
;         acc[ai][bj][m][n] = __builtin_amdgcn_mfma_f32_16x16x32_bf16(Bt[n][k], At[m][k], acc[ai][bj][m][n], 0, 0, 0); __builtin_amdgcn_s_setprio(0); } while (0)
; #define PG8_WAIT_V(n) asm volatile("s_waitcnt vmcnt(" #n ")" ::: "memory")
; #define PG8_WAIT_L(n) asm volatile("s_waitcnt lgkmcnt(" #n ")" ::: "memory")
; #define PG8_BAR __builtin_amdgcn_s_barrier()
; #define PG8_SCHED __builtin_amdgcn_sched_barrier(0)
; template <class Epi, class Sched, bool ALIGN_EPI = false, bool SP2 = false>
; __device__ __forceinline__ void gemm_phase(PG8_LAS unsigned char* lds, const Gemm g, const Sched& S, const Epi& E) {
;     ...
;             PG8_WAIT_V(8); PG8_WAIT_L(0); PG8_BAR; PG8_MMA(1, 0, At, B0); PG8_MMA(1, 1, At, B1); PG8_BAR; PG8_SCHED;
;             PG8_LDB(B0, 1, 0); PG8_LDB(B1, 1, 1); PG8_SCHED; PG8_LDA(At, 1, 0); PG8_STAGE(PG8_SA(0, 1), a2 + hstep, voffA);
;             PG8_WAIT_V(8); PG8_WAIT_L(0); PG8_BAR; PG8_MMA(0, 0, At, B0); PG8_MMA(0, 1, At, B1); PG8_BAR; PG8_SCHED;
	s_setprio 1
	s_waitcnt lgkmcnt(0)
	v_mfma_f32_16x16x32_bf16 v[60:63], v[96:99], v[160:163], 0
	v_mfma_f32_16x16x32_bf16 v[56:59], v[120:123], v[160:163], 0
	v_mfma_f32_16x16x32_bf16 v[44:47], v[96:99], v[168:171], 0
	v_mfma_f32_16x16x32_bf16 v[40:43], v[120:123], v[168:171], 0
	v_mfma_f32_16x16x32_bf16 v[28:31], v[96:99], v[176:179], 0
	v_mfma_f32_16x16x32_bf16 v[24:27], v[120:123], v[176:179], 0
	v_mfma_f32_16x16x32_bf16 v[12:15], v[96:99], v[202:205], 0
	v_mfma_f32_16x16x32_bf16 v[8:11], v[120:123], v[202:205], 0
	v_mfma_f32_16x16x32_bf16 v[60:63], v[108:111], v[164:167], v[60:63]
	v_mfma_f32_16x16x32_bf16 v[56:59], v[128:131], v[164:167], v[56:59]
	v_mfma_f32_16x16x32_bf16 v[44:47], v[108:111], v[172:175], v[44:47]
	v_mfma_f32_16x16x32_bf16 v[40:43], v[128:131], v[172:175], v[40:43]
	v_mfma_f32_16x16x32_bf16 v[28:31], v[108:111], v[180:183], v[28:31]
	v_mfma_f32_16x16x32_bf16 v[24:27], v[128:131], v[180:183], v[24:27]
	v_mfma_f32_16x16x32_bf16 v[12:15], v[108:111], v[206:209], v[12:15]
	v_mfma_f32_16x16x32_bf16 v[8:11], v[128:131], v[206:209], v[8:11]
	v_mfma_f32_16x16x32_bf16 v[52:55], v[144:147], v[160:163], 0
	v_mfma_f32_16x16x32_bf16 v[48:51], v[152:155], v[160:163], 0
	v_mfma_f32_16x16x32_bf16 v[36:39], v[144:147], v[168:171], 0
	v_mfma_f32_16x16x32_bf16 v[32:35], v[152:155], v[168:171], 0
	v_mfma_f32_16x16x32_bf16 v[20:23], v[144:147], v[176:179], 0
	v_mfma_f32_16x16x32_bf16 v[16:19], v[152:155], v[176:179], 0
	v_mfma_f32_16x16x32_bf16 v[4:7], v[144:147], v[202:205], 0
	v_mfma_f32_16x16x32_bf16 v[0:3], v[152:155], v[202:205], 0
	v_mfma_f32_16x16x32_bf16 v[52:55], v[148:151], v[164:167], v[52:55]
	v_mfma_f32_16x16x32_bf16 v[48:51], v[156:159], v[164:167], v[48:51]
	v_mfma_f32_16x16x32_bf16 v[36:39], v[148:151], v[172:175], v[36:39]
	v_mfma_f32_16x16x32_bf16 v[32:35], v[156:159], v[172:175], v[32:35]
	v_mfma_f32_16x16x32_bf16 v[20:23], v[148:151], v[180:183], v[20:23]
	v_mfma_f32_16x16x32_bf16 v[16:19], v[156:159], v[180:183], v[16:19]
	v_mfma_f32_16x16x32_bf16 v[4:7], v[148:151], v[206:209], v[4:7]
	v_mfma_f32_16x16x32_bf16 v[0:3], v[156:159], v[206:209], v[0:3]
	s_setprio 0
	s_barrier
	s_add_i32 s77, 0, 0x18000
	s_add_i32 s78, 0, 0x1c000
	v_add_u32_e32 v128, s77, v221
	v_add_u32_e32 v156, s78, v221
	ds_read_b128 v[96:99], v128
	ds_read_b128 v[108:111], v128 offset:1024
	ds_read_b128 v[120:123], v128 offset:2048
	ds_read_b128 v[128:131], v128 offset:3072
	ds_read_b128 v[144:147], v156
	ds_read_b128 v[148:151], v156 offset:1024
	ds_read_b128 v[152:155], v156 offset:2048
	ds_read_b128 v[156:159], v156 offset:3072
	s_add_u32 s56, s56, 0x40000
	s_addc_u32 s57, s57, 0
	s_mov_b32 m0, s60
	ds_read_b128 v[160:163], v225 offset:32768
	ds_read_b128 v[164:167], v225 offset:33792
	ds_read_b128 v[168:171], v225 offset:34816
	ds_read_b128 v[172:175], v225 offset:35840
	ds_read_b128 v[176:179], v225 offset:36864
	ds_read_b128 v[180:183], v225 offset:37888
	ds_read_b128 v[202:205], v225 offset:38912
	ds_read_b128 v[206:209], v225 offset:39936
	global_load_lds_dwordx4 v184, s[56:57]
	s_mov_b32 m0, s61
	s_nop 0
	global_load_lds_dwordx4 v188, s[56:57]
	s_waitcnt vmcnt(8)
	s_waitcnt lgkmcnt(0)
	s_barrier
	s_setprio 1
	s_waitcnt lgkmcnt(0)
	v_mfma_f32_16x16x32_bf16 v[140:143], v[96:99], v[160:163], v[140:143]
	v_mfma_f32_16x16x32_bf16 v[136:139], v[120:123], v[160:163], v[136:139]
	v_mfma_f32_16x16x32_bf16 v[116:119], v[96:99], v[168:171], v[116:119]
	v_mfma_f32_16x16x32_bf16 v[112:115], v[120:123], v[168:171], v[112:115]
	v_mfma_f32_16x16x32_bf16 v[92:95], v[96:99], v[176:179], v[92:95]
	v_mfma_f32_16x16x32_bf16 v[88:91], v[120:123], v[176:179], v[88:91]
	v_mfma_f32_16x16x32_bf16 v[76:79], v[96:99], v[202:205], v[76:79]
	v_mfma_f32_16x16x32_bf16 v[72:75], v[120:123], v[202:205], v[72:75]
	v_mfma_f32_16x16x32_bf16 v[140:143], v[108:111], v[164:167], v[140:143]
	v_mfma_f32_16x16x32_bf16 v[136:139], v[128:131], v[164:167], v[136:139]
	v_mfma_f32_16x16x32_bf16 v[116:119], v[108:111], v[172:175], v[116:119]
	v_mfma_f32_16x16x32_bf16 v[112:115], v[128:131], v[172:175], v[112:115]
	v_mfma_f32_16x16x32_bf16 v[92:95], v[108:111], v[180:183], v[92:95]
	v_mfma_f32_16x16x32_bf16 v[88:91], v[128:131], v[180:183], v[88:91]
	v_mfma_f32_16x16x32_bf16 v[76:79], v[108:111], v[206:209], v[76:79]
	v_mfma_f32_16x16x32_bf16 v[72:75], v[128:131], v[206:209], v[72:75]
	v_mfma_f32_16x16x32_bf16 v[132:135], v[144:147], v[160:163], v[132:135]
	v_mfma_f32_16x16x32_bf16 v[124:127], v[152:155], v[160:163], v[124:127]
	v_mfma_f32_16x16x32_bf16 v[104:107], v[144:147], v[168:171], v[104:107]
	v_mfma_f32_16x16x32_bf16 v[100:103], v[152:155], v[168:171], v[100:103]
	v_mfma_f32_16x16x32_bf16 v[84:87], v[144:147], v[176:179], v[84:87]
	v_mfma_f32_16x16x32_bf16 v[80:83], v[152:155], v[176:179], v[80:83]
	v_mfma_f32_16x16x32_bf16 v[68:71], v[144:147], v[202:205], v[68:71]
	v_mfma_f32_16x16x32_bf16 v[64:67], v[152:155], v[202:205], v[64:67]
	v_mfma_f32_16x16x32_bf16 v[132:135], v[148:151], v[164:167], v[132:135]
	v_mfma_f32_16x16x32_bf16 v[124:127], v[156:159], v[164:167], v[124:127]
	v_mfma_f32_16x16x32_bf16 v[104:107], v[148:151], v[172:175], v[104:107]
	v_mfma_f32_16x16x32_bf16 v[100:103], v[156:159], v[172:175], v[100:103]
	v_mfma_f32_16x16x32_bf16 v[84:87], v[148:151], v[180:183], v[84:87]
	v_mfma_f32_16x16x32_bf16 v[80:83], v[156:159], v[180:183], v[80:83]
	v_mfma_f32_16x16x32_bf16 v[68:71], v[148:151], v[206:209], v[68:71]
	v_mfma_f32_16x16x32_bf16 v[64:67], v[156:159], v[206:209], v[64:67]
	s_setprio 0
	s_barrier
; #define PG8_STAGE(bufoff, gbase, voff) do { _Pragma("unroll") for (int _i = 0; _i < 2; ++_i) \
;         __builtin_amdgcn_global_load_lds((const unsigned*)((const char*)(gbase) + (voff)[_i]), (PG8_LAS unsigned*)(lds + (bufoff) + ldsw + _i * 8192), 16, 0, 0); } while (0)
; #define PG8_LDA(dst, b, h) do { _Pragma("unroll") for (int m = 0; m < 4; ++m) _Pragma("unroll") for (int k = 0; k < 2; ++k) dst[m][k] = *(const PG8_LAS bf16x8*)(lds + PG8_SA(b, h) + aoff + m * 2048 + k * 1024); } while (0)
; #define PG8_MMA(ai, bj, At, Bt) do { __builtin_amdgcn_s_setprio(1); _Pragma("unroll") for (int m = 0; m < 4; ++m) _Pragma("unroll") for (int n = 0; n < 2; ++n) _Pragma("unroll") for (int k = 0; k < 2; ++k) \
;         acc[ai][bj][m][n] = __builtin_amdgcn_mfma_f32_16x16x32_bf16(Bt[n][k], At[m][k], acc[ai][bj][m][n], 0, 0, 0); __builtin_amdgcn_s_setprio(0); } while (0)
; #define PG8_WAIT_V(n) asm volatile("s_waitcnt vmcnt(" #n ")" ::: "memory")
; #define PG8_WAIT_L(n) asm volatile("s_waitcnt lgkmcnt(" #n ")" ::: "memory")
; #define PG8_BAR __builtin_amdgcn_s_barrier()
; #define PG8_SCHED __builtin_amdgcn_sched_barrier(0)
; template <class Epi, class Sched, bool ALIGN_EPI = false, bool SP2 = false>
; __device__ __forceinline__ void gemm_phase(PG8_LAS unsigned char* lds, const Gemm g, const Sched& S, const Epi& E) {
;     ...
;             PG8_LDA(At, 1, 1); PG8_STAGE(PG8_SB(1, 0), b3, voffB); PG8_STAGE(PG8_SB(1, 1), b3 + hstep, voffB); PG8_STAGE(PG8_SA(1, 0), a3, voffA);
;             PG8_WAIT_V(8); PG8_WAIT_L(0); PG8_BAR; PG8_MMA(1, 0, At, B0); PG8_MMA(1, 1, At, B1); PG8_BAR; PG8_SCHED;
	s_add_i32 s56, s77, s58
	s_mov_b32 m0, s56
	ds_read_b128 v[160:163], v225 offset:49152
	ds_read_b128 v[164:167], v225 offset:50176
	ds_read_b128 v[168:171], v225 offset:51200
	ds_read_b128 v[172:175], v225 offset:52224
	ds_read_b128 v[176:179], v225 offset:53248
	ds_read_b128 v[180:183], v225 offset:54272
	ds_read_b128 v[202:205], v225 offset:55296
	ds_read_b128 v[206:209], v225 offset:56320
	global_load_lds_dwordx4 v186, s[98:99]
	s_add_i32 m0, s56, 0x2000
	s_add_u32 s54, s54, 0x40080
	s_addc_u32 s55, s55, 0
	s_add_i32 s56, s78, s58
	global_load_lds_dwordx4 v190, s[98:99]
	s_mov_b32 m0, s56
	s_nop 0
	global_load_lds_dwordx4 v186, s[54:55]
	s_add_i32 m0, s56, 0x2000
	s_nop 0
	global_load_lds_dwordx4 v190, s[54:55]
	s_mov_b32 m0, s66
	s_nop 0
	global_load_lds_dwordx4 v184, s[100:101]
	s_mov_b32 m0, s67
	s_nop 0
	global_load_lds_dwordx4 v188, s[100:101]
	s_waitcnt vmcnt(8)
	s_waitcnt lgkmcnt(0)
	s_barrier
	s_setprio 1
	s_waitcnt lgkmcnt(0)
	v_mfma_f32_16x16x32_bf16 v[60:63], v[96:99], v[160:163], v[60:63]
	v_mfma_f32_16x16x32_bf16 v[56:59], v[120:123], v[160:163], v[56:59]
	v_mfma_f32_16x16x32_bf16 v[44:47], v[96:99], v[168:171], v[44:47]
	v_mfma_f32_16x16x32_bf16 v[40:43], v[120:123], v[168:171], v[40:43]
	v_mfma_f32_16x16x32_bf16 v[28:31], v[96:99], v[176:179], v[28:31]
	v_mfma_f32_16x16x32_bf16 v[24:27], v[120:123], v[176:179], v[24:27]
	v_mfma_f32_16x16x32_bf16 v[12:15], v[96:99], v[202:205], v[12:15]
	v_mfma_f32_16x16x32_bf16 v[8:11], v[120:123], v[202:205], v[8:11]
	v_mfma_f32_16x16x32_bf16 v[60:63], v[108:111], v[164:167], v[60:63]
	v_mfma_f32_16x16x32_bf16 v[56:59], v[128:131], v[164:167], v[56:59]
	v_mfma_f32_16x16x32_bf16 v[44:47], v[108:111], v[172:175], v[44:47]
	v_mfma_f32_16x16x32_bf16 v[40:43], v[128:131], v[172:175], v[40:43]
	v_mfma_f32_16x16x32_bf16 v[28:31], v[108:111], v[180:183], v[28:31]
	v_mfma_f32_16x16x32_bf16 v[24:27], v[128:131], v[180:183], v[24:27]
	v_mfma_f32_16x16x32_bf16 v[12:15], v[108:111], v[206:209], v[12:15]
	v_mfma_f32_16x16x32_bf16 v[8:11], v[128:131], v[206:209], v[8:11]
	v_mfma_f32_16x16x32_bf16 v[52:55], v[144:147], v[160:163], v[52:55]
	v_mfma_f32_16x16x32_bf16 v[48:51], v[152:155], v[160:163], v[48:51]
	v_mfma_f32_16x16x32_bf16 v[36:39], v[144:147], v[168:171], v[36:39]
	v_mfma_f32_16x16x32_bf16 v[32:35], v[152:155], v[168:171], v[32:35]
	v_mfma_f32_16x16x32_bf16 v[20:23], v[144:147], v[176:179], v[20:23]
	v_mfma_f32_16x16x32_bf16 v[16:19], v[152:155], v[176:179], v[16:19]
	v_mfma_f32_16x16x32_bf16 v[4:7], v[144:147], v[202:205], v[4:7]
	v_mfma_f32_16x16x32_bf16 v[0:3], v[152:155], v[202:205], v[0:3]
	v_mfma_f32_16x16x32_bf16 v[52:55], v[148:151], v[164:167], v[52:55]
	v_mfma_f32_16x16x32_bf16 v[48:51], v[156:159], v[164:167], v[48:51]
	v_mfma_f32_16x16x32_bf16 v[36:39], v[148:151], v[172:175], v[36:39]
	v_mfma_f32_16x16x32_bf16 v[32:35], v[156:159], v[172:175], v[32:35]
	v_mfma_f32_16x16x32_bf16 v[20:23], v[148:151], v[180:183], v[20:23]
	v_mfma_f32_16x16x32_bf16 v[16:19], v[156:159], v[180:183], v[16:19]
	v_mfma_f32_16x16x32_bf16 v[4:7], v[148:151], v[206:209], v[4:7]
	v_mfma_f32_16x16x32_bf16 v[0:3], v[156:159], v[206:209], v[0:3]
	s_setprio 0
	s_barrier
	s_add_i32 s76, s76, 2
	s_add_u32 s20, s20, 0x100
	s_addc_u32 s21, s21, 0
	s_add_u32 s74, s74, 0x100
	s_addc_u32 s75, s75, 0
	s_cmp_gt_u32 s76, 13

; #define PG8_STAGE(bufoff, gbase, voff) do { _Pragma("unroll") for (int _i = 0; _i < 2; ++_i) \
;         __builtin_amdgcn_global_load_lds((const unsigned*)((const char*)(gbase) + (voff)[_i]), (PG8_LAS unsigned*)(lds + (bufoff) + ldsw + _i * 8192), 16, 0, 0); } while (0)
; #define PG8_LDA(dst, b, h) do { _Pragma("unroll") for (int m = 0; m < 4; ++m) _Pragma("unroll") for (int k = 0; k < 2; ++k) dst[m][k] = *(const PG8_LAS bf16x8*)(lds + PG8_SA(b, h) + aoff + m * 2048 + k * 1024); } while (0)
; #define PG8_LDB(dst, b, h) do { _Pragma("unroll") for (int n = 0; n < 2; ++n) _Pragma("unroll") for (int k = 0; k < 2; ++k) dst[n][k] = *(const PG8_LAS bf16x8*)(lds + PG8_SB(b, h) + boff + n * 2048 + k * 1024); } while (0)
; #define PG8_MMA(ai, bj, At, Bt) do { __builtin_amdgcn_s_setprio(1); _Pragma("unroll") for (int m = 0; m < 4; ++m) _Pragma("unroll") for (int n = 0; n < 2; ++n) _Pragma("unroll") for (int k = 0; k < 2; ++k) \
;         acc[ai][bj][m][n] = __builtin_amdgcn_mfma_f32_16x16x32_bf16(Bt[n][k], At[m][k], acc[ai][bj][m][n], 0, 0, 0); __builtin_amdgcn_s_setprio(0); } while (0)
; #define PG8_WAIT_V(n) asm volatile("s_waitcnt vmcnt(" #n ")" ::: "memory")
; template <class Epi, class Sched, bool ALIGN_EPI = false, bool SP2 = false>
; __device__ __forceinline__ void gemm_phase(PG8_LAS unsigned char* lds, const Gemm g, const Sched& S, const Epi& E) {
;     ...
;         const char* nA = has_next ? (const char*)g.A + (size_t)nxt.pm * tstep : cA; const char* nB = has_next ? (const char*)g.Bt + (size_t)nxt.pn * tstep : cB;
;         for (int t = 0; t < nt; t += 2) {
;             const bool last = (t == nt - 2);
;             const char* a1 = cA + (size_t)(t + 1) * kstep;
;             const char* a2 = last ? nA : cA + (size_t)(t + 2) * kstep; const char* b2 = last ? nB : cB + (size_t)(t + 2) * kstep;
;             const char* a3 = a2 + kstep; const char* b3 = b2 + kstep;
;             if (last && has_next) S.a_ready(nxt);
;             if constexpr (SP2) {
;             PG8_LDB(B0, 0, 0); PG8_LDB(B1, 0, 1); PG8_SCHED; PG8_LDA(At, 0, 0); PG8_STAGE(PG8_SA(1, 1), a1 + hstep, voffA);
;             PG8_WAIT_V(8); PG8_WAIT_L(0); PG8_BAR; PG8_MMA(0, 0, At, B0); PG8_MMA(0, 1, At, B1); PG8_BAR; PG8_SCHED;
;             PG8_LDA(At, 0, 1); PG8_STAGE(PG8_SB(0, 0), b2, voffB); PG8_STAGE(PG8_SB(0, 1), b2 + hstep, voffB); PG8_STAGE(PG8_SA(0, 0), a2, voffA);
.LBB0_1739:
	s_ashr_i32 s15, s14, 31
	s_lshl_b64 s[16:17], s[14:15], 19
	s_add_u32 s16, s36, s16
	s_addc_u32 s17, s37, s17
	s_and_b64 s[18:19], s[4:5], exec
	s_cselect_b32 s15, s17, s21
	s_cselect_b32 s63, s16, s20
	s_ashr_i32 s13, s12, 31
	s_lshl_b64 s[18:19], s[12:13], 19
	s_add_u32 s18, s48, s18
	s_addc_u32 s19, s49, s19
	s_and_b64 s[42:43], s[4:5], exec
	s_cselect_b32 s13, s19, s39
	s_cselect_b32 s64, s18, s38
	s_add_u32 s20, s20, 0x40080
	s_addc_u32 s21, s21, 0
	s_add_u32 s65, s38, 0x100
	s_addc_u32 s66, s39, 0
	s_mov_b32 s67, -2
	ds_read_b128 v[154:157], v150
	ds_read_b128 v[158:161], v150 offset:1024
	ds_read_b128 v[162:165], v150 offset:2048
	ds_read_b128 v[166:169], v150 offset:3072
	ds_read_b128 v[170:173], v151
	ds_read_b128 v[174:177], v151 offset:1024
	ds_read_b128 v[178:181], v151 offset:2048
	ds_read_b128 v[182:185], v151 offset:3072
	s_add_u32 s38, s20, 0xfffc0080
	s_addc_u32 s39, s21, -1
	s_cmp_eq_u32 s67, 12
	s_cselect_b32 s43, s15, s39
	s_cselect_b32 s42, s63, s38
	s_cselect_b32 s39, s13, s66
	s_cselect_b32 s38, s64, s65
	s_add_i32 m0, s35, 0xc000
	ds_read_b128 v[186:189], v152
	ds_read_b128 v[190:193], v152 offset:1024
	ds_read_b128 v[198:201], v152 offset:2048
	ds_read_b128 v[202:205], v152 offset:3072
	ds_read_b128 v[206:209], v152 offset:4096
	ds_read_b128 v[210:213], v152 offset:5120
	ds_read_b128 v[214:217], v152 offset:6144
	ds_read_b128 v[218:221], v152 offset:7168
	global_load_lds_dwordx4 v136, s[20:21]
	s_add_i32 m0, s35, 0xe000
	s_nop 0
	global_load_lds_dwordx4 v138, s[20:21]
	s_waitcnt vmcnt(8)
	s_waitcnt lgkmcnt(0)
	s_barrier
	s_setprio 1
	s_waitcnt lgkmcnt(0)
	v_mfma_f32_16x16x32_bf16 v[124:127], v[154:157], v[186:189], 0
	v_mfma_f32_16x16x32_bf16 v[116:119], v[162:165], v[186:189], 0
	v_mfma_f32_16x16x32_bf16 v[108:111], v[154:157], v[198:201], 0
	v_mfma_f32_16x16x32_bf16 v[100:103], v[162:165], v[198:201], 0
	v_mfma_f32_16x16x32_bf16 v[92:95], v[154:157], v[206:209], 0
	v_mfma_f32_16x16x32_bf16 v[84:87], v[162:165], v[206:209], 0
	v_mfma_f32_16x16x32_bf16 v[76:79], v[154:157], v[214:217], 0
	v_mfma_f32_16x16x32_bf16 v[68:71], v[162:165], v[214:217], 0
	v_mfma_f32_16x16x32_bf16 v[124:127], v[158:161], v[190:193], v[124:127]
	v_mfma_f32_16x16x32_bf16 v[116:119], v[166:169], v[190:193], v[116:119]
	v_mfma_f32_16x16x32_bf16 v[108:111], v[158:161], v[202:205], v[108:111]
	v_mfma_f32_16x16x32_bf16 v[100:103], v[166:169], v[202:205], v[100:103]
	v_mfma_f32_16x16x32_bf16 v[92:95], v[158:161], v[210:213], v[92:95]
	v_mfma_f32_16x16x32_bf16 v[84:87], v[166:169], v[210:213], v[84:87]
	v_mfma_f32_16x16x32_bf16 v[76:79], v[158:161], v[218:221], v[76:79]
	v_mfma_f32_16x16x32_bf16 v[68:71], v[166:169], v[218:221], v[68:71]
	v_mfma_f32_16x16x32_bf16 v[120:123], v[170:173], v[186:189], 0
	v_mfma_f32_16x16x32_bf16 v[112:115], v[178:181], v[186:189], 0
	v_mfma_f32_16x16x32_bf16 v[104:107], v[170:173], v[198:201], 0
	v_mfma_f32_16x16x32_bf16 v[96:99], v[178:181], v[198:201], 0
	v_mfma_f32_16x16x32_bf16 v[88:91], v[170:173], v[206:209], 0
	v_mfma_f32_16x16x32_bf16 v[80:83], v[178:181], v[206:209], 0
	v_mfma_f32_16x16x32_bf16 v[72:75], v[170:173], v[214:217], 0
	v_mfma_f32_16x16x32_bf16 v[64:67], v[178:181], v[214:217], 0
	v_mfma_f32_16x16x32_bf16 v[120:123], v[174:177], v[190:193], v[120:123]
	v_mfma_f32_16x16x32_bf16 v[112:115], v[182:185], v[190:193], v[112:115]
	v_mfma_f32_16x16x32_bf16 v[104:107], v[174:177], v[202:205], v[104:107]
	v_mfma_f32_16x16x32_bf16 v[96:99], v[182:185], v[202:205], v[96:99]
	v_mfma_f32_16x16x32_bf16 v[88:91], v[174:177], v[210:213], v[88:91]
	v_mfma_f32_16x16x32_bf16 v[80:83], v[182:185], v[210:213], v[80:83]
	v_mfma_f32_16x16x32_bf16 v[72:75], v[174:177], v[218:221], v[72:75]
	v_mfma_f32_16x16x32_bf16 v[64:67], v[182:185], v[218:221], v[64:67]
	s_setprio 0
	s_barrier
	s_add_i32 s68, s58, s50
	s_add_u32 s98, s38, s8
	s_addc_u32 s99, s39, s9
	s_add_u32 s100, s42, s8
	s_addc_u32 s101, s43, s9
	s_mov_b32 m0, s68
	ds_read_b128 v[186:189], v152 offset:16384
	ds_read_b128 v[190:193], v152 offset:17408
	ds_read_b128 v[198:201], v152 offset:18432
	ds_read_b128 v[202:205], v152 offset:19456
	ds_read_b128 v[206:209], v152 offset:20480
	ds_read_b128 v[210:213], v152 offset:21504
	ds_read_b128 v[214:217], v152 offset:22528
	ds_read_b128 v[218:221], v152 offset:23552
	global_load_lds_dwordx4 v132, s[38:39]
	s_add_i32 m0, s68, 0x2000
	s_add_u32 s68, s38, 0x40000
	s_addc_u32 s69, s39, 0
	s_add_i32 s70, s59, s50
	global_load_lds_dwordx4 v128, s[38:39]
	s_mov_b32 m0, s70
	s_nop 0
	global_load_lds_dwordx4 v132, s[68:69]
	s_add_i32 m0, s70, 0x2000
	s_nop 0
	global_load_lds_dwordx4 v128, s[68:69]
	s_mov_b32 m0, s35
	s_nop 0
	global_load_lds_dwordx4 v134, s[42:43]
	s_mov_b32 m0, s52
	s_nop 0
	global_load_lds_dwordx4 v130, s[42:43]
	s_waitcnt vmcnt(8)
	s_waitcnt lgkmcnt(0)
	s_barrier
; #define PG8_STAGE(bufoff, gbase, voff) do { _Pragma("unroll") for (int _i = 0; _i < 2; ++_i) \
;         __builtin_amdgcn_global_load_lds((const unsigned*)((const char*)(gbase) + (voff)[_i]), (PG8_LAS unsigned*)(lds + (bufoff) + ldsw + _i * 8192), 16, 0, 0); } while (0)
; #define PG8_LDA(dst, b, h) do { _Pragma("unroll") for (int m = 0; m < 4; ++m) _Pragma("unroll") for (int k = 0; k < 2; ++k) dst[m][k] = *(const PG8_LAS bf16x8*)(lds + PG8_SA(b, h) + aoff + m * 2048 + k * 1024); } while (0)
; #define PG8_LDB(dst, b, h) do { _Pragma("unroll") for (int n = 0; n < 2; ++n) _Pragma("unroll") for (int k = 0; k < 2; ++k) dst[n][k] = *(const PG8_LAS bf16x8*)(lds + PG8_SB(b, h) + boff + n * 2048 + k * 1024); } while (0)
; #define PG8_MMA(ai, bj, At, Bt) do { __builtin_amdgcn_s_setprio(1); _Pragma("unroll") for (int m = 0; m < 4; ++m) _Pragma("unroll") for (int n = 0; n < 2; ++n) _Pragma("unroll") for (int k = 0; k < 2; ++k) \
;         acc[ai][bj][m][n] = __builtin_amdgcn_mfma_f32_16x16x32_bf16(Bt[n][k], At[m][k], acc[ai][bj][m][n], 0, 0, 0); __builtin_amdgcn_s_setprio(0); } while (0)
; #define PG8_WAIT_V(n) asm volatile("s_waitcnt vmcnt(" #n ")" ::: "memory")
; #define PG8_WAIT_L(n) asm volatile("s_waitcnt lgkmcnt(" #n ")" ::: "memory")
; #define PG8_BAR __builtin_amdgcn_s_barrier()
; #define PG8_SCHED __builtin_amdgcn_sched_barrier(0)
; template <class Epi, class Sched, bool ALIGN_EPI = false, bool SP2 = false>
; __device__ __forceinline__ void gemm_phase(PG8_LAS unsigned char* lds, const Gemm g, const Sched& S, const Epi& E) {
;     ...
;             PG8_WAIT_V(8); PG8_WAIT_L(0); PG8_BAR; PG8_MMA(1, 0, At, B0); PG8_MMA(1, 1, At, B1); PG8_BAR; PG8_SCHED;
;             PG8_LDB(B0, 1, 0); PG8_LDB(B1, 1, 1); PG8_SCHED; PG8_LDA(At, 1, 0); PG8_STAGE(PG8_SA(0, 1), a2 + hstep, voffA);
;             PG8_WAIT_V(8); PG8_WAIT_L(0); PG8_BAR; PG8_MMA(0, 0, At, B0); PG8_MMA(0, 1, At, B1); PG8_BAR; PG8_SCHED;
	s_setprio 1
	s_waitcnt lgkmcnt(0)
	v_mfma_f32_16x16x32_bf16 v[60:63], v[154:157], v[186:189], 0
	v_mfma_f32_16x16x32_bf16 v[52:55], v[162:165], v[186:189], 0
	v_mfma_f32_16x16x32_bf16 v[44:47], v[154:157], v[198:201], 0
	v_mfma_f32_16x16x32_bf16 v[36:39], v[162:165], v[198:201], 0
	v_mfma_f32_16x16x32_bf16 v[28:31], v[154:157], v[206:209], 0
	v_mfma_f32_16x16x32_bf16 v[20:23], v[162:165], v[206:209], 0
	v_mfma_f32_16x16x32_bf16 v[12:15], v[154:157], v[214:217], 0
	v_mfma_f32_16x16x32_bf16 v[4:7], v[162:165], v[214:217], 0
	v_mfma_f32_16x16x32_bf16 v[60:63], v[158:161], v[190:193], v[60:63]
	v_mfma_f32_16x16x32_bf16 v[52:55], v[166:169], v[190:193], v[52:55]
	v_mfma_f32_16x16x32_bf16 v[44:47], v[158:161], v[202:205], v[44:47]
	v_mfma_f32_16x16x32_bf16 v[36:39], v[166:169], v[202:205], v[36:39]
	v_mfma_f32_16x16x32_bf16 v[28:31], v[158:161], v[210:213], v[28:31]
	v_mfma_f32_16x16x32_bf16 v[20:23], v[166:169], v[210:213], v[20:23]
	v_mfma_f32_16x16x32_bf16 v[12:15], v[158:161], v[218:221], v[12:15]
	v_mfma_f32_16x16x32_bf16 v[4:7], v[166:169], v[218:221], v[4:7]
	v_mfma_f32_16x16x32_bf16 v[56:59], v[170:173], v[186:189], 0
	v_mfma_f32_16x16x32_bf16 v[48:51], v[178:181], v[186:189], 0
	v_mfma_f32_16x16x32_bf16 v[40:43], v[170:173], v[198:201], 0
	v_mfma_f32_16x16x32_bf16 v[32:35], v[178:181], v[198:201], 0
	v_mfma_f32_16x16x32_bf16 v[24:27], v[170:173], v[206:209], 0
	v_mfma_f32_16x16x32_bf16 v[16:19], v[178:181], v[206:209], 0
	v_mfma_f32_16x16x32_bf16 v[8:11], v[170:173], v[214:217], 0
	v_mfma_f32_16x16x32_bf16 v[0:3], v[178:181], v[214:217], 0
	v_mfma_f32_16x16x32_bf16 v[56:59], v[174:177], v[190:193], v[56:59]
	v_mfma_f32_16x16x32_bf16 v[48:51], v[182:185], v[190:193], v[48:51]
	v_mfma_f32_16x16x32_bf16 v[40:43], v[174:177], v[202:205], v[40:43]
	v_mfma_f32_16x16x32_bf16 v[32:35], v[182:185], v[202:205], v[32:35]
	v_mfma_f32_16x16x32_bf16 v[24:27], v[174:177], v[210:213], v[24:27]
	v_mfma_f32_16x16x32_bf16 v[16:19], v[182:185], v[210:213], v[16:19]
	v_mfma_f32_16x16x32_bf16 v[8:11], v[174:177], v[218:221], v[8:11]
	v_mfma_f32_16x16x32_bf16 v[0:3], v[182:185], v[218:221], v[0:3]
	s_setprio 0
	s_barrier
	s_add_i32 s68, 0, 0x18000
	v_add_u32_e32 v153, s68, v147
	s_add_i32 s69, 0, 0x1c000
	ds_read_b128 v[154:157], v153
	ds_read_b128 v[158:161], v153 offset:1024
	ds_read_b128 v[162:165], v153 offset:2048
	ds_read_b128 v[166:169], v153 offset:3072
	v_add_u32_e32 v153, s69, v147
	ds_read_b128 v[170:173], v153
	ds_read_b128 v[174:177], v153 offset:1024
	ds_read_b128 v[178:181], v153 offset:2048
	ds_read_b128 v[182:185], v153 offset:3072
	s_add_u32 s42, s42, 0x40000
	s_addc_u32 s43, s43, 0
	s_mov_b32 m0, s53
	ds_read_b128 v[186:189], v152 offset:32768
	ds_read_b128 v[190:193], v152 offset:33792
	ds_read_b128 v[198:201], v152 offset:34816
	ds_read_b128 v[202:205], v152 offset:35840
	ds_read_b128 v[206:209], v152 offset:36864
	ds_read_b128 v[210:213], v152 offset:37888
	ds_read_b128 v[214:217], v152 offset:38912
	ds_read_b128 v[218:221], v152 offset:39936
	global_load_lds_dwordx4 v134, s[42:43]
	s_mov_b32 m0, s54
	s_nop 0
	global_load_lds_dwordx4 v130, s[42:43]
	s_waitcnt vmcnt(8)
	s_waitcnt lgkmcnt(0)
	s_barrier
	s_setprio 1
	s_waitcnt lgkmcnt(0)
	v_mfma_f32_16x16x32_bf16 v[124:127], v[154:157], v[186:189], v[124:127]
	v_mfma_f32_16x16x32_bf16 v[116:119], v[162:165], v[186:189], v[116:119]
	v_mfma_f32_16x16x32_bf16 v[108:111], v[154:157], v[198:201], v[108:111]
	v_mfma_f32_16x16x32_bf16 v[100:103], v[162:165], v[198:201], v[100:103]
	v_mfma_f32_16x16x32_bf16 v[92:95], v[154:157], v[206:209], v[92:95]
	v_mfma_f32_16x16x32_bf16 v[84:87], v[162:165], v[206:209], v[84:87]
	v_mfma_f32_16x16x32_bf16 v[76:79], v[154:157], v[214:217], v[76:79]
	v_mfma_f32_16x16x32_bf16 v[68:71], v[162:165], v[214:217], v[68:71]
	v_mfma_f32_16x16x32_bf16 v[124:127], v[158:161], v[190:193], v[124:127]
	v_mfma_f32_16x16x32_bf16 v[116:119], v[166:169], v[190:193], v[116:119]
	v_mfma_f32_16x16x32_bf16 v[108:111], v[158:161], v[202:205], v[108:111]
	v_mfma_f32_16x16x32_bf16 v[100:103], v[166:169], v[202:205], v[100:103]
	v_mfma_f32_16x16x32_bf16 v[92:95], v[158:161], v[210:213], v[92:95]
	v_mfma_f32_16x16x32_bf16 v[84:87], v[166:169], v[210:213], v[84:87]
	v_mfma_f32_16x16x32_bf16 v[76:79], v[158:161], v[218:221], v[76:79]
	v_mfma_f32_16x16x32_bf16 v[68:71], v[166:169], v[218:221], v[68:71]
	v_mfma_f32_16x16x32_bf16 v[120:123], v[170:173], v[186:189], v[120:123]
	v_mfma_f32_16x16x32_bf16 v[112:115], v[178:181], v[186:189], v[112:115]
	v_mfma_f32_16x16x32_bf16 v[104:107], v[170:173], v[198:201], v[104:107]
	v_mfma_f32_16x16x32_bf16 v[96:99], v[178:181], v[198:201], v[96:99]
	v_mfma_f32_16x16x32_bf16 v[88:91], v[170:173], v[206:209], v[88:91]
	v_mfma_f32_16x16x32_bf16 v[80:83], v[178:181], v[206:209], v[80:83]
	v_mfma_f32_16x16x32_bf16 v[72:75], v[170:173], v[214:217], v[72:75]
	v_mfma_f32_16x16x32_bf16 v[64:67], v[178:181], v[214:217], v[64:67]
	v_mfma_f32_16x16x32_bf16 v[120:123], v[174:177], v[190:193], v[120:123]
	v_mfma_f32_16x16x32_bf16 v[112:115], v[182:185], v[190:193], v[112:115]
	v_mfma_f32_16x16x32_bf16 v[104:107], v[174:177], v[202:205], v[104:107]
	v_mfma_f32_16x16x32_bf16 v[96:99], v[182:185], v[202:205], v[96:99]
	v_mfma_f32_16x16x32_bf16 v[88:91], v[174:177], v[210:213], v[88:91]
	v_mfma_f32_16x16x32_bf16 v[80:83], v[182:185], v[210:213], v[80:83]
	v_mfma_f32_16x16x32_bf16 v[72:75], v[174:177], v[218:221], v[72:75]
	v_mfma_f32_16x16x32_bf16 v[64:67], v[182:185], v[218:221], v[64:67]
	s_setprio 0
	s_barrier
; #define PG8_STAGE(bufoff, gbase, voff) do { _Pragma("unroll") for (int _i = 0; _i < 2; ++_i) \
;         __builtin_amdgcn_global_load_lds((const unsigned*)((const char*)(gbase) + (voff)[_i]), (PG8_LAS unsigned*)(lds + (bufoff) + ldsw + _i * 8192), 16, 0, 0); } while (0)
; #define PG8_LDA(dst, b, h) do { _Pragma("unroll") for (int m = 0; m < 4; ++m) _Pragma("unroll") for (int k = 0; k < 2; ++k) dst[m][k] = *(const PG8_LAS bf16x8*)(lds + PG8_SA(b, h) + aoff + m * 2048 + k * 1024); } while (0)
; #define PG8_LDB(dst, b, h) do { _Pragma("unroll") for (int n = 0; n < 2; ++n) _Pragma("unroll") for (int k = 0; k < 2; ++k) dst[n][k] = *(const PG8_LAS bf16x8*)(lds + PG8_SB(b, h) + boff + n * 2048 + k * 1024); } while (0)
; #define PG8_MMA(ai, bj, At, Bt) do { __builtin_amdgcn_s_setprio(1); _Pragma("unroll") for (int m = 0; m < 4; ++m) _Pragma("unroll") for (int n = 0; n < 2; ++n) _Pragma("unroll") for (int k = 0; k < 2; ++k) \
;         acc[ai][bj][m][n] = __builtin_amdgcn_mfma_f32_16x16x32_bf16(Bt[n][k], At[m][k], acc[ai][bj][m][n], 0, 0, 0); __builtin_amdgcn_s_setprio(0); } while (0)
; #define PG8_WAIT_V(n) asm volatile("s_waitcnt vmcnt(" #n ")" ::: "memory")
; template <class Epi, class Sched, bool ALIGN_EPI = false, bool SP2 = false>
; __device__ __forceinline__ void gemm_phase(PG8_LAS unsigned char* lds, const Gemm g, const Sched& S, const Epi& E) {
;     ...
;             PG8_LDB(B0, 0, 0); PG8_LDB(B1, 0, 1); PG8_SCHED; PG8_LDA(At, 0, 0); PG8_STAGE(PG8_SA(1, 1), a1 + hstep, voffA);
;             PG8_WAIT_V(8); PG8_WAIT_L(0); PG8_BAR; PG8_MMA(0, 0, At, B0); PG8_MMA(0, 1, At, B1); PG8_BAR; PG8_SCHED;
;             PG8_LDA(At, 0, 1); PG8_STAGE(PG8_SB(0, 0), b2, voffB); PG8_STAGE(PG8_SB(0, 1), b2 + hstep, voffB); PG8_STAGE(PG8_SA(0, 0), a2, voffA);
;             PG8_WAIT_V(8); PG8_WAIT_L(0); PG8_BAR; PG8_MMA(1, 0, At, B0); PG8_MMA(1, 1, At, B1); PG8_BAR; PG8_SCHED;
;             PG8_LDB(B0, 1, 0); PG8_LDB(B1, 1, 1); PG8_SCHED; PG8_LDA(At, 1, 0); PG8_STAGE(PG8_SA(0, 1), a2 + hstep, voffA);
;             PG8_WAIT_V(8); PG8_WAIT_L(0); PG8_BAR; PG8_MMA(0, 0, At, B0); PG8_MMA(0, 1, At, B1); PG8_BAR; PG8_SCHED;
;             PG8_LDA(At, 1, 1); PG8_STAGE(PG8_SB(1, 0), b3, voffB); PG8_STAGE(PG8_SB(1, 1), b3 + hstep, voffB); PG8_STAGE(PG8_SA(1, 0), a3, voffA);
;             PG8_WAIT_V(8); PG8_WAIT_L(0); PG8_BAR; PG8_MMA(1, 0, At, B0); PG8_MMA(1, 1, At, B1); PG8_BAR; PG8_SCHED;
	s_add_i32 s42, s68, s50
	s_mov_b32 m0, s42
	ds_read_b128 v[186:189], v152 offset:49152
	ds_read_b128 v[190:193], v152 offset:50176
	ds_read_b128 v[198:201], v152 offset:51200
	ds_read_b128 v[202:205], v152 offset:52224
	ds_read_b128 v[206:209], v152 offset:53248
	ds_read_b128 v[210:213], v152 offset:54272
	ds_read_b128 v[214:217], v152 offset:55296
	ds_read_b128 v[218:221], v152 offset:56320
	global_load_lds_dwordx4 v132, s[98:99]
	s_add_i32 m0, s42, 0x2000
	s_add_u32 s38, s38, 0x40080
	s_addc_u32 s39, s39, 0
	s_add_i32 s42, s69, s50
	global_load_lds_dwordx4 v128, s[98:99]
	s_mov_b32 m0, s42
	s_nop 0
	global_load_lds_dwordx4 v132, s[38:39]
	s_add_i32 m0, s42, 0x2000
	s_nop 0
	global_load_lds_dwordx4 v128, s[38:39]
	s_mov_b32 m0, s56
	s_nop 0
	global_load_lds_dwordx4 v134, s[100:101]
	s_mov_b32 m0, s57
	s_nop 0
	global_load_lds_dwordx4 v130, s[100:101]
	s_waitcnt vmcnt(8)
	s_waitcnt lgkmcnt(0)
	s_barrier
	s_setprio 1
	s_waitcnt lgkmcnt(0)
	v_mfma_f32_16x16x32_bf16 v[60:63], v[154:157], v[186:189], v[60:63]
	v_mfma_f32_16x16x32_bf16 v[52:55], v[162:165], v[186:189], v[52:55]
	v_mfma_f32_16x16x32_bf16 v[44:47], v[154:157], v[198:201], v[44:47]
	v_mfma_f32_16x16x32_bf16 v[36:39], v[162:165], v[198:201], v[36:39]
	v_mfma_f32_16x16x32_bf16 v[28:31], v[154:157], v[206:209], v[28:31]
	v_mfma_f32_16x16x32_bf16 v[20:23], v[162:165], v[206:209], v[20:23]
	v_mfma_f32_16x16x32_bf16 v[12:15], v[154:157], v[214:217], v[12:15]
	v_mfma_f32_16x16x32_bf16 v[4:7], v[162:165], v[214:217], v[4:7]
	v_mfma_f32_16x16x32_bf16 v[60:63], v[158:161], v[190:193], v[60:63]
	v_mfma_f32_16x16x32_bf16 v[52:55], v[166:169], v[190:193], v[52:55]
	v_mfma_f32_16x16x32_bf16 v[44:47], v[158:161], v[202:205], v[44:47]
	v_mfma_f32_16x16x32_bf16 v[36:39], v[166:169], v[202:205], v[36:39]
	v_mfma_f32_16x16x32_bf16 v[28:31], v[158:161], v[210:213], v[28:31]
	v_mfma_f32_16x16x32_bf16 v[20:23], v[166:169], v[210:213], v[20:23]
	v_mfma_f32_16x16x32_bf16 v[12:15], v[158:161], v[218:221], v[12:15]
	v_mfma_f32_16x16x32_bf16 v[4:7], v[166:169], v[218:221], v[4:7]
	v_mfma_f32_16x16x32_bf16 v[56:59], v[170:173], v[186:189], v[56:59]
	v_mfma_f32_16x16x32_bf16 v[48:51], v[178:181], v[186:189], v[48:51]
	v_mfma_f32_16x16x32_bf16 v[40:43], v[170:173], v[198:201], v[40:43]
	v_mfma_f32_16x16x32_bf16 v[32:35], v[178:181], v[198:201], v[32:35]
	v_mfma_f32_16x16x32_bf16 v[24:27], v[170:173], v[206:209], v[24:27]
	v_mfma_f32_16x16x32_bf16 v[16:19], v[178:181], v[206:209], v[16:19]
	v_mfma_f32_16x16x32_bf16 v[8:11], v[170:173], v[214:217], v[8:11]
	v_mfma_f32_16x16x32_bf16 v[0:3], v[178:181], v[214:217], v[0:3]
	v_mfma_f32_16x16x32_bf16 v[56:59], v[174:177], v[190:193], v[56:59]
	v_mfma_f32_16x16x32_bf16 v[48:51], v[182:185], v[190:193], v[48:51]
	v_mfma_f32_16x16x32_bf16 v[40:43], v[174:177], v[202:205], v[40:43]
	v_mfma_f32_16x16x32_bf16 v[32:35], v[182:185], v[202:205], v[32:35]
	v_mfma_f32_16x16x32_bf16 v[24:27], v[174:177], v[210:213], v[24:27]
	v_mfma_f32_16x16x32_bf16 v[16:19], v[182:185], v[210:213], v[16:19]
	v_mfma_f32_16x16x32_bf16 v[8:11], v[174:177], v[218:221], v[8:11]
	v_mfma_f32_16x16x32_bf16 v[0:3], v[182:185], v[218:221], v[0:3]
	s_setprio 0
	s_barrier
	s_add_i32 s67, s67, 2
	s_add_u32 s20, s20, 0x100
	s_addc_u32 s21, s21, 0
	s_add_u32 s65, s65, 0x100
	s_addc_u32 s66, s66, 0
	s_cmp_gt_u32 s67, 13
.LBB0_1740:
	ds_read_b128 v[154:157], v150
	ds_read_b128 v[158:161], v150 offset:1024
	ds_read_b128 v[162:165], v150 offset:2048
	ds_read_b128 v[166:169], v150 offset:3072
	ds_read_b128 v[170:173], v151
	ds_read_b128 v[174:177], v151 offset:1024
	ds_read_b128 v[178:181], v151 offset:2048
	ds_read_b128 v[182:185], v151 offset:3072
	s_add_u32 s38, s20, 0xfffc0080
	s_addc_u32 s39, s21, -1
	s_cmp_eq_u32 s67, 12
	s_cselect_b32 s43, s15, s39
	s_cselect_b32 s42, s63, s38
	s_cselect_b32 s39, s13, s66
	s_cselect_b32 s38, s64, s65
	s_add_i32 m0, s35, 0xc000
	ds_read_b128 v[186:189], v152
	ds_read_b128 v[190:193], v152 offset:1024
	ds_read_b128 v[198:201], v152 offset:2048
	ds_read_b128 v[202:205], v152 offset:3072
	ds_read_b128 v[206:209], v152 offset:4096
	ds_read_b128 v[210:213], v152 offset:5120
	ds_read_b128 v[214:217], v152 offset:6144
	ds_read_b128 v[218:221], v152 offset:7168
	global_load_lds_dwordx4 v136, s[20:21]
	s_add_i32 m0, s35, 0xe000
	s_nop 0
	global_load_lds_dwordx4 v138, s[20:21]
	s_waitcnt vmcnt(8)
	s_waitcnt lgkmcnt(0)
	s_barrier
	s_setprio 1
	s_waitcnt lgkmcnt(0)
	v_mfma_f32_16x16x32_bf16 v[124:127], v[154:157], v[186:189], v[124:127]
	v_mfma_f32_16x16x32_bf16 v[116:119], v[162:165], v[186:189], v[116:119]
	v_mfma_f32_16x16x32_bf16 v[108:111], v[154:157], v[198:201], v[108:111]
	v_mfma_f32_16x16x32_bf16 v[100:103], v[162:165], v[198:201], v[100:103]
	v_mfma_f32_16x16x32_bf16 v[92:95], v[154:157], v[206:209], v[92:95]
	v_mfma_f32_16x16x32_bf16 v[84:87], v[162:165], v[206:209], v[84:87]
	v_mfma_f32_16x16x32_bf16 v[76:79], v[154:157], v[214:217], v[76:79]
	v_mfma_f32_16x16x32_bf16 v[68:71], v[162:165], v[214:217], v[68:71]
	v_mfma_f32_16x16x32_bf16 v[124:127], v[158:161], v[190:193], v[124:127]
	v_mfma_f32_16x16x32_bf16 v[116:119], v[166:169], v[190:193], v[116:119]
	v_mfma_f32_16x16x32_bf16 v[108:111], v[158:161], v[202:205], v[108:111]
	v_mfma_f32_16x16x32_bf16 v[100:103], v[166:169], v[202:205], v[100:103]
	v_mfma_f32_16x16x32_bf16 v[92:95], v[158:161], v[210:213], v[92:95]
	v_mfma_f32_16x16x32_bf16 v[84:87], v[166:169], v[210:213], v[84:87]
	v_mfma_f32_16x16x32_bf16 v[76:79], v[158:161], v[218:221], v[76:79]
	v_mfma_f32_16x16x32_bf16 v[68:71], v[166:169], v[218:221], v[68:71]
	v_mfma_f32_16x16x32_bf16 v[120:123], v[170:173], v[186:189], v[120:123]
	v_mfma_f32_16x16x32_bf16 v[112:115], v[178:181], v[186:189], v[112:115]
	v_mfma_f32_16x16x32_bf16 v[104:107], v[170:173], v[198:201], v[104:107]
	v_mfma_f32_16x16x32_bf16 v[96:99], v[178:181], v[198:201], v[96:99]
	v_mfma_f32_16x16x32_bf16 v[88:91], v[170:173], v[206:209], v[88:91]
	v_mfma_f32_16x16x32_bf16 v[80:83], v[178:181], v[206:209], v[80:83]
	v_mfma_f32_16x16x32_bf16 v[72:75], v[170:173], v[214:217], v[72:75]
	v_mfma_f32_16x16x32_bf16 v[64:67], v[178:181], v[214:217], v[64:67]
	v_mfma_f32_16x16x32_bf16 v[120:123], v[174:177], v[190:193], v[120:123]
	v_mfma_f32_16x16x32_bf16 v[112:115], v[182:185], v[190:193], v[112:115]
	v_mfma_f32_16x16x32_bf16 v[104:107], v[174:177], v[202:205], v[104:107]
	v_mfma_f32_16x16x32_bf16 v[96:99], v[182:185], v[202:205], v[96:99]
	v_mfma_f32_16x16x32_bf16 v[88:91], v[174:177], v[210:213], v[88:91]
	v_mfma_f32_16x16x32_bf16 v[80:83], v[182:185], v[210:213], v[80:83]
	v_mfma_f32_16x16x32_bf16 v[72:75], v[174:177], v[218:221], v[72:75]
	v_mfma_f32_16x16x32_bf16 v[64:67], v[182:185], v[218:221], v[64:67]
	s_setprio 0
	s_barrier
; #define PG8_STAGE(bufoff, gbase, voff) do { _Pragma("unroll") for (int _i = 0; _i < 2; ++_i) \
;         __builtin_amdgcn_global_load_lds((const unsigned*)((const char*)(gbase) + (voff)[_i]), (PG8_LAS unsigned*)(lds + (bufoff) + ldsw + _i * 8192), 16, 0, 0); } while (0)
; #define PG8_LDA(dst, b, h) do { _Pragma("unroll") for (int m = 0; m < 4; ++m) _Pragma("unroll") for (int k = 0; k < 2; ++k) dst[m][k] = *(const PG8_LAS bf16x8*)(lds + PG8_SA(b, h) + aoff + m * 2048 + k * 1024); } while (0)
; #define PG8_LDB(dst, b, h) do { _Pragma("unroll") for (int n = 0; n < 2; ++n) _Pragma("unroll") for (int k = 0; k < 2; ++k) dst[n][k] = *(const PG8_LAS bf16x8*)(lds + PG8_SB(b, h) + boff + n * 2048 + k * 1024); } while (0)
; #define PG8_MMA(ai, bj, At, Bt) do { __builtin_amdgcn_s_setprio(1); _Pragma("unroll") for (int m = 0; m < 4; ++m) _Pragma("unroll") for (int n = 0; n < 2; ++n) _Pragma("unroll") for (int k = 0; k < 2; ++k) \
;         acc[ai][bj][m][n] = __builtin_amdgcn_mfma_f32_16x16x32_bf16(Bt[n][k], At[m][k], acc[ai][bj][m][n], 0, 0, 0); __builtin_amdgcn_s_setprio(0); } while (0)
; #define PG8_WAIT_V(n) asm volatile("s_waitcnt vmcnt(" #n ")" ::: "memory")
; #define PG8_WAIT_L(n) asm volatile("s_waitcnt lgkmcnt(" #n ")" ::: "memory")
; #define PG8_BAR __builtin_amdgcn_s_barrier()
; #define PG8_SCHED __builtin_amdgcn_sched_barrier(0)
; template <class Epi, class Sched, bool ALIGN_EPI = false, bool SP2 = false>
; __device__ __forceinline__ void gemm_phase(PG8_LAS unsigned char* lds, const Gemm g, const Sched& S, const Epi& E) {
;     ...
;             PG8_LDA(At, 0, 1); PG8_STAGE(PG8_SB(0, 0), b2, voffB); PG8_STAGE(PG8_SB(0, 1), b2 + hstep, voffB); PG8_STAGE(PG8_SA(0, 0), a2, voffA);
;             PG8_WAIT_V(8); PG8_WAIT_L(0); PG8_BAR; PG8_MMA(1, 0, At, B0); PG8_MMA(1, 1, At, B1); PG8_BAR; PG8_SCHED;
;             PG8_LDB(B0, 1, 0); PG8_LDB(B1, 1, 1); PG8_SCHED; PG8_LDA(At, 1, 0); PG8_STAGE(PG8_SA(0, 1), a2 + hstep, voffA);
;             PG8_WAIT_V(8); PG8_WAIT_L(0); PG8_BAR; PG8_MMA(0, 0, At, B0); PG8_MMA(0, 1, At, B1); PG8_BAR; PG8_SCHED;
	s_add_i32 s68, s58, s50
	s_add_u32 s98, s38, s8
	s_addc_u32 s99, s39, s9
	s_add_u32 s100, s42, s8
	s_addc_u32 s101, s43, s9
	s_mov_b32 m0, s68
	ds_read_b128 v[186:189], v152 offset:16384
	ds_read_b128 v[190:193], v152 offset:17408
	ds_read_b128 v[198:201], v152 offset:18432
	ds_read_b128 v[202:205], v152 offset:19456
	ds_read_b128 v[206:209], v152 offset:20480
	ds_read_b128 v[210:213], v152 offset:21504
	ds_read_b128 v[214:217], v152 offset:22528
	ds_read_b128 v[218:221], v152 offset:23552
	global_load_lds_dwordx4 v132, s[38:39]
	s_add_i32 m0, s68, 0x2000
	s_add_u32 s68, s38, 0x40000
	s_addc_u32 s69, s39, 0
	s_add_i32 s70, s59, s50
	global_load_lds_dwordx4 v128, s[38:39]
	s_mov_b32 m0, s70
	s_nop 0
	global_load_lds_dwordx4 v132, s[68:69]
	s_add_i32 m0, s70, 0x2000
	s_nop 0
	global_load_lds_dwordx4 v128, s[68:69]
	s_mov_b32 m0, s35
	s_nop 0
	global_load_lds_dwordx4 v134, s[42:43]
	s_mov_b32 m0, s52
	s_nop 0
	global_load_lds_dwordx4 v130, s[42:43]
	s_waitcnt vmcnt(8)
	s_waitcnt lgkmcnt(0)
	s_barrier
	s_setprio 1
	s_waitcnt lgkmcnt(0)
	v_mfma_f32_16x16x32_bf16 v[60:63], v[154:157], v[186:189], v[60:63]
	v_mfma_f32_16x16x32_bf16 v[52:55], v[162:165], v[186:189], v[52:55]
	v_mfma_f32_16x16x32_bf16 v[44:47], v[154:157], v[198:201], v[44:47]
	v_mfma_f32_16x16x32_bf16 v[36:39], v[162:165], v[198:201], v[36:39]
	v_mfma_f32_16x16x32_bf16 v[28:31], v[154:157], v[206:209], v[28:31]
	v_mfma_f32_16x16x32_bf16 v[20:23], v[162:165], v[206:209], v[20:23]
	v_mfma_f32_16x16x32_bf16 v[12:15], v[154:157], v[214:217], v[12:15]
	v_mfma_f32_16x16x32_bf16 v[4:7], v[162:165], v[214:217], v[4:7]
	v_mfma_f32_16x16x32_bf16 v[60:63], v[158:161], v[190:193], v[60:63]
	v_mfma_f32_16x16x32_bf16 v[52:55], v[166:169], v[190:193], v[52:55]
	v_mfma_f32_16x16x32_bf16 v[44:47], v[158:161], v[202:205], v[44:47]
	v_mfma_f32_16x16x32_bf16 v[36:39], v[166:169], v[202:205], v[36:39]
	v_mfma_f32_16x16x32_bf16 v[28:31], v[158:161], v[210:213], v[28:31]
	v_mfma_f32_16x16x32_bf16 v[20:23], v[166:169], v[210:213], v[20:23]
	v_mfma_f32_16x16x32_bf16 v[12:15], v[158:161], v[218:221], v[12:15]
	v_mfma_f32_16x16x32_bf16 v[4:7], v[166:169], v[218:221], v[4:7]
	v_mfma_f32_16x16x32_bf16 v[56:59], v[170:173], v[186:189], v[56:59]
	v_mfma_f32_16x16x32_bf16 v[48:51], v[178:181], v[186:189], v[48:51]
	v_mfma_f32_16x16x32_bf16 v[40:43], v[170:173], v[198:201], v[40:43]
	v_mfma_f32_16x16x32_bf16 v[32:35], v[178:181], v[198:201], v[32:35]
	v_mfma_f32_16x16x32_bf16 v[24:27], v[170:173], v[206:209], v[24:27]
	v_mfma_f32_16x16x32_bf16 v[16:19], v[178:181], v[206:209], v[16:19]
	v_mfma_f32_16x16x32_bf16 v[8:11], v[170:173], v[214:217], v[8:11]
	v_mfma_f32_16x16x32_bf16 v[0:3], v[178:181], v[214:217], v[0:3]
	v_mfma_f32_16x16x32_bf16 v[56:59], v[174:177], v[190:193], v[56:59]
	v_mfma_f32_16x16x32_bf16 v[48:51], v[182:185], v[190:193], v[48:51]
	v_mfma_f32_16x16x32_bf16 v[40:43], v[174:177], v[202:205], v[40:43]
	v_mfma_f32_16x16x32_bf16 v[32:35], v[182:185], v[202:205], v[32:35]
	v_mfma_f32_16x16x32_bf16 v[24:27], v[174:177], v[210:213], v[24:27]
	v_mfma_f32_16x16x32_bf16 v[16:19], v[182:185], v[210:213], v[16:19]
	v_mfma_f32_16x16x32_bf16 v[8:11], v[174:177], v[218:221], v[8:11]
	v_mfma_f32_16x16x32_bf16 v[0:3], v[182:185], v[218:221], v[0:3]
	s_setprio 0
	s_barrier
	s_add_i32 s68, 0, 0x18000
	v_add_u32_e32 v153, s68, v147
	s_add_i32 s69, 0, 0x1c000
	ds_read_b128 v[154:157], v153
	ds_read_b128 v[158:161], v153 offset:1024
	ds_read_b128 v[162:165], v153 offset:2048
	ds_read_b128 v[166:169], v153 offset:3072
	v_add_u32_e32 v153, s69, v147
	ds_read_b128 v[170:173], v153
	ds_read_b128 v[174:177], v153 offset:1024
	ds_read_b128 v[178:181], v153 offset:2048
	ds_read_b128 v[182:185], v153 offset:3072
	s_add_u32 s42, s42, 0x40000
	s_addc_u32 s43, s43, 0
	s_mov_b32 m0, s53
	ds_read_b128 v[186:189], v152 offset:32768
	ds_read_b128 v[190:193], v152 offset:33792
	ds_read_b128 v[198:201], v152 offset:34816
	ds_read_b128 v[202:205], v152 offset:35840
	ds_read_b128 v[206:209], v152 offset:36864
	ds_read_b128 v[210:213], v152 offset:37888
	ds_read_b128 v[214:217], v152 offset:38912
	ds_read_b128 v[218:221], v152 offset:39936
	global_load_lds_dwordx4 v134, s[42:43]
	s_mov_b32 m0, s54
	s_nop 0
	global_load_lds_dwordx4 v130, s[42:43]
	s_waitcnt vmcnt(8)
	s_waitcnt lgkmcnt(0)
	s_barrier
; #define PG8_STAGE(bufoff, gbase, voff) do { _Pragma("unroll") for (int _i = 0; _i < 2; ++_i) \
;         __builtin_amdgcn_global_load_lds((const unsigned*)((const char*)(gbase) + (voff)[_i]), (PG8_LAS unsigned*)(lds + (bufoff) + ldsw + _i * 8192), 16, 0, 0); } while (0)
; #define PG8_LDA(dst, b, h) do { _Pragma("unroll") for (int m = 0; m < 4; ++m) _Pragma("unroll") for (int k = 0; k < 2; ++k) dst[m][k] = *(const PG8_LAS bf16x8*)(lds + PG8_SA(b, h) + aoff + m * 2048 + k * 1024); } while (0)
; #define PG8_MMA(ai, bj, At, Bt) do { __builtin_amdgcn_s_setprio(1); _Pragma("unroll") for (int m = 0; m < 4; ++m) _Pragma("unroll") for (int n = 0; n < 2; ++n) _Pragma("unroll") for (int k = 0; k < 2; ++k) \
;         acc[ai][bj][m][n] = __builtin_amdgcn_mfma_f32_16x16x32_bf16(Bt[n][k], At[m][k], acc[ai][bj][m][n], 0, 0, 0); __builtin_amdgcn_s_setprio(0); } while (0)
; #define PG8_WAIT_V(n) asm volatile("s_waitcnt vmcnt(" #n ")" ::: "memory")
; #define PG8_WAIT_L(n) asm volatile("s_waitcnt lgkmcnt(" #n ")" ::: "memory")
; #define PG8_BAR __builtin_amdgcn_s_barrier()
; #define PG8_SCHED __builtin_amdgcn_sched_barrier(0)
; template <class Epi, class Sched, bool ALIGN_EPI = false, bool SP2 = false>
; __device__ __forceinline__ void gemm_phase(PG8_LAS unsigned char* lds, const Gemm g, const Sched& S, const Epi& E) {
;     ...
;             PG8_WAIT_V(8); PG8_WAIT_L(0); PG8_BAR; PG8_MMA(0, 0, At, B0); PG8_MMA(0, 1, At, B1); PG8_BAR; PG8_SCHED;
;             PG8_LDA(At, 1, 1); PG8_STAGE(PG8_SB(1, 0), b3, voffB); PG8_STAGE(PG8_SB(1, 1), b3 + hstep, voffB); PG8_STAGE(PG8_SA(1, 0), a3, voffA);
;             PG8_WAIT_V(8); PG8_WAIT_L(0); PG8_BAR; PG8_MMA(1, 0, At, B0); PG8_MMA(1, 1, At, B1); PG8_BAR; PG8_SCHED;
	s_setprio 1
	s_waitcnt lgkmcnt(0)
	v_mfma_f32_16x16x32_bf16 v[124:127], v[154:157], v[186:189], v[124:127]
	v_mfma_f32_16x16x32_bf16 v[116:119], v[162:165], v[186:189], v[116:119]
	v_mfma_f32_16x16x32_bf16 v[108:111], v[154:157], v[198:201], v[108:111]
	v_mfma_f32_16x16x32_bf16 v[100:103], v[162:165], v[198:201], v[100:103]
	v_mfma_f32_16x16x32_bf16 v[92:95], v[154:157], v[206:209], v[92:95]
	v_mfma_f32_16x16x32_bf16 v[84:87], v[162:165], v[206:209], v[84:87]
	v_mfma_f32_16x16x32_bf16 v[76:79], v[154:157], v[214:217], v[76:79]
	v_mfma_f32_16x16x32_bf16 v[68:71], v[162:165], v[214:217], v[68:71]
	v_mfma_f32_16x16x32_bf16 v[124:127], v[158:161], v[190:193], v[124:127]
	v_mfma_f32_16x16x32_bf16 v[116:119], v[166:169], v[190:193], v[116:119]
	v_mfma_f32_16x16x32_bf16 v[108:111], v[158:161], v[202:205], v[108:111]
	v_mfma_f32_16x16x32_bf16 v[100:103], v[166:169], v[202:205], v[100:103]
	v_mfma_f32_16x16x32_bf16 v[92:95], v[158:161], v[210:213], v[92:95]
	v_mfma_f32_16x16x32_bf16 v[84:87], v[166:169], v[210:213], v[84:87]
	v_mfma_f32_16x16x32_bf16 v[76:79], v[158:161], v[218:221], v[76:79]
	v_mfma_f32_16x16x32_bf16 v[68:71], v[166:169], v[218:221], v[68:71]
	v_mfma_f32_16x16x32_bf16 v[120:123], v[170:173], v[186:189], v[120:123]
	v_mfma_f32_16x16x32_bf16 v[112:115], v[178:181], v[186:189], v[112:115]
	v_mfma_f32_16x16x32_bf16 v[104:107], v[170:173], v[198:201], v[104:107]
	v_mfma_f32_16x16x32_bf16 v[96:99], v[178:181], v[198:201], v[96:99]
	v_mfma_f32_16x16x32_bf16 v[88:91], v[170:173], v[206:209], v[88:91]
	v_mfma_f32_16x16x32_bf16 v[80:83], v[178:181], v[206:209], v[80:83]
	v_mfma_f32_16x16x32_bf16 v[72:75], v[170:173], v[214:217], v[72:75]
	v_mfma_f32_16x16x32_bf16 v[64:67], v[178:181], v[214:217], v[64:67]
	v_mfma_f32_16x16x32_bf16 v[120:123], v[174:177], v[190:193], v[120:123]
	v_mfma_f32_16x16x32_bf16 v[112:115], v[182:185], v[190:193], v[112:115]
	v_mfma_f32_16x16x32_bf16 v[104:107], v[174:177], v[202:205], v[104:107]
	v_mfma_f32_16x16x32_bf16 v[96:99], v[182:185], v[202:205], v[96:99]
	v_mfma_f32_16x16x32_bf16 v[88:91], v[174:177], v[210:213], v[88:91]
	v_mfma_f32_16x16x32_bf16 v[80:83], v[182:185], v[210:213], v[80:83]
	v_mfma_f32_16x16x32_bf16 v[72:75], v[174:177], v[218:221], v[72:75]
	v_mfma_f32_16x16x32_bf16 v[64:67], v[182:185], v[218:221], v[64:67]
	s_setprio 0
	s_barrier
	s_add_i32 s42, s68, s50
	s_mov_b32 m0, s42
	ds_read_b128 v[186:189], v152 offset:49152
	ds_read_b128 v[190:193], v152 offset:50176
	ds_read_b128 v[198:201], v152 offset:51200
	ds_read_b128 v[202:205], v152 offset:52224
	ds_read_b128 v[206:209], v152 offset:53248
	ds_read_b128 v[210:213], v152 offset:54272
	ds_read_b128 v[214:217], v152 offset:55296
	ds_read_b128 v[218:221], v152 offset:56320
	global_load_lds_dwordx4 v132, s[98:99]
	s_add_i32 m0, s42, 0x2000
	s_add_u32 s38, s38, 0x40080
	s_addc_u32 s39, s39, 0
	s_add_i32 s42, s69, s50
	global_load_lds_dwordx4 v128, s[98:99]
	s_mov_b32 m0, s42
	s_nop 0
	global_load_lds_dwordx4 v132, s[38:39]
	s_add_i32 m0, s42, 0x2000
	s_nop 0
	global_load_lds_dwordx4 v128, s[38:39]
	s_mov_b32 m0, s56
	s_nop 0
	global_load_lds_dwordx4 v134, s[100:101]
	s_mov_b32 m0, s57
	s_nop 0
	global_load_lds_dwordx4 v130, s[100:101]
	s_waitcnt vmcnt(8)
	s_waitcnt lgkmcnt(0)
	s_barrier
	s_setprio 1
	s_waitcnt lgkmcnt(0)
	v_mfma_f32_16x16x32_bf16 v[60:63], v[154:157], v[186:189], v[60:63]
	v_mfma_f32_16x16x32_bf16 v[52:55], v[162:165], v[186:189], v[52:55]
	v_mfma_f32_16x16x32_bf16 v[44:47], v[154:157], v[198:201], v[44:47]
	v_mfma_f32_16x16x32_bf16 v[36:39], v[162:165], v[198:201], v[36:39]
	v_mfma_f32_16x16x32_bf16 v[28:31], v[154:157], v[206:209], v[28:31]
	v_mfma_f32_16x16x32_bf16 v[20:23], v[162:165], v[206:209], v[20:23]
	v_mfma_f32_16x16x32_bf16 v[12:15], v[154:157], v[214:217], v[12:15]
	v_mfma_f32_16x16x32_bf16 v[4:7], v[162:165], v[214:217], v[4:7]
	v_mfma_f32_16x16x32_bf16 v[60:63], v[158:161], v[190:193], v[60:63]
	v_mfma_f32_16x16x32_bf16 v[52:55], v[166:169], v[190:193], v[52:55]
	v_mfma_f32_16x16x32_bf16 v[44:47], v[158:161], v[202:205], v[44:47]
	v_mfma_f32_16x16x32_bf16 v[36:39], v[166:169], v[202:205], v[36:39]
	v_mfma_f32_16x16x32_bf16 v[28:31], v[158:161], v[210:213], v[28:31]
	v_mfma_f32_16x16x32_bf16 v[20:23], v[166:169], v[210:213], v[20:23]
	v_mfma_f32_16x16x32_bf16 v[12:15], v[158:161], v[218:221], v[12:15]
	v_mfma_f32_16x16x32_bf16 v[4:7], v[166:169], v[218:221], v[4:7]
	v_mfma_f32_16x16x32_bf16 v[56:59], v[170:173], v[186:189], v[56:59]
	v_mfma_f32_16x16x32_bf16 v[48:51], v[178:181], v[186:189], v[48:51]
	v_mfma_f32_16x16x32_bf16 v[40:43], v[170:173], v[198:201], v[40:43]
	v_mfma_f32_16x16x32_bf16 v[32:35], v[178:181], v[198:201], v[32:35]
	v_mfma_f32_16x16x32_bf16 v[24:27], v[170:173], v[206:209], v[24:27]
	v_mfma_f32_16x16x32_bf16 v[16:19], v[178:181], v[206:209], v[16:19]
	v_mfma_f32_16x16x32_bf16 v[8:11], v[170:173], v[214:217], v[8:11]
	v_mfma_f32_16x16x32_bf16 v[0:3], v[178:181], v[214:217], v[0:3]
	v_mfma_f32_16x16x32_bf16 v[56:59], v[174:177], v[190:193], v[56:59]
	v_mfma_f32_16x16x32_bf16 v[48:51], v[182:185], v[190:193], v[48:51]
	v_mfma_f32_16x16x32_bf16 v[40:43], v[174:177], v[202:205], v[40:43]
	v_mfma_f32_16x16x32_bf16 v[32:35], v[182:185], v[202:205], v[32:35]
	v_mfma_f32_16x16x32_bf16 v[24:27], v[174:177], v[210:213], v[24:27]
	v_mfma_f32_16x16x32_bf16 v[16:19], v[182:185], v[210:213], v[16:19]
	v_mfma_f32_16x16x32_bf16 v[8:11], v[174:177], v[218:221], v[8:11]
	v_mfma_f32_16x16x32_bf16 v[0:3], v[182:185], v[218:221], v[0:3]
	s_setprio 0
	s_barrier
	s_add_i32 s67, s67, 2
	s_add_u32 s20, s20, 0x100
	s_addc_u32 s21, s21, 0
	s_add_u32 s65, s65, 0x100
	s_addc_u32 s66, s66, 0
	s_cmp_gt_u32 s67, 13
	s_cbranch_scc0 .LBB0_1740
	s_and_b64 vcc, exec, s[10:11]
	s_cbranch_vccz .LBB0_1743
	s_barrier

; #define PG8_STAGE(bufoff, gbase, voff) do { _Pragma("unroll") for (int _i = 0; _i < 2; ++_i) \
;         __builtin_amdgcn_global_load_lds((const unsigned*)((const char*)(gbase) + (voff)[_i]), (PG8_LAS unsigned*)(lds + (bufoff) + ldsw + _i * 8192), 16, 0, 0); } while (0)
; #define PG8_LDA(dst, b, h) do { _Pragma("unroll") for (int m = 0; m < 4; ++m) _Pragma("unroll") for (int k = 0; k < 2; ++k) dst[m][k] = *(const PG8_LAS bf16x8*)(lds + PG8_SA(b, h) + aoff + m * 2048 + k * 1024); } while (0)
; #define PG8_LDB(dst, b, h) do { _Pragma("unroll") for (int n = 0; n < 2; ++n) _Pragma("unroll") for (int k = 0; k < 2; ++k) dst[n][k] = *(const PG8_LAS bf16x8*)(lds + PG8_SB(b, h) + boff + n * 2048 + k * 1024); } while (0)
; #define PG8_MMA(ai, bj, At, Bt) do { __builtin_amdgcn_s_setprio(1); _Pragma("unroll") for (int m = 0; m < 4; ++m) _Pragma("unroll") for (int n = 0; n < 2; ++n) _Pragma("unroll") for (int k = 0; k < 2; ++k) \
;         acc[ai][bj][m][n] = __builtin_amdgcn_mfma_f32_16x16x32_bf16(Bt[n][k], At[m][k], acc[ai][bj][m][n], 0, 0, 0); __builtin_amdgcn_s_setprio(0); } while (0)
; #define PG8_WAIT_V(n) asm volatile("s_waitcnt vmcnt(" #n ")" ::: "memory")
; #define PG8_WAIT_L(n) asm volatile("s_waitcnt lgkmcnt(" #n ")" ::: "memory")
; #define PG8_BAR __builtin_amdgcn_s_barrier()
; #define PG8_SCHED __builtin_amdgcn_sched_barrier(0)
; template <class Epi, class Sched, bool ALIGN_EPI = false, bool SP2 = false>
; __device__ __forceinline__ void gemm_phase(PG8_LAS unsigned char* lds, const Gemm g, const Sched& S, const Epi& E) {
;     ...
;             PG8_LDB(B0, 0, 0); PG8_LDB(B1, 0, 1); PG8_SCHED; PG8_LDA(At, 0, 0); PG8_STAGE(PG8_SA(1, 1), a1 + hstep, voffA);
;             PG8_WAIT_V(8); PG8_WAIT_L(0); PG8_BAR; PG8_MMA(0, 0, At, B0); PG8_MMA(0, 1, At, B1); PG8_BAR; PG8_SCHED;
;             PG8_LDA(At, 0, 1); PG8_STAGE(PG8_SB(0, 0), b2, voffB); PG8_STAGE(PG8_SB(0, 1), b2 + hstep, voffB); PG8_STAGE(PG8_SA(0, 0), a2, voffA);
;             PG8_WAIT_V(8); PG8_WAIT_L(0); PG8_BAR; PG8_MMA(1, 0, At, B0); PG8_MMA(1, 1, At, B1); PG8_BAR; PG8_SCHED;
.LBB0_1824:
	s_add_u32 s20, s20, 0xb0080
	s_addc_u32 s21, s21, 0
	s_add_u32 s68, s34, 0x100
	s_addc_u32 s69, s35, 0
	s_mov_b32 s70, -2
	s_waitcnt lgkmcnt(0)
	ds_read_b128 v[96:99], v222
	ds_read_b128 v[108:111], v222 offset:1024
	ds_read_b128 v[120:123], v222 offset:2048
	ds_read_b128 v[128:131], v222 offset:3072
	ds_read_b128 v[144:147], v223
	ds_read_b128 v[148:151], v223 offset:1024
	ds_read_b128 v[152:155], v223 offset:2048
	ds_read_b128 v[156:159], v223 offset:3072
	s_add_u32 s34, s20, 0xfff50080
	s_addc_u32 s35, s21, -1
	s_cmp_eq_u32 s70, 40
	s_cselect_b32 s47, s1, s35
	s_cselect_b32 s46, s0, s34
	s_cselect_b32 s35, s45, s69
	s_cselect_b32 s34, s44, s68
	s_add_i32 m0, s49, 0xc000
	ds_read_b128 v[160:163], v224
	ds_read_b128 v[164:167], v224 offset:1024
	ds_read_b128 v[168:171], v224 offset:2048
	ds_read_b128 v[172:175], v224 offset:3072
	ds_read_b128 v[176:179], v224 offset:4096
	ds_read_b128 v[180:183], v224 offset:5120
	ds_read_b128 v[202:205], v224 offset:6144
	ds_read_b128 v[206:209], v224 offset:7168
	global_load_lds_dwordx4 v192, s[20:21]
	s_add_i32 m0, s49, 0xe000
	s_nop 0
	global_load_lds_dwordx4 v194, s[20:21]
	s_waitcnt vmcnt(8)
	s_waitcnt lgkmcnt(0)
	s_barrier
	s_setprio 1
	s_waitcnt lgkmcnt(0)
	v_mfma_f32_16x16x32_bf16 v[140:143], v[96:99], v[160:163], 0
	v_mfma_f32_16x16x32_bf16 v[136:139], v[120:123], v[160:163], 0
	v_mfma_f32_16x16x32_bf16 v[116:119], v[96:99], v[168:171], 0
	v_mfma_f32_16x16x32_bf16 v[112:115], v[120:123], v[168:171], 0
	v_mfma_f32_16x16x32_bf16 v[92:95], v[96:99], v[176:179], 0
	v_mfma_f32_16x16x32_bf16 v[88:91], v[120:123], v[176:179], 0
	v_mfma_f32_16x16x32_bf16 v[76:79], v[96:99], v[202:205], 0
	v_mfma_f32_16x16x32_bf16 v[72:75], v[120:123], v[202:205], 0
	v_mfma_f32_16x16x32_bf16 v[140:143], v[108:111], v[164:167], v[140:143]
	v_mfma_f32_16x16x32_bf16 v[136:139], v[128:131], v[164:167], v[136:139]
	v_mfma_f32_16x16x32_bf16 v[116:119], v[108:111], v[172:175], v[116:119]
	v_mfma_f32_16x16x32_bf16 v[112:115], v[128:131], v[172:175], v[112:115]
	v_mfma_f32_16x16x32_bf16 v[92:95], v[108:111], v[180:183], v[92:95]
	v_mfma_f32_16x16x32_bf16 v[88:91], v[128:131], v[180:183], v[88:91]
	v_mfma_f32_16x16x32_bf16 v[76:79], v[108:111], v[206:209], v[76:79]
	v_mfma_f32_16x16x32_bf16 v[72:75], v[128:131], v[206:209], v[72:75]
	v_mfma_f32_16x16x32_bf16 v[132:135], v[144:147], v[160:163], 0
	v_mfma_f32_16x16x32_bf16 v[124:127], v[152:155], v[160:163], 0
	v_mfma_f32_16x16x32_bf16 v[104:107], v[144:147], v[168:171], 0
	v_mfma_f32_16x16x32_bf16 v[100:103], v[152:155], v[168:171], 0
	v_mfma_f32_16x16x32_bf16 v[84:87], v[144:147], v[176:179], 0
	v_mfma_f32_16x16x32_bf16 v[80:83], v[152:155], v[176:179], 0
	v_mfma_f32_16x16x32_bf16 v[68:71], v[144:147], v[202:205], 0
	v_mfma_f32_16x16x32_bf16 v[64:67], v[152:155], v[202:205], 0
	v_mfma_f32_16x16x32_bf16 v[132:135], v[148:151], v[164:167], v[132:135]
	v_mfma_f32_16x16x32_bf16 v[124:127], v[156:159], v[164:167], v[124:127]
	v_mfma_f32_16x16x32_bf16 v[104:107], v[148:151], v[172:175], v[104:107]
	v_mfma_f32_16x16x32_bf16 v[100:103], v[156:159], v[172:175], v[100:103]
	v_mfma_f32_16x16x32_bf16 v[84:87], v[148:151], v[180:183], v[84:87]
	v_mfma_f32_16x16x32_bf16 v[80:83], v[156:159], v[180:183], v[80:83]
	v_mfma_f32_16x16x32_bf16 v[68:71], v[148:151], v[206:209], v[68:71]
	v_mfma_f32_16x16x32_bf16 v[64:67], v[156:159], v[206:209], v[64:67]
	s_setprio 0
	s_barrier
	s_add_i32 s71, s62, s48
	s_add_u32 s98, s34, s12
	s_addc_u32 s99, s35, s13
	s_add_u32 s100, s46, s12
	s_addc_u32 s101, s47, s13
	s_mov_b32 m0, s71
	ds_read_b128 v[160:163], v224 offset:16384
	ds_read_b128 v[164:167], v224 offset:17408
	ds_read_b128 v[168:171], v224 offset:18432
	ds_read_b128 v[172:175], v224 offset:19456
	ds_read_b128 v[176:179], v224 offset:20480
	ds_read_b128 v[180:183], v224 offset:21504
	ds_read_b128 v[202:205], v224 offset:22528
	ds_read_b128 v[206:209], v224 offset:23552
	global_load_lds_dwordx4 v186, s[34:35]
	s_add_i32 m0, s71, 0x2000
	s_add_u32 s72, s34, 0xb0000
	s_addc_u32 s73, s35, 0
	s_add_i32 s71, s63, s48
	global_load_lds_dwordx4 v190, s[34:35]
	s_mov_b32 m0, s71
	s_nop 0
	global_load_lds_dwordx4 v186, s[72:73]
	s_add_i32 m0, s71, 0x2000
	s_nop 0
	global_load_lds_dwordx4 v190, s[72:73]
	s_mov_b32 m0, s49
	s_nop 0
	global_load_lds_dwordx4 v184, s[46:47]
	s_mov_b32 m0, s50
	s_nop 0
	global_load_lds_dwordx4 v188, s[46:47]
	s_waitcnt vmcnt(8)
	s_waitcnt lgkmcnt(0)
	s_barrier
	s_setprio 1
	s_waitcnt lgkmcnt(0)
	v_mfma_f32_16x16x32_bf16 v[60:63], v[96:99], v[160:163], 0
	v_mfma_f32_16x16x32_bf16 v[56:59], v[120:123], v[160:163], 0
	v_mfma_f32_16x16x32_bf16 v[44:47], v[96:99], v[168:171], 0
	v_mfma_f32_16x16x32_bf16 v[40:43], v[120:123], v[168:171], 0
	v_mfma_f32_16x16x32_bf16 v[28:31], v[96:99], v[176:179], 0
	v_mfma_f32_16x16x32_bf16 v[24:27], v[120:123], v[176:179], 0
	v_mfma_f32_16x16x32_bf16 v[12:15], v[96:99], v[202:205], 0
	v_mfma_f32_16x16x32_bf16 v[8:11], v[120:123], v[202:205], 0
	v_mfma_f32_16x16x32_bf16 v[60:63], v[108:111], v[164:167], v[60:63]
	v_mfma_f32_16x16x32_bf16 v[56:59], v[128:131], v[164:167], v[56:59]
	v_mfma_f32_16x16x32_bf16 v[44:47], v[108:111], v[172:175], v[44:47]
	v_mfma_f32_16x16x32_bf16 v[40:43], v[128:131], v[172:175], v[40:43]
	v_mfma_f32_16x16x32_bf16 v[28:31], v[108:111], v[180:183], v[28:31]
	v_mfma_f32_16x16x32_bf16 v[24:27], v[128:131], v[180:183], v[24:27]
	v_mfma_f32_16x16x32_bf16 v[12:15], v[108:111], v[206:209], v[12:15]
	v_mfma_f32_16x16x32_bf16 v[8:11], v[128:131], v[206:209], v[8:11]
	v_mfma_f32_16x16x32_bf16 v[52:55], v[144:147], v[160:163], 0
	v_mfma_f32_16x16x32_bf16 v[48:51], v[152:155], v[160:163], 0
	v_mfma_f32_16x16x32_bf16 v[36:39], v[144:147], v[168:171], 0
	v_mfma_f32_16x16x32_bf16 v[32:35], v[152:155], v[168:171], 0
	v_mfma_f32_16x16x32_bf16 v[20:23], v[144:147], v[176:179], 0
	v_mfma_f32_16x16x32_bf16 v[16:19], v[152:155], v[176:179], 0
	v_mfma_f32_16x16x32_bf16 v[4:7], v[144:147], v[202:205], 0
	v_mfma_f32_16x16x32_bf16 v[0:3], v[152:155], v[202:205], 0
	v_mfma_f32_16x16x32_bf16 v[52:55], v[148:151], v[164:167], v[52:55]
	v_mfma_f32_16x16x32_bf16 v[48:51], v[156:159], v[164:167], v[48:51]
	v_mfma_f32_16x16x32_bf16 v[36:39], v[148:151], v[172:175], v[36:39]
	v_mfma_f32_16x16x32_bf16 v[32:35], v[156:159], v[172:175], v[32:35]
	v_mfma_f32_16x16x32_bf16 v[20:23], v[148:151], v[180:183], v[20:23]
	v_mfma_f32_16x16x32_bf16 v[16:19], v[156:159], v[180:183], v[16:19]
	v_mfma_f32_16x16x32_bf16 v[4:7], v[148:151], v[206:209], v[4:7]
	v_mfma_f32_16x16x32_bf16 v[0:3], v[156:159], v[206:209], v[0:3]
	s_setprio 0
	s_barrier
; #define PG8_STAGE(bufoff, gbase, voff) do { _Pragma("unroll") for (int _i = 0; _i < 2; ++_i) \
;         __builtin_amdgcn_global_load_lds((const unsigned*)((const char*)(gbase) + (voff)[_i]), (PG8_LAS unsigned*)(lds + (bufoff) + ldsw + _i * 8192), 16, 0, 0); } while (0)
; #define PG8_LDA(dst, b, h) do { _Pragma("unroll") for (int m = 0; m < 4; ++m) _Pragma("unroll") for (int k = 0; k < 2; ++k) dst[m][k] = *(const PG8_LAS bf16x8*)(lds + PG8_SA(b, h) + aoff + m * 2048 + k * 1024); } while (0)
; #define PG8_LDB(dst, b, h) do { _Pragma("unroll") for (int n = 0; n < 2; ++n) _Pragma("unroll") for (int k = 0; k < 2; ++k) dst[n][k] = *(const PG8_LAS bf16x8*)(lds + PG8_SB(b, h) + boff + n * 2048 + k * 1024); } while (0)
; #define PG8_MMA(ai, bj, At, Bt) do { __builtin_amdgcn_s_setprio(1); _Pragma("unroll") for (int m = 0; m < 4; ++m) _Pragma("unroll") for (int n = 0; n < 2; ++n) _Pragma("unroll") for (int k = 0; k < 2; ++k) \
;         acc[ai][bj][m][n] = __builtin_amdgcn_mfma_f32_16x16x32_bf16(Bt[n][k], At[m][k], acc[ai][bj][m][n], 0, 0, 0); __builtin_amdgcn_s_setprio(0); } while (0)
; #define PG8_WAIT_V(n) asm volatile("s_waitcnt vmcnt(" #n ")" ::: "memory")
; #define PG8_WAIT_L(n) asm volatile("s_waitcnt lgkmcnt(" #n ")" ::: "memory")
; #define PG8_BAR __builtin_amdgcn_s_barrier()
; #define PG8_SCHED __builtin_amdgcn_sched_barrier(0)
; template <class Epi, class Sched, bool ALIGN_EPI = false, bool SP2 = false>
; __device__ __forceinline__ void gemm_phase(PG8_LAS unsigned char* lds, const Gemm g, const Sched& S, const Epi& E) {
;     ...
;             PG8_LDB(B0, 1, 0); PG8_LDB(B1, 1, 1); PG8_SCHED; PG8_LDA(At, 1, 0); PG8_STAGE(PG8_SA(0, 1), a2 + hstep, voffA);
;             PG8_WAIT_V(8); PG8_WAIT_L(0); PG8_BAR; PG8_MMA(0, 0, At, B0); PG8_MMA(0, 1, At, B1); PG8_BAR; PG8_SCHED;
;             PG8_LDA(At, 1, 1); PG8_STAGE(PG8_SB(1, 0), b3, voffB); PG8_STAGE(PG8_SB(1, 1), b3 + hstep, voffB); PG8_STAGE(PG8_SA(1, 0), a3, voffA);
;             PG8_WAIT_V(8); PG8_WAIT_L(0); PG8_BAR; PG8_MMA(1, 0, At, B0); PG8_MMA(1, 1, At, B1); PG8_BAR; PG8_SCHED;
	s_add_i32 s71, 0, 0x18000
	s_add_i32 s72, 0, 0x1c000
	v_add_u32_e32 v128, s71, v197
	v_add_u32_e32 v156, s72, v197
	ds_read_b128 v[96:99], v128
	ds_read_b128 v[108:111], v128 offset:1024
	ds_read_b128 v[120:123], v128 offset:2048
	ds_read_b128 v[128:131], v128 offset:3072
	ds_read_b128 v[144:147], v156
	ds_read_b128 v[148:151], v156 offset:1024
	ds_read_b128 v[152:155], v156 offset:2048
	ds_read_b128 v[156:159], v156 offset:3072
	s_add_u32 s46, s46, 0xb0000
	s_addc_u32 s47, s47, 0
	s_mov_b32 m0, s51
	ds_read_b128 v[160:163], v224 offset:32768
	ds_read_b128 v[164:167], v224 offset:33792
	ds_read_b128 v[168:171], v224 offset:34816
	ds_read_b128 v[172:175], v224 offset:35840
	ds_read_b128 v[176:179], v224 offset:36864
	ds_read_b128 v[180:183], v224 offset:37888
	ds_read_b128 v[202:205], v224 offset:38912
	ds_read_b128 v[206:209], v224 offset:39936
	global_load_lds_dwordx4 v184, s[46:47]
	s_mov_b32 m0, s52
	s_nop 0
	global_load_lds_dwordx4 v188, s[46:47]
	s_waitcnt vmcnt(8)
	s_waitcnt lgkmcnt(0)
	s_barrier
	s_setprio 1
	s_waitcnt lgkmcnt(0)
	v_mfma_f32_16x16x32_bf16 v[140:143], v[96:99], v[160:163], v[140:143]
	v_mfma_f32_16x16x32_bf16 v[136:139], v[120:123], v[160:163], v[136:139]
	v_mfma_f32_16x16x32_bf16 v[116:119], v[96:99], v[168:171], v[116:119]
	v_mfma_f32_16x16x32_bf16 v[112:115], v[120:123], v[168:171], v[112:115]
	v_mfma_f32_16x16x32_bf16 v[92:95], v[96:99], v[176:179], v[92:95]
	v_mfma_f32_16x16x32_bf16 v[88:91], v[120:123], v[176:179], v[88:91]
	v_mfma_f32_16x16x32_bf16 v[76:79], v[96:99], v[202:205], v[76:79]
	v_mfma_f32_16x16x32_bf16 v[72:75], v[120:123], v[202:205], v[72:75]
	v_mfma_f32_16x16x32_bf16 v[140:143], v[108:111], v[164:167], v[140:143]
	v_mfma_f32_16x16x32_bf16 v[136:139], v[128:131], v[164:167], v[136:139]
	v_mfma_f32_16x16x32_bf16 v[116:119], v[108:111], v[172:175], v[116:119]
	v_mfma_f32_16x16x32_bf16 v[112:115], v[128:131], v[172:175], v[112:115]
	v_mfma_f32_16x16x32_bf16 v[92:95], v[108:111], v[180:183], v[92:95]
	v_mfma_f32_16x16x32_bf16 v[88:91], v[128:131], v[180:183], v[88:91]
	v_mfma_f32_16x16x32_bf16 v[76:79], v[108:111], v[206:209], v[76:79]
	v_mfma_f32_16x16x32_bf16 v[72:75], v[128:131], v[206:209], v[72:75]
	v_mfma_f32_16x16x32_bf16 v[132:135], v[144:147], v[160:163], v[132:135]
	v_mfma_f32_16x16x32_bf16 v[124:127], v[152:155], v[160:163], v[124:127]
	v_mfma_f32_16x16x32_bf16 v[104:107], v[144:147], v[168:171], v[104:107]
	v_mfma_f32_16x16x32_bf16 v[100:103], v[152:155], v[168:171], v[100:103]
	v_mfma_f32_16x16x32_bf16 v[84:87], v[144:147], v[176:179], v[84:87]
	v_mfma_f32_16x16x32_bf16 v[80:83], v[152:155], v[176:179], v[80:83]
	v_mfma_f32_16x16x32_bf16 v[68:71], v[144:147], v[202:205], v[68:71]
	v_mfma_f32_16x16x32_bf16 v[64:67], v[152:155], v[202:205], v[64:67]
	v_mfma_f32_16x16x32_bf16 v[132:135], v[148:151], v[164:167], v[132:135]
	v_mfma_f32_16x16x32_bf16 v[124:127], v[156:159], v[164:167], v[124:127]
	v_mfma_f32_16x16x32_bf16 v[104:107], v[148:151], v[172:175], v[104:107]
	v_mfma_f32_16x16x32_bf16 v[100:103], v[156:159], v[172:175], v[100:103]
	v_mfma_f32_16x16x32_bf16 v[84:87], v[148:151], v[180:183], v[84:87]
	v_mfma_f32_16x16x32_bf16 v[80:83], v[156:159], v[180:183], v[80:83]
	v_mfma_f32_16x16x32_bf16 v[68:71], v[148:151], v[206:209], v[68:71]
	v_mfma_f32_16x16x32_bf16 v[64:67], v[156:159], v[206:209], v[64:67]
	s_setprio 0
	s_barrier
	s_add_i32 s46, s71, s48
	s_mov_b32 m0, s46
	ds_read_b128 v[160:163], v224 offset:49152
	ds_read_b128 v[164:167], v224 offset:50176
	ds_read_b128 v[168:171], v224 offset:51200
	ds_read_b128 v[172:175], v224 offset:52224
	ds_read_b128 v[176:179], v224 offset:53248
	ds_read_b128 v[180:183], v224 offset:54272
	ds_read_b128 v[202:205], v224 offset:55296
	ds_read_b128 v[206:209], v224 offset:56320
	global_load_lds_dwordx4 v186, s[98:99]
	s_add_i32 m0, s46, 0x2000
	s_add_u32 s34, s34, 0xb0080
	s_addc_u32 s35, s35, 0
	s_add_i32 s46, s72, s48
	global_load_lds_dwordx4 v190, s[98:99]
	s_mov_b32 m0, s46
	s_nop 0
	global_load_lds_dwordx4 v186, s[34:35]
	s_add_i32 m0, s46, 0x2000
	s_nop 0
	global_load_lds_dwordx4 v190, s[34:35]
	s_mov_b32 m0, s57
	s_nop 0
	global_load_lds_dwordx4 v184, s[100:101]
	s_mov_b32 m0, s58
	s_nop 0
	global_load_lds_dwordx4 v188, s[100:101]
	s_waitcnt vmcnt(8)
	s_waitcnt lgkmcnt(0)
	s_barrier
	s_setprio 1
	s_waitcnt lgkmcnt(0)
	v_mfma_f32_16x16x32_bf16 v[60:63], v[96:99], v[160:163], v[60:63]
	v_mfma_f32_16x16x32_bf16 v[56:59], v[120:123], v[160:163], v[56:59]
	v_mfma_f32_16x16x32_bf16 v[44:47], v[96:99], v[168:171], v[44:47]
	v_mfma_f32_16x16x32_bf16 v[40:43], v[120:123], v[168:171], v[40:43]
	v_mfma_f32_16x16x32_bf16 v[28:31], v[96:99], v[176:179], v[28:31]
	v_mfma_f32_16x16x32_bf16 v[24:27], v[120:123], v[176:179], v[24:27]
	v_mfma_f32_16x16x32_bf16 v[12:15], v[96:99], v[202:205], v[12:15]
	v_mfma_f32_16x16x32_bf16 v[8:11], v[120:123], v[202:205], v[8:11]
	v_mfma_f32_16x16x32_bf16 v[60:63], v[108:111], v[164:167], v[60:63]
	v_mfma_f32_16x16x32_bf16 v[56:59], v[128:131], v[164:167], v[56:59]
	v_mfma_f32_16x16x32_bf16 v[44:47], v[108:111], v[172:175], v[44:47]
	v_mfma_f32_16x16x32_bf16 v[40:43], v[128:131], v[172:175], v[40:43]
	v_mfma_f32_16x16x32_bf16 v[28:31], v[108:111], v[180:183], v[28:31]
	v_mfma_f32_16x16x32_bf16 v[24:27], v[128:131], v[180:183], v[24:27]
	v_mfma_f32_16x16x32_bf16 v[12:15], v[108:111], v[206:209], v[12:15]
	v_mfma_f32_16x16x32_bf16 v[8:11], v[128:131], v[206:209], v[8:11]
	v_mfma_f32_16x16x32_bf16 v[52:55], v[144:147], v[160:163], v[52:55]
	v_mfma_f32_16x16x32_bf16 v[48:51], v[152:155], v[160:163], v[48:51]
	v_mfma_f32_16x16x32_bf16 v[36:39], v[144:147], v[168:171], v[36:39]
	v_mfma_f32_16x16x32_bf16 v[32:35], v[152:155], v[168:171], v[32:35]
	v_mfma_f32_16x16x32_bf16 v[20:23], v[144:147], v[176:179], v[20:23]
	v_mfma_f32_16x16x32_bf16 v[16:19], v[152:155], v[176:179], v[16:19]
	v_mfma_f32_16x16x32_bf16 v[4:7], v[144:147], v[202:205], v[4:7]
	v_mfma_f32_16x16x32_bf16 v[0:3], v[152:155], v[202:205], v[0:3]
	v_mfma_f32_16x16x32_bf16 v[52:55], v[148:151], v[164:167], v[52:55]
	v_mfma_f32_16x16x32_bf16 v[48:51], v[156:159], v[164:167], v[48:51]
	v_mfma_f32_16x16x32_bf16 v[36:39], v[148:151], v[172:175], v[36:39]
	v_mfma_f32_16x16x32_bf16 v[32:35], v[156:159], v[172:175], v[32:35]
	v_mfma_f32_16x16x32_bf16 v[20:23], v[148:151], v[180:183], v[20:23]
	v_mfma_f32_16x16x32_bf16 v[16:19], v[156:159], v[180:183], v[16:19]
	v_mfma_f32_16x16x32_bf16 v[4:7], v[148:151], v[206:209], v[4:7]
	v_mfma_f32_16x16x32_bf16 v[0:3], v[156:159], v[206:209], v[0:3]
	s_setprio 0
	s_barrier
	s_add_i32 s70, s70, 2
	s_add_u32 s20, s20, 0x100
	s_addc_u32 s21, s21, 0
	s_add_u32 s68, s68, 0x100
	s_addc_u32 s69, s69, 0
	s_cmp_gt_u32 s70, 41
; #define PG8_STAGE(bufoff, gbase, voff) do { _Pragma("unroll") for (int _i = 0; _i < 2; ++_i) \
;         __builtin_amdgcn_global_load_lds((const unsigned*)((const char*)(gbase) + (voff)[_i]), (PG8_LAS unsigned*)(lds + (bufoff) + ldsw + _i * 8192), 16, 0, 0); } while (0)
; #define PG8_LDA(dst, b, h) do { _Pragma("unroll") for (int m = 0; m < 4; ++m) _Pragma("unroll") for (int k = 0; k < 2; ++k) dst[m][k] = *(const PG8_LAS bf16x8*)(lds + PG8_SA(b, h) + aoff + m * 2048 + k * 1024); } while (0)
; #define PG8_LDB(dst, b, h) do { _Pragma("unroll") for (int n = 0; n < 2; ++n) _Pragma("unroll") for (int k = 0; k < 2; ++k) dst[n][k] = *(const PG8_LAS bf16x8*)(lds + PG8_SB(b, h) + boff + n * 2048 + k * 1024); } while (0)
; #define PG8_MMA(ai, bj, At, Bt) do { __builtin_amdgcn_s_setprio(1); _Pragma("unroll") for (int m = 0; m < 4; ++m) _Pragma("unroll") for (int n = 0; n < 2; ++n) _Pragma("unroll") for (int k = 0; k < 2; ++k) \
;         acc[ai][bj][m][n] = __builtin_amdgcn_mfma_f32_16x16x32_bf16(Bt[n][k], At[m][k], acc[ai][bj][m][n], 0, 0, 0); __builtin_amdgcn_s_setprio(0); } while (0)
; #define PG8_WAIT_V(n) asm volatile("s_waitcnt vmcnt(" #n ")" ::: "memory")
; #define PG8_WAIT_L(n) asm volatile("s_waitcnt lgkmcnt(" #n ")" ::: "memory")
; #define PG8_BAR __builtin_amdgcn_s_barrier()
; #define PG8_SCHED __builtin_amdgcn_sched_barrier(0)
; template <class Epi, class Sched, bool ALIGN_EPI = false, bool SP2 = false>
; __device__ __forceinline__ void gemm_phase(PG8_LAS unsigned char* lds, const Gemm g, const Sched& S, const Epi& E) {
;     ...
;             PG8_LDB(B0, 0, 0); PG8_LDB(B1, 0, 1); PG8_SCHED; PG8_LDA(At, 0, 0); PG8_STAGE(PG8_SA(1, 1), a1 + hstep, voffA);
;             PG8_WAIT_V(8); PG8_WAIT_L(0); PG8_BAR; PG8_MMA(0, 0, At, B0); PG8_MMA(0, 1, At, B1); PG8_BAR; PG8_SCHED;
;             PG8_LDA(At, 0, 1); PG8_STAGE(PG8_SB(0, 0), b2, voffB); PG8_STAGE(PG8_SB(0, 1), b2 + hstep, voffB); PG8_STAGE(PG8_SA(0, 0), a2, voffA);
;             PG8_WAIT_V(8); PG8_WAIT_L(0); PG8_BAR; PG8_MMA(1, 0, At, B0); PG8_MMA(1, 1, At, B1); PG8_BAR; PG8_SCHED;
.LBB0_1825:
	ds_read_b128 v[96:99], v222
	ds_read_b128 v[108:111], v222 offset:1024
	ds_read_b128 v[120:123], v222 offset:2048
	ds_read_b128 v[128:131], v222 offset:3072
	ds_read_b128 v[144:147], v223
	ds_read_b128 v[148:151], v223 offset:1024
	ds_read_b128 v[152:155], v223 offset:2048
	ds_read_b128 v[156:159], v223 offset:3072
	s_add_u32 s34, s20, 0xfff50080
	s_addc_u32 s35, s21, -1
	s_cmp_eq_u32 s70, 40
	s_cselect_b32 s47, s1, s35
	s_cselect_b32 s46, s0, s34
	s_cselect_b32 s35, s45, s69
	s_cselect_b32 s34, s44, s68
	s_add_i32 m0, s49, 0xc000
	ds_read_b128 v[160:163], v224
	ds_read_b128 v[164:167], v224 offset:1024
	ds_read_b128 v[168:171], v224 offset:2048
	ds_read_b128 v[172:175], v224 offset:3072
	ds_read_b128 v[176:179], v224 offset:4096
	ds_read_b128 v[180:183], v224 offset:5120
	ds_read_b128 v[202:205], v224 offset:6144
	ds_read_b128 v[206:209], v224 offset:7168
	global_load_lds_dwordx4 v192, s[20:21]
	s_add_i32 m0, s49, 0xe000
	s_nop 0
	global_load_lds_dwordx4 v194, s[20:21]
	s_waitcnt vmcnt(8)
	s_waitcnt lgkmcnt(0)
	s_barrier
	s_setprio 1
	s_waitcnt lgkmcnt(0)
	v_mfma_f32_16x16x32_bf16 v[140:143], v[96:99], v[160:163], v[140:143]
	v_mfma_f32_16x16x32_bf16 v[136:139], v[120:123], v[160:163], v[136:139]
	v_mfma_f32_16x16x32_bf16 v[116:119], v[96:99], v[168:171], v[116:119]
	v_mfma_f32_16x16x32_bf16 v[112:115], v[120:123], v[168:171], v[112:115]
	v_mfma_f32_16x16x32_bf16 v[92:95], v[96:99], v[176:179], v[92:95]
	v_mfma_f32_16x16x32_bf16 v[88:91], v[120:123], v[176:179], v[88:91]
	v_mfma_f32_16x16x32_bf16 v[76:79], v[96:99], v[202:205], v[76:79]
	v_mfma_f32_16x16x32_bf16 v[72:75], v[120:123], v[202:205], v[72:75]
	v_mfma_f32_16x16x32_bf16 v[140:143], v[108:111], v[164:167], v[140:143]
	v_mfma_f32_16x16x32_bf16 v[136:139], v[128:131], v[164:167], v[136:139]
	v_mfma_f32_16x16x32_bf16 v[116:119], v[108:111], v[172:175], v[116:119]
	v_mfma_f32_16x16x32_bf16 v[112:115], v[128:131], v[172:175], v[112:115]
	v_mfma_f32_16x16x32_bf16 v[92:95], v[108:111], v[180:183], v[92:95]
	v_mfma_f32_16x16x32_bf16 v[88:91], v[128:131], v[180:183], v[88:91]
	v_mfma_f32_16x16x32_bf16 v[76:79], v[108:111], v[206:209], v[76:79]
	v_mfma_f32_16x16x32_bf16 v[72:75], v[128:131], v[206:209], v[72:75]
	v_mfma_f32_16x16x32_bf16 v[132:135], v[144:147], v[160:163], v[132:135]
	v_mfma_f32_16x16x32_bf16 v[124:127], v[152:155], v[160:163], v[124:127]
	v_mfma_f32_16x16x32_bf16 v[104:107], v[144:147], v[168:171], v[104:107]
	v_mfma_f32_16x16x32_bf16 v[100:103], v[152:155], v[168:171], v[100:103]
	v_mfma_f32_16x16x32_bf16 v[84:87], v[144:147], v[176:179], v[84:87]
	v_mfma_f32_16x16x32_bf16 v[80:83], v[152:155], v[176:179], v[80:83]
	v_mfma_f32_16x16x32_bf16 v[68:71], v[144:147], v[202:205], v[68:71]
	v_mfma_f32_16x16x32_bf16 v[64:67], v[152:155], v[202:205], v[64:67]
	v_mfma_f32_16x16x32_bf16 v[132:135], v[148:151], v[164:167], v[132:135]
	v_mfma_f32_16x16x32_bf16 v[124:127], v[156:159], v[164:167], v[124:127]
	v_mfma_f32_16x16x32_bf16 v[104:107], v[148:151], v[172:175], v[104:107]
	v_mfma_f32_16x16x32_bf16 v[100:103], v[156:159], v[172:175], v[100:103]
	v_mfma_f32_16x16x32_bf16 v[84:87], v[148:151], v[180:183], v[84:87]
	v_mfma_f32_16x16x32_bf16 v[80:83], v[156:159], v[180:183], v[80:83]
	v_mfma_f32_16x16x32_bf16 v[68:71], v[148:151], v[206:209], v[68:71]
	v_mfma_f32_16x16x32_bf16 v[64:67], v[156:159], v[206:209], v[64:67]
	s_setprio 0
	s_barrier
	s_add_i32 s71, s62, s48
	s_add_u32 s98, s34, s12
	s_addc_u32 s99, s35, s13
	s_add_u32 s100, s46, s12
	s_addc_u32 s101, s47, s13
	s_mov_b32 m0, s71
	ds_read_b128 v[160:163], v224 offset:16384
	ds_read_b128 v[164:167], v224 offset:17408
	ds_read_b128 v[168:171], v224 offset:18432
	ds_read_b128 v[172:175], v224 offset:19456
	ds_read_b128 v[176:179], v224 offset:20480
	ds_read_b128 v[180:183], v224 offset:21504
	ds_read_b128 v[202:205], v224 offset:22528
	ds_read_b128 v[206:209], v224 offset:23552
	global_load_lds_dwordx4 v186, s[34:35]
	s_add_i32 m0, s71, 0x2000
	s_add_u32 s72, s34, 0xb0000
	s_addc_u32 s73, s35, 0
	s_add_i32 s71, s63, s48
	global_load_lds_dwordx4 v190, s[34:35]
	s_mov_b32 m0, s71
	s_nop 0
	global_load_lds_dwordx4 v186, s[72:73]
	s_add_i32 m0, s71, 0x2000
	s_nop 0
	global_load_lds_dwordx4 v190, s[72:73]
	s_mov_b32 m0, s49
	s_nop 0
	global_load_lds_dwordx4 v184, s[46:47]
	s_mov_b32 m0, s50
	s_nop 0
	global_load_lds_dwordx4 v188, s[46:47]
	s_waitcnt vmcnt(8)
	s_waitcnt lgkmcnt(0)
	s_barrier
	s_setprio 1
	s_waitcnt lgkmcnt(0)
	v_mfma_f32_16x16x32_bf16 v[60:63], v[96:99], v[160:163], v[60:63]
	v_mfma_f32_16x16x32_bf16 v[56:59], v[120:123], v[160:163], v[56:59]
	v_mfma_f32_16x16x32_bf16 v[44:47], v[96:99], v[168:171], v[44:47]
	v_mfma_f32_16x16x32_bf16 v[40:43], v[120:123], v[168:171], v[40:43]
	v_mfma_f32_16x16x32_bf16 v[28:31], v[96:99], v[176:179], v[28:31]
	v_mfma_f32_16x16x32_bf16 v[24:27], v[120:123], v[176:179], v[24:27]
	v_mfma_f32_16x16x32_bf16 v[12:15], v[96:99], v[202:205], v[12:15]
	v_mfma_f32_16x16x32_bf16 v[8:11], v[120:123], v[202:205], v[8:11]
	v_mfma_f32_16x16x32_bf16 v[60:63], v[108:111], v[164:167], v[60:63]
	v_mfma_f32_16x16x32_bf16 v[56:59], v[128:131], v[164:167], v[56:59]
	v_mfma_f32_16x16x32_bf16 v[44:47], v[108:111], v[172:175], v[44:47]
	v_mfma_f32_16x16x32_bf16 v[40:43], v[128:131], v[172:175], v[40:43]
	v_mfma_f32_16x16x32_bf16 v[28:31], v[108:111], v[180:183], v[28:31]
	v_mfma_f32_16x16x32_bf16 v[24:27], v[128:131], v[180:183], v[24:27]
	v_mfma_f32_16x16x32_bf16 v[12:15], v[108:111], v[206:209], v[12:15]
	v_mfma_f32_16x16x32_bf16 v[8:11], v[128:131], v[206:209], v[8:11]
	v_mfma_f32_16x16x32_bf16 v[52:55], v[144:147], v[160:163], v[52:55]
	v_mfma_f32_16x16x32_bf16 v[48:51], v[152:155], v[160:163], v[48:51]
	v_mfma_f32_16x16x32_bf16 v[36:39], v[144:147], v[168:171], v[36:39]
	v_mfma_f32_16x16x32_bf16 v[32:35], v[152:155], v[168:171], v[32:35]
	v_mfma_f32_16x16x32_bf16 v[20:23], v[144:147], v[176:179], v[20:23]
	v_mfma_f32_16x16x32_bf16 v[16:19], v[152:155], v[176:179], v[16:19]
	v_mfma_f32_16x16x32_bf16 v[4:7], v[144:147], v[202:205], v[4:7]
	v_mfma_f32_16x16x32_bf16 v[0:3], v[152:155], v[202:205], v[0:3]
	v_mfma_f32_16x16x32_bf16 v[52:55], v[148:151], v[164:167], v[52:55]
	v_mfma_f32_16x16x32_bf16 v[48:51], v[156:159], v[164:167], v[48:51]
	v_mfma_f32_16x16x32_bf16 v[36:39], v[148:151], v[172:175], v[36:39]
	v_mfma_f32_16x16x32_bf16 v[32:35], v[156:159], v[172:175], v[32:35]
	v_mfma_f32_16x16x32_bf16 v[20:23], v[148:151], v[180:183], v[20:23]
	v_mfma_f32_16x16x32_bf16 v[16:19], v[156:159], v[180:183], v[16:19]
	v_mfma_f32_16x16x32_bf16 v[4:7], v[148:151], v[206:209], v[4:7]
	v_mfma_f32_16x16x32_bf16 v[0:3], v[156:159], v[206:209], v[0:3]
	s_setprio 0
	s_barrier
; #define PG8_STAGE(bufoff, gbase, voff) do { _Pragma("unroll") for (int _i = 0; _i < 2; ++_i) \
;         __builtin_amdgcn_global_load_lds((const unsigned*)((const char*)(gbase) + (voff)[_i]), (PG8_LAS unsigned*)(lds + (bufoff) + ldsw + _i * 8192), 16, 0, 0); } while (0)
; #define PG8_LDA(dst, b, h) do { _Pragma("unroll") for (int m = 0; m < 4; ++m) _Pragma("unroll") for (int k = 0; k < 2; ++k) dst[m][k] = *(const PG8_LAS bf16x8*)(lds + PG8_SA(b, h) + aoff + m * 2048 + k * 1024); } while (0)
; #define PG8_LDB(dst, b, h) do { _Pragma("unroll") for (int n = 0; n < 2; ++n) _Pragma("unroll") for (int k = 0; k < 2; ++k) dst[n][k] = *(const PG8_LAS bf16x8*)(lds + PG8_SB(b, h) + boff + n * 2048 + k * 1024); } while (0)
; #define PG8_MMA(ai, bj, At, Bt) do { __builtin_amdgcn_s_setprio(1); _Pragma("unroll") for (int m = 0; m < 4; ++m) _Pragma("unroll") for (int n = 0; n < 2; ++n) _Pragma("unroll") for (int k = 0; k < 2; ++k) \
;         acc[ai][bj][m][n] = __builtin_amdgcn_mfma_f32_16x16x32_bf16(Bt[n][k], At[m][k], acc[ai][bj][m][n], 0, 0, 0); __builtin_amdgcn_s_setprio(0); } while (0)
; #define PG8_WAIT_V(n) asm volatile("s_waitcnt vmcnt(" #n ")" ::: "memory")
; #define PG8_WAIT_L(n) asm volatile("s_waitcnt lgkmcnt(" #n ")" ::: "memory")
; #define PG8_BAR __builtin_amdgcn_s_barrier()
; #define PG8_SCHED __builtin_amdgcn_sched_barrier(0)
; template <class Epi, class Sched, bool ALIGN_EPI = false, bool SP2 = false>
; __device__ __forceinline__ void gemm_phase(PG8_LAS unsigned char* lds, const Gemm g, const Sched& S, const Epi& E) {
;     ...
;         for (int t = 0; t < nt; t += 2) {
;     ...
;             PG8_LDB(B0, 1, 0); PG8_LDB(B1, 1, 1); PG8_SCHED; PG8_LDA(At, 1, 0); PG8_STAGE(PG8_SA(0, 1), a2 + hstep, voffA);
;             PG8_WAIT_V(8); PG8_WAIT_L(0); PG8_BAR; PG8_MMA(0, 0, At, B0); PG8_MMA(0, 1, At, B1); PG8_BAR; PG8_SCHED;
;             PG8_LDA(At, 1, 1); PG8_STAGE(PG8_SB(1, 0), b3, voffB); PG8_STAGE(PG8_SB(1, 1), b3 + hstep, voffB); PG8_STAGE(PG8_SA(1, 0), a3, voffA);
;             PG8_WAIT_V(8); PG8_WAIT_L(0); PG8_BAR; PG8_MMA(1, 0, At, B0); PG8_MMA(1, 1, At, B1); PG8_BAR; PG8_SCHED;
;     ...
;         if constexpr (ALIGN_EPI) { if (wr == 0) PG8_BAR; }
	s_add_i32 s71, 0, 0x18000
	s_add_i32 s72, 0, 0x1c000
	v_add_u32_e32 v128, s71, v197
	v_add_u32_e32 v156, s72, v197
	ds_read_b128 v[96:99], v128
	ds_read_b128 v[108:111], v128 offset:1024
	ds_read_b128 v[120:123], v128 offset:2048
	ds_read_b128 v[128:131], v128 offset:3072
	ds_read_b128 v[144:147], v156
	ds_read_b128 v[148:151], v156 offset:1024
	ds_read_b128 v[152:155], v156 offset:2048
	ds_read_b128 v[156:159], v156 offset:3072
	s_add_u32 s46, s46, 0xb0000
	s_addc_u32 s47, s47, 0
	s_mov_b32 m0, s51
	ds_read_b128 v[160:163], v224 offset:32768
	ds_read_b128 v[164:167], v224 offset:33792
	ds_read_b128 v[168:171], v224 offset:34816
	ds_read_b128 v[172:175], v224 offset:35840
	ds_read_b128 v[176:179], v224 offset:36864
	ds_read_b128 v[180:183], v224 offset:37888
	ds_read_b128 v[202:205], v224 offset:38912
	ds_read_b128 v[206:209], v224 offset:39936
	global_load_lds_dwordx4 v184, s[46:47]
	s_mov_b32 m0, s52
	s_nop 0
	global_load_lds_dwordx4 v188, s[46:47]
	s_waitcnt vmcnt(8)
	s_waitcnt lgkmcnt(0)
	s_barrier
	s_setprio 1
	s_waitcnt lgkmcnt(0)
	v_mfma_f32_16x16x32_bf16 v[140:143], v[96:99], v[160:163], v[140:143]
	v_mfma_f32_16x16x32_bf16 v[136:139], v[120:123], v[160:163], v[136:139]
	v_mfma_f32_16x16x32_bf16 v[116:119], v[96:99], v[168:171], v[116:119]
	v_mfma_f32_16x16x32_bf16 v[112:115], v[120:123], v[168:171], v[112:115]
	v_mfma_f32_16x16x32_bf16 v[92:95], v[96:99], v[176:179], v[92:95]
	v_mfma_f32_16x16x32_bf16 v[88:91], v[120:123], v[176:179], v[88:91]
	v_mfma_f32_16x16x32_bf16 v[76:79], v[96:99], v[202:205], v[76:79]
	v_mfma_f32_16x16x32_bf16 v[72:75], v[120:123], v[202:205], v[72:75]
	v_mfma_f32_16x16x32_bf16 v[140:143], v[108:111], v[164:167], v[140:143]
	v_mfma_f32_16x16x32_bf16 v[136:139], v[128:131], v[164:167], v[136:139]
	v_mfma_f32_16x16x32_bf16 v[116:119], v[108:111], v[172:175], v[116:119]
	v_mfma_f32_16x16x32_bf16 v[112:115], v[128:131], v[172:175], v[112:115]
	v_mfma_f32_16x16x32_bf16 v[92:95], v[108:111], v[180:183], v[92:95]
	v_mfma_f32_16x16x32_bf16 v[88:91], v[128:131], v[180:183], v[88:91]
	v_mfma_f32_16x16x32_bf16 v[76:79], v[108:111], v[206:209], v[76:79]
	v_mfma_f32_16x16x32_bf16 v[72:75], v[128:131], v[206:209], v[72:75]
	v_mfma_f32_16x16x32_bf16 v[132:135], v[144:147], v[160:163], v[132:135]
	v_mfma_f32_16x16x32_bf16 v[124:127], v[152:155], v[160:163], v[124:127]
	v_mfma_f32_16x16x32_bf16 v[104:107], v[144:147], v[168:171], v[104:107]
	v_mfma_f32_16x16x32_bf16 v[100:103], v[152:155], v[168:171], v[100:103]
	v_mfma_f32_16x16x32_bf16 v[84:87], v[144:147], v[176:179], v[84:87]
	v_mfma_f32_16x16x32_bf16 v[80:83], v[152:155], v[176:179], v[80:83]
	v_mfma_f32_16x16x32_bf16 v[68:71], v[144:147], v[202:205], v[68:71]
	v_mfma_f32_16x16x32_bf16 v[64:67], v[152:155], v[202:205], v[64:67]
	v_mfma_f32_16x16x32_bf16 v[132:135], v[148:151], v[164:167], v[132:135]
	v_mfma_f32_16x16x32_bf16 v[124:127], v[156:159], v[164:167], v[124:127]
	v_mfma_f32_16x16x32_bf16 v[104:107], v[148:151], v[172:175], v[104:107]
	v_mfma_f32_16x16x32_bf16 v[100:103], v[156:159], v[172:175], v[100:103]
	v_mfma_f32_16x16x32_bf16 v[84:87], v[148:151], v[180:183], v[84:87]
	v_mfma_f32_16x16x32_bf16 v[80:83], v[156:159], v[180:183], v[80:83]
	v_mfma_f32_16x16x32_bf16 v[68:71], v[148:151], v[206:209], v[68:71]
	v_mfma_f32_16x16x32_bf16 v[64:67], v[156:159], v[206:209], v[64:67]
	s_setprio 0
	s_barrier
	s_add_i32 s46, s71, s48
	s_mov_b32 m0, s46
	ds_read_b128 v[160:163], v224 offset:49152
	ds_read_b128 v[164:167], v224 offset:50176
	ds_read_b128 v[168:171], v224 offset:51200
	ds_read_b128 v[172:175], v224 offset:52224
	ds_read_b128 v[176:179], v224 offset:53248
	ds_read_b128 v[180:183], v224 offset:54272
	ds_read_b128 v[202:205], v224 offset:55296
	ds_read_b128 v[206:209], v224 offset:56320
	global_load_lds_dwordx4 v186, s[98:99]
	s_add_i32 m0, s46, 0x2000
	s_add_u32 s34, s34, 0xb0080
	s_addc_u32 s35, s35, 0
	s_add_i32 s46, s72, s48
	global_load_lds_dwordx4 v190, s[98:99]
	s_mov_b32 m0, s46
	s_nop 0
	global_load_lds_dwordx4 v186, s[34:35]
	s_add_i32 m0, s46, 0x2000
	s_nop 0
	global_load_lds_dwordx4 v190, s[34:35]
	s_mov_b32 m0, s57
	s_nop 0
	global_load_lds_dwordx4 v184, s[100:101]
	s_mov_b32 m0, s58
	s_nop 0
	global_load_lds_dwordx4 v188, s[100:101]
	s_waitcnt vmcnt(8)
	s_waitcnt lgkmcnt(0)
	s_barrier
	s_setprio 1
	s_waitcnt lgkmcnt(0)
	v_mfma_f32_16x16x32_bf16 v[60:63], v[96:99], v[160:163], v[60:63]
	v_mfma_f32_16x16x32_bf16 v[56:59], v[120:123], v[160:163], v[56:59]
	v_mfma_f32_16x16x32_bf16 v[44:47], v[96:99], v[168:171], v[44:47]
	v_mfma_f32_16x16x32_bf16 v[40:43], v[120:123], v[168:171], v[40:43]
	v_mfma_f32_16x16x32_bf16 v[28:31], v[96:99], v[176:179], v[28:31]
	v_mfma_f32_16x16x32_bf16 v[24:27], v[120:123], v[176:179], v[24:27]
	v_mfma_f32_16x16x32_bf16 v[12:15], v[96:99], v[202:205], v[12:15]
	v_mfma_f32_16x16x32_bf16 v[8:11], v[120:123], v[202:205], v[8:11]
	v_mfma_f32_16x16x32_bf16 v[60:63], v[108:111], v[164:167], v[60:63]
	v_mfma_f32_16x16x32_bf16 v[56:59], v[128:131], v[164:167], v[56:59]
	v_mfma_f32_16x16x32_bf16 v[44:47], v[108:111], v[172:175], v[44:47]
	v_mfma_f32_16x16x32_bf16 v[40:43], v[128:131], v[172:175], v[40:43]
	v_mfma_f32_16x16x32_bf16 v[28:31], v[108:111], v[180:183], v[28:31]
	v_mfma_f32_16x16x32_bf16 v[24:27], v[128:131], v[180:183], v[24:27]
	v_mfma_f32_16x16x32_bf16 v[12:15], v[108:111], v[206:209], v[12:15]
	v_mfma_f32_16x16x32_bf16 v[8:11], v[128:131], v[206:209], v[8:11]
	v_mfma_f32_16x16x32_bf16 v[52:55], v[144:147], v[160:163], v[52:55]
	v_mfma_f32_16x16x32_bf16 v[48:51], v[152:155], v[160:163], v[48:51]
	v_mfma_f32_16x16x32_bf16 v[36:39], v[144:147], v[168:171], v[36:39]
	v_mfma_f32_16x16x32_bf16 v[32:35], v[152:155], v[168:171], v[32:35]
	v_mfma_f32_16x16x32_bf16 v[20:23], v[144:147], v[176:179], v[20:23]
	v_mfma_f32_16x16x32_bf16 v[16:19], v[152:155], v[176:179], v[16:19]
	v_mfma_f32_16x16x32_bf16 v[4:7], v[144:147], v[202:205], v[4:7]
	v_mfma_f32_16x16x32_bf16 v[0:3], v[152:155], v[202:205], v[0:3]
	v_mfma_f32_16x16x32_bf16 v[52:55], v[148:151], v[164:167], v[52:55]
	v_mfma_f32_16x16x32_bf16 v[48:51], v[156:159], v[164:167], v[48:51]
	v_mfma_f32_16x16x32_bf16 v[36:39], v[148:151], v[172:175], v[36:39]
	v_mfma_f32_16x16x32_bf16 v[32:35], v[156:159], v[172:175], v[32:35]
	v_mfma_f32_16x16x32_bf16 v[20:23], v[148:151], v[180:183], v[20:23]
	v_mfma_f32_16x16x32_bf16 v[16:19], v[156:159], v[180:183], v[16:19]
	v_mfma_f32_16x16x32_bf16 v[4:7], v[148:151], v[206:209], v[4:7]
	v_mfma_f32_16x16x32_bf16 v[0:3], v[156:159], v[206:209], v[0:3]
	s_setprio 0
	s_barrier
	s_add_i32 s70, s70, 2
	s_add_u32 s20, s20, 0x100
	s_addc_u32 s21, s21, 0
	s_add_u32 s68, s68, 0x100
	s_addc_u32 s69, s69, 0
	s_cmp_gt_u32 s70, 41
	s_cbranch_scc0 .LBB0_1825
	s_and_b64 vcc, exec, s[14:15]
	s_cbranch_vccz .LBB0_1828
	s_barrier
